# norm-pass output stores marked sc1 (write-through) so less dirty L2 remains for the grid barrier's writeback
# baseline (speedup 1.0000x reference)
; __device__ __forceinline__ unsigned cvt_pk_bf16(float lo, float hi) { unsigned r; asm("v_cvt_pk_bf16_f32 %0, %1, %2" : "=v"(r) : "v"(lo), "v"(hi)); return r; }
; __device__ __forceinline__ void norm_pass(const Ctx& X, const float* xs, const float* cs, int nrows, const float* gain, const float* modl, int si, bf16_t* HN) {
;     for (int r = X.gw; r < nrows; r += X.NGW) {
;         const float* row = r < MX ? xs + (size_t)r * D : cs + (size_t)(r - MX) * D;
;         const int mb = r < MX ? (r >> 12) : 8;
;         const float* sh = modl + (size_t)mb * 9216 + si * 1024; const float* scl = sh + 1024;
;         f32x4 v[4]; float s = 0.f;
; #pragma unroll
;         for (int j = 0; j < 4; ++j) { v[j] = *(const f32x4*)(row + (X.lane + 64 * j) * 4); s += (v[j].x * v[j].x + v[j].y * v[j].y) + (v[j].z * v[j].z + v[j].w * v[j].w); }
;         const float rstd = rsqrtf(wave_sum(s) * (1.0f / 1024.0f) + 1e-6f);
; #pragma unroll
;         for (int j = 0; j < 4; ++j) { const int c = (X.lane + 64 * j) * 4; const f32x4 gn = *(const f32x4*)(gain + c), a = *(const f32x4*)(scl + c), b = *(const f32x4*)(sh + c);
;             const f32x4 o = v[j] * rstd * gn * (a + 1.0f) + b; u32x2 w; w.x = cvt_pk_bf16(o.x, o.y); w.y = cvt_pk_bf16(o.z, o.w); *(u32x2*)(HN + (size_t)r * D + c) = w; }
.Lhn32_blk:
	global_load_dwordx4 v[16:19], v2, s[48:49]
	global_load_dwordx4 v[20:23], v2, s[48:49] offset:16
	global_load_dwordx4 v[24:27], v2, s[48:49] offset:2048
	global_load_dwordx4 v[28:31], v2, s[48:49] offset:2064
	s_lshr_b32 s1, s14, 8
	s_mul_i32 s1, s1, 0x9000
	s_add_u32 s4, s88, s1
	s_addc_u32 s5, s89, 0
	global_load_dwordx4 v[48:51], v2, s[4:5]
	global_load_dwordx4 v[52:55], v2, s[4:5] offset:16
	global_load_dwordx4 v[56:59], v2, s[4:5] offset:2048
	global_load_dwordx4 v[60:63], v2, s[4:5] offset:2064
	s_add_u32 s4, s4, 0x1000
	s_addc_u32 s5, s5, 0
	global_load_dwordx4 v[32:35], v2, s[4:5]
	global_load_dwordx4 v[36:39], v2, s[4:5] offset:16
	global_load_dwordx4 v[40:43], v2, s[4:5] offset:2048
	global_load_dwordx4 v[44:47], v2, s[4:5] offset:2064
	s_add_u32 s4, s88, 0x48000
	s_addc_u32 s5, s89, 0
	global_load_dwordx4 v[176:179], v2, s[4:5]
	global_load_dwordx4 v[180:183], v2, s[4:5] offset:16
	global_load_dwordx4 v[184:187], v2, s[4:5] offset:2048
	global_load_dwordx4 v[188:191], v2, s[4:5] offset:2064
	s_add_u32 s4, s4, 0x1000
	s_addc_u32 s5, s5, 0
	global_load_dwordx4 v[160:163], v2, s[4:5]
	global_load_dwordx4 v[164:167], v2, s[4:5] offset:16
	global_load_dwordx4 v[168:171], v2, s[4:5] offset:2048
	global_load_dwordx4 v[172:175], v2, s[4:5] offset:2064
	s_lshl_b32 s1, s14, 16
	s_add_u32 s6, s36, s1
	s_addc_u32 s7, s37, 0
	s_lshl_b32 s1, s14, 15
	s_add_u32 s8, s18, s1
	s_addc_u32 s9, s19, 0
	s_lshl_b32 s1, s14, 12
	s_add_u32 s10, s40, s1
	s_addc_u32 s11, s41, 0
	s_lshl_b32 s1, s14, 11
	s_add_u32 s12, s18, s1
	s_addc_u32 s13, s19, 0
	s_add_u32 s12, s12, 0x4000000
	s_addc_u32 s13, s13, 0
	global_load_dwordx4 v[64:67], v2, s[6:7]
	global_load_dwordx4 v[68:71], v2, s[6:7] offset:16
	global_load_dwordx4 v[72:75], v2, s[6:7] offset:2048
	global_load_dwordx4 v[76:79], v2, s[6:7] offset:2064
	s_add_u32 s6, s6, 0x1000
	s_addc_u32 s7, s7, 0
	global_load_dwordx4 v[80:83], v2, s[6:7]
	global_load_dwordx4 v[84:87], v2, s[6:7] offset:16
	global_load_dwordx4 v[88:91], v2, s[6:7] offset:2048
	global_load_dwordx4 v[92:95], v2, s[6:7] offset:2064
	s_add_u32 s6, s6, 0x1000
	s_addc_u32 s7, s7, 0
	global_load_dwordx4 v[96:99], v2, s[6:7]
	global_load_dwordx4 v[100:103], v2, s[6:7] offset:16
	global_load_dwordx4 v[104:107], v2, s[6:7] offset:2048
	global_load_dwordx4 v[108:111], v2, s[6:7] offset:2064
	s_add_u32 s6, s6, 0x1000
	s_addc_u32 s7, s7, 0
	global_load_dwordx4 v[112:115], v2, s[6:7]
	global_load_dwordx4 v[116:119], v2, s[6:7] offset:16
	global_load_dwordx4 v[120:123], v2, s[6:7] offset:2048
	global_load_dwordx4 v[124:127], v2, s[6:7] offset:2064
	s_add_u32 s6, s6, 0x1000
	s_addc_u32 s7, s7, 0
	global_load_dwordx4 v[128:131], v2, s[6:7]
	global_load_dwordx4 v[132:135], v2, s[6:7] offset:16
	global_load_dwordx4 v[136:139], v2, s[6:7] offset:2048
	global_load_dwordx4 v[140:143], v2, s[6:7] offset:2064
	s_add_u32 s6, s6, 0x1000
	s_addc_u32 s7, s7, 0
	global_load_dwordx4 v[144:147], v2, s[6:7]
	global_load_dwordx4 v[148:151], v2, s[6:7] offset:16
	global_load_dwordx4 v[152:155], v2, s[6:7] offset:2048
	global_load_dwordx4 v[156:159], v2, s[6:7] offset:2064
	s_add_u32 s6, s6, 0x1000
	s_addc_u32 s7, s7, 0
	s_waitcnt vmcnt(24)
	v_pk_add_f32 v[32:33], v[32:33], 1.0 op_sel_hi:[1,0]
	v_pk_add_f32 v[34:35], v[34:35], 1.0 op_sel_hi:[1,0]
	v_pk_add_f32 v[36:37], v[36:37], 1.0 op_sel_hi:[1,0]
	v_pk_add_f32 v[38:39], v[38:39], 1.0 op_sel_hi:[1,0]
	v_pk_add_f32 v[40:41], v[40:41], 1.0 op_sel_hi:[1,0]
	v_pk_add_f32 v[42:43], v[42:43], 1.0 op_sel_hi:[1,0]
	v_pk_add_f32 v[44:45], v[44:45], 1.0 op_sel_hi:[1,0]
	v_pk_add_f32 v[46:47], v[46:47], 1.0 op_sel_hi:[1,0]
	v_pk_add_f32 v[160:161], v[160:161], 1.0 op_sel_hi:[1,0]
	v_pk_add_f32 v[162:163], v[162:163], 1.0 op_sel_hi:[1,0]
	v_pk_add_f32 v[164:165], v[164:165], 1.0 op_sel_hi:[1,0]
	v_pk_add_f32 v[166:167], v[166:167], 1.0 op_sel_hi:[1,0]
	v_pk_add_f32 v[168:169], v[168:169], 1.0 op_sel_hi:[1,0]
	v_pk_add_f32 v[170:171], v[170:171], 1.0 op_sel_hi:[1,0]
	v_pk_add_f32 v[172:173], v[172:173], 1.0 op_sel_hi:[1,0]
	v_pk_add_f32 v[174:175], v[174:175], 1.0 op_sel_hi:[1,0]
	s_waitcnt vmcnt(20)
	v_pk_mul_f32 v[200:201], v[64:65], v[64:65]
	v_pk_fma_f32 v[200:201], v[66:67], v[66:67], v[200:201]
	v_pk_fma_f32 v[200:201], v[68:69], v[68:69], v[200:201]
	v_pk_fma_f32 v[200:201], v[70:71], v[70:71], v[200:201]
	v_pk_fma_f32 v[200:201], v[72:73], v[72:73], v[200:201]
	v_pk_fma_f32 v[200:201], v[74:75], v[74:75], v[200:201]
	v_pk_fma_f32 v[200:201], v[76:77], v[76:77], v[200:201]
	v_pk_fma_f32 v[200:201], v[78:79], v[78:79], v[200:201]
	v_add_f32_e32 v200, v200, v201
	s_nop 1
	v_add_f32_dpp v200, v200, v200 quad_perm:[1,0,3,2] row_mask:0xf bank_mask:0xf
	s_nop 1
	v_add_f32_dpp v200, v200, v200 quad_perm:[2,3,0,1] row_mask:0xf bank_mask:0xf
	s_nop 1
	v_add_f32_dpp v200, v200, v200 row_half_mirror row_mask:0xf bank_mask:0xf
	s_nop 1
	v_add_f32_dpp v200, v200, v200 row_mirror row_mask:0xf bank_mask:0xf
	s_nop 1
	v_mov_b32_e32 v201, v200
	s_nop 1
	v_permlane16_swap_b32_e32 v200, v201
	s_nop 0
	v_add_f32_e32 v200, v200, v201
	v_mov_b32_e32 v201, v200
	s_nop 1
	v_permlane32_swap_b32_e32 v200, v201
	s_nop 0
	v_add_f32_e32 v200, v200, v201
	v_fmamk_f32 v200, v200, 0x3a800000, v3
	v_rsq_f32_e32 v200, v200
	s_nop 0
	v_pk_mul_f32 v[64:65], v[64:65], v[200:201] op_sel_hi:[1,0]
	v_pk_mul_f32 v[66:67], v[66:67], v[200:201] op_sel_hi:[1,0]
	v_pk_mul_f32 v[68:69], v[68:69], v[200:201] op_sel_hi:[1,0]
	v_pk_mul_f32 v[70:71], v[70:71], v[200:201] op_sel_hi:[1,0]
	v_pk_mul_f32 v[72:73], v[72:73], v[200:201] op_sel_hi:[1,0]
	v_pk_mul_f32 v[74:75], v[74:75], v[200:201] op_sel_hi:[1,0]
	v_pk_mul_f32 v[76:77], v[76:77], v[200:201] op_sel_hi:[1,0]
; __device__ __forceinline__ unsigned cvt_pk_bf16(float lo, float hi) { unsigned r; asm("v_cvt_pk_bf16_f32 %0, %1, %2" : "=v"(r) : "v"(lo), "v"(hi)); return r; }
; __device__ __forceinline__ void norm_pass(const Ctx& X, const float* xs, const float* cs, int nrows, const float* gain, const float* modl, int si, bf16_t* HN) {
;     ...
;         f32x4 v[4]; float s = 0.f;
; #pragma unroll
;         for (int j = 0; j < 4; ++j) { v[j] = *(const f32x4*)(row + (X.lane + 64 * j) * 4); s += (v[j].x * v[j].x + v[j].y * v[j].y) + (v[j].z * v[j].z + v[j].w * v[j].w); }
;         const float rstd = rsqrtf(wave_sum(s) * (1.0f / 1024.0f) + 1e-6f);
; #pragma unroll
;         for (int j = 0; j < 4; ++j) { const int c = (X.lane + 64 * j) * 4; const f32x4 gn = *(const f32x4*)(gain + c), a = *(const f32x4*)(scl + c), b = *(const f32x4*)(sh + c);
;             const f32x4 o = v[j] * rstd * gn * (a + 1.0f) + b; u32x2 w; w.x = cvt_pk_bf16(o.x, o.y); w.y = cvt_pk_bf16(o.z, o.w); *(u32x2*)(HN + (size_t)r * D + c) = w; }
	v_pk_mul_f32 v[78:79], v[78:79], v[200:201] op_sel_hi:[1,0]
	v_pk_mul_f32 v[64:65], v[16:17], v[64:65]
	v_pk_mul_f32 v[66:67], v[18:19], v[66:67]
	v_pk_mul_f32 v[68:69], v[20:21], v[68:69]
	v_pk_mul_f32 v[70:71], v[22:23], v[70:71]
	v_pk_mul_f32 v[72:73], v[24:25], v[72:73]
	v_pk_mul_f32 v[74:75], v[26:27], v[74:75]
	v_pk_mul_f32 v[76:77], v[28:29], v[76:77]
	v_pk_mul_f32 v[78:79], v[30:31], v[78:79]
	v_pk_fma_f32 v[64:65], v[32:33], v[64:65], v[48:49]
	v_pk_fma_f32 v[66:67], v[34:35], v[66:67], v[50:51]
	v_pk_fma_f32 v[68:69], v[36:37], v[68:69], v[52:53]
	v_pk_fma_f32 v[70:71], v[38:39], v[70:71], v[54:55]
	v_pk_fma_f32 v[72:73], v[40:41], v[72:73], v[56:57]
	v_pk_fma_f32 v[74:75], v[42:43], v[74:75], v[58:59]
	v_pk_fma_f32 v[76:77], v[44:45], v[76:77], v[60:61]
	v_pk_fma_f32 v[78:79], v[46:47], v[78:79], v[62:63]
	v_cvt_pk_bf16_f32 v192, v64, v65
	v_cvt_pk_bf16_f32 v193, v66, v67
	v_cvt_pk_bf16_f32 v194, v68, v69
	v_cvt_pk_bf16_f32 v195, v70, v71
	v_cvt_pk_bf16_f32 v196, v72, v73
	v_cvt_pk_bf16_f32 v197, v74, v75
	v_cvt_pk_bf16_f32 v198, v76, v77
	v_cvt_pk_bf16_f32 v199, v78, v79
	global_store_dwordx4 v1, v[192:195], s[8:9] sc1
	global_store_dwordx4 v1, v[196:199], s[8:9] offset:1024 sc1
	global_load_dwordx4 v[64:67], v2, s[6:7]
	global_load_dwordx4 v[68:71], v2, s[6:7] offset:16
	global_load_dwordx4 v[72:75], v2, s[6:7] offset:2048
	global_load_dwordx4 v[76:79], v2, s[6:7] offset:2064
	s_add_u32 s6, s6, 0x1000
	s_addc_u32 s7, s7, 0
	s_waitcnt vmcnt(22)
	v_pk_mul_f32 v[200:201], v[80:81], v[80:81]
	v_pk_fma_f32 v[200:201], v[82:83], v[82:83], v[200:201]
	v_pk_fma_f32 v[200:201], v[84:85], v[84:85], v[200:201]
	v_pk_fma_f32 v[200:201], v[86:87], v[86:87], v[200:201]
	v_pk_fma_f32 v[200:201], v[88:89], v[88:89], v[200:201]
	v_pk_fma_f32 v[200:201], v[90:91], v[90:91], v[200:201]
	v_pk_fma_f32 v[200:201], v[92:93], v[92:93], v[200:201]
	v_pk_fma_f32 v[200:201], v[94:95], v[94:95], v[200:201]
	v_add_f32_e32 v200, v200, v201
	s_nop 1
	v_add_f32_dpp v200, v200, v200 quad_perm:[1,0,3,2] row_mask:0xf bank_mask:0xf
	s_nop 1
	v_add_f32_dpp v200, v200, v200 quad_perm:[2,3,0,1] row_mask:0xf bank_mask:0xf
	s_nop 1
	v_add_f32_dpp v200, v200, v200 row_half_mirror row_mask:0xf bank_mask:0xf
	s_nop 1
	v_add_f32_dpp v200, v200, v200 row_mirror row_mask:0xf bank_mask:0xf
	s_nop 1
	v_mov_b32_e32 v201, v200
	s_nop 1
	v_permlane16_swap_b32_e32 v200, v201
	s_nop 0
	v_add_f32_e32 v200, v200, v201
	v_mov_b32_e32 v201, v200
	s_nop 1
	v_permlane32_swap_b32_e32 v200, v201
	s_nop 0
	v_add_f32_e32 v200, v200, v201
	v_fmamk_f32 v200, v200, 0x3a800000, v3
	v_rsq_f32_e32 v200, v200
	s_nop 0
	v_pk_mul_f32 v[80:81], v[80:81], v[200:201] op_sel_hi:[1,0]
	v_pk_mul_f32 v[82:83], v[82:83], v[200:201] op_sel_hi:[1,0]
	v_pk_mul_f32 v[84:85], v[84:85], v[200:201] op_sel_hi:[1,0]
	v_pk_mul_f32 v[86:87], v[86:87], v[200:201] op_sel_hi:[1,0]
	v_pk_mul_f32 v[88:89], v[88:89], v[200:201] op_sel_hi:[1,0]
	v_pk_mul_f32 v[90:91], v[90:91], v[200:201] op_sel_hi:[1,0]
	v_pk_mul_f32 v[92:93], v[92:93], v[200:201] op_sel_hi:[1,0]
	v_pk_mul_f32 v[94:95], v[94:95], v[200:201] op_sel_hi:[1,0]
	v_pk_mul_f32 v[80:81], v[16:17], v[80:81]
	v_pk_mul_f32 v[82:83], v[18:19], v[82:83]
	v_pk_mul_f32 v[84:85], v[20:21], v[84:85]
	v_pk_mul_f32 v[86:87], v[22:23], v[86:87]
	v_pk_mul_f32 v[88:89], v[24:25], v[88:89]
	v_pk_mul_f32 v[90:91], v[26:27], v[90:91]
	v_pk_mul_f32 v[92:93], v[28:29], v[92:93]
	v_pk_mul_f32 v[94:95], v[30:31], v[94:95]
	v_pk_fma_f32 v[80:81], v[32:33], v[80:81], v[48:49]
	v_pk_fma_f32 v[82:83], v[34:35], v[82:83], v[50:51]
	v_pk_fma_f32 v[84:85], v[36:37], v[84:85], v[52:53]
	v_pk_fma_f32 v[86:87], v[38:39], v[86:87], v[54:55]
	v_pk_fma_f32 v[88:89], v[40:41], v[88:89], v[56:57]
	v_pk_fma_f32 v[90:91], v[42:43], v[90:91], v[58:59]
	v_pk_fma_f32 v[92:93], v[44:45], v[92:93], v[60:61]
	v_pk_fma_f32 v[94:95], v[46:47], v[94:95], v[62:63]
	v_cvt_pk_bf16_f32 v192, v80, v81
	v_cvt_pk_bf16_f32 v193, v82, v83
	v_cvt_pk_bf16_f32 v194, v84, v85
	v_cvt_pk_bf16_f32 v195, v86, v87
	v_cvt_pk_bf16_f32 v196, v88, v89
	v_cvt_pk_bf16_f32 v197, v90, v91
	v_cvt_pk_bf16_f32 v198, v92, v93
	v_cvt_pk_bf16_f32 v199, v94, v95
	global_store_dwordx4 v1, v[192:195], s[8:9] offset:2048 sc1
	global_store_dwordx4 v1, v[196:199], s[8:9] offset:3072 sc1
	s_add_u32 s8, s8, 0x1000
	s_addc_u32 s9, s9, 0
	global_load_dwordx4 v[80:83], v2, s[6:7]
	global_load_dwordx4 v[84:87], v2, s[6:7] offset:16
	global_load_dwordx4 v[88:91], v2, s[6:7] offset:2048
	global_load_dwordx4 v[92:95], v2, s[6:7] offset:2064
	s_add_u32 s6, s6, 0x1000
	s_addc_u32 s7, s7, 0
	s_waitcnt vmcnt(24)
; __device__ __forceinline__ unsigned cvt_pk_bf16(float lo, float hi) { unsigned r; asm("v_cvt_pk_bf16_f32 %0, %1, %2" : "=v"(r) : "v"(lo), "v"(hi)); return r; }
; __device__ __forceinline__ void norm_pass(const Ctx& X, const float* xs, const float* cs, int nrows, const float* gain, const float* modl, int si, bf16_t* HN) {
;     ...
;         f32x4 v[4]; float s = 0.f;
; #pragma unroll
;         for (int j = 0; j < 4; ++j) { v[j] = *(const f32x4*)(row + (X.lane + 64 * j) * 4); s += (v[j].x * v[j].x + v[j].y * v[j].y) + (v[j].z * v[j].z + v[j].w * v[j].w); }
;         const float rstd = rsqrtf(wave_sum(s) * (1.0f / 1024.0f) + 1e-6f);
; #pragma unroll
;         for (int j = 0; j < 4; ++j) { const int c = (X.lane + 64 * j) * 4; const f32x4 gn = *(const f32x4*)(gain + c), a = *(const f32x4*)(scl + c), b = *(const f32x4*)(sh + c);
;             const f32x4 o = v[j] * rstd * gn * (a + 1.0f) + b; u32x2 w; w.x = cvt_pk_bf16(o.x, o.y); w.y = cvt_pk_bf16(o.z, o.w); *(u32x2*)(HN + (size_t)r * D + c) = w; }
	v_pk_mul_f32 v[200:201], v[96:97], v[96:97]
	v_pk_fma_f32 v[200:201], v[98:99], v[98:99], v[200:201]
	v_pk_fma_f32 v[200:201], v[100:101], v[100:101], v[200:201]
	v_pk_fma_f32 v[200:201], v[102:103], v[102:103], v[200:201]
	v_pk_fma_f32 v[200:201], v[104:105], v[104:105], v[200:201]
	v_pk_fma_f32 v[200:201], v[106:107], v[106:107], v[200:201]
	v_pk_fma_f32 v[200:201], v[108:109], v[108:109], v[200:201]
	v_pk_fma_f32 v[200:201], v[110:111], v[110:111], v[200:201]
	v_add_f32_e32 v200, v200, v201
	s_nop 1
	v_add_f32_dpp v200, v200, v200 quad_perm:[1,0,3,2] row_mask:0xf bank_mask:0xf
	s_nop 1
	v_add_f32_dpp v200, v200, v200 quad_perm:[2,3,0,1] row_mask:0xf bank_mask:0xf
	s_nop 1
	v_add_f32_dpp v200, v200, v200 row_half_mirror row_mask:0xf bank_mask:0xf
	s_nop 1
	v_add_f32_dpp v200, v200, v200 row_mirror row_mask:0xf bank_mask:0xf
	s_nop 1
	v_mov_b32_e32 v201, v200
	s_nop 1
	v_permlane16_swap_b32_e32 v200, v201
	s_nop 0
	v_add_f32_e32 v200, v200, v201
	v_mov_b32_e32 v201, v200
	s_nop 1
	v_permlane32_swap_b32_e32 v200, v201
	s_nop 0
	v_add_f32_e32 v200, v200, v201
	v_fmamk_f32 v200, v200, 0x3a800000, v3
	v_rsq_f32_e32 v200, v200
	s_nop 0
	v_pk_mul_f32 v[96:97], v[96:97], v[200:201] op_sel_hi:[1,0]
	v_pk_mul_f32 v[98:99], v[98:99], v[200:201] op_sel_hi:[1,0]
	v_pk_mul_f32 v[100:101], v[100:101], v[200:201] op_sel_hi:[1,0]
	v_pk_mul_f32 v[102:103], v[102:103], v[200:201] op_sel_hi:[1,0]
	v_pk_mul_f32 v[104:105], v[104:105], v[200:201] op_sel_hi:[1,0]
	v_pk_mul_f32 v[106:107], v[106:107], v[200:201] op_sel_hi:[1,0]
	v_pk_mul_f32 v[108:109], v[108:109], v[200:201] op_sel_hi:[1,0]
	v_pk_mul_f32 v[110:111], v[110:111], v[200:201] op_sel_hi:[1,0]
	v_pk_mul_f32 v[96:97], v[16:17], v[96:97]
	v_pk_mul_f32 v[98:99], v[18:19], v[98:99]
	v_pk_mul_f32 v[100:101], v[20:21], v[100:101]
	v_pk_mul_f32 v[102:103], v[22:23], v[102:103]
	v_pk_mul_f32 v[104:105], v[24:25], v[104:105]
	v_pk_mul_f32 v[106:107], v[26:27], v[106:107]
	v_pk_mul_f32 v[108:109], v[28:29], v[108:109]
	v_pk_mul_f32 v[110:111], v[30:31], v[110:111]
	v_pk_fma_f32 v[96:97], v[32:33], v[96:97], v[48:49]
	v_pk_fma_f32 v[98:99], v[34:35], v[98:99], v[50:51]
	v_pk_fma_f32 v[100:101], v[36:37], v[100:101], v[52:53]
	v_pk_fma_f32 v[102:103], v[38:39], v[102:103], v[54:55]
	v_pk_fma_f32 v[104:105], v[40:41], v[104:105], v[56:57]
	v_pk_fma_f32 v[106:107], v[42:43], v[106:107], v[58:59]
	v_pk_fma_f32 v[108:109], v[44:45], v[108:109], v[60:61]
	v_pk_fma_f32 v[110:111], v[46:47], v[110:111], v[62:63]
	v_cvt_pk_bf16_f32 v192, v96, v97
	v_cvt_pk_bf16_f32 v193, v98, v99
	v_cvt_pk_bf16_f32 v194, v100, v101
	v_cvt_pk_bf16_f32 v195, v102, v103
	v_cvt_pk_bf16_f32 v196, v104, v105
	v_cvt_pk_bf16_f32 v197, v106, v107
	v_cvt_pk_bf16_f32 v198, v108, v109
	v_cvt_pk_bf16_f32 v199, v110, v111
	global_store_dwordx4 v1, v[192:195], s[8:9] sc1
	global_store_dwordx4 v1, v[196:199], s[8:9] offset:1024 sc1
	global_load_dwordx4 v[96:99], v2, s[6:7]
	global_load_dwordx4 v[100:103], v2, s[6:7] offset:16
	global_load_dwordx4 v[104:107], v2, s[6:7] offset:2048
	global_load_dwordx4 v[108:111], v2, s[6:7] offset:2064
	s_add_u32 s6, s6, 0x1000
	s_addc_u32 s7, s7, 0
	s_waitcnt vmcnt(26)
	v_pk_mul_f32 v[200:201], v[112:113], v[112:113]
	v_pk_fma_f32 v[200:201], v[114:115], v[114:115], v[200:201]
	v_pk_fma_f32 v[200:201], v[116:117], v[116:117], v[200:201]
	v_pk_fma_f32 v[200:201], v[118:119], v[118:119], v[200:201]
	v_pk_fma_f32 v[200:201], v[120:121], v[120:121], v[200:201]
	v_pk_fma_f32 v[200:201], v[122:123], v[122:123], v[200:201]
	v_pk_fma_f32 v[200:201], v[124:125], v[124:125], v[200:201]
	v_pk_fma_f32 v[200:201], v[126:127], v[126:127], v[200:201]
	v_add_f32_e32 v200, v200, v201
	s_nop 1
	v_add_f32_dpp v200, v200, v200 quad_perm:[1,0,3,2] row_mask:0xf bank_mask:0xf
	s_nop 1
	v_add_f32_dpp v200, v200, v200 quad_perm:[2,3,0,1] row_mask:0xf bank_mask:0xf
	s_nop 1
	v_add_f32_dpp v200, v200, v200 row_half_mirror row_mask:0xf bank_mask:0xf
	s_nop 1
	v_add_f32_dpp v200, v200, v200 row_mirror row_mask:0xf bank_mask:0xf
	s_nop 1
	v_mov_b32_e32 v201, v200
	s_nop 1
	v_permlane16_swap_b32_e32 v200, v201
	s_nop 0
	v_add_f32_e32 v200, v200, v201
	v_mov_b32_e32 v201, v200
	s_nop 1
	v_permlane32_swap_b32_e32 v200, v201
	s_nop 0
	v_add_f32_e32 v200, v200, v201
	v_fmamk_f32 v200, v200, 0x3a800000, v3
	v_rsq_f32_e32 v200, v200
	s_nop 0
	v_pk_mul_f32 v[112:113], v[112:113], v[200:201] op_sel_hi:[1,0]
	v_pk_mul_f32 v[114:115], v[114:115], v[200:201] op_sel_hi:[1,0]
	v_pk_mul_f32 v[116:117], v[116:117], v[200:201] op_sel_hi:[1,0]
	v_pk_mul_f32 v[118:119], v[118:119], v[200:201] op_sel_hi:[1,0]
	v_pk_mul_f32 v[120:121], v[120:121], v[200:201] op_sel_hi:[1,0]
	v_pk_mul_f32 v[122:123], v[122:123], v[200:201] op_sel_hi:[1,0]
	v_pk_mul_f32 v[124:125], v[124:125], v[200:201] op_sel_hi:[1,0]
	v_pk_mul_f32 v[126:127], v[126:127], v[200:201] op_sel_hi:[1,0]
	v_pk_mul_f32 v[112:113], v[16:17], v[112:113]
	v_pk_mul_f32 v[114:115], v[18:19], v[114:115]
	v_pk_mul_f32 v[116:117], v[20:21], v[116:117]
	v_pk_mul_f32 v[118:119], v[22:23], v[118:119]
	v_pk_mul_f32 v[120:121], v[24:25], v[120:121]
	v_pk_mul_f32 v[122:123], v[26:27], v[122:123]
	v_pk_mul_f32 v[124:125], v[28:29], v[124:125]
	v_pk_mul_f32 v[126:127], v[30:31], v[126:127]
	v_pk_fma_f32 v[112:113], v[32:33], v[112:113], v[48:49]
	v_pk_fma_f32 v[114:115], v[34:35], v[114:115], v[50:51]
	v_pk_fma_f32 v[116:117], v[36:37], v[116:117], v[52:53]
	v_pk_fma_f32 v[118:119], v[38:39], v[118:119], v[54:55]
	v_pk_fma_f32 v[120:121], v[40:41], v[120:121], v[56:57]
	v_pk_fma_f32 v[122:123], v[42:43], v[122:123], v[58:59]
	v_pk_fma_f32 v[124:125], v[44:45], v[124:125], v[60:61]
	v_pk_fma_f32 v[126:127], v[46:47], v[126:127], v[62:63]
	v_cvt_pk_bf16_f32 v192, v112, v113
	v_cvt_pk_bf16_f32 v193, v114, v115
	v_cvt_pk_bf16_f32 v194, v116, v117
	v_cvt_pk_bf16_f32 v195, v118, v119
	v_cvt_pk_bf16_f32 v196, v120, v121
	v_cvt_pk_bf16_f32 v197, v122, v123
	v_cvt_pk_bf16_f32 v198, v124, v125
	v_cvt_pk_bf16_f32 v199, v126, v127
	global_store_dwordx4 v1, v[192:195], s[8:9] offset:2048 sc1
	global_store_dwordx4 v1, v[196:199], s[8:9] offset:3072 sc1
	s_add_u32 s8, s8, 0x1000
	s_addc_u32 s9, s9, 0
	global_load_dwordx4 v[112:115], v2, s[6:7]
	global_load_dwordx4 v[116:119], v2, s[6:7] offset:16
	global_load_dwordx4 v[120:123], v2, s[6:7] offset:2048
	global_load_dwordx4 v[124:127], v2, s[6:7] offset:2064
	s_add_u32 s6, s6, 0x1000
	s_addc_u32 s7, s7, 0
	s_waitcnt vmcnt(28)
; __device__ __forceinline__ unsigned cvt_pk_bf16(float lo, float hi) { unsigned r; asm("v_cvt_pk_bf16_f32 %0, %1, %2" : "=v"(r) : "v"(lo), "v"(hi)); return r; }
; __device__ __forceinline__ void norm_pass(const Ctx& X, const float* xs, const float* cs, int nrows, const float* gain, const float* modl, int si, bf16_t* HN) {
;     ...
;         f32x4 v[4]; float s = 0.f;
; #pragma unroll
;         for (int j = 0; j < 4; ++j) { v[j] = *(const f32x4*)(row + (X.lane + 64 * j) * 4); s += (v[j].x * v[j].x + v[j].y * v[j].y) + (v[j].z * v[j].z + v[j].w * v[j].w); }
;         const float rstd = rsqrtf(wave_sum(s) * (1.0f / 1024.0f) + 1e-6f);
; #pragma unroll
;         for (int j = 0; j < 4; ++j) { const int c = (X.lane + 64 * j) * 4; const f32x4 gn = *(const f32x4*)(gain + c), a = *(const f32x4*)(scl + c), b = *(const f32x4*)(sh + c);
;             const f32x4 o = v[j] * rstd * gn * (a + 1.0f) + b; u32x2 w; w.x = cvt_pk_bf16(o.x, o.y); w.y = cvt_pk_bf16(o.z, o.w); *(u32x2*)(HN + (size_t)r * D + c) = w; }
	v_pk_mul_f32 v[200:201], v[128:129], v[128:129]
	v_pk_fma_f32 v[200:201], v[130:131], v[130:131], v[200:201]
	v_pk_fma_f32 v[200:201], v[132:133], v[132:133], v[200:201]
	v_pk_fma_f32 v[200:201], v[134:135], v[134:135], v[200:201]
	v_pk_fma_f32 v[200:201], v[136:137], v[136:137], v[200:201]
	v_pk_fma_f32 v[200:201], v[138:139], v[138:139], v[200:201]
	v_pk_fma_f32 v[200:201], v[140:141], v[140:141], v[200:201]
	v_pk_fma_f32 v[200:201], v[142:143], v[142:143], v[200:201]
	v_add_f32_e32 v200, v200, v201
	s_nop 1
	v_add_f32_dpp v200, v200, v200 quad_perm:[1,0,3,2] row_mask:0xf bank_mask:0xf
	s_nop 1
	v_add_f32_dpp v200, v200, v200 quad_perm:[2,3,0,1] row_mask:0xf bank_mask:0xf
	s_nop 1
	v_add_f32_dpp v200, v200, v200 row_half_mirror row_mask:0xf bank_mask:0xf
	s_nop 1
	v_add_f32_dpp v200, v200, v200 row_mirror row_mask:0xf bank_mask:0xf
	s_nop 1
	v_mov_b32_e32 v201, v200
	s_nop 1
	v_permlane16_swap_b32_e32 v200, v201
	s_nop 0
	v_add_f32_e32 v200, v200, v201
	v_mov_b32_e32 v201, v200
	s_nop 1
	v_permlane32_swap_b32_e32 v200, v201
	s_nop 0
	v_add_f32_e32 v200, v200, v201
	v_fmamk_f32 v200, v200, 0x3a800000, v3
	v_rsq_f32_e32 v200, v200
	s_nop 0
	v_pk_mul_f32 v[128:129], v[128:129], v[200:201] op_sel_hi:[1,0]
	v_pk_mul_f32 v[130:131], v[130:131], v[200:201] op_sel_hi:[1,0]
	v_pk_mul_f32 v[132:133], v[132:133], v[200:201] op_sel_hi:[1,0]
	v_pk_mul_f32 v[134:135], v[134:135], v[200:201] op_sel_hi:[1,0]
	v_pk_mul_f32 v[136:137], v[136:137], v[200:201] op_sel_hi:[1,0]
	v_pk_mul_f32 v[138:139], v[138:139], v[200:201] op_sel_hi:[1,0]
	v_pk_mul_f32 v[140:141], v[140:141], v[200:201] op_sel_hi:[1,0]
	v_pk_mul_f32 v[142:143], v[142:143], v[200:201] op_sel_hi:[1,0]
	v_pk_mul_f32 v[128:129], v[16:17], v[128:129]
	v_pk_mul_f32 v[130:131], v[18:19], v[130:131]
	v_pk_mul_f32 v[132:133], v[20:21], v[132:133]
	v_pk_mul_f32 v[134:135], v[22:23], v[134:135]
	v_pk_mul_f32 v[136:137], v[24:25], v[136:137]
	v_pk_mul_f32 v[138:139], v[26:27], v[138:139]
	v_pk_mul_f32 v[140:141], v[28:29], v[140:141]
	v_pk_mul_f32 v[142:143], v[30:31], v[142:143]
	v_pk_fma_f32 v[128:129], v[32:33], v[128:129], v[48:49]
	v_pk_fma_f32 v[130:131], v[34:35], v[130:131], v[50:51]
	v_pk_fma_f32 v[132:133], v[36:37], v[132:133], v[52:53]
	v_pk_fma_f32 v[134:135], v[38:39], v[134:135], v[54:55]
	v_pk_fma_f32 v[136:137], v[40:41], v[136:137], v[56:57]
	v_pk_fma_f32 v[138:139], v[42:43], v[138:139], v[58:59]
	v_pk_fma_f32 v[140:141], v[44:45], v[140:141], v[60:61]
	v_pk_fma_f32 v[142:143], v[46:47], v[142:143], v[62:63]
	v_cvt_pk_bf16_f32 v192, v128, v129
	v_cvt_pk_bf16_f32 v193, v130, v131
	v_cvt_pk_bf16_f32 v194, v132, v133
	v_cvt_pk_bf16_f32 v195, v134, v135
	v_cvt_pk_bf16_f32 v196, v136, v137
	v_cvt_pk_bf16_f32 v197, v138, v139
	v_cvt_pk_bf16_f32 v198, v140, v141
	v_cvt_pk_bf16_f32 v199, v142, v143
	global_store_dwordx4 v1, v[192:195], s[8:9] sc1
	global_store_dwordx4 v1, v[196:199], s[8:9] offset:1024 sc1
	global_load_dwordx4 v[128:131], v2, s[6:7]
	global_load_dwordx4 v[132:135], v2, s[6:7] offset:16
	global_load_dwordx4 v[136:139], v2, s[6:7] offset:2048
	global_load_dwordx4 v[140:143], v2, s[6:7] offset:2064
	s_add_u32 s6, s6, 0x1000
	s_addc_u32 s7, s7, 0
	s_waitcnt vmcnt(30)
	v_pk_mul_f32 v[200:201], v[144:145], v[144:145]
	v_pk_fma_f32 v[200:201], v[146:147], v[146:147], v[200:201]
	v_pk_fma_f32 v[200:201], v[148:149], v[148:149], v[200:201]
	v_pk_fma_f32 v[200:201], v[150:151], v[150:151], v[200:201]
	v_pk_fma_f32 v[200:201], v[152:153], v[152:153], v[200:201]
	v_pk_fma_f32 v[200:201], v[154:155], v[154:155], v[200:201]
	v_pk_fma_f32 v[200:201], v[156:157], v[156:157], v[200:201]
	v_pk_fma_f32 v[200:201], v[158:159], v[158:159], v[200:201]
	v_add_f32_e32 v200, v200, v201
	s_nop 1
	v_add_f32_dpp v200, v200, v200 quad_perm:[1,0,3,2] row_mask:0xf bank_mask:0xf
	s_nop 1
	v_add_f32_dpp v200, v200, v200 quad_perm:[2,3,0,1] row_mask:0xf bank_mask:0xf
	s_nop 1
	v_add_f32_dpp v200, v200, v200 row_half_mirror row_mask:0xf bank_mask:0xf
	s_nop 1
	v_add_f32_dpp v200, v200, v200 row_mirror row_mask:0xf bank_mask:0xf
	s_nop 1
	v_mov_b32_e32 v201, v200
	s_nop 1
	v_permlane16_swap_b32_e32 v200, v201
	s_nop 0
	v_add_f32_e32 v200, v200, v201
	v_mov_b32_e32 v201, v200
	s_nop 1
	v_permlane32_swap_b32_e32 v200, v201
	s_nop 0
	v_add_f32_e32 v200, v200, v201
	v_fmamk_f32 v200, v200, 0x3a800000, v3
	v_rsq_f32_e32 v200, v200
	s_nop 0
	v_pk_mul_f32 v[144:145], v[144:145], v[200:201] op_sel_hi:[1,0]
	v_pk_mul_f32 v[146:147], v[146:147], v[200:201] op_sel_hi:[1,0]
	v_pk_mul_f32 v[148:149], v[148:149], v[200:201] op_sel_hi:[1,0]
	v_pk_mul_f32 v[150:151], v[150:151], v[200:201] op_sel_hi:[1,0]
	v_pk_mul_f32 v[152:153], v[152:153], v[200:201] op_sel_hi:[1,0]
	v_pk_mul_f32 v[154:155], v[154:155], v[200:201] op_sel_hi:[1,0]
	v_pk_mul_f32 v[156:157], v[156:157], v[200:201] op_sel_hi:[1,0]
	v_pk_mul_f32 v[158:159], v[158:159], v[200:201] op_sel_hi:[1,0]
	v_pk_mul_f32 v[144:145], v[16:17], v[144:145]
	v_pk_mul_f32 v[146:147], v[18:19], v[146:147]
	v_pk_mul_f32 v[148:149], v[20:21], v[148:149]
	v_pk_mul_f32 v[150:151], v[22:23], v[150:151]
	v_pk_mul_f32 v[152:153], v[24:25], v[152:153]
	v_pk_mul_f32 v[154:155], v[26:27], v[154:155]
	v_pk_mul_f32 v[156:157], v[28:29], v[156:157]
	v_pk_mul_f32 v[158:159], v[30:31], v[158:159]
	v_pk_fma_f32 v[144:145], v[32:33], v[144:145], v[48:49]
	v_pk_fma_f32 v[146:147], v[34:35], v[146:147], v[50:51]
	v_pk_fma_f32 v[148:149], v[36:37], v[148:149], v[52:53]
	v_pk_fma_f32 v[150:151], v[38:39], v[150:151], v[54:55]
	v_pk_fma_f32 v[152:153], v[40:41], v[152:153], v[56:57]
	v_pk_fma_f32 v[154:155], v[42:43], v[154:155], v[58:59]
	v_pk_fma_f32 v[156:157], v[44:45], v[156:157], v[60:61]
	v_pk_fma_f32 v[158:159], v[46:47], v[158:159], v[62:63]
	v_cvt_pk_bf16_f32 v192, v144, v145
	v_cvt_pk_bf16_f32 v193, v146, v147
	v_cvt_pk_bf16_f32 v194, v148, v149
	v_cvt_pk_bf16_f32 v195, v150, v151
	v_cvt_pk_bf16_f32 v196, v152, v153
	v_cvt_pk_bf16_f32 v197, v154, v155
	v_cvt_pk_bf16_f32 v198, v156, v157
	v_cvt_pk_bf16_f32 v199, v158, v159
	global_store_dwordx4 v1, v[192:195], s[8:9] offset:2048 sc1
	global_store_dwordx4 v1, v[196:199], s[8:9] offset:3072 sc1
	s_add_u32 s8, s8, 0x1000
	s_addc_u32 s9, s9, 0
	global_load_dwordx4 v[144:147], v2, s[6:7]
	global_load_dwordx4 v[148:151], v2, s[6:7] offset:16
	global_load_dwordx4 v[152:155], v2, s[6:7] offset:2048
	global_load_dwordx4 v[156:159], v2, s[6:7] offset:2064
	s_add_u32 s6, s6, 0x1000
	s_addc_u32 s7, s7, 0
	s_waitcnt vmcnt(30)
; __device__ __forceinline__ unsigned cvt_pk_bf16(float lo, float hi) { unsigned r; asm("v_cvt_pk_bf16_f32 %0, %1, %2" : "=v"(r) : "v"(lo), "v"(hi)); return r; }
; __device__ __forceinline__ void norm_pass(const Ctx& X, const float* xs, const float* cs, int nrows, const float* gain, const float* modl, int si, bf16_t* HN) {
;     ...
;         f32x4 v[4]; float s = 0.f;
; #pragma unroll
;         for (int j = 0; j < 4; ++j) { v[j] = *(const f32x4*)(row + (X.lane + 64 * j) * 4); s += (v[j].x * v[j].x + v[j].y * v[j].y) + (v[j].z * v[j].z + v[j].w * v[j].w); }
;         const float rstd = rsqrtf(wave_sum(s) * (1.0f / 1024.0f) + 1e-6f);
; #pragma unroll
;         for (int j = 0; j < 4; ++j) { const int c = (X.lane + 64 * j) * 4; const f32x4 gn = *(const f32x4*)(gain + c), a = *(const f32x4*)(scl + c), b = *(const f32x4*)(sh + c);
;             const f32x4 o = v[j] * rstd * gn * (a + 1.0f) + b; u32x2 w; w.x = cvt_pk_bf16(o.x, o.y); w.y = cvt_pk_bf16(o.z, o.w); *(u32x2*)(HN + (size_t)r * D + c) = w; }
	v_pk_mul_f32 v[200:201], v[64:65], v[64:65]
	v_pk_fma_f32 v[200:201], v[66:67], v[66:67], v[200:201]
	v_pk_fma_f32 v[200:201], v[68:69], v[68:69], v[200:201]
	v_pk_fma_f32 v[200:201], v[70:71], v[70:71], v[200:201]
	v_pk_fma_f32 v[200:201], v[72:73], v[72:73], v[200:201]
	v_pk_fma_f32 v[200:201], v[74:75], v[74:75], v[200:201]
	v_pk_fma_f32 v[200:201], v[76:77], v[76:77], v[200:201]
	v_pk_fma_f32 v[200:201], v[78:79], v[78:79], v[200:201]
	v_add_f32_e32 v200, v200, v201
	s_nop 1
	v_add_f32_dpp v200, v200, v200 quad_perm:[1,0,3,2] row_mask:0xf bank_mask:0xf
	s_nop 1
	v_add_f32_dpp v200, v200, v200 quad_perm:[2,3,0,1] row_mask:0xf bank_mask:0xf
	s_nop 1
	v_add_f32_dpp v200, v200, v200 row_half_mirror row_mask:0xf bank_mask:0xf
	s_nop 1
	v_add_f32_dpp v200, v200, v200 row_mirror row_mask:0xf bank_mask:0xf
	s_nop 1
	v_mov_b32_e32 v201, v200
	s_nop 1
	v_permlane16_swap_b32_e32 v200, v201
	s_nop 0
	v_add_f32_e32 v200, v200, v201
	v_mov_b32_e32 v201, v200
	s_nop 1
	v_permlane32_swap_b32_e32 v200, v201
	s_nop 0
	v_add_f32_e32 v200, v200, v201
	v_fmamk_f32 v200, v200, 0x3a800000, v3
	v_rsq_f32_e32 v200, v200
	s_nop 0
	v_pk_mul_f32 v[64:65], v[64:65], v[200:201] op_sel_hi:[1,0]
	v_pk_mul_f32 v[66:67], v[66:67], v[200:201] op_sel_hi:[1,0]
	v_pk_mul_f32 v[68:69], v[68:69], v[200:201] op_sel_hi:[1,0]
	v_pk_mul_f32 v[70:71], v[70:71], v[200:201] op_sel_hi:[1,0]
	v_pk_mul_f32 v[72:73], v[72:73], v[200:201] op_sel_hi:[1,0]
	v_pk_mul_f32 v[74:75], v[74:75], v[200:201] op_sel_hi:[1,0]
	v_pk_mul_f32 v[76:77], v[76:77], v[200:201] op_sel_hi:[1,0]
	v_pk_mul_f32 v[78:79], v[78:79], v[200:201] op_sel_hi:[1,0]
	v_pk_mul_f32 v[64:65], v[16:17], v[64:65]
	v_pk_mul_f32 v[66:67], v[18:19], v[66:67]
	v_pk_mul_f32 v[68:69], v[20:21], v[68:69]
	v_pk_mul_f32 v[70:71], v[22:23], v[70:71]
	v_pk_mul_f32 v[72:73], v[24:25], v[72:73]
	v_pk_mul_f32 v[74:75], v[26:27], v[74:75]
	v_pk_mul_f32 v[76:77], v[28:29], v[76:77]
	v_pk_mul_f32 v[78:79], v[30:31], v[78:79]
	v_pk_fma_f32 v[64:65], v[32:33], v[64:65], v[48:49]
	v_pk_fma_f32 v[66:67], v[34:35], v[66:67], v[50:51]
	v_pk_fma_f32 v[68:69], v[36:37], v[68:69], v[52:53]
	v_pk_fma_f32 v[70:71], v[38:39], v[70:71], v[54:55]
	v_pk_fma_f32 v[72:73], v[40:41], v[72:73], v[56:57]
	v_pk_fma_f32 v[74:75], v[42:43], v[74:75], v[58:59]
	v_pk_fma_f32 v[76:77], v[44:45], v[76:77], v[60:61]
	v_pk_fma_f32 v[78:79], v[46:47], v[78:79], v[62:63]
	v_cvt_pk_bf16_f32 v192, v64, v65
	v_cvt_pk_bf16_f32 v193, v66, v67
	v_cvt_pk_bf16_f32 v194, v68, v69
	v_cvt_pk_bf16_f32 v195, v70, v71
	v_cvt_pk_bf16_f32 v196, v72, v73
	v_cvt_pk_bf16_f32 v197, v74, v75
	v_cvt_pk_bf16_f32 v198, v76, v77
	v_cvt_pk_bf16_f32 v199, v78, v79
	global_store_dwordx4 v1, v[192:195], s[8:9] sc1
	global_store_dwordx4 v1, v[196:199], s[8:9] offset:1024 sc1
	global_load_dwordx4 v[64:67], v2, s[6:7]
	global_load_dwordx4 v[68:71], v2, s[6:7] offset:16
	global_load_dwordx4 v[72:75], v2, s[6:7] offset:2048
	global_load_dwordx4 v[76:79], v2, s[6:7] offset:2064
	s_add_u32 s6, s6, 0x1000
	s_addc_u32 s7, s7, 0
	s_waitcnt vmcnt(30)
	v_pk_mul_f32 v[200:201], v[80:81], v[80:81]
	v_pk_fma_f32 v[200:201], v[82:83], v[82:83], v[200:201]
	v_pk_fma_f32 v[200:201], v[84:85], v[84:85], v[200:201]
	v_pk_fma_f32 v[200:201], v[86:87], v[86:87], v[200:201]
	v_pk_fma_f32 v[200:201], v[88:89], v[88:89], v[200:201]
	v_pk_fma_f32 v[200:201], v[90:91], v[90:91], v[200:201]
	v_pk_fma_f32 v[200:201], v[92:93], v[92:93], v[200:201]
	v_pk_fma_f32 v[200:201], v[94:95], v[94:95], v[200:201]
	v_add_f32_e32 v200, v200, v201
	s_nop 1
	v_add_f32_dpp v200, v200, v200 quad_perm:[1,0,3,2] row_mask:0xf bank_mask:0xf
	s_nop 1
	v_add_f32_dpp v200, v200, v200 quad_perm:[2,3,0,1] row_mask:0xf bank_mask:0xf
	s_nop 1
	v_add_f32_dpp v200, v200, v200 row_half_mirror row_mask:0xf bank_mask:0xf
	s_nop 1
	v_add_f32_dpp v200, v200, v200 row_mirror row_mask:0xf bank_mask:0xf
	s_nop 1
	v_mov_b32_e32 v201, v200
	s_nop 1
	v_permlane16_swap_b32_e32 v200, v201
	s_nop 0
	v_add_f32_e32 v200, v200, v201
	v_mov_b32_e32 v201, v200
	s_nop 1
	v_permlane32_swap_b32_e32 v200, v201
	s_nop 0
	v_add_f32_e32 v200, v200, v201
	v_fmamk_f32 v200, v200, 0x3a800000, v3
	v_rsq_f32_e32 v200, v200
	s_nop 0
	v_pk_mul_f32 v[80:81], v[80:81], v[200:201] op_sel_hi:[1,0]
	v_pk_mul_f32 v[82:83], v[82:83], v[200:201] op_sel_hi:[1,0]
	v_pk_mul_f32 v[84:85], v[84:85], v[200:201] op_sel_hi:[1,0]
	v_pk_mul_f32 v[86:87], v[86:87], v[200:201] op_sel_hi:[1,0]
	v_pk_mul_f32 v[88:89], v[88:89], v[200:201] op_sel_hi:[1,0]
	v_pk_mul_f32 v[90:91], v[90:91], v[200:201] op_sel_hi:[1,0]
	v_pk_mul_f32 v[92:93], v[92:93], v[200:201] op_sel_hi:[1,0]
	v_pk_mul_f32 v[94:95], v[94:95], v[200:201] op_sel_hi:[1,0]
	v_pk_mul_f32 v[80:81], v[16:17], v[80:81]
	v_pk_mul_f32 v[82:83], v[18:19], v[82:83]
	v_pk_mul_f32 v[84:85], v[20:21], v[84:85]
	v_pk_mul_f32 v[86:87], v[22:23], v[86:87]
	v_pk_mul_f32 v[88:89], v[24:25], v[88:89]
	v_pk_mul_f32 v[90:91], v[26:27], v[90:91]
	v_pk_mul_f32 v[92:93], v[28:29], v[92:93]
	v_pk_mul_f32 v[94:95], v[30:31], v[94:95]
	v_pk_fma_f32 v[80:81], v[32:33], v[80:81], v[48:49]
	v_pk_fma_f32 v[82:83], v[34:35], v[82:83], v[50:51]
	v_pk_fma_f32 v[84:85], v[36:37], v[84:85], v[52:53]
	v_pk_fma_f32 v[86:87], v[38:39], v[86:87], v[54:55]
	v_pk_fma_f32 v[88:89], v[40:41], v[88:89], v[56:57]
	v_pk_fma_f32 v[90:91], v[42:43], v[90:91], v[58:59]
	v_pk_fma_f32 v[92:93], v[44:45], v[92:93], v[60:61]
	v_pk_fma_f32 v[94:95], v[46:47], v[94:95], v[62:63]
	v_cvt_pk_bf16_f32 v192, v80, v81
	v_cvt_pk_bf16_f32 v193, v82, v83
	v_cvt_pk_bf16_f32 v194, v84, v85
	v_cvt_pk_bf16_f32 v195, v86, v87
	v_cvt_pk_bf16_f32 v196, v88, v89
	v_cvt_pk_bf16_f32 v197, v90, v91
	v_cvt_pk_bf16_f32 v198, v92, v93
	v_cvt_pk_bf16_f32 v199, v94, v95
	global_store_dwordx4 v1, v[192:195], s[8:9] offset:2048 sc1
	global_store_dwordx4 v1, v[196:199], s[8:9] offset:3072 sc1
	s_add_u32 s8, s8, 0x1000
	s_addc_u32 s9, s9, 0
	global_load_dwordx4 v[80:83], v2, s[6:7]
	global_load_dwordx4 v[84:87], v2, s[6:7] offset:16
	global_load_dwordx4 v[88:91], v2, s[6:7] offset:2048
	global_load_dwordx4 v[92:95], v2, s[6:7] offset:2064
	s_add_u32 s6, s6, 0x1000
	s_addc_u32 s7, s7, 0
	s_waitcnt vmcnt(30)
; __device__ __forceinline__ unsigned cvt_pk_bf16(float lo, float hi) { unsigned r; asm("v_cvt_pk_bf16_f32 %0, %1, %2" : "=v"(r) : "v"(lo), "v"(hi)); return r; }
; __device__ __forceinline__ void norm_pass(const Ctx& X, const float* xs, const float* cs, int nrows, const float* gain, const float* modl, int si, bf16_t* HN) {
;     ...
;         f32x4 v[4]; float s = 0.f;
; #pragma unroll
;         for (int j = 0; j < 4; ++j) { v[j] = *(const f32x4*)(row + (X.lane + 64 * j) * 4); s += (v[j].x * v[j].x + v[j].y * v[j].y) + (v[j].z * v[j].z + v[j].w * v[j].w); }
;         const float rstd = rsqrtf(wave_sum(s) * (1.0f / 1024.0f) + 1e-6f);
; #pragma unroll
;         for (int j = 0; j < 4; ++j) { const int c = (X.lane + 64 * j) * 4; const f32x4 gn = *(const f32x4*)(gain + c), a = *(const f32x4*)(scl + c), b = *(const f32x4*)(sh + c);
;             const f32x4 o = v[j] * rstd * gn * (a + 1.0f) + b; u32x2 w; w.x = cvt_pk_bf16(o.x, o.y); w.y = cvt_pk_bf16(o.z, o.w); *(u32x2*)(HN + (size_t)r * D + c) = w; }
	v_pk_mul_f32 v[200:201], v[96:97], v[96:97]
	v_pk_fma_f32 v[200:201], v[98:99], v[98:99], v[200:201]
	v_pk_fma_f32 v[200:201], v[100:101], v[100:101], v[200:201]
	v_pk_fma_f32 v[200:201], v[102:103], v[102:103], v[200:201]
	v_pk_fma_f32 v[200:201], v[104:105], v[104:105], v[200:201]
	v_pk_fma_f32 v[200:201], v[106:107], v[106:107], v[200:201]
	v_pk_fma_f32 v[200:201], v[108:109], v[108:109], v[200:201]
	v_pk_fma_f32 v[200:201], v[110:111], v[110:111], v[200:201]
	v_add_f32_e32 v200, v200, v201
	s_nop 1
	v_add_f32_dpp v200, v200, v200 quad_perm:[1,0,3,2] row_mask:0xf bank_mask:0xf
	s_nop 1
	v_add_f32_dpp v200, v200, v200 quad_perm:[2,3,0,1] row_mask:0xf bank_mask:0xf
	s_nop 1
	v_add_f32_dpp v200, v200, v200 row_half_mirror row_mask:0xf bank_mask:0xf
	s_nop 1
	v_add_f32_dpp v200, v200, v200 row_mirror row_mask:0xf bank_mask:0xf
	s_nop 1
	v_mov_b32_e32 v201, v200
	s_nop 1
	v_permlane16_swap_b32_e32 v200, v201
	s_nop 0
	v_add_f32_e32 v200, v200, v201
	v_mov_b32_e32 v201, v200
	s_nop 1
	v_permlane32_swap_b32_e32 v200, v201
	s_nop 0
	v_add_f32_e32 v200, v200, v201
	v_fmamk_f32 v200, v200, 0x3a800000, v3
	v_rsq_f32_e32 v200, v200
	s_nop 0
	v_pk_mul_f32 v[96:97], v[96:97], v[200:201] op_sel_hi:[1,0]
	v_pk_mul_f32 v[98:99], v[98:99], v[200:201] op_sel_hi:[1,0]
	v_pk_mul_f32 v[100:101], v[100:101], v[200:201] op_sel_hi:[1,0]
	v_pk_mul_f32 v[102:103], v[102:103], v[200:201] op_sel_hi:[1,0]
	v_pk_mul_f32 v[104:105], v[104:105], v[200:201] op_sel_hi:[1,0]
	v_pk_mul_f32 v[106:107], v[106:107], v[200:201] op_sel_hi:[1,0]
	v_pk_mul_f32 v[108:109], v[108:109], v[200:201] op_sel_hi:[1,0]
	v_pk_mul_f32 v[110:111], v[110:111], v[200:201] op_sel_hi:[1,0]
	v_pk_mul_f32 v[96:97], v[16:17], v[96:97]
	v_pk_mul_f32 v[98:99], v[18:19], v[98:99]
	v_pk_mul_f32 v[100:101], v[20:21], v[100:101]
	v_pk_mul_f32 v[102:103], v[22:23], v[102:103]
	v_pk_mul_f32 v[104:105], v[24:25], v[104:105]
	v_pk_mul_f32 v[106:107], v[26:27], v[106:107]
	v_pk_mul_f32 v[108:109], v[28:29], v[108:109]
	v_pk_mul_f32 v[110:111], v[30:31], v[110:111]
	v_pk_fma_f32 v[96:97], v[32:33], v[96:97], v[48:49]
	v_pk_fma_f32 v[98:99], v[34:35], v[98:99], v[50:51]
	v_pk_fma_f32 v[100:101], v[36:37], v[100:101], v[52:53]
	v_pk_fma_f32 v[102:103], v[38:39], v[102:103], v[54:55]
	v_pk_fma_f32 v[104:105], v[40:41], v[104:105], v[56:57]
	v_pk_fma_f32 v[106:107], v[42:43], v[106:107], v[58:59]
	v_pk_fma_f32 v[108:109], v[44:45], v[108:109], v[60:61]
	v_pk_fma_f32 v[110:111], v[46:47], v[110:111], v[62:63]
	v_cvt_pk_bf16_f32 v192, v96, v97
	v_cvt_pk_bf16_f32 v193, v98, v99
	v_cvt_pk_bf16_f32 v194, v100, v101
	v_cvt_pk_bf16_f32 v195, v102, v103
	v_cvt_pk_bf16_f32 v196, v104, v105
	v_cvt_pk_bf16_f32 v197, v106, v107
	v_cvt_pk_bf16_f32 v198, v108, v109
	v_cvt_pk_bf16_f32 v199, v110, v111
	global_store_dwordx4 v1, v[192:195], s[8:9] sc1
	global_store_dwordx4 v1, v[196:199], s[8:9] offset:1024 sc1
	global_load_dwordx4 v[96:99], v2, s[6:7]
	global_load_dwordx4 v[100:103], v2, s[6:7] offset:16
	global_load_dwordx4 v[104:107], v2, s[6:7] offset:2048
	global_load_dwordx4 v[108:111], v2, s[6:7] offset:2064
	s_add_u32 s6, s6, 0x1000
	s_addc_u32 s7, s7, 0
	s_waitcnt vmcnt(30)
	v_pk_mul_f32 v[200:201], v[112:113], v[112:113]
	v_pk_fma_f32 v[200:201], v[114:115], v[114:115], v[200:201]
	v_pk_fma_f32 v[200:201], v[116:117], v[116:117], v[200:201]
	v_pk_fma_f32 v[200:201], v[118:119], v[118:119], v[200:201]
	v_pk_fma_f32 v[200:201], v[120:121], v[120:121], v[200:201]
	v_pk_fma_f32 v[200:201], v[122:123], v[122:123], v[200:201]
	v_pk_fma_f32 v[200:201], v[124:125], v[124:125], v[200:201]
	v_pk_fma_f32 v[200:201], v[126:127], v[126:127], v[200:201]
	v_add_f32_e32 v200, v200, v201
	s_nop 1
	v_add_f32_dpp v200, v200, v200 quad_perm:[1,0,3,2] row_mask:0xf bank_mask:0xf
	s_nop 1
	v_add_f32_dpp v200, v200, v200 quad_perm:[2,3,0,1] row_mask:0xf bank_mask:0xf
	s_nop 1
	v_add_f32_dpp v200, v200, v200 row_half_mirror row_mask:0xf bank_mask:0xf
	s_nop 1
	v_add_f32_dpp v200, v200, v200 row_mirror row_mask:0xf bank_mask:0xf
	s_nop 1
	v_mov_b32_e32 v201, v200
	s_nop 1
	v_permlane16_swap_b32_e32 v200, v201
	s_nop 0
	v_add_f32_e32 v200, v200, v201
	v_mov_b32_e32 v201, v200
	s_nop 1
	v_permlane32_swap_b32_e32 v200, v201
	s_nop 0
	v_add_f32_e32 v200, v200, v201
	v_fmamk_f32 v200, v200, 0x3a800000, v3
	v_rsq_f32_e32 v200, v200
	s_nop 0
	v_pk_mul_f32 v[112:113], v[112:113], v[200:201] op_sel_hi:[1,0]
	v_pk_mul_f32 v[114:115], v[114:115], v[200:201] op_sel_hi:[1,0]
	v_pk_mul_f32 v[116:117], v[116:117], v[200:201] op_sel_hi:[1,0]
	v_pk_mul_f32 v[118:119], v[118:119], v[200:201] op_sel_hi:[1,0]
	v_pk_mul_f32 v[120:121], v[120:121], v[200:201] op_sel_hi:[1,0]
	v_pk_mul_f32 v[122:123], v[122:123], v[200:201] op_sel_hi:[1,0]
	v_pk_mul_f32 v[124:125], v[124:125], v[200:201] op_sel_hi:[1,0]
	v_pk_mul_f32 v[126:127], v[126:127], v[200:201] op_sel_hi:[1,0]
	v_pk_mul_f32 v[112:113], v[16:17], v[112:113]
	v_pk_mul_f32 v[114:115], v[18:19], v[114:115]
	v_pk_mul_f32 v[116:117], v[20:21], v[116:117]
	v_pk_mul_f32 v[118:119], v[22:23], v[118:119]
	v_pk_mul_f32 v[120:121], v[24:25], v[120:121]
	v_pk_mul_f32 v[122:123], v[26:27], v[122:123]
	v_pk_mul_f32 v[124:125], v[28:29], v[124:125]
	v_pk_mul_f32 v[126:127], v[30:31], v[126:127]
	v_pk_fma_f32 v[112:113], v[32:33], v[112:113], v[48:49]
	v_pk_fma_f32 v[114:115], v[34:35], v[114:115], v[50:51]
	v_pk_fma_f32 v[116:117], v[36:37], v[116:117], v[52:53]
	v_pk_fma_f32 v[118:119], v[38:39], v[118:119], v[54:55]
	v_pk_fma_f32 v[120:121], v[40:41], v[120:121], v[56:57]
	v_pk_fma_f32 v[122:123], v[42:43], v[122:123], v[58:59]
	v_pk_fma_f32 v[124:125], v[44:45], v[124:125], v[60:61]
	v_pk_fma_f32 v[126:127], v[46:47], v[126:127], v[62:63]
	v_cvt_pk_bf16_f32 v192, v112, v113
	v_cvt_pk_bf16_f32 v193, v114, v115
	v_cvt_pk_bf16_f32 v194, v116, v117
	v_cvt_pk_bf16_f32 v195, v118, v119
	v_cvt_pk_bf16_f32 v196, v120, v121
	v_cvt_pk_bf16_f32 v197, v122, v123
	v_cvt_pk_bf16_f32 v198, v124, v125
	v_cvt_pk_bf16_f32 v199, v126, v127
	global_store_dwordx4 v1, v[192:195], s[8:9] offset:2048 sc1
	global_store_dwordx4 v1, v[196:199], s[8:9] offset:3072 sc1
	s_add_u32 s8, s8, 0x1000
	s_addc_u32 s9, s9, 0
	global_load_dwordx4 v[112:115], v2, s[6:7]
	global_load_dwordx4 v[116:119], v2, s[6:7] offset:16
	global_load_dwordx4 v[120:123], v2, s[6:7] offset:2048
	global_load_dwordx4 v[124:127], v2, s[6:7] offset:2064
	s_add_u32 s6, s6, 0x1000
	s_addc_u32 s7, s7, 0
	s_waitcnt vmcnt(30)
; __device__ __forceinline__ unsigned cvt_pk_bf16(float lo, float hi) { unsigned r; asm("v_cvt_pk_bf16_f32 %0, %1, %2" : "=v"(r) : "v"(lo), "v"(hi)); return r; }
; __device__ __forceinline__ void norm_pass(const Ctx& X, const float* xs, const float* cs, int nrows, const float* gain, const float* modl, int si, bf16_t* HN) {
;     ...
;         const float* row = r < MX ? xs + (size_t)r * D : cs + (size_t)(r - MX) * D;
;         const int mb = r < MX ? (r >> 12) : 8;
;         const float* sh = modl + (size_t)mb * 9216 + si * 1024; const float* scl = sh + 1024;
;         f32x4 v[4]; float s = 0.f;
; #pragma unroll
;         for (int j = 0; j < 4; ++j) { v[j] = *(const f32x4*)(row + (X.lane + 64 * j) * 4); s += (v[j].x * v[j].x + v[j].y * v[j].y) + (v[j].z * v[j].z + v[j].w * v[j].w); }
;         const float rstd = rsqrtf(wave_sum(s) * (1.0f / 1024.0f) + 1e-6f);
; #pragma unroll
;         for (int j = 0; j < 4; ++j) { const int c = (X.lane + 64 * j) * 4; const f32x4 gn = *(const f32x4*)(gain + c), a = *(const f32x4*)(scl + c), b = *(const f32x4*)(sh + c);
;             const f32x4 o = v[j] * rstd * gn * (a + 1.0f) + b; u32x2 w; w.x = cvt_pk_bf16(o.x, o.y); w.y = cvt_pk_bf16(o.z, o.w); *(u32x2*)(HN + (size_t)r * D + c) = w; }
	v_pk_mul_f32 v[200:201], v[128:129], v[128:129]
	v_pk_fma_f32 v[200:201], v[130:131], v[130:131], v[200:201]
	v_pk_fma_f32 v[200:201], v[132:133], v[132:133], v[200:201]
	v_pk_fma_f32 v[200:201], v[134:135], v[134:135], v[200:201]
	v_pk_fma_f32 v[200:201], v[136:137], v[136:137], v[200:201]
	v_pk_fma_f32 v[200:201], v[138:139], v[138:139], v[200:201]
	v_pk_fma_f32 v[200:201], v[140:141], v[140:141], v[200:201]
	v_pk_fma_f32 v[200:201], v[142:143], v[142:143], v[200:201]
	v_add_f32_e32 v200, v200, v201
	s_nop 1
	v_add_f32_dpp v200, v200, v200 quad_perm:[1,0,3,2] row_mask:0xf bank_mask:0xf
	s_nop 1
	v_add_f32_dpp v200, v200, v200 quad_perm:[2,3,0,1] row_mask:0xf bank_mask:0xf
	s_nop 1
	v_add_f32_dpp v200, v200, v200 row_half_mirror row_mask:0xf bank_mask:0xf
	s_nop 1
	v_add_f32_dpp v200, v200, v200 row_mirror row_mask:0xf bank_mask:0xf
	s_nop 1
	v_mov_b32_e32 v201, v200
	s_nop 1
	v_permlane16_swap_b32_e32 v200, v201
	s_nop 0
	v_add_f32_e32 v200, v200, v201
	v_mov_b32_e32 v201, v200
	s_nop 1
	v_permlane32_swap_b32_e32 v200, v201
	s_nop 0
	v_add_f32_e32 v200, v200, v201
	v_fmamk_f32 v200, v200, 0x3a800000, v3
	v_rsq_f32_e32 v200, v200
	s_nop 0
	v_pk_mul_f32 v[128:129], v[128:129], v[200:201] op_sel_hi:[1,0]
	v_pk_mul_f32 v[130:131], v[130:131], v[200:201] op_sel_hi:[1,0]
	v_pk_mul_f32 v[132:133], v[132:133], v[200:201] op_sel_hi:[1,0]
	v_pk_mul_f32 v[134:135], v[134:135], v[200:201] op_sel_hi:[1,0]
	v_pk_mul_f32 v[136:137], v[136:137], v[200:201] op_sel_hi:[1,0]
	v_pk_mul_f32 v[138:139], v[138:139], v[200:201] op_sel_hi:[1,0]
	v_pk_mul_f32 v[140:141], v[140:141], v[200:201] op_sel_hi:[1,0]
	v_pk_mul_f32 v[142:143], v[142:143], v[200:201] op_sel_hi:[1,0]
	v_pk_mul_f32 v[128:129], v[16:17], v[128:129]
	v_pk_mul_f32 v[130:131], v[18:19], v[130:131]
	v_pk_mul_f32 v[132:133], v[20:21], v[132:133]
	v_pk_mul_f32 v[134:135], v[22:23], v[134:135]
	v_pk_mul_f32 v[136:137], v[24:25], v[136:137]
	v_pk_mul_f32 v[138:139], v[26:27], v[138:139]
	v_pk_mul_f32 v[140:141], v[28:29], v[140:141]
	v_pk_mul_f32 v[142:143], v[30:31], v[142:143]
	v_pk_fma_f32 v[128:129], v[32:33], v[128:129], v[48:49]
	v_pk_fma_f32 v[130:131], v[34:35], v[130:131], v[50:51]
	v_pk_fma_f32 v[132:133], v[36:37], v[132:133], v[52:53]
	v_pk_fma_f32 v[134:135], v[38:39], v[134:135], v[54:55]
	v_pk_fma_f32 v[136:137], v[40:41], v[136:137], v[56:57]
	v_pk_fma_f32 v[138:139], v[42:43], v[138:139], v[58:59]
	v_pk_fma_f32 v[140:141], v[44:45], v[140:141], v[60:61]
	v_pk_fma_f32 v[142:143], v[46:47], v[142:143], v[62:63]
	v_cvt_pk_bf16_f32 v192, v128, v129
	v_cvt_pk_bf16_f32 v193, v130, v131
	v_cvt_pk_bf16_f32 v194, v132, v133
	v_cvt_pk_bf16_f32 v195, v134, v135
	v_cvt_pk_bf16_f32 v196, v136, v137
	v_cvt_pk_bf16_f32 v197, v138, v139
	v_cvt_pk_bf16_f32 v198, v140, v141
	v_cvt_pk_bf16_f32 v199, v142, v143
	global_store_dwordx4 v1, v[192:195], s[8:9] sc1
	global_store_dwordx4 v1, v[196:199], s[8:9] offset:1024 sc1
	global_load_dwordx4 v[128:131], v2, s[10:11]
	global_load_dwordx4 v[132:135], v2, s[10:11] offset:16
	global_load_dwordx4 v[136:139], v2, s[10:11] offset:2048
	global_load_dwordx4 v[140:143], v2, s[10:11] offset:2064
	s_waitcnt vmcnt(30)
	v_pk_mul_f32 v[200:201], v[144:145], v[144:145]
	v_pk_fma_f32 v[200:201], v[146:147], v[146:147], v[200:201]
	v_pk_fma_f32 v[200:201], v[148:149], v[148:149], v[200:201]
	v_pk_fma_f32 v[200:201], v[150:151], v[150:151], v[200:201]
	v_pk_fma_f32 v[200:201], v[152:153], v[152:153], v[200:201]
	v_pk_fma_f32 v[200:201], v[154:155], v[154:155], v[200:201]
	v_pk_fma_f32 v[200:201], v[156:157], v[156:157], v[200:201]
	v_pk_fma_f32 v[200:201], v[158:159], v[158:159], v[200:201]
	v_add_f32_e32 v200, v200, v201
	s_nop 1
	v_add_f32_dpp v200, v200, v200 quad_perm:[1,0,3,2] row_mask:0xf bank_mask:0xf
	s_nop 1
	v_add_f32_dpp v200, v200, v200 quad_perm:[2,3,0,1] row_mask:0xf bank_mask:0xf
	s_nop 1
	v_add_f32_dpp v200, v200, v200 row_half_mirror row_mask:0xf bank_mask:0xf
	s_nop 1
	v_add_f32_dpp v200, v200, v200 row_mirror row_mask:0xf bank_mask:0xf
	s_nop 1
	v_mov_b32_e32 v201, v200
	s_nop 1
	v_permlane16_swap_b32_e32 v200, v201
	s_nop 0
	v_add_f32_e32 v200, v200, v201
	v_mov_b32_e32 v201, v200
	s_nop 1
	v_permlane32_swap_b32_e32 v200, v201
	s_nop 0
	v_add_f32_e32 v200, v200, v201
	v_fmamk_f32 v200, v200, 0x3a800000, v3
	v_rsq_f32_e32 v200, v200
	s_nop 0
	v_pk_mul_f32 v[144:145], v[144:145], v[200:201] op_sel_hi:[1,0]
	v_pk_mul_f32 v[146:147], v[146:147], v[200:201] op_sel_hi:[1,0]
	v_pk_mul_f32 v[148:149], v[148:149], v[200:201] op_sel_hi:[1,0]
	v_pk_mul_f32 v[150:151], v[150:151], v[200:201] op_sel_hi:[1,0]
	v_pk_mul_f32 v[152:153], v[152:153], v[200:201] op_sel_hi:[1,0]
	v_pk_mul_f32 v[154:155], v[154:155], v[200:201] op_sel_hi:[1,0]
	v_pk_mul_f32 v[156:157], v[156:157], v[200:201] op_sel_hi:[1,0]
	v_pk_mul_f32 v[158:159], v[158:159], v[200:201] op_sel_hi:[1,0]
	v_pk_mul_f32 v[144:145], v[16:17], v[144:145]
	v_pk_mul_f32 v[146:147], v[18:19], v[146:147]
	v_pk_mul_f32 v[148:149], v[20:21], v[148:149]
	v_pk_mul_f32 v[150:151], v[22:23], v[150:151]
	v_pk_mul_f32 v[152:153], v[24:25], v[152:153]
	v_pk_mul_f32 v[154:155], v[26:27], v[154:155]
	v_pk_mul_f32 v[156:157], v[28:29], v[156:157]
	v_pk_mul_f32 v[158:159], v[30:31], v[158:159]
	v_pk_fma_f32 v[144:145], v[32:33], v[144:145], v[48:49]
	v_pk_fma_f32 v[146:147], v[34:35], v[146:147], v[50:51]
	v_pk_fma_f32 v[148:149], v[36:37], v[148:149], v[52:53]
	v_pk_fma_f32 v[150:151], v[38:39], v[150:151], v[54:55]
	v_pk_fma_f32 v[152:153], v[40:41], v[152:153], v[56:57]
	v_pk_fma_f32 v[154:155], v[42:43], v[154:155], v[58:59]
	v_pk_fma_f32 v[156:157], v[44:45], v[156:157], v[60:61]
	v_pk_fma_f32 v[158:159], v[46:47], v[158:159], v[62:63]
	v_cvt_pk_bf16_f32 v192, v144, v145
	v_cvt_pk_bf16_f32 v193, v146, v147
	v_cvt_pk_bf16_f32 v194, v148, v149
	v_cvt_pk_bf16_f32 v195, v150, v151
	v_cvt_pk_bf16_f32 v196, v152, v153
	v_cvt_pk_bf16_f32 v197, v154, v155
	v_cvt_pk_bf16_f32 v198, v156, v157
	v_cvt_pk_bf16_f32 v199, v158, v159
	global_store_dwordx4 v1, v[192:195], s[8:9] offset:2048 sc1
	global_store_dwordx4 v1, v[196:199], s[8:9] offset:3072 sc1
	s_add_u32 s8, s8, 0x1000
	s_addc_u32 s9, s9, 0
	s_waitcnt vmcnt(26)
; __device__ __forceinline__ unsigned cvt_pk_bf16(float lo, float hi) { unsigned r; asm("v_cvt_pk_bf16_f32 %0, %1, %2" : "=v"(r) : "v"(lo), "v"(hi)); return r; }
; __device__ __forceinline__ void norm_pass(const Ctx& X, const float* xs, const float* cs, int nrows, const float* gain, const float* modl, int si, bf16_t* HN) {
;     ...
;         f32x4 v[4]; float s = 0.f;
; #pragma unroll
;         for (int j = 0; j < 4; ++j) { v[j] = *(const f32x4*)(row + (X.lane + 64 * j) * 4); s += (v[j].x * v[j].x + v[j].y * v[j].y) + (v[j].z * v[j].z + v[j].w * v[j].w); }
;         const float rstd = rsqrtf(wave_sum(s) * (1.0f / 1024.0f) + 1e-6f);
; #pragma unroll
;         for (int j = 0; j < 4; ++j) { const int c = (X.lane + 64 * j) * 4; const f32x4 gn = *(const f32x4*)(gain + c), a = *(const f32x4*)(scl + c), b = *(const f32x4*)(sh + c);
;             const f32x4 o = v[j] * rstd * gn * (a + 1.0f) + b; u32x2 w; w.x = cvt_pk_bf16(o.x, o.y); w.y = cvt_pk_bf16(o.z, o.w); *(u32x2*)(HN + (size_t)r * D + c) = w; }
	v_pk_mul_f32 v[200:201], v[64:65], v[64:65]
	v_pk_fma_f32 v[200:201], v[66:67], v[66:67], v[200:201]
	v_pk_fma_f32 v[200:201], v[68:69], v[68:69], v[200:201]
	v_pk_fma_f32 v[200:201], v[70:71], v[70:71], v[200:201]
	v_pk_fma_f32 v[200:201], v[72:73], v[72:73], v[200:201]
	v_pk_fma_f32 v[200:201], v[74:75], v[74:75], v[200:201]
	v_pk_fma_f32 v[200:201], v[76:77], v[76:77], v[200:201]
	v_pk_fma_f32 v[200:201], v[78:79], v[78:79], v[200:201]
	v_add_f32_e32 v200, v200, v201
	s_nop 1
	v_add_f32_dpp v200, v200, v200 quad_perm:[1,0,3,2] row_mask:0xf bank_mask:0xf
	s_nop 1
	v_add_f32_dpp v200, v200, v200 quad_perm:[2,3,0,1] row_mask:0xf bank_mask:0xf
	s_nop 1
	v_add_f32_dpp v200, v200, v200 row_half_mirror row_mask:0xf bank_mask:0xf
	s_nop 1
	v_add_f32_dpp v200, v200, v200 row_mirror row_mask:0xf bank_mask:0xf
	s_nop 1
	v_mov_b32_e32 v201, v200
	s_nop 1
	v_permlane16_swap_b32_e32 v200, v201
	s_nop 0
	v_add_f32_e32 v200, v200, v201
	v_mov_b32_e32 v201, v200
	s_nop 1
	v_permlane32_swap_b32_e32 v200, v201
	s_nop 0
	v_add_f32_e32 v200, v200, v201
	v_fmamk_f32 v200, v200, 0x3a800000, v3
	v_rsq_f32_e32 v200, v200
	s_nop 0
	v_pk_mul_f32 v[64:65], v[64:65], v[200:201] op_sel_hi:[1,0]
	v_pk_mul_f32 v[66:67], v[66:67], v[200:201] op_sel_hi:[1,0]
	v_pk_mul_f32 v[68:69], v[68:69], v[200:201] op_sel_hi:[1,0]
	v_pk_mul_f32 v[70:71], v[70:71], v[200:201] op_sel_hi:[1,0]
	v_pk_mul_f32 v[72:73], v[72:73], v[200:201] op_sel_hi:[1,0]
	v_pk_mul_f32 v[74:75], v[74:75], v[200:201] op_sel_hi:[1,0]
	v_pk_mul_f32 v[76:77], v[76:77], v[200:201] op_sel_hi:[1,0]
	v_pk_mul_f32 v[78:79], v[78:79], v[200:201] op_sel_hi:[1,0]
	v_pk_mul_f32 v[64:65], v[16:17], v[64:65]
	v_pk_mul_f32 v[66:67], v[18:19], v[66:67]
	v_pk_mul_f32 v[68:69], v[20:21], v[68:69]
	v_pk_mul_f32 v[70:71], v[22:23], v[70:71]
	v_pk_mul_f32 v[72:73], v[24:25], v[72:73]
	v_pk_mul_f32 v[74:75], v[26:27], v[74:75]
	v_pk_mul_f32 v[76:77], v[28:29], v[76:77]
	v_pk_mul_f32 v[78:79], v[30:31], v[78:79]
	v_pk_fma_f32 v[64:65], v[32:33], v[64:65], v[48:49]
	v_pk_fma_f32 v[66:67], v[34:35], v[66:67], v[50:51]
	v_pk_fma_f32 v[68:69], v[36:37], v[68:69], v[52:53]
	v_pk_fma_f32 v[70:71], v[38:39], v[70:71], v[54:55]
	v_pk_fma_f32 v[72:73], v[40:41], v[72:73], v[56:57]
	v_pk_fma_f32 v[74:75], v[42:43], v[74:75], v[58:59]
	v_pk_fma_f32 v[76:77], v[44:45], v[76:77], v[60:61]
	v_pk_fma_f32 v[78:79], v[46:47], v[78:79], v[62:63]
	v_cvt_pk_bf16_f32 v192, v64, v65
	v_cvt_pk_bf16_f32 v193, v66, v67
	v_cvt_pk_bf16_f32 v194, v68, v69
	v_cvt_pk_bf16_f32 v195, v70, v71
	v_cvt_pk_bf16_f32 v196, v72, v73
	v_cvt_pk_bf16_f32 v197, v74, v75
	v_cvt_pk_bf16_f32 v198, v76, v77
	v_cvt_pk_bf16_f32 v199, v78, v79
	global_store_dwordx4 v1, v[192:195], s[8:9] sc1
	global_store_dwordx4 v1, v[196:199], s[8:9] offset:1024 sc1
	s_waitcnt vmcnt(22)
	v_pk_mul_f32 v[200:201], v[80:81], v[80:81]
	v_pk_fma_f32 v[200:201], v[82:83], v[82:83], v[200:201]
	v_pk_fma_f32 v[200:201], v[84:85], v[84:85], v[200:201]
	v_pk_fma_f32 v[200:201], v[86:87], v[86:87], v[200:201]
	v_pk_fma_f32 v[200:201], v[88:89], v[88:89], v[200:201]
	v_pk_fma_f32 v[200:201], v[90:91], v[90:91], v[200:201]
	v_pk_fma_f32 v[200:201], v[92:93], v[92:93], v[200:201]
	v_pk_fma_f32 v[200:201], v[94:95], v[94:95], v[200:201]
	v_add_f32_e32 v200, v200, v201
	s_nop 1
	v_add_f32_dpp v200, v200, v200 quad_perm:[1,0,3,2] row_mask:0xf bank_mask:0xf
	s_nop 1
	v_add_f32_dpp v200, v200, v200 quad_perm:[2,3,0,1] row_mask:0xf bank_mask:0xf
	s_nop 1
	v_add_f32_dpp v200, v200, v200 row_half_mirror row_mask:0xf bank_mask:0xf
	s_nop 1
	v_add_f32_dpp v200, v200, v200 row_mirror row_mask:0xf bank_mask:0xf
	s_nop 1
	v_mov_b32_e32 v201, v200
	s_nop 1
	v_permlane16_swap_b32_e32 v200, v201
	s_nop 0
	v_add_f32_e32 v200, v200, v201
	v_mov_b32_e32 v201, v200
	s_nop 1
	v_permlane32_swap_b32_e32 v200, v201
	s_nop 0
	v_add_f32_e32 v200, v200, v201
	v_fmamk_f32 v200, v200, 0x3a800000, v3
	v_rsq_f32_e32 v200, v200
	s_nop 0
	v_pk_mul_f32 v[80:81], v[80:81], v[200:201] op_sel_hi:[1,0]
	v_pk_mul_f32 v[82:83], v[82:83], v[200:201] op_sel_hi:[1,0]
	v_pk_mul_f32 v[84:85], v[84:85], v[200:201] op_sel_hi:[1,0]
	v_pk_mul_f32 v[86:87], v[86:87], v[200:201] op_sel_hi:[1,0]
	v_pk_mul_f32 v[88:89], v[88:89], v[200:201] op_sel_hi:[1,0]
	v_pk_mul_f32 v[90:91], v[90:91], v[200:201] op_sel_hi:[1,0]
	v_pk_mul_f32 v[92:93], v[92:93], v[200:201] op_sel_hi:[1,0]
	v_pk_mul_f32 v[94:95], v[94:95], v[200:201] op_sel_hi:[1,0]
	v_pk_mul_f32 v[80:81], v[16:17], v[80:81]
	v_pk_mul_f32 v[82:83], v[18:19], v[82:83]
	v_pk_mul_f32 v[84:85], v[20:21], v[84:85]
	v_pk_mul_f32 v[86:87], v[22:23], v[86:87]
	v_pk_mul_f32 v[88:89], v[24:25], v[88:89]
	v_pk_mul_f32 v[90:91], v[26:27], v[90:91]
	v_pk_mul_f32 v[92:93], v[28:29], v[92:93]
	v_pk_mul_f32 v[94:95], v[30:31], v[94:95]
	v_pk_fma_f32 v[80:81], v[32:33], v[80:81], v[48:49]
	v_pk_fma_f32 v[82:83], v[34:35], v[82:83], v[50:51]
	v_pk_fma_f32 v[84:85], v[36:37], v[84:85], v[52:53]
	v_pk_fma_f32 v[86:87], v[38:39], v[86:87], v[54:55]
	v_pk_fma_f32 v[88:89], v[40:41], v[88:89], v[56:57]
	v_pk_fma_f32 v[90:91], v[42:43], v[90:91], v[58:59]
	v_pk_fma_f32 v[92:93], v[44:45], v[92:93], v[60:61]
	v_pk_fma_f32 v[94:95], v[46:47], v[94:95], v[62:63]
	v_cvt_pk_bf16_f32 v192, v80, v81
	v_cvt_pk_bf16_f32 v193, v82, v83
	v_cvt_pk_bf16_f32 v194, v84, v85
	v_cvt_pk_bf16_f32 v195, v86, v87
	v_cvt_pk_bf16_f32 v196, v88, v89
	v_cvt_pk_bf16_f32 v197, v90, v91
	v_cvt_pk_bf16_f32 v198, v92, v93
	v_cvt_pk_bf16_f32 v199, v94, v95
	global_store_dwordx4 v1, v[192:195], s[8:9] offset:2048 sc1
	global_store_dwordx4 v1, v[196:199], s[8:9] offset:3072 sc1
	s_add_u32 s8, s8, 0x1000
	s_addc_u32 s9, s9, 0
	s_waitcnt vmcnt(18)
; __device__ __forceinline__ unsigned cvt_pk_bf16(float lo, float hi) { unsigned r; asm("v_cvt_pk_bf16_f32 %0, %1, %2" : "=v"(r) : "v"(lo), "v"(hi)); return r; }
; __device__ __forceinline__ void norm_pass(const Ctx& X, const float* xs, const float* cs, int nrows, const float* gain, const float* modl, int si, bf16_t* HN) {
;     ...
;         f32x4 v[4]; float s = 0.f;
; #pragma unroll
;         for (int j = 0; j < 4; ++j) { v[j] = *(const f32x4*)(row + (X.lane + 64 * j) * 4); s += (v[j].x * v[j].x + v[j].y * v[j].y) + (v[j].z * v[j].z + v[j].w * v[j].w); }
;         const float rstd = rsqrtf(wave_sum(s) * (1.0f / 1024.0f) + 1e-6f);
; #pragma unroll
;         for (int j = 0; j < 4; ++j) { const int c = (X.lane + 64 * j) * 4; const f32x4 gn = *(const f32x4*)(gain + c), a = *(const f32x4*)(scl + c), b = *(const f32x4*)(sh + c);
;             const f32x4 o = v[j] * rstd * gn * (a + 1.0f) + b; u32x2 w; w.x = cvt_pk_bf16(o.x, o.y); w.y = cvt_pk_bf16(o.z, o.w); *(u32x2*)(HN + (size_t)r * D + c) = w; }
	v_pk_mul_f32 v[200:201], v[96:97], v[96:97]
	v_pk_fma_f32 v[200:201], v[98:99], v[98:99], v[200:201]
	v_pk_fma_f32 v[200:201], v[100:101], v[100:101], v[200:201]
	v_pk_fma_f32 v[200:201], v[102:103], v[102:103], v[200:201]
	v_pk_fma_f32 v[200:201], v[104:105], v[104:105], v[200:201]
	v_pk_fma_f32 v[200:201], v[106:107], v[106:107], v[200:201]
	v_pk_fma_f32 v[200:201], v[108:109], v[108:109], v[200:201]
	v_pk_fma_f32 v[200:201], v[110:111], v[110:111], v[200:201]
	v_add_f32_e32 v200, v200, v201
	s_nop 1
	v_add_f32_dpp v200, v200, v200 quad_perm:[1,0,3,2] row_mask:0xf bank_mask:0xf
	s_nop 1
	v_add_f32_dpp v200, v200, v200 quad_perm:[2,3,0,1] row_mask:0xf bank_mask:0xf
	s_nop 1
	v_add_f32_dpp v200, v200, v200 row_half_mirror row_mask:0xf bank_mask:0xf
	s_nop 1
	v_add_f32_dpp v200, v200, v200 row_mirror row_mask:0xf bank_mask:0xf
	s_nop 1
	v_mov_b32_e32 v201, v200
	s_nop 1
	v_permlane16_swap_b32_e32 v200, v201
	s_nop 0
	v_add_f32_e32 v200, v200, v201
	v_mov_b32_e32 v201, v200
	s_nop 1
	v_permlane32_swap_b32_e32 v200, v201
	s_nop 0
	v_add_f32_e32 v200, v200, v201
	v_fmamk_f32 v200, v200, 0x3a800000, v3
	v_rsq_f32_e32 v200, v200
	s_nop 0
	v_pk_mul_f32 v[96:97], v[96:97], v[200:201] op_sel_hi:[1,0]
	v_pk_mul_f32 v[98:99], v[98:99], v[200:201] op_sel_hi:[1,0]
	v_pk_mul_f32 v[100:101], v[100:101], v[200:201] op_sel_hi:[1,0]
	v_pk_mul_f32 v[102:103], v[102:103], v[200:201] op_sel_hi:[1,0]
	v_pk_mul_f32 v[104:105], v[104:105], v[200:201] op_sel_hi:[1,0]
	v_pk_mul_f32 v[106:107], v[106:107], v[200:201] op_sel_hi:[1,0]
	v_pk_mul_f32 v[108:109], v[108:109], v[200:201] op_sel_hi:[1,0]
	v_pk_mul_f32 v[110:111], v[110:111], v[200:201] op_sel_hi:[1,0]
	v_pk_mul_f32 v[96:97], v[16:17], v[96:97]
	v_pk_mul_f32 v[98:99], v[18:19], v[98:99]
	v_pk_mul_f32 v[100:101], v[20:21], v[100:101]
	v_pk_mul_f32 v[102:103], v[22:23], v[102:103]
	v_pk_mul_f32 v[104:105], v[24:25], v[104:105]
	v_pk_mul_f32 v[106:107], v[26:27], v[106:107]
	v_pk_mul_f32 v[108:109], v[28:29], v[108:109]
	v_pk_mul_f32 v[110:111], v[30:31], v[110:111]
	v_pk_fma_f32 v[96:97], v[32:33], v[96:97], v[48:49]
	v_pk_fma_f32 v[98:99], v[34:35], v[98:99], v[50:51]
	v_pk_fma_f32 v[100:101], v[36:37], v[100:101], v[52:53]
	v_pk_fma_f32 v[102:103], v[38:39], v[102:103], v[54:55]
	v_pk_fma_f32 v[104:105], v[40:41], v[104:105], v[56:57]
	v_pk_fma_f32 v[106:107], v[42:43], v[106:107], v[58:59]
	v_pk_fma_f32 v[108:109], v[44:45], v[108:109], v[60:61]
	v_pk_fma_f32 v[110:111], v[46:47], v[110:111], v[62:63]
	v_cvt_pk_bf16_f32 v192, v96, v97
	v_cvt_pk_bf16_f32 v193, v98, v99
	v_cvt_pk_bf16_f32 v194, v100, v101
	v_cvt_pk_bf16_f32 v195, v102, v103
	v_cvt_pk_bf16_f32 v196, v104, v105
	v_cvt_pk_bf16_f32 v197, v106, v107
	v_cvt_pk_bf16_f32 v198, v108, v109
	v_cvt_pk_bf16_f32 v199, v110, v111
	global_store_dwordx4 v1, v[192:195], s[8:9] sc1
	global_store_dwordx4 v1, v[196:199], s[8:9] offset:1024 sc1
	s_waitcnt vmcnt(14)
	v_pk_mul_f32 v[200:201], v[112:113], v[112:113]
	v_pk_fma_f32 v[200:201], v[114:115], v[114:115], v[200:201]
	v_pk_fma_f32 v[200:201], v[116:117], v[116:117], v[200:201]
	v_pk_fma_f32 v[200:201], v[118:119], v[118:119], v[200:201]
	v_pk_fma_f32 v[200:201], v[120:121], v[120:121], v[200:201]
	v_pk_fma_f32 v[200:201], v[122:123], v[122:123], v[200:201]
	v_pk_fma_f32 v[200:201], v[124:125], v[124:125], v[200:201]
	v_pk_fma_f32 v[200:201], v[126:127], v[126:127], v[200:201]
	v_add_f32_e32 v200, v200, v201
	s_nop 1
	v_add_f32_dpp v200, v200, v200 quad_perm:[1,0,3,2] row_mask:0xf bank_mask:0xf
	s_nop 1
	v_add_f32_dpp v200, v200, v200 quad_perm:[2,3,0,1] row_mask:0xf bank_mask:0xf
	s_nop 1
	v_add_f32_dpp v200, v200, v200 row_half_mirror row_mask:0xf bank_mask:0xf
	s_nop 1
	v_add_f32_dpp v200, v200, v200 row_mirror row_mask:0xf bank_mask:0xf
	s_nop 1
	v_mov_b32_e32 v201, v200
	s_nop 1
	v_permlane16_swap_b32_e32 v200, v201
	s_nop 0
	v_add_f32_e32 v200, v200, v201
	v_mov_b32_e32 v201, v200
	s_nop 1
	v_permlane32_swap_b32_e32 v200, v201
	s_nop 0
	v_add_f32_e32 v200, v200, v201
	v_fmamk_f32 v200, v200, 0x3a800000, v3
	v_rsq_f32_e32 v200, v200
	s_nop 0
	v_pk_mul_f32 v[112:113], v[112:113], v[200:201] op_sel_hi:[1,0]
	v_pk_mul_f32 v[114:115], v[114:115], v[200:201] op_sel_hi:[1,0]
	v_pk_mul_f32 v[116:117], v[116:117], v[200:201] op_sel_hi:[1,0]
	v_pk_mul_f32 v[118:119], v[118:119], v[200:201] op_sel_hi:[1,0]
	v_pk_mul_f32 v[120:121], v[120:121], v[200:201] op_sel_hi:[1,0]
	v_pk_mul_f32 v[122:123], v[122:123], v[200:201] op_sel_hi:[1,0]
	v_pk_mul_f32 v[124:125], v[124:125], v[200:201] op_sel_hi:[1,0]
	v_pk_mul_f32 v[126:127], v[126:127], v[200:201] op_sel_hi:[1,0]
	v_pk_mul_f32 v[112:113], v[16:17], v[112:113]
	v_pk_mul_f32 v[114:115], v[18:19], v[114:115]
	v_pk_mul_f32 v[116:117], v[20:21], v[116:117]
	v_pk_mul_f32 v[118:119], v[22:23], v[118:119]
	v_pk_mul_f32 v[120:121], v[24:25], v[120:121]
	v_pk_mul_f32 v[122:123], v[26:27], v[122:123]
	v_pk_mul_f32 v[124:125], v[28:29], v[124:125]
	v_pk_mul_f32 v[126:127], v[30:31], v[126:127]
	v_pk_fma_f32 v[112:113], v[32:33], v[112:113], v[48:49]
	v_pk_fma_f32 v[114:115], v[34:35], v[114:115], v[50:51]
	v_pk_fma_f32 v[116:117], v[36:37], v[116:117], v[52:53]
	v_pk_fma_f32 v[118:119], v[38:39], v[118:119], v[54:55]
	v_pk_fma_f32 v[120:121], v[40:41], v[120:121], v[56:57]
	v_pk_fma_f32 v[122:123], v[42:43], v[122:123], v[58:59]
	v_pk_fma_f32 v[124:125], v[44:45], v[124:125], v[60:61]
	v_pk_fma_f32 v[126:127], v[46:47], v[126:127], v[62:63]
	v_cvt_pk_bf16_f32 v192, v112, v113
	v_cvt_pk_bf16_f32 v193, v114, v115
	v_cvt_pk_bf16_f32 v194, v116, v117
	v_cvt_pk_bf16_f32 v195, v118, v119
	v_cvt_pk_bf16_f32 v196, v120, v121
	v_cvt_pk_bf16_f32 v197, v122, v123
	v_cvt_pk_bf16_f32 v198, v124, v125
	v_cvt_pk_bf16_f32 v199, v126, v127
	global_store_dwordx4 v1, v[192:195], s[8:9] offset:2048 sc1
	global_store_dwordx4 v1, v[196:199], s[8:9] offset:3072 sc1
	s_add_u32 s8, s8, 0x1000
	s_addc_u32 s9, s9, 0
	s_waitcnt vmcnt(10)
; __device__ __forceinline__ unsigned cvt_pk_bf16(float lo, float hi) { unsigned r; asm("v_cvt_pk_bf16_f32 %0, %1, %2" : "=v"(r) : "v"(lo), "v"(hi)); return r; }
; __device__ __forceinline__ void norm_pass(const Ctx& X, const float* xs, const float* cs, int nrows, const float* gain, const float* modl, int si, bf16_t* HN) {
;     ...
;         const float* row = r < MX ? xs + (size_t)r * D : cs + (size_t)(r - MX) * D;
;         const int mb = r < MX ? (r >> 12) : 8;
;         const float* sh = modl + (size_t)mb * 9216 + si * 1024; const float* scl = sh + 1024;
;         f32x4 v[4]; float s = 0.f;
; #pragma unroll
;         for (int j = 0; j < 4; ++j) { v[j] = *(const f32x4*)(row + (X.lane + 64 * j) * 4); s += (v[j].x * v[j].x + v[j].y * v[j].y) + (v[j].z * v[j].z + v[j].w * v[j].w); }
;         const float rstd = rsqrtf(wave_sum(s) * (1.0f / 1024.0f) + 1e-6f);
; #pragma unroll
;         for (int j = 0; j < 4; ++j) { const int c = (X.lane + 64 * j) * 4; const f32x4 gn = *(const f32x4*)(gain + c), a = *(const f32x4*)(scl + c), b = *(const f32x4*)(sh + c);
;             const f32x4 o = v[j] * rstd * gn * (a + 1.0f) + b; u32x2 w; w.x = cvt_pk_bf16(o.x, o.y); w.y = cvt_pk_bf16(o.z, o.w); *(u32x2*)(HN + (size_t)r * D + c) = w; }
;     }
	v_pk_mul_f32 v[200:201], v[128:129], v[128:129]
	v_pk_fma_f32 v[200:201], v[130:131], v[130:131], v[200:201]
	v_pk_fma_f32 v[200:201], v[132:133], v[132:133], v[200:201]
	v_pk_fma_f32 v[200:201], v[134:135], v[134:135], v[200:201]
	v_pk_fma_f32 v[200:201], v[136:137], v[136:137], v[200:201]
	v_pk_fma_f32 v[200:201], v[138:139], v[138:139], v[200:201]
	v_pk_fma_f32 v[200:201], v[140:141], v[140:141], v[200:201]
	v_pk_fma_f32 v[200:201], v[142:143], v[142:143], v[200:201]
	v_add_f32_e32 v200, v200, v201
	s_nop 1
	v_add_f32_dpp v200, v200, v200 quad_perm:[1,0,3,2] row_mask:0xf bank_mask:0xf
	s_nop 1
	v_add_f32_dpp v200, v200, v200 quad_perm:[2,3,0,1] row_mask:0xf bank_mask:0xf
	s_nop 1
	v_add_f32_dpp v200, v200, v200 row_half_mirror row_mask:0xf bank_mask:0xf
	s_nop 1
	v_add_f32_dpp v200, v200, v200 row_mirror row_mask:0xf bank_mask:0xf
	s_nop 1
	v_mov_b32_e32 v201, v200
	s_nop 1
	v_permlane16_swap_b32_e32 v200, v201
	s_nop 0
	v_add_f32_e32 v200, v200, v201
	v_mov_b32_e32 v201, v200
	s_nop 1
	v_permlane32_swap_b32_e32 v200, v201
	s_nop 0
	v_add_f32_e32 v200, v200, v201
	v_fmamk_f32 v200, v200, 0x3a800000, v3
	v_rsq_f32_e32 v200, v200
	s_nop 0
	v_pk_mul_f32 v[128:129], v[128:129], v[200:201] op_sel_hi:[1,0]
	v_pk_mul_f32 v[130:131], v[130:131], v[200:201] op_sel_hi:[1,0]
	v_pk_mul_f32 v[132:133], v[132:133], v[200:201] op_sel_hi:[1,0]
	v_pk_mul_f32 v[134:135], v[134:135], v[200:201] op_sel_hi:[1,0]
	v_pk_mul_f32 v[136:137], v[136:137], v[200:201] op_sel_hi:[1,0]
	v_pk_mul_f32 v[138:139], v[138:139], v[200:201] op_sel_hi:[1,0]
	v_pk_mul_f32 v[140:141], v[140:141], v[200:201] op_sel_hi:[1,0]
	v_pk_mul_f32 v[142:143], v[142:143], v[200:201] op_sel_hi:[1,0]
	v_pk_mul_f32 v[128:129], v[16:17], v[128:129]
	v_pk_mul_f32 v[130:131], v[18:19], v[130:131]
	v_pk_mul_f32 v[132:133], v[20:21], v[132:133]
	v_pk_mul_f32 v[134:135], v[22:23], v[134:135]
	v_pk_mul_f32 v[136:137], v[24:25], v[136:137]
	v_pk_mul_f32 v[138:139], v[26:27], v[138:139]
	v_pk_mul_f32 v[140:141], v[28:29], v[140:141]
	v_pk_mul_f32 v[142:143], v[30:31], v[142:143]
	v_pk_fma_f32 v[128:129], v[160:161], v[128:129], v[176:177]
	v_pk_fma_f32 v[130:131], v[162:163], v[130:131], v[178:179]
	v_pk_fma_f32 v[132:133], v[164:165], v[132:133], v[180:181]
	v_pk_fma_f32 v[134:135], v[166:167], v[134:135], v[182:183]
	v_pk_fma_f32 v[136:137], v[168:169], v[136:137], v[184:185]
	v_pk_fma_f32 v[138:139], v[170:171], v[138:139], v[186:187]
	v_pk_fma_f32 v[140:141], v[172:173], v[140:141], v[188:189]
	v_pk_fma_f32 v[142:143], v[174:175], v[142:143], v[190:191]
	v_cvt_pk_bf16_f32 v192, v128, v129
	v_cvt_pk_bf16_f32 v193, v130, v131
	v_cvt_pk_bf16_f32 v194, v132, v133
	v_cvt_pk_bf16_f32 v195, v134, v135
	v_cvt_pk_bf16_f32 v196, v136, v137
	v_cvt_pk_bf16_f32 v197, v138, v139
	v_cvt_pk_bf16_f32 v198, v140, v141
	v_cvt_pk_bf16_f32 v199, v142, v143
	global_store_dwordx4 v1, v[192:195], s[12:13] sc1
	global_store_dwordx4 v1, v[196:199], s[12:13] offset:1024 sc1
	s_add_i32 s14, s14, s20
	s_cmp_lt_i32 s14, 0x800
	s_cbranch_scc0 .LBB0_194
	s_waitcnt vmcnt(0)
	s_branch .Lhn32_blk

; __device__ __forceinline__ unsigned cvt_pk_bf16(float lo, float hi) { unsigned r; asm("v_cvt_pk_bf16_f32 %0, %1, %2" : "=v"(r) : "v"(lo), "v"(hi)); return r; }
; __device__ __forceinline__ void norm_pass_bf16(const Ctx& X, const bf16_t* xs, const bf16_t* cs, int nrows, const float* gain, const float* modl, int si, bf16_t* HN) {
;     for (int r = X.gw; r < nrows; r += X.NGW) {
;         const int mb = r < MX ? (r >> 12) : 8;
;         const float* sh = modl + (size_t)mb * 9216 + si * 1024; const float* scl = sh + 1024;
;         const bf16_t* rowp = r < MX ? xs + (size_t)r * D : cs + (size_t)(r - MX) * D;
;         u32x4 q[2]; float v[2][8]; float s = 0.f;
; #pragma unroll
;         for (int j = 0; j < 2; ++j) q[j] = *(const u32x4*)(rowp + (X.lane + 64 * j) * 8);
; #pragma unroll
;         for (int j = 0; j < 2; ++j) {
;             v[j][0] = bf2f(q[j].x & 0xffffu); v[j][1] = bf2f(q[j].x >> 16); v[j][2] = bf2f(q[j].y & 0xffffu); v[j][3] = bf2f(q[j].y >> 16);
;             v[j][4] = bf2f(q[j].z & 0xffffu); v[j][5] = bf2f(q[j].z >> 16); v[j][6] = bf2f(q[j].w & 0xffffu); v[j][7] = bf2f(q[j].w >> 16);
; #pragma unroll
;             for (int e = 0; e < 8; ++e) s += v[j][e] * v[j][e]; }
;         const float rstd = rsqrtf(wave_sum(s) * (1.0f / 1024.0f) + 1e-6f);
; #pragma unroll
;         for (int j = 0; j < 2; ++j) { const int c = (X.lane + 64 * j) * 8; float o[8];
; #pragma unroll
;             for (int h = 0; h < 2; ++h) { const f32x4 gn = *(const f32x4*)(gain + c + 4 * h), a = *(const f32x4*)(scl + c + 4 * h), b = *(const f32x4*)(sh + c + 4 * h);
; #pragma unroll
;                 for (int e = 0; e < 4; ++e) o[4 * h + e] = v[j][4 * h + e] * rstd * gn[e] * (a[e] + 1.0f) + b[e]; }
;             u32x4 w; w.x = cvt_pk_bf16(o[0], o[1]); w.y = cvt_pk_bf16(o[2], o[3]); w.z = cvt_pk_bf16(o[4], o[5]); w.w = cvt_pk_bf16(o[6], o[7]); *(u32x4*)(HN + (size_t)r * D + c) = w; }
.Lhn_A_blk:
	s_add_u32 s6, s48, 0x1000
	s_addc_u32 s7, s49, 0
	global_load_dwordx4 v[16:19], v2, s[6:7]
	global_load_dwordx4 v[20:23], v2, s[6:7] offset:16
	global_load_dwordx4 v[24:27], v2, s[6:7] offset:2048
	global_load_dwordx4 v[28:31], v2, s[6:7] offset:2064
	s_lshr_b32 s5, s12, 8
	s_mul_i32 s5, s5, 0x9000
	s_add_u32 s6, s88, s5
	s_addc_u32 s7, s89, 0
	s_add_u32 s6, s6, 0x3000
	s_addc_u32 s7, s7, 0
	global_load_dwordx4 v[48:51], v2, s[6:7]
	global_load_dwordx4 v[52:55], v2, s[6:7] offset:16
	global_load_dwordx4 v[56:59], v2, s[6:7] offset:2048
	global_load_dwordx4 v[60:63], v2, s[6:7] offset:2064
	s_add_u32 s6, s6, 0x1000
	s_addc_u32 s7, s7, 0
	global_load_dwordx4 v[32:35], v2, s[6:7]
	global_load_dwordx4 v[36:39], v2, s[6:7] offset:16
	global_load_dwordx4 v[40:43], v2, s[6:7] offset:2048
	global_load_dwordx4 v[44:47], v2, s[6:7] offset:2064
	s_lshl_b32 s5, s12, 15
	s_add_u32 s8, s86, s5
	s_addc_u32 s9, s87, 0
	s_add_u32 s10, s88, s5
	s_addc_u32 s11, s89, 0
	s_add_u32 s10, s10, 0x13000000
	s_addc_u32 s11, s11, 0
	global_load_dwordx4 v[64:67], v1, s[8:9]
	global_load_dwordx4 v[68:71], v1, s[8:9] offset:1024
	global_load_dwordx4 v[72:75], v1, s[8:9] offset:2048
	global_load_dwordx4 v[76:79], v1, s[8:9] offset:3072
	s_add_u32 s8, s8, 0x1000
	s_addc_u32 s9, s9, 0
	global_load_dwordx4 v[80:83], v1, s[8:9]
	global_load_dwordx4 v[84:87], v1, s[8:9] offset:1024
	global_load_dwordx4 v[88:91], v1, s[8:9] offset:2048
	global_load_dwordx4 v[92:95], v1, s[8:9] offset:3072
	s_add_u32 s8, s8, 0x1000
	s_addc_u32 s9, s9, 0
	global_load_dwordx4 v[96:99], v1, s[8:9]
	global_load_dwordx4 v[100:103], v1, s[8:9] offset:1024
	global_load_dwordx4 v[104:107], v1, s[8:9] offset:2048
	global_load_dwordx4 v[108:111], v1, s[8:9] offset:3072
	s_add_u32 s8, s8, 0x1000
	s_addc_u32 s9, s9, 0
	global_load_dwordx4 v[112:115], v1, s[8:9]
	global_load_dwordx4 v[116:119], v1, s[8:9] offset:1024
	global_load_dwordx4 v[120:123], v1, s[8:9] offset:2048
	global_load_dwordx4 v[124:127], v1, s[8:9] offset:3072
	s_add_u32 s8, s8, 0x1000
	s_addc_u32 s9, s9, 0
	s_waitcnt vmcnt(16)
	v_pk_add_f32 v[32:33], v[32:33], 1.0 op_sel_hi:[1,0]
	v_pk_add_f32 v[34:35], v[34:35], 1.0 op_sel_hi:[1,0]
	v_pk_add_f32 v[36:37], v[36:37], 1.0 op_sel_hi:[1,0]
	v_pk_add_f32 v[38:39], v[38:39], 1.0 op_sel_hi:[1,0]
	v_pk_add_f32 v[40:41], v[40:41], 1.0 op_sel_hi:[1,0]
	v_pk_add_f32 v[42:43], v[42:43], 1.0 op_sel_hi:[1,0]
	v_pk_add_f32 v[44:45], v[44:45], 1.0 op_sel_hi:[1,0]
	v_pk_add_f32 v[46:47], v[46:47], 1.0 op_sel_hi:[1,0]
	s_waitcnt vmcnt(14)
	v_lshlrev_b32_e32 v128, 16, v64
	v_and_b32_e32 v129, 0xffff0000, v64
	v_lshlrev_b32_e32 v130, 16, v65
	v_and_b32_e32 v131, 0xffff0000, v65
	v_lshlrev_b32_e32 v132, 16, v66
	v_and_b32_e32 v133, 0xffff0000, v66
	v_lshlrev_b32_e32 v134, 16, v67
	v_and_b32_e32 v135, 0xffff0000, v67
	v_lshlrev_b32_e32 v136, 16, v68
	v_and_b32_e32 v137, 0xffff0000, v68
	v_lshlrev_b32_e32 v138, 16, v69
	v_and_b32_e32 v139, 0xffff0000, v69
	v_lshlrev_b32_e32 v140, 16, v70
	v_and_b32_e32 v141, 0xffff0000, v70
	v_lshlrev_b32_e32 v142, 16, v71
	v_and_b32_e32 v143, 0xffff0000, v71
	v_pk_mul_f32 v[144:145], v[128:129], v[128:129]
	v_pk_fma_f32 v[144:145], v[130:131], v[130:131], v[144:145]
	v_pk_fma_f32 v[144:145], v[132:133], v[132:133], v[144:145]
	v_pk_fma_f32 v[144:145], v[134:135], v[134:135], v[144:145]
	v_pk_fma_f32 v[144:145], v[136:137], v[136:137], v[144:145]
	v_pk_fma_f32 v[144:145], v[138:139], v[138:139], v[144:145]
	v_pk_fma_f32 v[144:145], v[140:141], v[140:141], v[144:145]
	v_pk_fma_f32 v[144:145], v[142:143], v[142:143], v[144:145]
	v_add_f32_e32 v144, v144, v145
	s_nop 1
	v_add_f32_dpp v144, v144, v144 quad_perm:[1,0,3,2] row_mask:0xf bank_mask:0xf
	s_nop 1
	v_add_f32_dpp v144, v144, v144 quad_perm:[2,3,0,1] row_mask:0xf bank_mask:0xf
	s_nop 1
	v_add_f32_dpp v144, v144, v144 row_half_mirror row_mask:0xf bank_mask:0xf
	s_nop 1
	v_add_f32_dpp v144, v144, v144 row_mirror row_mask:0xf bank_mask:0xf
	s_nop 0
	v_mov_b32_e32 v145, v144
	s_nop 1
	v_permlane16_swap_b32_e32 v144, v145
	s_nop 0
	v_add_f32_e32 v144, v144, v145
	v_mov_b32_e32 v145, v144
	s_nop 1
	v_permlane32_swap_b32_e32 v144, v145
	s_nop 0
	v_add_f32_e32 v144, v144, v145
	v_fmamk_f32 v144, v144, 0x3a800000, v3
	v_rsq_f32_e32 v144, v144
	s_nop 0
	v_pk_mul_f32 v[128:129], v[128:129], v[144:145] op_sel_hi:[1,0]
	v_pk_mul_f32 v[130:131], v[130:131], v[144:145] op_sel_hi:[1,0]
	v_pk_mul_f32 v[132:133], v[132:133], v[144:145] op_sel_hi:[1,0]
	v_pk_mul_f32 v[134:135], v[134:135], v[144:145] op_sel_hi:[1,0]
	v_pk_mul_f32 v[136:137], v[136:137], v[144:145] op_sel_hi:[1,0]
	v_pk_mul_f32 v[138:139], v[138:139], v[144:145] op_sel_hi:[1,0]
	v_pk_mul_f32 v[140:141], v[140:141], v[144:145] op_sel_hi:[1,0]
	v_pk_mul_f32 v[142:143], v[142:143], v[144:145] op_sel_hi:[1,0]
	v_pk_mul_f32 v[128:129], v[16:17], v[128:129]
	v_pk_mul_f32 v[130:131], v[18:19], v[130:131]
	v_pk_mul_f32 v[132:133], v[20:21], v[132:133]
	v_pk_mul_f32 v[134:135], v[22:23], v[134:135]
	v_pk_mul_f32 v[136:137], v[24:25], v[136:137]
	v_pk_mul_f32 v[138:139], v[26:27], v[138:139]
	v_pk_mul_f32 v[140:141], v[28:29], v[140:141]
	v_pk_mul_f32 v[142:143], v[30:31], v[142:143]
	v_pk_fma_f32 v[128:129], v[32:33], v[128:129], v[48:49]
	v_pk_fma_f32 v[130:131], v[34:35], v[130:131], v[50:51]
	v_pk_fma_f32 v[132:133], v[36:37], v[132:133], v[52:53]
	v_pk_fma_f32 v[134:135], v[38:39], v[134:135], v[54:55]
	v_pk_fma_f32 v[136:137], v[40:41], v[136:137], v[56:57]
	v_pk_fma_f32 v[138:139], v[42:43], v[138:139], v[58:59]
	v_pk_fma_f32 v[140:141], v[44:45], v[140:141], v[60:61]
	v_pk_fma_f32 v[142:143], v[46:47], v[142:143], v[62:63]
	v_cvt_pk_bf16_f32 v148, v128, v129
	v_cvt_pk_bf16_f32 v149, v130, v131
	v_cvt_pk_bf16_f32 v150, v132, v133
	v_cvt_pk_bf16_f32 v151, v134, v135
	v_cvt_pk_bf16_f32 v152, v136, v137
	v_cvt_pk_bf16_f32 v153, v138, v139
	v_cvt_pk_bf16_f32 v154, v140, v141
	v_cvt_pk_bf16_f32 v155, v142, v143
	global_store_dwordx4 v1, v[148:151], s[10:11] sc1
	global_store_dwordx4 v1, v[152:155], s[10:11] offset:1024 sc1
	global_load_dwordx4 v[64:67], v1, s[8:9]
	global_load_dwordx4 v[68:71], v1, s[8:9] offset:1024
	s_waitcnt vmcnt(16)
; __device__ __forceinline__ unsigned cvt_pk_bf16(float lo, float hi) { unsigned r; asm("v_cvt_pk_bf16_f32 %0, %1, %2" : "=v"(r) : "v"(lo), "v"(hi)); return r; }
; __device__ __forceinline__ void norm_pass_bf16(const Ctx& X, const bf16_t* xs, const bf16_t* cs, int nrows, const float* gain, const float* modl, int si, bf16_t* HN) {
;     ...
;         u32x4 q[2]; float v[2][8]; float s = 0.f;
; #pragma unroll
;         for (int j = 0; j < 2; ++j) q[j] = *(const u32x4*)(rowp + (X.lane + 64 * j) * 8);
; #pragma unroll
;         for (int j = 0; j < 2; ++j) {
;             v[j][0] = bf2f(q[j].x & 0xffffu); v[j][1] = bf2f(q[j].x >> 16); v[j][2] = bf2f(q[j].y & 0xffffu); v[j][3] = bf2f(q[j].y >> 16);
;             v[j][4] = bf2f(q[j].z & 0xffffu); v[j][5] = bf2f(q[j].z >> 16); v[j][6] = bf2f(q[j].w & 0xffffu); v[j][7] = bf2f(q[j].w >> 16);
; #pragma unroll
;             for (int e = 0; e < 8; ++e) s += v[j][e] * v[j][e]; }
;         const float rstd = rsqrtf(wave_sum(s) * (1.0f / 1024.0f) + 1e-6f);
; #pragma unroll
;         for (int j = 0; j < 2; ++j) { const int c = (X.lane + 64 * j) * 8; float o[8];
; #pragma unroll
;             for (int h = 0; h < 2; ++h) { const f32x4 gn = *(const f32x4*)(gain + c + 4 * h), a = *(const f32x4*)(scl + c + 4 * h), b = *(const f32x4*)(sh + c + 4 * h);
; #pragma unroll
;                 for (int e = 0; e < 4; ++e) o[4 * h + e] = v[j][4 * h + e] * rstd * gn[e] * (a[e] + 1.0f) + b[e]; }
;             u32x4 w; w.x = cvt_pk_bf16(o[0], o[1]); w.y = cvt_pk_bf16(o[2], o[3]); w.z = cvt_pk_bf16(o[4], o[5]); w.w = cvt_pk_bf16(o[6], o[7]); *(u32x4*)(HN + (size_t)r * D + c) = w; }
	v_lshlrev_b32_e32 v128, 16, v72
	v_and_b32_e32 v129, 0xffff0000, v72
	v_lshlrev_b32_e32 v130, 16, v73
	v_and_b32_e32 v131, 0xffff0000, v73
	v_lshlrev_b32_e32 v132, 16, v74
	v_and_b32_e32 v133, 0xffff0000, v74
	v_lshlrev_b32_e32 v134, 16, v75
	v_and_b32_e32 v135, 0xffff0000, v75
	v_lshlrev_b32_e32 v136, 16, v76
	v_and_b32_e32 v137, 0xffff0000, v76
	v_lshlrev_b32_e32 v138, 16, v77
	v_and_b32_e32 v139, 0xffff0000, v77
	v_lshlrev_b32_e32 v140, 16, v78
	v_and_b32_e32 v141, 0xffff0000, v78
	v_lshlrev_b32_e32 v142, 16, v79
	v_and_b32_e32 v143, 0xffff0000, v79
	v_pk_mul_f32 v[144:145], v[128:129], v[128:129]
	v_pk_fma_f32 v[144:145], v[130:131], v[130:131], v[144:145]
	v_pk_fma_f32 v[144:145], v[132:133], v[132:133], v[144:145]
	v_pk_fma_f32 v[144:145], v[134:135], v[134:135], v[144:145]
	v_pk_fma_f32 v[144:145], v[136:137], v[136:137], v[144:145]
	v_pk_fma_f32 v[144:145], v[138:139], v[138:139], v[144:145]
	v_pk_fma_f32 v[144:145], v[140:141], v[140:141], v[144:145]
	v_pk_fma_f32 v[144:145], v[142:143], v[142:143], v[144:145]
	v_add_f32_e32 v144, v144, v145
	s_nop 1
	v_add_f32_dpp v144, v144, v144 quad_perm:[1,0,3,2] row_mask:0xf bank_mask:0xf
	s_nop 1
	v_add_f32_dpp v144, v144, v144 quad_perm:[2,3,0,1] row_mask:0xf bank_mask:0xf
	s_nop 1
	v_add_f32_dpp v144, v144, v144 row_half_mirror row_mask:0xf bank_mask:0xf
	s_nop 1
	v_add_f32_dpp v144, v144, v144 row_mirror row_mask:0xf bank_mask:0xf
	s_nop 0
	v_mov_b32_e32 v145, v144
	s_nop 1
	v_permlane16_swap_b32_e32 v144, v145
	s_nop 0
	v_add_f32_e32 v144, v144, v145
	v_mov_b32_e32 v145, v144
	s_nop 1
	v_permlane32_swap_b32_e32 v144, v145
	s_nop 0
	v_add_f32_e32 v144, v144, v145
	v_fmamk_f32 v144, v144, 0x3a800000, v3
	v_rsq_f32_e32 v144, v144
	s_nop 0
	v_pk_mul_f32 v[128:129], v[128:129], v[144:145] op_sel_hi:[1,0]
	v_pk_mul_f32 v[130:131], v[130:131], v[144:145] op_sel_hi:[1,0]
	v_pk_mul_f32 v[132:133], v[132:133], v[144:145] op_sel_hi:[1,0]
	v_pk_mul_f32 v[134:135], v[134:135], v[144:145] op_sel_hi:[1,0]
	v_pk_mul_f32 v[136:137], v[136:137], v[144:145] op_sel_hi:[1,0]
	v_pk_mul_f32 v[138:139], v[138:139], v[144:145] op_sel_hi:[1,0]
	v_pk_mul_f32 v[140:141], v[140:141], v[144:145] op_sel_hi:[1,0]
	v_pk_mul_f32 v[142:143], v[142:143], v[144:145] op_sel_hi:[1,0]
	v_pk_mul_f32 v[128:129], v[16:17], v[128:129]
	v_pk_mul_f32 v[130:131], v[18:19], v[130:131]
	v_pk_mul_f32 v[132:133], v[20:21], v[132:133]
	v_pk_mul_f32 v[134:135], v[22:23], v[134:135]
	v_pk_mul_f32 v[136:137], v[24:25], v[136:137]
	v_pk_mul_f32 v[138:139], v[26:27], v[138:139]
	v_pk_mul_f32 v[140:141], v[28:29], v[140:141]
	v_pk_mul_f32 v[142:143], v[30:31], v[142:143]
	v_pk_fma_f32 v[128:129], v[32:33], v[128:129], v[48:49]
	v_pk_fma_f32 v[130:131], v[34:35], v[130:131], v[50:51]
	v_pk_fma_f32 v[132:133], v[36:37], v[132:133], v[52:53]
	v_pk_fma_f32 v[134:135], v[38:39], v[134:135], v[54:55]
	v_pk_fma_f32 v[136:137], v[40:41], v[136:137], v[56:57]
	v_pk_fma_f32 v[138:139], v[42:43], v[138:139], v[58:59]
	v_pk_fma_f32 v[140:141], v[44:45], v[140:141], v[60:61]
	v_pk_fma_f32 v[142:143], v[46:47], v[142:143], v[62:63]
	v_cvt_pk_bf16_f32 v148, v128, v129
	v_cvt_pk_bf16_f32 v149, v130, v131
	v_cvt_pk_bf16_f32 v150, v132, v133
	v_cvt_pk_bf16_f32 v151, v134, v135
	v_cvt_pk_bf16_f32 v152, v136, v137
	v_cvt_pk_bf16_f32 v153, v138, v139
	v_cvt_pk_bf16_f32 v154, v140, v141
	v_cvt_pk_bf16_f32 v155, v142, v143
	global_store_dwordx4 v1, v[148:151], s[10:11] offset:2048 sc1
	global_store_dwordx4 v1, v[152:155], s[10:11] offset:3072 sc1
	s_add_u32 s10, s10, 0x1000
	s_addc_u32 s11, s11, 0
	global_load_dwordx4 v[72:75], v1, s[8:9] offset:2048
	global_load_dwordx4 v[76:79], v1, s[8:9] offset:3072
	s_add_u32 s8, s8, 0x1000
	s_addc_u32 s9, s9, 0
	s_waitcnt vmcnt(18)
	v_lshlrev_b32_e32 v128, 16, v80
	v_and_b32_e32 v129, 0xffff0000, v80
	v_lshlrev_b32_e32 v130, 16, v81
	v_and_b32_e32 v131, 0xffff0000, v81
	v_lshlrev_b32_e32 v132, 16, v82
	v_and_b32_e32 v133, 0xffff0000, v82
	v_lshlrev_b32_e32 v134, 16, v83
	v_and_b32_e32 v135, 0xffff0000, v83
	v_lshlrev_b32_e32 v136, 16, v84
	v_and_b32_e32 v137, 0xffff0000, v84
	v_lshlrev_b32_e32 v138, 16, v85
	v_and_b32_e32 v139, 0xffff0000, v85
	v_lshlrev_b32_e32 v140, 16, v86
	v_and_b32_e32 v141, 0xffff0000, v86
	v_lshlrev_b32_e32 v142, 16, v87
	v_and_b32_e32 v143, 0xffff0000, v87
	v_pk_mul_f32 v[144:145], v[128:129], v[128:129]
	v_pk_fma_f32 v[144:145], v[130:131], v[130:131], v[144:145]
	v_pk_fma_f32 v[144:145], v[132:133], v[132:133], v[144:145]
	v_pk_fma_f32 v[144:145], v[134:135], v[134:135], v[144:145]
	v_pk_fma_f32 v[144:145], v[136:137], v[136:137], v[144:145]
	v_pk_fma_f32 v[144:145], v[138:139], v[138:139], v[144:145]
	v_pk_fma_f32 v[144:145], v[140:141], v[140:141], v[144:145]
	v_pk_fma_f32 v[144:145], v[142:143], v[142:143], v[144:145]
	v_add_f32_e32 v144, v144, v145
	s_nop 1
	v_add_f32_dpp v144, v144, v144 quad_perm:[1,0,3,2] row_mask:0xf bank_mask:0xf
	s_nop 1
	v_add_f32_dpp v144, v144, v144 quad_perm:[2,3,0,1] row_mask:0xf bank_mask:0xf
	s_nop 1
	v_add_f32_dpp v144, v144, v144 row_half_mirror row_mask:0xf bank_mask:0xf
	s_nop 1
	v_add_f32_dpp v144, v144, v144 row_mirror row_mask:0xf bank_mask:0xf
	s_nop 0
	v_mov_b32_e32 v145, v144
	s_nop 1
	v_permlane16_swap_b32_e32 v144, v145
	s_nop 0
	v_add_f32_e32 v144, v144, v145
	v_mov_b32_e32 v145, v144
	s_nop 1
	v_permlane32_swap_b32_e32 v144, v145
	s_nop 0
	v_add_f32_e32 v144, v144, v145
	v_fmamk_f32 v144, v144, 0x3a800000, v3
	v_rsq_f32_e32 v144, v144
	s_nop 0
	v_pk_mul_f32 v[128:129], v[128:129], v[144:145] op_sel_hi:[1,0]
	v_pk_mul_f32 v[130:131], v[130:131], v[144:145] op_sel_hi:[1,0]
	v_pk_mul_f32 v[132:133], v[132:133], v[144:145] op_sel_hi:[1,0]
; __device__ __forceinline__ unsigned cvt_pk_bf16(float lo, float hi) { unsigned r; asm("v_cvt_pk_bf16_f32 %0, %1, %2" : "=v"(r) : "v"(lo), "v"(hi)); return r; }
; __device__ __forceinline__ void norm_pass_bf16(const Ctx& X, const bf16_t* xs, const bf16_t* cs, int nrows, const float* gain, const float* modl, int si, bf16_t* HN) {
;     ...
;         u32x4 q[2]; float v[2][8]; float s = 0.f;
; #pragma unroll
;         for (int j = 0; j < 2; ++j) q[j] = *(const u32x4*)(rowp + (X.lane + 64 * j) * 8);
; #pragma unroll
;         for (int j = 0; j < 2; ++j) {
;             v[j][0] = bf2f(q[j].x & 0xffffu); v[j][1] = bf2f(q[j].x >> 16); v[j][2] = bf2f(q[j].y & 0xffffu); v[j][3] = bf2f(q[j].y >> 16);
;             v[j][4] = bf2f(q[j].z & 0xffffu); v[j][5] = bf2f(q[j].z >> 16); v[j][6] = bf2f(q[j].w & 0xffffu); v[j][7] = bf2f(q[j].w >> 16);
; #pragma unroll
;             for (int e = 0; e < 8; ++e) s += v[j][e] * v[j][e]; }
;         const float rstd = rsqrtf(wave_sum(s) * (1.0f / 1024.0f) + 1e-6f);
; #pragma unroll
;         for (int j = 0; j < 2; ++j) { const int c = (X.lane + 64 * j) * 8; float o[8];
; #pragma unroll
;             for (int h = 0; h < 2; ++h) { const f32x4 gn = *(const f32x4*)(gain + c + 4 * h), a = *(const f32x4*)(scl + c + 4 * h), b = *(const f32x4*)(sh + c + 4 * h);
; #pragma unroll
;                 for (int e = 0; e < 4; ++e) o[4 * h + e] = v[j][4 * h + e] * rstd * gn[e] * (a[e] + 1.0f) + b[e]; }
;             u32x4 w; w.x = cvt_pk_bf16(o[0], o[1]); w.y = cvt_pk_bf16(o[2], o[3]); w.z = cvt_pk_bf16(o[4], o[5]); w.w = cvt_pk_bf16(o[6], o[7]); *(u32x4*)(HN + (size_t)r * D + c) = w; }
	v_pk_mul_f32 v[134:135], v[134:135], v[144:145] op_sel_hi:[1,0]
	v_pk_mul_f32 v[136:137], v[136:137], v[144:145] op_sel_hi:[1,0]
	v_pk_mul_f32 v[138:139], v[138:139], v[144:145] op_sel_hi:[1,0]
	v_pk_mul_f32 v[140:141], v[140:141], v[144:145] op_sel_hi:[1,0]
	v_pk_mul_f32 v[142:143], v[142:143], v[144:145] op_sel_hi:[1,0]
	v_pk_mul_f32 v[128:129], v[16:17], v[128:129]
	v_pk_mul_f32 v[130:131], v[18:19], v[130:131]
	v_pk_mul_f32 v[132:133], v[20:21], v[132:133]
	v_pk_mul_f32 v[134:135], v[22:23], v[134:135]
	v_pk_mul_f32 v[136:137], v[24:25], v[136:137]
	v_pk_mul_f32 v[138:139], v[26:27], v[138:139]
	v_pk_mul_f32 v[140:141], v[28:29], v[140:141]
	v_pk_mul_f32 v[142:143], v[30:31], v[142:143]
	v_pk_fma_f32 v[128:129], v[32:33], v[128:129], v[48:49]
	v_pk_fma_f32 v[130:131], v[34:35], v[130:131], v[50:51]
	v_pk_fma_f32 v[132:133], v[36:37], v[132:133], v[52:53]
	v_pk_fma_f32 v[134:135], v[38:39], v[134:135], v[54:55]
	v_pk_fma_f32 v[136:137], v[40:41], v[136:137], v[56:57]
	v_pk_fma_f32 v[138:139], v[42:43], v[138:139], v[58:59]
	v_pk_fma_f32 v[140:141], v[44:45], v[140:141], v[60:61]
	v_pk_fma_f32 v[142:143], v[46:47], v[142:143], v[62:63]
	v_cvt_pk_bf16_f32 v148, v128, v129
	v_cvt_pk_bf16_f32 v149, v130, v131
	v_cvt_pk_bf16_f32 v150, v132, v133
	v_cvt_pk_bf16_f32 v151, v134, v135
	v_cvt_pk_bf16_f32 v152, v136, v137
	v_cvt_pk_bf16_f32 v153, v138, v139
	v_cvt_pk_bf16_f32 v154, v140, v141
	v_cvt_pk_bf16_f32 v155, v142, v143
	global_store_dwordx4 v1, v[148:151], s[10:11] sc1
	global_store_dwordx4 v1, v[152:155], s[10:11] offset:1024 sc1
	global_load_dwordx4 v[80:83], v1, s[8:9]
	global_load_dwordx4 v[84:87], v1, s[8:9] offset:1024
	s_waitcnt vmcnt(20)
	v_lshlrev_b32_e32 v128, 16, v88
	v_and_b32_e32 v129, 0xffff0000, v88
	v_lshlrev_b32_e32 v130, 16, v89
	v_and_b32_e32 v131, 0xffff0000, v89
	v_lshlrev_b32_e32 v132, 16, v90
	v_and_b32_e32 v133, 0xffff0000, v90
	v_lshlrev_b32_e32 v134, 16, v91
	v_and_b32_e32 v135, 0xffff0000, v91
	v_lshlrev_b32_e32 v136, 16, v92
	v_and_b32_e32 v137, 0xffff0000, v92
	v_lshlrev_b32_e32 v138, 16, v93
	v_and_b32_e32 v139, 0xffff0000, v93
	v_lshlrev_b32_e32 v140, 16, v94
	v_and_b32_e32 v141, 0xffff0000, v94
	v_lshlrev_b32_e32 v142, 16, v95
	v_and_b32_e32 v143, 0xffff0000, v95
	v_pk_mul_f32 v[144:145], v[128:129], v[128:129]
	v_pk_fma_f32 v[144:145], v[130:131], v[130:131], v[144:145]
	v_pk_fma_f32 v[144:145], v[132:133], v[132:133], v[144:145]
	v_pk_fma_f32 v[144:145], v[134:135], v[134:135], v[144:145]
	v_pk_fma_f32 v[144:145], v[136:137], v[136:137], v[144:145]
	v_pk_fma_f32 v[144:145], v[138:139], v[138:139], v[144:145]
	v_pk_fma_f32 v[144:145], v[140:141], v[140:141], v[144:145]
	v_pk_fma_f32 v[144:145], v[142:143], v[142:143], v[144:145]
	v_add_f32_e32 v144, v144, v145
	s_nop 1
	v_add_f32_dpp v144, v144, v144 quad_perm:[1,0,3,2] row_mask:0xf bank_mask:0xf
	s_nop 1
	v_add_f32_dpp v144, v144, v144 quad_perm:[2,3,0,1] row_mask:0xf bank_mask:0xf
	s_nop 1
	v_add_f32_dpp v144, v144, v144 row_half_mirror row_mask:0xf bank_mask:0xf
	s_nop 1
	v_add_f32_dpp v144, v144, v144 row_mirror row_mask:0xf bank_mask:0xf
	s_nop 0
	v_mov_b32_e32 v145, v144
	s_nop 1
	v_permlane16_swap_b32_e32 v144, v145
	s_nop 0
	v_add_f32_e32 v144, v144, v145
	v_mov_b32_e32 v145, v144
	s_nop 1
	v_permlane32_swap_b32_e32 v144, v145
	s_nop 0
	v_add_f32_e32 v144, v144, v145
	v_fmamk_f32 v144, v144, 0x3a800000, v3
	v_rsq_f32_e32 v144, v144
	s_nop 0
	v_pk_mul_f32 v[128:129], v[128:129], v[144:145] op_sel_hi:[1,0]
	v_pk_mul_f32 v[130:131], v[130:131], v[144:145] op_sel_hi:[1,0]
	v_pk_mul_f32 v[132:133], v[132:133], v[144:145] op_sel_hi:[1,0]
	v_pk_mul_f32 v[134:135], v[134:135], v[144:145] op_sel_hi:[1,0]
	v_pk_mul_f32 v[136:137], v[136:137], v[144:145] op_sel_hi:[1,0]
	v_pk_mul_f32 v[138:139], v[138:139], v[144:145] op_sel_hi:[1,0]
	v_pk_mul_f32 v[140:141], v[140:141], v[144:145] op_sel_hi:[1,0]
	v_pk_mul_f32 v[142:143], v[142:143], v[144:145] op_sel_hi:[1,0]
	v_pk_mul_f32 v[128:129], v[16:17], v[128:129]
	v_pk_mul_f32 v[130:131], v[18:19], v[130:131]
	v_pk_mul_f32 v[132:133], v[20:21], v[132:133]
	v_pk_mul_f32 v[134:135], v[22:23], v[134:135]
	v_pk_mul_f32 v[136:137], v[24:25], v[136:137]
	v_pk_mul_f32 v[138:139], v[26:27], v[138:139]
	v_pk_mul_f32 v[140:141], v[28:29], v[140:141]
	v_pk_mul_f32 v[142:143], v[30:31], v[142:143]
	v_pk_fma_f32 v[128:129], v[32:33], v[128:129], v[48:49]
	v_pk_fma_f32 v[130:131], v[34:35], v[130:131], v[50:51]
	v_pk_fma_f32 v[132:133], v[36:37], v[132:133], v[52:53]
	v_pk_fma_f32 v[134:135], v[38:39], v[134:135], v[54:55]
	v_pk_fma_f32 v[136:137], v[40:41], v[136:137], v[56:57]
	v_pk_fma_f32 v[138:139], v[42:43], v[138:139], v[58:59]
	v_pk_fma_f32 v[140:141], v[44:45], v[140:141], v[60:61]
	v_pk_fma_f32 v[142:143], v[46:47], v[142:143], v[62:63]
	v_cvt_pk_bf16_f32 v148, v128, v129
	v_cvt_pk_bf16_f32 v149, v130, v131
	v_cvt_pk_bf16_f32 v150, v132, v133
	v_cvt_pk_bf16_f32 v151, v134, v135
	v_cvt_pk_bf16_f32 v152, v136, v137
	v_cvt_pk_bf16_f32 v153, v138, v139
	v_cvt_pk_bf16_f32 v154, v140, v141
	v_cvt_pk_bf16_f32 v155, v142, v143
	global_store_dwordx4 v1, v[148:151], s[10:11] offset:2048 sc1
	global_store_dwordx4 v1, v[152:155], s[10:11] offset:3072 sc1
	s_add_u32 s10, s10, 0x1000
	s_addc_u32 s11, s11, 0
	global_load_dwordx4 v[88:91], v1, s[8:9] offset:2048
	global_load_dwordx4 v[92:95], v1, s[8:9] offset:3072
	s_add_u32 s8, s8, 0x1000
	s_addc_u32 s9, s9, 0
	s_waitcnt vmcnt(22)
; __device__ __forceinline__ unsigned cvt_pk_bf16(float lo, float hi) { unsigned r; asm("v_cvt_pk_bf16_f32 %0, %1, %2" : "=v"(r) : "v"(lo), "v"(hi)); return r; }
; __device__ __forceinline__ void norm_pass_bf16(const Ctx& X, const bf16_t* xs, const bf16_t* cs, int nrows, const float* gain, const float* modl, int si, bf16_t* HN) {
;     ...
;         u32x4 q[2]; float v[2][8]; float s = 0.f;
; #pragma unroll
;         for (int j = 0; j < 2; ++j) q[j] = *(const u32x4*)(rowp + (X.lane + 64 * j) * 8);
; #pragma unroll
;         for (int j = 0; j < 2; ++j) {
;             v[j][0] = bf2f(q[j].x & 0xffffu); v[j][1] = bf2f(q[j].x >> 16); v[j][2] = bf2f(q[j].y & 0xffffu); v[j][3] = bf2f(q[j].y >> 16);
;             v[j][4] = bf2f(q[j].z & 0xffffu); v[j][5] = bf2f(q[j].z >> 16); v[j][6] = bf2f(q[j].w & 0xffffu); v[j][7] = bf2f(q[j].w >> 16);
; #pragma unroll
;             for (int e = 0; e < 8; ++e) s += v[j][e] * v[j][e]; }
;         const float rstd = rsqrtf(wave_sum(s) * (1.0f / 1024.0f) + 1e-6f);
; #pragma unroll
;         for (int j = 0; j < 2; ++j) { const int c = (X.lane + 64 * j) * 8; float o[8];
; #pragma unroll
;             for (int h = 0; h < 2; ++h) { const f32x4 gn = *(const f32x4*)(gain + c + 4 * h), a = *(const f32x4*)(scl + c + 4 * h), b = *(const f32x4*)(sh + c + 4 * h);
; #pragma unroll
;                 for (int e = 0; e < 4; ++e) o[4 * h + e] = v[j][4 * h + e] * rstd * gn[e] * (a[e] + 1.0f) + b[e]; }
;             u32x4 w; w.x = cvt_pk_bf16(o[0], o[1]); w.y = cvt_pk_bf16(o[2], o[3]); w.z = cvt_pk_bf16(o[4], o[5]); w.w = cvt_pk_bf16(o[6], o[7]); *(u32x4*)(HN + (size_t)r * D + c) = w; }
	v_lshlrev_b32_e32 v128, 16, v96
	v_and_b32_e32 v129, 0xffff0000, v96
	v_lshlrev_b32_e32 v130, 16, v97
	v_and_b32_e32 v131, 0xffff0000, v97
	v_lshlrev_b32_e32 v132, 16, v98
	v_and_b32_e32 v133, 0xffff0000, v98
	v_lshlrev_b32_e32 v134, 16, v99
	v_and_b32_e32 v135, 0xffff0000, v99
	v_lshlrev_b32_e32 v136, 16, v100
	v_and_b32_e32 v137, 0xffff0000, v100
	v_lshlrev_b32_e32 v138, 16, v101
	v_and_b32_e32 v139, 0xffff0000, v101
	v_lshlrev_b32_e32 v140, 16, v102
	v_and_b32_e32 v141, 0xffff0000, v102
	v_lshlrev_b32_e32 v142, 16, v103
	v_and_b32_e32 v143, 0xffff0000, v103
	v_pk_mul_f32 v[144:145], v[128:129], v[128:129]
	v_pk_fma_f32 v[144:145], v[130:131], v[130:131], v[144:145]
	v_pk_fma_f32 v[144:145], v[132:133], v[132:133], v[144:145]
	v_pk_fma_f32 v[144:145], v[134:135], v[134:135], v[144:145]
	v_pk_fma_f32 v[144:145], v[136:137], v[136:137], v[144:145]
	v_pk_fma_f32 v[144:145], v[138:139], v[138:139], v[144:145]
	v_pk_fma_f32 v[144:145], v[140:141], v[140:141], v[144:145]
	v_pk_fma_f32 v[144:145], v[142:143], v[142:143], v[144:145]
	v_add_f32_e32 v144, v144, v145
	s_nop 1
	v_add_f32_dpp v144, v144, v144 quad_perm:[1,0,3,2] row_mask:0xf bank_mask:0xf
	s_nop 1
	v_add_f32_dpp v144, v144, v144 quad_perm:[2,3,0,1] row_mask:0xf bank_mask:0xf
	s_nop 1
	v_add_f32_dpp v144, v144, v144 row_half_mirror row_mask:0xf bank_mask:0xf
	s_nop 1
	v_add_f32_dpp v144, v144, v144 row_mirror row_mask:0xf bank_mask:0xf
	s_nop 0
	v_mov_b32_e32 v145, v144
	s_nop 1
	v_permlane16_swap_b32_e32 v144, v145
	s_nop 0
	v_add_f32_e32 v144, v144, v145
	v_mov_b32_e32 v145, v144
	s_nop 1
	v_permlane32_swap_b32_e32 v144, v145
	s_nop 0
	v_add_f32_e32 v144, v144, v145
	v_fmamk_f32 v144, v144, 0x3a800000, v3
	v_rsq_f32_e32 v144, v144
	s_nop 0
	v_pk_mul_f32 v[128:129], v[128:129], v[144:145] op_sel_hi:[1,0]
	v_pk_mul_f32 v[130:131], v[130:131], v[144:145] op_sel_hi:[1,0]
	v_pk_mul_f32 v[132:133], v[132:133], v[144:145] op_sel_hi:[1,0]
	v_pk_mul_f32 v[134:135], v[134:135], v[144:145] op_sel_hi:[1,0]
	v_pk_mul_f32 v[136:137], v[136:137], v[144:145] op_sel_hi:[1,0]
	v_pk_mul_f32 v[138:139], v[138:139], v[144:145] op_sel_hi:[1,0]
	v_pk_mul_f32 v[140:141], v[140:141], v[144:145] op_sel_hi:[1,0]
	v_pk_mul_f32 v[142:143], v[142:143], v[144:145] op_sel_hi:[1,0]
	v_pk_mul_f32 v[128:129], v[16:17], v[128:129]
	v_pk_mul_f32 v[130:131], v[18:19], v[130:131]
	v_pk_mul_f32 v[132:133], v[20:21], v[132:133]
	v_pk_mul_f32 v[134:135], v[22:23], v[134:135]
	v_pk_mul_f32 v[136:137], v[24:25], v[136:137]
	v_pk_mul_f32 v[138:139], v[26:27], v[138:139]
	v_pk_mul_f32 v[140:141], v[28:29], v[140:141]
	v_pk_mul_f32 v[142:143], v[30:31], v[142:143]
	v_pk_fma_f32 v[128:129], v[32:33], v[128:129], v[48:49]
	v_pk_fma_f32 v[130:131], v[34:35], v[130:131], v[50:51]
	v_pk_fma_f32 v[132:133], v[36:37], v[132:133], v[52:53]
	v_pk_fma_f32 v[134:135], v[38:39], v[134:135], v[54:55]
	v_pk_fma_f32 v[136:137], v[40:41], v[136:137], v[56:57]
	v_pk_fma_f32 v[138:139], v[42:43], v[138:139], v[58:59]
	v_pk_fma_f32 v[140:141], v[44:45], v[140:141], v[60:61]
	v_pk_fma_f32 v[142:143], v[46:47], v[142:143], v[62:63]
	v_cvt_pk_bf16_f32 v148, v128, v129
	v_cvt_pk_bf16_f32 v149, v130, v131
	v_cvt_pk_bf16_f32 v150, v132, v133
	v_cvt_pk_bf16_f32 v151, v134, v135
	v_cvt_pk_bf16_f32 v152, v136, v137
	v_cvt_pk_bf16_f32 v153, v138, v139
	v_cvt_pk_bf16_f32 v154, v140, v141
	v_cvt_pk_bf16_f32 v155, v142, v143
	global_store_dwordx4 v1, v[148:151], s[10:11] sc1
	global_store_dwordx4 v1, v[152:155], s[10:11] offset:1024 sc1
	global_load_dwordx4 v[96:99], v1, s[8:9]
	global_load_dwordx4 v[100:103], v1, s[8:9] offset:1024
	s_waitcnt vmcnt(24)
	v_lshlrev_b32_e32 v128, 16, v104
	v_and_b32_e32 v129, 0xffff0000, v104
	v_lshlrev_b32_e32 v130, 16, v105
	v_and_b32_e32 v131, 0xffff0000, v105
	v_lshlrev_b32_e32 v132, 16, v106
	v_and_b32_e32 v133, 0xffff0000, v106
	v_lshlrev_b32_e32 v134, 16, v107
	v_and_b32_e32 v135, 0xffff0000, v107
	v_lshlrev_b32_e32 v136, 16, v108
	v_and_b32_e32 v137, 0xffff0000, v108
	v_lshlrev_b32_e32 v138, 16, v109
	v_and_b32_e32 v139, 0xffff0000, v109
	v_lshlrev_b32_e32 v140, 16, v110
	v_and_b32_e32 v141, 0xffff0000, v110
	v_lshlrev_b32_e32 v142, 16, v111
	v_and_b32_e32 v143, 0xffff0000, v111
	v_pk_mul_f32 v[144:145], v[128:129], v[128:129]
	v_pk_fma_f32 v[144:145], v[130:131], v[130:131], v[144:145]
	v_pk_fma_f32 v[144:145], v[132:133], v[132:133], v[144:145]
	v_pk_fma_f32 v[144:145], v[134:135], v[134:135], v[144:145]
	v_pk_fma_f32 v[144:145], v[136:137], v[136:137], v[144:145]
	v_pk_fma_f32 v[144:145], v[138:139], v[138:139], v[144:145]
	v_pk_fma_f32 v[144:145], v[140:141], v[140:141], v[144:145]
	v_pk_fma_f32 v[144:145], v[142:143], v[142:143], v[144:145]
	v_add_f32_e32 v144, v144, v145
	s_nop 1
	v_add_f32_dpp v144, v144, v144 quad_perm:[1,0,3,2] row_mask:0xf bank_mask:0xf
	s_nop 1
	v_add_f32_dpp v144, v144, v144 quad_perm:[2,3,0,1] row_mask:0xf bank_mask:0xf
	s_nop 1
	v_add_f32_dpp v144, v144, v144 row_half_mirror row_mask:0xf bank_mask:0xf
	s_nop 1
	v_add_f32_dpp v144, v144, v144 row_mirror row_mask:0xf bank_mask:0xf
	s_nop 0
	v_mov_b32_e32 v145, v144
	s_nop 1
	v_permlane16_swap_b32_e32 v144, v145
	s_nop 0
	v_add_f32_e32 v144, v144, v145
	v_mov_b32_e32 v145, v144
	s_nop 1
	v_permlane32_swap_b32_e32 v144, v145
	s_nop 0
	v_add_f32_e32 v144, v144, v145
	v_fmamk_f32 v144, v144, 0x3a800000, v3
	v_rsq_f32_e32 v144, v144
	s_nop 0
	v_pk_mul_f32 v[128:129], v[128:129], v[144:145] op_sel_hi:[1,0]
	v_pk_mul_f32 v[130:131], v[130:131], v[144:145] op_sel_hi:[1,0]
	v_pk_mul_f32 v[132:133], v[132:133], v[144:145] op_sel_hi:[1,0]
	v_pk_mul_f32 v[134:135], v[134:135], v[144:145] op_sel_hi:[1,0]
	v_pk_mul_f32 v[136:137], v[136:137], v[144:145] op_sel_hi:[1,0]
; __device__ __forceinline__ unsigned cvt_pk_bf16(float lo, float hi) { unsigned r; asm("v_cvt_pk_bf16_f32 %0, %1, %2" : "=v"(r) : "v"(lo), "v"(hi)); return r; }
; __device__ __forceinline__ void norm_pass_bf16(const Ctx& X, const bf16_t* xs, const bf16_t* cs, int nrows, const float* gain, const float* modl, int si, bf16_t* HN) {
;     ...
;         u32x4 q[2]; float v[2][8]; float s = 0.f;
; #pragma unroll
;         for (int j = 0; j < 2; ++j) q[j] = *(const u32x4*)(rowp + (X.lane + 64 * j) * 8);
; #pragma unroll
;         for (int j = 0; j < 2; ++j) {
;             v[j][0] = bf2f(q[j].x & 0xffffu); v[j][1] = bf2f(q[j].x >> 16); v[j][2] = bf2f(q[j].y & 0xffffu); v[j][3] = bf2f(q[j].y >> 16);
;             v[j][4] = bf2f(q[j].z & 0xffffu); v[j][5] = bf2f(q[j].z >> 16); v[j][6] = bf2f(q[j].w & 0xffffu); v[j][7] = bf2f(q[j].w >> 16);
; #pragma unroll
;             for (int e = 0; e < 8; ++e) s += v[j][e] * v[j][e]; }
;         const float rstd = rsqrtf(wave_sum(s) * (1.0f / 1024.0f) + 1e-6f);
; #pragma unroll
;         for (int j = 0; j < 2; ++j) { const int c = (X.lane + 64 * j) * 8; float o[8];
; #pragma unroll
;             for (int h = 0; h < 2; ++h) { const f32x4 gn = *(const f32x4*)(gain + c + 4 * h), a = *(const f32x4*)(scl + c + 4 * h), b = *(const f32x4*)(sh + c + 4 * h);
; #pragma unroll
;                 for (int e = 0; e < 4; ++e) o[4 * h + e] = v[j][4 * h + e] * rstd * gn[e] * (a[e] + 1.0f) + b[e]; }
;             u32x4 w; w.x = cvt_pk_bf16(o[0], o[1]); w.y = cvt_pk_bf16(o[2], o[3]); w.z = cvt_pk_bf16(o[4], o[5]); w.w = cvt_pk_bf16(o[6], o[7]); *(u32x4*)(HN + (size_t)r * D + c) = w; }
	v_pk_mul_f32 v[138:139], v[138:139], v[144:145] op_sel_hi:[1,0]
	v_pk_mul_f32 v[140:141], v[140:141], v[144:145] op_sel_hi:[1,0]
	v_pk_mul_f32 v[142:143], v[142:143], v[144:145] op_sel_hi:[1,0]
	v_pk_mul_f32 v[128:129], v[16:17], v[128:129]
	v_pk_mul_f32 v[130:131], v[18:19], v[130:131]
	v_pk_mul_f32 v[132:133], v[20:21], v[132:133]
	v_pk_mul_f32 v[134:135], v[22:23], v[134:135]
	v_pk_mul_f32 v[136:137], v[24:25], v[136:137]
	v_pk_mul_f32 v[138:139], v[26:27], v[138:139]
	v_pk_mul_f32 v[140:141], v[28:29], v[140:141]
	v_pk_mul_f32 v[142:143], v[30:31], v[142:143]
	v_pk_fma_f32 v[128:129], v[32:33], v[128:129], v[48:49]
	v_pk_fma_f32 v[130:131], v[34:35], v[130:131], v[50:51]
	v_pk_fma_f32 v[132:133], v[36:37], v[132:133], v[52:53]
	v_pk_fma_f32 v[134:135], v[38:39], v[134:135], v[54:55]
	v_pk_fma_f32 v[136:137], v[40:41], v[136:137], v[56:57]
	v_pk_fma_f32 v[138:139], v[42:43], v[138:139], v[58:59]
	v_pk_fma_f32 v[140:141], v[44:45], v[140:141], v[60:61]
	v_pk_fma_f32 v[142:143], v[46:47], v[142:143], v[62:63]
	v_cvt_pk_bf16_f32 v148, v128, v129
	v_cvt_pk_bf16_f32 v149, v130, v131
	v_cvt_pk_bf16_f32 v150, v132, v133
	v_cvt_pk_bf16_f32 v151, v134, v135
	v_cvt_pk_bf16_f32 v152, v136, v137
	v_cvt_pk_bf16_f32 v153, v138, v139
	v_cvt_pk_bf16_f32 v154, v140, v141
	v_cvt_pk_bf16_f32 v155, v142, v143
	global_store_dwordx4 v1, v[148:151], s[10:11] offset:2048 sc1
	global_store_dwordx4 v1, v[152:155], s[10:11] offset:3072 sc1
	s_add_u32 s10, s10, 0x1000
	s_addc_u32 s11, s11, 0
	global_load_dwordx4 v[104:107], v1, s[8:9] offset:2048
	global_load_dwordx4 v[108:111], v1, s[8:9] offset:3072
	s_add_u32 s8, s8, 0x1000
	s_addc_u32 s9, s9, 0
	s_waitcnt vmcnt(26)
	v_lshlrev_b32_e32 v128, 16, v112
	v_and_b32_e32 v129, 0xffff0000, v112
	v_lshlrev_b32_e32 v130, 16, v113
	v_and_b32_e32 v131, 0xffff0000, v113
	v_lshlrev_b32_e32 v132, 16, v114
	v_and_b32_e32 v133, 0xffff0000, v114
	v_lshlrev_b32_e32 v134, 16, v115
	v_and_b32_e32 v135, 0xffff0000, v115
	v_lshlrev_b32_e32 v136, 16, v116
	v_and_b32_e32 v137, 0xffff0000, v116
	v_lshlrev_b32_e32 v138, 16, v117
	v_and_b32_e32 v139, 0xffff0000, v117
	v_lshlrev_b32_e32 v140, 16, v118
	v_and_b32_e32 v141, 0xffff0000, v118
	v_lshlrev_b32_e32 v142, 16, v119
	v_and_b32_e32 v143, 0xffff0000, v119
	v_pk_mul_f32 v[144:145], v[128:129], v[128:129]
	v_pk_fma_f32 v[144:145], v[130:131], v[130:131], v[144:145]
	v_pk_fma_f32 v[144:145], v[132:133], v[132:133], v[144:145]
	v_pk_fma_f32 v[144:145], v[134:135], v[134:135], v[144:145]
	v_pk_fma_f32 v[144:145], v[136:137], v[136:137], v[144:145]
	v_pk_fma_f32 v[144:145], v[138:139], v[138:139], v[144:145]
	v_pk_fma_f32 v[144:145], v[140:141], v[140:141], v[144:145]
	v_pk_fma_f32 v[144:145], v[142:143], v[142:143], v[144:145]
	v_add_f32_e32 v144, v144, v145
	s_nop 1
	v_add_f32_dpp v144, v144, v144 quad_perm:[1,0,3,2] row_mask:0xf bank_mask:0xf
	s_nop 1
	v_add_f32_dpp v144, v144, v144 quad_perm:[2,3,0,1] row_mask:0xf bank_mask:0xf
	s_nop 1
	v_add_f32_dpp v144, v144, v144 row_half_mirror row_mask:0xf bank_mask:0xf
	s_nop 1
	v_add_f32_dpp v144, v144, v144 row_mirror row_mask:0xf bank_mask:0xf
	s_nop 0
	v_mov_b32_e32 v145, v144
	s_nop 1
	v_permlane16_swap_b32_e32 v144, v145
	s_nop 0
	v_add_f32_e32 v144, v144, v145
	v_mov_b32_e32 v145, v144
	s_nop 1
	v_permlane32_swap_b32_e32 v144, v145
	s_nop 0
	v_add_f32_e32 v144, v144, v145
	v_fmamk_f32 v144, v144, 0x3a800000, v3
	v_rsq_f32_e32 v144, v144
	s_nop 0
	v_pk_mul_f32 v[128:129], v[128:129], v[144:145] op_sel_hi:[1,0]
	v_pk_mul_f32 v[130:131], v[130:131], v[144:145] op_sel_hi:[1,0]
	v_pk_mul_f32 v[132:133], v[132:133], v[144:145] op_sel_hi:[1,0]
	v_pk_mul_f32 v[134:135], v[134:135], v[144:145] op_sel_hi:[1,0]
	v_pk_mul_f32 v[136:137], v[136:137], v[144:145] op_sel_hi:[1,0]
	v_pk_mul_f32 v[138:139], v[138:139], v[144:145] op_sel_hi:[1,0]
	v_pk_mul_f32 v[140:141], v[140:141], v[144:145] op_sel_hi:[1,0]
	v_pk_mul_f32 v[142:143], v[142:143], v[144:145] op_sel_hi:[1,0]
	v_pk_mul_f32 v[128:129], v[16:17], v[128:129]
	v_pk_mul_f32 v[130:131], v[18:19], v[130:131]
	v_pk_mul_f32 v[132:133], v[20:21], v[132:133]
	v_pk_mul_f32 v[134:135], v[22:23], v[134:135]
	v_pk_mul_f32 v[136:137], v[24:25], v[136:137]
	v_pk_mul_f32 v[138:139], v[26:27], v[138:139]
	v_pk_mul_f32 v[140:141], v[28:29], v[140:141]
	v_pk_mul_f32 v[142:143], v[30:31], v[142:143]
	v_pk_fma_f32 v[128:129], v[32:33], v[128:129], v[48:49]
	v_pk_fma_f32 v[130:131], v[34:35], v[130:131], v[50:51]
	v_pk_fma_f32 v[132:133], v[36:37], v[132:133], v[52:53]
	v_pk_fma_f32 v[134:135], v[38:39], v[134:135], v[54:55]
	v_pk_fma_f32 v[136:137], v[40:41], v[136:137], v[56:57]
	v_pk_fma_f32 v[138:139], v[42:43], v[138:139], v[58:59]
	v_pk_fma_f32 v[140:141], v[44:45], v[140:141], v[60:61]
	v_pk_fma_f32 v[142:143], v[46:47], v[142:143], v[62:63]
	v_cvt_pk_bf16_f32 v148, v128, v129
	v_cvt_pk_bf16_f32 v149, v130, v131
	v_cvt_pk_bf16_f32 v150, v132, v133
	v_cvt_pk_bf16_f32 v151, v134, v135
	v_cvt_pk_bf16_f32 v152, v136, v137
	v_cvt_pk_bf16_f32 v153, v138, v139
	v_cvt_pk_bf16_f32 v154, v140, v141
	v_cvt_pk_bf16_f32 v155, v142, v143
	global_store_dwordx4 v1, v[148:151], s[10:11] sc1
	global_store_dwordx4 v1, v[152:155], s[10:11] offset:1024 sc1
	global_load_dwordx4 v[112:115], v1, s[8:9]
	global_load_dwordx4 v[116:119], v1, s[8:9] offset:1024
	s_waitcnt vmcnt(28)
; __device__ __forceinline__ unsigned cvt_pk_bf16(float lo, float hi) { unsigned r; asm("v_cvt_pk_bf16_f32 %0, %1, %2" : "=v"(r) : "v"(lo), "v"(hi)); return r; }
; __device__ __forceinline__ void norm_pass_bf16(const Ctx& X, const bf16_t* xs, const bf16_t* cs, int nrows, const float* gain, const float* modl, int si, bf16_t* HN) {
;     ...
;         u32x4 q[2]; float v[2][8]; float s = 0.f;
; #pragma unroll
;         for (int j = 0; j < 2; ++j) q[j] = *(const u32x4*)(rowp + (X.lane + 64 * j) * 8);
; #pragma unroll
;         for (int j = 0; j < 2; ++j) {
;             v[j][0] = bf2f(q[j].x & 0xffffu); v[j][1] = bf2f(q[j].x >> 16); v[j][2] = bf2f(q[j].y & 0xffffu); v[j][3] = bf2f(q[j].y >> 16);
;             v[j][4] = bf2f(q[j].z & 0xffffu); v[j][5] = bf2f(q[j].z >> 16); v[j][6] = bf2f(q[j].w & 0xffffu); v[j][7] = bf2f(q[j].w >> 16);
; #pragma unroll
;             for (int e = 0; e < 8; ++e) s += v[j][e] * v[j][e]; }
;         const float rstd = rsqrtf(wave_sum(s) * (1.0f / 1024.0f) + 1e-6f);
; #pragma unroll
;         for (int j = 0; j < 2; ++j) { const int c = (X.lane + 64 * j) * 8; float o[8];
; #pragma unroll
;             for (int h = 0; h < 2; ++h) { const f32x4 gn = *(const f32x4*)(gain + c + 4 * h), a = *(const f32x4*)(scl + c + 4 * h), b = *(const f32x4*)(sh + c + 4 * h);
; #pragma unroll
;                 for (int e = 0; e < 4; ++e) o[4 * h + e] = v[j][4 * h + e] * rstd * gn[e] * (a[e] + 1.0f) + b[e]; }
;             u32x4 w; w.x = cvt_pk_bf16(o[0], o[1]); w.y = cvt_pk_bf16(o[2], o[3]); w.z = cvt_pk_bf16(o[4], o[5]); w.w = cvt_pk_bf16(o[6], o[7]); *(u32x4*)(HN + (size_t)r * D + c) = w; }
	v_lshlrev_b32_e32 v128, 16, v120
	v_and_b32_e32 v129, 0xffff0000, v120
	v_lshlrev_b32_e32 v130, 16, v121
	v_and_b32_e32 v131, 0xffff0000, v121
	v_lshlrev_b32_e32 v132, 16, v122
	v_and_b32_e32 v133, 0xffff0000, v122
	v_lshlrev_b32_e32 v134, 16, v123
	v_and_b32_e32 v135, 0xffff0000, v123
	v_lshlrev_b32_e32 v136, 16, v124
	v_and_b32_e32 v137, 0xffff0000, v124
	v_lshlrev_b32_e32 v138, 16, v125
	v_and_b32_e32 v139, 0xffff0000, v125
	v_lshlrev_b32_e32 v140, 16, v126
	v_and_b32_e32 v141, 0xffff0000, v126
	v_lshlrev_b32_e32 v142, 16, v127
	v_and_b32_e32 v143, 0xffff0000, v127
	v_pk_mul_f32 v[144:145], v[128:129], v[128:129]
	v_pk_fma_f32 v[144:145], v[130:131], v[130:131], v[144:145]
	v_pk_fma_f32 v[144:145], v[132:133], v[132:133], v[144:145]
	v_pk_fma_f32 v[144:145], v[134:135], v[134:135], v[144:145]
	v_pk_fma_f32 v[144:145], v[136:137], v[136:137], v[144:145]
	v_pk_fma_f32 v[144:145], v[138:139], v[138:139], v[144:145]
	v_pk_fma_f32 v[144:145], v[140:141], v[140:141], v[144:145]
	v_pk_fma_f32 v[144:145], v[142:143], v[142:143], v[144:145]
	v_add_f32_e32 v144, v144, v145
	s_nop 1
	v_add_f32_dpp v144, v144, v144 quad_perm:[1,0,3,2] row_mask:0xf bank_mask:0xf
	s_nop 1
	v_add_f32_dpp v144, v144, v144 quad_perm:[2,3,0,1] row_mask:0xf bank_mask:0xf
	s_nop 1
	v_add_f32_dpp v144, v144, v144 row_half_mirror row_mask:0xf bank_mask:0xf
	s_nop 1
	v_add_f32_dpp v144, v144, v144 row_mirror row_mask:0xf bank_mask:0xf
	s_nop 0
	v_mov_b32_e32 v145, v144
	s_nop 1
	v_permlane16_swap_b32_e32 v144, v145
	s_nop 0
	v_add_f32_e32 v144, v144, v145
	v_mov_b32_e32 v145, v144
	s_nop 1
	v_permlane32_swap_b32_e32 v144, v145
	s_nop 0
	v_add_f32_e32 v144, v144, v145
	v_fmamk_f32 v144, v144, 0x3a800000, v3
	v_rsq_f32_e32 v144, v144
	s_nop 0
	v_pk_mul_f32 v[128:129], v[128:129], v[144:145] op_sel_hi:[1,0]
	v_pk_mul_f32 v[130:131], v[130:131], v[144:145] op_sel_hi:[1,0]
	v_pk_mul_f32 v[132:133], v[132:133], v[144:145] op_sel_hi:[1,0]
	v_pk_mul_f32 v[134:135], v[134:135], v[144:145] op_sel_hi:[1,0]
	v_pk_mul_f32 v[136:137], v[136:137], v[144:145] op_sel_hi:[1,0]
	v_pk_mul_f32 v[138:139], v[138:139], v[144:145] op_sel_hi:[1,0]
	v_pk_mul_f32 v[140:141], v[140:141], v[144:145] op_sel_hi:[1,0]
	v_pk_mul_f32 v[142:143], v[142:143], v[144:145] op_sel_hi:[1,0]
	v_pk_mul_f32 v[128:129], v[16:17], v[128:129]
	v_pk_mul_f32 v[130:131], v[18:19], v[130:131]
	v_pk_mul_f32 v[132:133], v[20:21], v[132:133]
	v_pk_mul_f32 v[134:135], v[22:23], v[134:135]
	v_pk_mul_f32 v[136:137], v[24:25], v[136:137]
	v_pk_mul_f32 v[138:139], v[26:27], v[138:139]
	v_pk_mul_f32 v[140:141], v[28:29], v[140:141]
	v_pk_mul_f32 v[142:143], v[30:31], v[142:143]
	v_pk_fma_f32 v[128:129], v[32:33], v[128:129], v[48:49]
	v_pk_fma_f32 v[130:131], v[34:35], v[130:131], v[50:51]
	v_pk_fma_f32 v[132:133], v[36:37], v[132:133], v[52:53]
	v_pk_fma_f32 v[134:135], v[38:39], v[134:135], v[54:55]
	v_pk_fma_f32 v[136:137], v[40:41], v[136:137], v[56:57]
	v_pk_fma_f32 v[138:139], v[42:43], v[138:139], v[58:59]
	v_pk_fma_f32 v[140:141], v[44:45], v[140:141], v[60:61]
	v_pk_fma_f32 v[142:143], v[46:47], v[142:143], v[62:63]
	v_cvt_pk_bf16_f32 v148, v128, v129
	v_cvt_pk_bf16_f32 v149, v130, v131
	v_cvt_pk_bf16_f32 v150, v132, v133
	v_cvt_pk_bf16_f32 v151, v134, v135
	v_cvt_pk_bf16_f32 v152, v136, v137
	v_cvt_pk_bf16_f32 v153, v138, v139
	v_cvt_pk_bf16_f32 v154, v140, v141
	v_cvt_pk_bf16_f32 v155, v142, v143
	global_store_dwordx4 v1, v[148:151], s[10:11] offset:2048 sc1
	global_store_dwordx4 v1, v[152:155], s[10:11] offset:3072 sc1
	s_add_u32 s10, s10, 0x1000
	s_addc_u32 s11, s11, 0
	global_load_dwordx4 v[120:123], v1, s[8:9] offset:2048
	global_load_dwordx4 v[124:127], v1, s[8:9] offset:3072
	s_add_u32 s8, s8, 0x1000
	s_addc_u32 s9, s9, 0
	s_waitcnt vmcnt(28)
	v_lshlrev_b32_e32 v128, 16, v64
	v_and_b32_e32 v129, 0xffff0000, v64
	v_lshlrev_b32_e32 v130, 16, v65
	v_and_b32_e32 v131, 0xffff0000, v65
	v_lshlrev_b32_e32 v132, 16, v66
	v_and_b32_e32 v133, 0xffff0000, v66
	v_lshlrev_b32_e32 v134, 16, v67
	v_and_b32_e32 v135, 0xffff0000, v67
	v_lshlrev_b32_e32 v136, 16, v68
	v_and_b32_e32 v137, 0xffff0000, v68
	v_lshlrev_b32_e32 v138, 16, v69
	v_and_b32_e32 v139, 0xffff0000, v69
	v_lshlrev_b32_e32 v140, 16, v70
	v_and_b32_e32 v141, 0xffff0000, v70
	v_lshlrev_b32_e32 v142, 16, v71
	v_and_b32_e32 v143, 0xffff0000, v71
	v_pk_mul_f32 v[144:145], v[128:129], v[128:129]
	v_pk_fma_f32 v[144:145], v[130:131], v[130:131], v[144:145]
	v_pk_fma_f32 v[144:145], v[132:133], v[132:133], v[144:145]
	v_pk_fma_f32 v[144:145], v[134:135], v[134:135], v[144:145]
	v_pk_fma_f32 v[144:145], v[136:137], v[136:137], v[144:145]
	v_pk_fma_f32 v[144:145], v[138:139], v[138:139], v[144:145]
	v_pk_fma_f32 v[144:145], v[140:141], v[140:141], v[144:145]
	v_pk_fma_f32 v[144:145], v[142:143], v[142:143], v[144:145]
	v_add_f32_e32 v144, v144, v145
	s_nop 1
	v_add_f32_dpp v144, v144, v144 quad_perm:[1,0,3,2] row_mask:0xf bank_mask:0xf
	s_nop 1
	v_add_f32_dpp v144, v144, v144 quad_perm:[2,3,0,1] row_mask:0xf bank_mask:0xf
	s_nop 1
	v_add_f32_dpp v144, v144, v144 row_half_mirror row_mask:0xf bank_mask:0xf
	s_nop 1
	v_add_f32_dpp v144, v144, v144 row_mirror row_mask:0xf bank_mask:0xf
	s_nop 0
	v_mov_b32_e32 v145, v144
	s_nop 1
	v_permlane16_swap_b32_e32 v144, v145
	s_nop 0
	v_add_f32_e32 v144, v144, v145
	v_mov_b32_e32 v145, v144
	s_nop 1
	v_permlane32_swap_b32_e32 v144, v145
	s_nop 0
	v_add_f32_e32 v144, v144, v145
	v_fmamk_f32 v144, v144, 0x3a800000, v3
	v_rsq_f32_e32 v144, v144
	s_nop 0
	v_pk_mul_f32 v[128:129], v[128:129], v[144:145] op_sel_hi:[1,0]
	v_pk_mul_f32 v[130:131], v[130:131], v[144:145] op_sel_hi:[1,0]
	v_pk_mul_f32 v[132:133], v[132:133], v[144:145] op_sel_hi:[1,0]
; __device__ __forceinline__ unsigned cvt_pk_bf16(float lo, float hi) { unsigned r; asm("v_cvt_pk_bf16_f32 %0, %1, %2" : "=v"(r) : "v"(lo), "v"(hi)); return r; }
; __device__ __forceinline__ void norm_pass_bf16(const Ctx& X, const bf16_t* xs, const bf16_t* cs, int nrows, const float* gain, const float* modl, int si, bf16_t* HN) {
;     ...
;         u32x4 q[2]; float v[2][8]; float s = 0.f;
; #pragma unroll
;         for (int j = 0; j < 2; ++j) q[j] = *(const u32x4*)(rowp + (X.lane + 64 * j) * 8);
; #pragma unroll
;         for (int j = 0; j < 2; ++j) {
;             v[j][0] = bf2f(q[j].x & 0xffffu); v[j][1] = bf2f(q[j].x >> 16); v[j][2] = bf2f(q[j].y & 0xffffu); v[j][3] = bf2f(q[j].y >> 16);
;             v[j][4] = bf2f(q[j].z & 0xffffu); v[j][5] = bf2f(q[j].z >> 16); v[j][6] = bf2f(q[j].w & 0xffffu); v[j][7] = bf2f(q[j].w >> 16);
; #pragma unroll
;             for (int e = 0; e < 8; ++e) s += v[j][e] * v[j][e]; }
;         const float rstd = rsqrtf(wave_sum(s) * (1.0f / 1024.0f) + 1e-6f);
; #pragma unroll
;         for (int j = 0; j < 2; ++j) { const int c = (X.lane + 64 * j) * 8; float o[8];
; #pragma unroll
;             for (int h = 0; h < 2; ++h) { const f32x4 gn = *(const f32x4*)(gain + c + 4 * h), a = *(const f32x4*)(scl + c + 4 * h), b = *(const f32x4*)(sh + c + 4 * h);
; #pragma unroll
;                 for (int e = 0; e < 4; ++e) o[4 * h + e] = v[j][4 * h + e] * rstd * gn[e] * (a[e] + 1.0f) + b[e]; }
;             u32x4 w; w.x = cvt_pk_bf16(o[0], o[1]); w.y = cvt_pk_bf16(o[2], o[3]); w.z = cvt_pk_bf16(o[4], o[5]); w.w = cvt_pk_bf16(o[6], o[7]); *(u32x4*)(HN + (size_t)r * D + c) = w; }
	v_pk_mul_f32 v[134:135], v[134:135], v[144:145] op_sel_hi:[1,0]
	v_pk_mul_f32 v[136:137], v[136:137], v[144:145] op_sel_hi:[1,0]
	v_pk_mul_f32 v[138:139], v[138:139], v[144:145] op_sel_hi:[1,0]
	v_pk_mul_f32 v[140:141], v[140:141], v[144:145] op_sel_hi:[1,0]
	v_pk_mul_f32 v[142:143], v[142:143], v[144:145] op_sel_hi:[1,0]
	v_pk_mul_f32 v[128:129], v[16:17], v[128:129]
	v_pk_mul_f32 v[130:131], v[18:19], v[130:131]
	v_pk_mul_f32 v[132:133], v[20:21], v[132:133]
	v_pk_mul_f32 v[134:135], v[22:23], v[134:135]
	v_pk_mul_f32 v[136:137], v[24:25], v[136:137]
	v_pk_mul_f32 v[138:139], v[26:27], v[138:139]
	v_pk_mul_f32 v[140:141], v[28:29], v[140:141]
	v_pk_mul_f32 v[142:143], v[30:31], v[142:143]
	v_pk_fma_f32 v[128:129], v[32:33], v[128:129], v[48:49]
	v_pk_fma_f32 v[130:131], v[34:35], v[130:131], v[50:51]
	v_pk_fma_f32 v[132:133], v[36:37], v[132:133], v[52:53]
	v_pk_fma_f32 v[134:135], v[38:39], v[134:135], v[54:55]
	v_pk_fma_f32 v[136:137], v[40:41], v[136:137], v[56:57]
	v_pk_fma_f32 v[138:139], v[42:43], v[138:139], v[58:59]
	v_pk_fma_f32 v[140:141], v[44:45], v[140:141], v[60:61]
	v_pk_fma_f32 v[142:143], v[46:47], v[142:143], v[62:63]
	v_cvt_pk_bf16_f32 v148, v128, v129
	v_cvt_pk_bf16_f32 v149, v130, v131
	v_cvt_pk_bf16_f32 v150, v132, v133
	v_cvt_pk_bf16_f32 v151, v134, v135
	v_cvt_pk_bf16_f32 v152, v136, v137
	v_cvt_pk_bf16_f32 v153, v138, v139
	v_cvt_pk_bf16_f32 v154, v140, v141
	v_cvt_pk_bf16_f32 v155, v142, v143
	global_store_dwordx4 v1, v[148:151], s[10:11] sc1
	global_store_dwordx4 v1, v[152:155], s[10:11] offset:1024 sc1
	s_waitcnt vmcnt(26)
	v_lshlrev_b32_e32 v128, 16, v72
	v_and_b32_e32 v129, 0xffff0000, v72
	v_lshlrev_b32_e32 v130, 16, v73
	v_and_b32_e32 v131, 0xffff0000, v73
	v_lshlrev_b32_e32 v132, 16, v74
	v_and_b32_e32 v133, 0xffff0000, v74
	v_lshlrev_b32_e32 v134, 16, v75
	v_and_b32_e32 v135, 0xffff0000, v75
	v_lshlrev_b32_e32 v136, 16, v76
	v_and_b32_e32 v137, 0xffff0000, v76
	v_lshlrev_b32_e32 v138, 16, v77
	v_and_b32_e32 v139, 0xffff0000, v77
	v_lshlrev_b32_e32 v140, 16, v78
	v_and_b32_e32 v141, 0xffff0000, v78
	v_lshlrev_b32_e32 v142, 16, v79
	v_and_b32_e32 v143, 0xffff0000, v79
	v_pk_mul_f32 v[144:145], v[128:129], v[128:129]
	v_pk_fma_f32 v[144:145], v[130:131], v[130:131], v[144:145]
	v_pk_fma_f32 v[144:145], v[132:133], v[132:133], v[144:145]
	v_pk_fma_f32 v[144:145], v[134:135], v[134:135], v[144:145]
	v_pk_fma_f32 v[144:145], v[136:137], v[136:137], v[144:145]
	v_pk_fma_f32 v[144:145], v[138:139], v[138:139], v[144:145]
	v_pk_fma_f32 v[144:145], v[140:141], v[140:141], v[144:145]
	v_pk_fma_f32 v[144:145], v[142:143], v[142:143], v[144:145]
	v_add_f32_e32 v144, v144, v145
	s_nop 1
	v_add_f32_dpp v144, v144, v144 quad_perm:[1,0,3,2] row_mask:0xf bank_mask:0xf
	s_nop 1
	v_add_f32_dpp v144, v144, v144 quad_perm:[2,3,0,1] row_mask:0xf bank_mask:0xf
	s_nop 1
	v_add_f32_dpp v144, v144, v144 row_half_mirror row_mask:0xf bank_mask:0xf
	s_nop 1
	v_add_f32_dpp v144, v144, v144 row_mirror row_mask:0xf bank_mask:0xf
	s_nop 0
	v_mov_b32_e32 v145, v144
	s_nop 1
	v_permlane16_swap_b32_e32 v144, v145
	s_nop 0
	v_add_f32_e32 v144, v144, v145
	v_mov_b32_e32 v145, v144
	s_nop 1
	v_permlane32_swap_b32_e32 v144, v145
	s_nop 0
	v_add_f32_e32 v144, v144, v145
	v_fmamk_f32 v144, v144, 0x3a800000, v3
	v_rsq_f32_e32 v144, v144
	s_nop 0
	v_pk_mul_f32 v[128:129], v[128:129], v[144:145] op_sel_hi:[1,0]
	v_pk_mul_f32 v[130:131], v[130:131], v[144:145] op_sel_hi:[1,0]
	v_pk_mul_f32 v[132:133], v[132:133], v[144:145] op_sel_hi:[1,0]
	v_pk_mul_f32 v[134:135], v[134:135], v[144:145] op_sel_hi:[1,0]
	v_pk_mul_f32 v[136:137], v[136:137], v[144:145] op_sel_hi:[1,0]
	v_pk_mul_f32 v[138:139], v[138:139], v[144:145] op_sel_hi:[1,0]
	v_pk_mul_f32 v[140:141], v[140:141], v[144:145] op_sel_hi:[1,0]
	v_pk_mul_f32 v[142:143], v[142:143], v[144:145] op_sel_hi:[1,0]
	v_pk_mul_f32 v[128:129], v[16:17], v[128:129]
	v_pk_mul_f32 v[130:131], v[18:19], v[130:131]
	v_pk_mul_f32 v[132:133], v[20:21], v[132:133]
	v_pk_mul_f32 v[134:135], v[22:23], v[134:135]
	v_pk_mul_f32 v[136:137], v[24:25], v[136:137]
	v_pk_mul_f32 v[138:139], v[26:27], v[138:139]
	v_pk_mul_f32 v[140:141], v[28:29], v[140:141]
	v_pk_mul_f32 v[142:143], v[30:31], v[142:143]
	v_pk_fma_f32 v[128:129], v[32:33], v[128:129], v[48:49]
	v_pk_fma_f32 v[130:131], v[34:35], v[130:131], v[50:51]
	v_pk_fma_f32 v[132:133], v[36:37], v[132:133], v[52:53]
	v_pk_fma_f32 v[134:135], v[38:39], v[134:135], v[54:55]
	v_pk_fma_f32 v[136:137], v[40:41], v[136:137], v[56:57]
	v_pk_fma_f32 v[138:139], v[42:43], v[138:139], v[58:59]
	v_pk_fma_f32 v[140:141], v[44:45], v[140:141], v[60:61]
	v_pk_fma_f32 v[142:143], v[46:47], v[142:143], v[62:63]
	v_cvt_pk_bf16_f32 v148, v128, v129
	v_cvt_pk_bf16_f32 v149, v130, v131
	v_cvt_pk_bf16_f32 v150, v132, v133
	v_cvt_pk_bf16_f32 v151, v134, v135
	v_cvt_pk_bf16_f32 v152, v136, v137
	v_cvt_pk_bf16_f32 v153, v138, v139
	v_cvt_pk_bf16_f32 v154, v140, v141
	v_cvt_pk_bf16_f32 v155, v142, v143
	global_store_dwordx4 v1, v[148:151], s[10:11] offset:2048 sc1
	global_store_dwordx4 v1, v[152:155], s[10:11] offset:3072 sc1
	s_add_u32 s10, s10, 0x1000
	s_addc_u32 s11, s11, 0
	s_waitcnt vmcnt(24)
; __device__ __forceinline__ unsigned cvt_pk_bf16(float lo, float hi) { unsigned r; asm("v_cvt_pk_bf16_f32 %0, %1, %2" : "=v"(r) : "v"(lo), "v"(hi)); return r; }
; __device__ __forceinline__ void norm_pass_bf16(const Ctx& X, const bf16_t* xs, const bf16_t* cs, int nrows, const float* gain, const float* modl, int si, bf16_t* HN) {
;     ...
;         u32x4 q[2]; float v[2][8]; float s = 0.f;
; #pragma unroll
;         for (int j = 0; j < 2; ++j) q[j] = *(const u32x4*)(rowp + (X.lane + 64 * j) * 8);
; #pragma unroll
;         for (int j = 0; j < 2; ++j) {
;             v[j][0] = bf2f(q[j].x & 0xffffu); v[j][1] = bf2f(q[j].x >> 16); v[j][2] = bf2f(q[j].y & 0xffffu); v[j][3] = bf2f(q[j].y >> 16);
;             v[j][4] = bf2f(q[j].z & 0xffffu); v[j][5] = bf2f(q[j].z >> 16); v[j][6] = bf2f(q[j].w & 0xffffu); v[j][7] = bf2f(q[j].w >> 16);
; #pragma unroll
;             for (int e = 0; e < 8; ++e) s += v[j][e] * v[j][e]; }
;         const float rstd = rsqrtf(wave_sum(s) * (1.0f / 1024.0f) + 1e-6f);
; #pragma unroll
;         for (int j = 0; j < 2; ++j) { const int c = (X.lane + 64 * j) * 8; float o[8];
; #pragma unroll
;             for (int h = 0; h < 2; ++h) { const f32x4 gn = *(const f32x4*)(gain + c + 4 * h), a = *(const f32x4*)(scl + c + 4 * h), b = *(const f32x4*)(sh + c + 4 * h);
; #pragma unroll
;                 for (int e = 0; e < 4; ++e) o[4 * h + e] = v[j][4 * h + e] * rstd * gn[e] * (a[e] + 1.0f) + b[e]; }
;             u32x4 w; w.x = cvt_pk_bf16(o[0], o[1]); w.y = cvt_pk_bf16(o[2], o[3]); w.z = cvt_pk_bf16(o[4], o[5]); w.w = cvt_pk_bf16(o[6], o[7]); *(u32x4*)(HN + (size_t)r * D + c) = w; }
	v_lshlrev_b32_e32 v128, 16, v80
	v_and_b32_e32 v129, 0xffff0000, v80
	v_lshlrev_b32_e32 v130, 16, v81
	v_and_b32_e32 v131, 0xffff0000, v81
	v_lshlrev_b32_e32 v132, 16, v82
	v_and_b32_e32 v133, 0xffff0000, v82
	v_lshlrev_b32_e32 v134, 16, v83
	v_and_b32_e32 v135, 0xffff0000, v83
	v_lshlrev_b32_e32 v136, 16, v84
	v_and_b32_e32 v137, 0xffff0000, v84
	v_lshlrev_b32_e32 v138, 16, v85
	v_and_b32_e32 v139, 0xffff0000, v85
	v_lshlrev_b32_e32 v140, 16, v86
	v_and_b32_e32 v141, 0xffff0000, v86
	v_lshlrev_b32_e32 v142, 16, v87
	v_and_b32_e32 v143, 0xffff0000, v87
	v_pk_mul_f32 v[144:145], v[128:129], v[128:129]
	v_pk_fma_f32 v[144:145], v[130:131], v[130:131], v[144:145]
	v_pk_fma_f32 v[144:145], v[132:133], v[132:133], v[144:145]
	v_pk_fma_f32 v[144:145], v[134:135], v[134:135], v[144:145]
	v_pk_fma_f32 v[144:145], v[136:137], v[136:137], v[144:145]
	v_pk_fma_f32 v[144:145], v[138:139], v[138:139], v[144:145]
	v_pk_fma_f32 v[144:145], v[140:141], v[140:141], v[144:145]
	v_pk_fma_f32 v[144:145], v[142:143], v[142:143], v[144:145]
	v_add_f32_e32 v144, v144, v145
	s_nop 1
	v_add_f32_dpp v144, v144, v144 quad_perm:[1,0,3,2] row_mask:0xf bank_mask:0xf
	s_nop 1
	v_add_f32_dpp v144, v144, v144 quad_perm:[2,3,0,1] row_mask:0xf bank_mask:0xf
	s_nop 1
	v_add_f32_dpp v144, v144, v144 row_half_mirror row_mask:0xf bank_mask:0xf
	s_nop 1
	v_add_f32_dpp v144, v144, v144 row_mirror row_mask:0xf bank_mask:0xf
	s_nop 0
	v_mov_b32_e32 v145, v144
	s_nop 1
	v_permlane16_swap_b32_e32 v144, v145
	s_nop 0
	v_add_f32_e32 v144, v144, v145
	v_mov_b32_e32 v145, v144
	s_nop 1
	v_permlane32_swap_b32_e32 v144, v145
	s_nop 0
	v_add_f32_e32 v144, v144, v145
	v_fmamk_f32 v144, v144, 0x3a800000, v3
	v_rsq_f32_e32 v144, v144
	s_nop 0
	v_pk_mul_f32 v[128:129], v[128:129], v[144:145] op_sel_hi:[1,0]
	v_pk_mul_f32 v[130:131], v[130:131], v[144:145] op_sel_hi:[1,0]
	v_pk_mul_f32 v[132:133], v[132:133], v[144:145] op_sel_hi:[1,0]
	v_pk_mul_f32 v[134:135], v[134:135], v[144:145] op_sel_hi:[1,0]
	v_pk_mul_f32 v[136:137], v[136:137], v[144:145] op_sel_hi:[1,0]
	v_pk_mul_f32 v[138:139], v[138:139], v[144:145] op_sel_hi:[1,0]
	v_pk_mul_f32 v[140:141], v[140:141], v[144:145] op_sel_hi:[1,0]
	v_pk_mul_f32 v[142:143], v[142:143], v[144:145] op_sel_hi:[1,0]
	v_pk_mul_f32 v[128:129], v[16:17], v[128:129]
	v_pk_mul_f32 v[130:131], v[18:19], v[130:131]
	v_pk_mul_f32 v[132:133], v[20:21], v[132:133]
	v_pk_mul_f32 v[134:135], v[22:23], v[134:135]
	v_pk_mul_f32 v[136:137], v[24:25], v[136:137]
	v_pk_mul_f32 v[138:139], v[26:27], v[138:139]
	v_pk_mul_f32 v[140:141], v[28:29], v[140:141]
	v_pk_mul_f32 v[142:143], v[30:31], v[142:143]
	v_pk_fma_f32 v[128:129], v[32:33], v[128:129], v[48:49]
	v_pk_fma_f32 v[130:131], v[34:35], v[130:131], v[50:51]
	v_pk_fma_f32 v[132:133], v[36:37], v[132:133], v[52:53]
	v_pk_fma_f32 v[134:135], v[38:39], v[134:135], v[54:55]
	v_pk_fma_f32 v[136:137], v[40:41], v[136:137], v[56:57]
	v_pk_fma_f32 v[138:139], v[42:43], v[138:139], v[58:59]
	v_pk_fma_f32 v[140:141], v[44:45], v[140:141], v[60:61]
	v_pk_fma_f32 v[142:143], v[46:47], v[142:143], v[62:63]
	v_cvt_pk_bf16_f32 v148, v128, v129
	v_cvt_pk_bf16_f32 v149, v130, v131
	v_cvt_pk_bf16_f32 v150, v132, v133
	v_cvt_pk_bf16_f32 v151, v134, v135
	v_cvt_pk_bf16_f32 v152, v136, v137
	v_cvt_pk_bf16_f32 v153, v138, v139
	v_cvt_pk_bf16_f32 v154, v140, v141
	v_cvt_pk_bf16_f32 v155, v142, v143
	global_store_dwordx4 v1, v[148:151], s[10:11] sc1
	global_store_dwordx4 v1, v[152:155], s[10:11] offset:1024 sc1
	s_waitcnt vmcnt(22)
	v_lshlrev_b32_e32 v128, 16, v88
	v_and_b32_e32 v129, 0xffff0000, v88
	v_lshlrev_b32_e32 v130, 16, v89
	v_and_b32_e32 v131, 0xffff0000, v89
	v_lshlrev_b32_e32 v132, 16, v90
	v_and_b32_e32 v133, 0xffff0000, v90
	v_lshlrev_b32_e32 v134, 16, v91
	v_and_b32_e32 v135, 0xffff0000, v91
	v_lshlrev_b32_e32 v136, 16, v92
	v_and_b32_e32 v137, 0xffff0000, v92
	v_lshlrev_b32_e32 v138, 16, v93
	v_and_b32_e32 v139, 0xffff0000, v93
	v_lshlrev_b32_e32 v140, 16, v94
	v_and_b32_e32 v141, 0xffff0000, v94
	v_lshlrev_b32_e32 v142, 16, v95
	v_and_b32_e32 v143, 0xffff0000, v95
	v_pk_mul_f32 v[144:145], v[128:129], v[128:129]
	v_pk_fma_f32 v[144:145], v[130:131], v[130:131], v[144:145]
	v_pk_fma_f32 v[144:145], v[132:133], v[132:133], v[144:145]
	v_pk_fma_f32 v[144:145], v[134:135], v[134:135], v[144:145]
	v_pk_fma_f32 v[144:145], v[136:137], v[136:137], v[144:145]
	v_pk_fma_f32 v[144:145], v[138:139], v[138:139], v[144:145]
	v_pk_fma_f32 v[144:145], v[140:141], v[140:141], v[144:145]
	v_pk_fma_f32 v[144:145], v[142:143], v[142:143], v[144:145]
	v_add_f32_e32 v144, v144, v145
	s_nop 1
	v_add_f32_dpp v144, v144, v144 quad_perm:[1,0,3,2] row_mask:0xf bank_mask:0xf
	s_nop 1
	v_add_f32_dpp v144, v144, v144 quad_perm:[2,3,0,1] row_mask:0xf bank_mask:0xf
	s_nop 1
	v_add_f32_dpp v144, v144, v144 row_half_mirror row_mask:0xf bank_mask:0xf
	s_nop 1
	v_add_f32_dpp v144, v144, v144 row_mirror row_mask:0xf bank_mask:0xf
	s_nop 0
	v_mov_b32_e32 v145, v144
	s_nop 1
	v_permlane16_swap_b32_e32 v144, v145
	s_nop 0
	v_add_f32_e32 v144, v144, v145
	v_mov_b32_e32 v145, v144
	s_nop 1
	v_permlane32_swap_b32_e32 v144, v145
	s_nop 0
	v_add_f32_e32 v144, v144, v145
	v_fmamk_f32 v144, v144, 0x3a800000, v3
	v_rsq_f32_e32 v144, v144
	s_nop 0
	v_pk_mul_f32 v[128:129], v[128:129], v[144:145] op_sel_hi:[1,0]
	v_pk_mul_f32 v[130:131], v[130:131], v[144:145] op_sel_hi:[1,0]
	v_pk_mul_f32 v[132:133], v[132:133], v[144:145] op_sel_hi:[1,0]
	v_pk_mul_f32 v[134:135], v[134:135], v[144:145] op_sel_hi:[1,0]
	v_pk_mul_f32 v[136:137], v[136:137], v[144:145] op_sel_hi:[1,0]
	v_pk_mul_f32 v[138:139], v[138:139], v[144:145] op_sel_hi:[1,0]
	v_pk_mul_f32 v[140:141], v[140:141], v[144:145] op_sel_hi:[1,0]
; __device__ __forceinline__ unsigned cvt_pk_bf16(float lo, float hi) { unsigned r; asm("v_cvt_pk_bf16_f32 %0, %1, %2" : "=v"(r) : "v"(lo), "v"(hi)); return r; }
; __device__ __forceinline__ void norm_pass_bf16(const Ctx& X, const bf16_t* xs, const bf16_t* cs, int nrows, const float* gain, const float* modl, int si, bf16_t* HN) {
;     ...
;         u32x4 q[2]; float v[2][8]; float s = 0.f;
; #pragma unroll
;         for (int j = 0; j < 2; ++j) q[j] = *(const u32x4*)(rowp + (X.lane + 64 * j) * 8);
; #pragma unroll
;         for (int j = 0; j < 2; ++j) {
;             v[j][0] = bf2f(q[j].x & 0xffffu); v[j][1] = bf2f(q[j].x >> 16); v[j][2] = bf2f(q[j].y & 0xffffu); v[j][3] = bf2f(q[j].y >> 16);
;             v[j][4] = bf2f(q[j].z & 0xffffu); v[j][5] = bf2f(q[j].z >> 16); v[j][6] = bf2f(q[j].w & 0xffffu); v[j][7] = bf2f(q[j].w >> 16);
; #pragma unroll
;             for (int e = 0; e < 8; ++e) s += v[j][e] * v[j][e]; }
;         const float rstd = rsqrtf(wave_sum(s) * (1.0f / 1024.0f) + 1e-6f);
; #pragma unroll
;         for (int j = 0; j < 2; ++j) { const int c = (X.lane + 64 * j) * 8; float o[8];
; #pragma unroll
;             for (int h = 0; h < 2; ++h) { const f32x4 gn = *(const f32x4*)(gain + c + 4 * h), a = *(const f32x4*)(scl + c + 4 * h), b = *(const f32x4*)(sh + c + 4 * h);
; #pragma unroll
;                 for (int e = 0; e < 4; ++e) o[4 * h + e] = v[j][4 * h + e] * rstd * gn[e] * (a[e] + 1.0f) + b[e]; }
;             u32x4 w; w.x = cvt_pk_bf16(o[0], o[1]); w.y = cvt_pk_bf16(o[2], o[3]); w.z = cvt_pk_bf16(o[4], o[5]); w.w = cvt_pk_bf16(o[6], o[7]); *(u32x4*)(HN + (size_t)r * D + c) = w; }
	v_pk_mul_f32 v[142:143], v[142:143], v[144:145] op_sel_hi:[1,0]
	v_pk_mul_f32 v[128:129], v[16:17], v[128:129]
	v_pk_mul_f32 v[130:131], v[18:19], v[130:131]
	v_pk_mul_f32 v[132:133], v[20:21], v[132:133]
	v_pk_mul_f32 v[134:135], v[22:23], v[134:135]
	v_pk_mul_f32 v[136:137], v[24:25], v[136:137]
	v_pk_mul_f32 v[138:139], v[26:27], v[138:139]
	v_pk_mul_f32 v[140:141], v[28:29], v[140:141]
	v_pk_mul_f32 v[142:143], v[30:31], v[142:143]
	v_pk_fma_f32 v[128:129], v[32:33], v[128:129], v[48:49]
	v_pk_fma_f32 v[130:131], v[34:35], v[130:131], v[50:51]
	v_pk_fma_f32 v[132:133], v[36:37], v[132:133], v[52:53]
	v_pk_fma_f32 v[134:135], v[38:39], v[134:135], v[54:55]
	v_pk_fma_f32 v[136:137], v[40:41], v[136:137], v[56:57]
	v_pk_fma_f32 v[138:139], v[42:43], v[138:139], v[58:59]
	v_pk_fma_f32 v[140:141], v[44:45], v[140:141], v[60:61]
	v_pk_fma_f32 v[142:143], v[46:47], v[142:143], v[62:63]
	v_cvt_pk_bf16_f32 v148, v128, v129
	v_cvt_pk_bf16_f32 v149, v130, v131
	v_cvt_pk_bf16_f32 v150, v132, v133
	v_cvt_pk_bf16_f32 v151, v134, v135
	v_cvt_pk_bf16_f32 v152, v136, v137
	v_cvt_pk_bf16_f32 v153, v138, v139
	v_cvt_pk_bf16_f32 v154, v140, v141
	v_cvt_pk_bf16_f32 v155, v142, v143
	global_store_dwordx4 v1, v[148:151], s[10:11] offset:2048 sc1
	global_store_dwordx4 v1, v[152:155], s[10:11] offset:3072 sc1
	s_add_u32 s10, s10, 0x1000
	s_addc_u32 s11, s11, 0
	s_waitcnt vmcnt(20)
	v_lshlrev_b32_e32 v128, 16, v96
	v_and_b32_e32 v129, 0xffff0000, v96
	v_lshlrev_b32_e32 v130, 16, v97
	v_and_b32_e32 v131, 0xffff0000, v97
	v_lshlrev_b32_e32 v132, 16, v98
	v_and_b32_e32 v133, 0xffff0000, v98
	v_lshlrev_b32_e32 v134, 16, v99
	v_and_b32_e32 v135, 0xffff0000, v99
	v_lshlrev_b32_e32 v136, 16, v100
	v_and_b32_e32 v137, 0xffff0000, v100
	v_lshlrev_b32_e32 v138, 16, v101
	v_and_b32_e32 v139, 0xffff0000, v101
	v_lshlrev_b32_e32 v140, 16, v102
	v_and_b32_e32 v141, 0xffff0000, v102
	v_lshlrev_b32_e32 v142, 16, v103
	v_and_b32_e32 v143, 0xffff0000, v103
	v_pk_mul_f32 v[144:145], v[128:129], v[128:129]
	v_pk_fma_f32 v[144:145], v[130:131], v[130:131], v[144:145]
	v_pk_fma_f32 v[144:145], v[132:133], v[132:133], v[144:145]
	v_pk_fma_f32 v[144:145], v[134:135], v[134:135], v[144:145]
	v_pk_fma_f32 v[144:145], v[136:137], v[136:137], v[144:145]
	v_pk_fma_f32 v[144:145], v[138:139], v[138:139], v[144:145]
	v_pk_fma_f32 v[144:145], v[140:141], v[140:141], v[144:145]
	v_pk_fma_f32 v[144:145], v[142:143], v[142:143], v[144:145]
	v_add_f32_e32 v144, v144, v145
	s_nop 1
	v_add_f32_dpp v144, v144, v144 quad_perm:[1,0,3,2] row_mask:0xf bank_mask:0xf
	s_nop 1
	v_add_f32_dpp v144, v144, v144 quad_perm:[2,3,0,1] row_mask:0xf bank_mask:0xf
	s_nop 1
	v_add_f32_dpp v144, v144, v144 row_half_mirror row_mask:0xf bank_mask:0xf
	s_nop 1
	v_add_f32_dpp v144, v144, v144 row_mirror row_mask:0xf bank_mask:0xf
	s_nop 0
	v_mov_b32_e32 v145, v144
	s_nop 1
	v_permlane16_swap_b32_e32 v144, v145
	s_nop 0
	v_add_f32_e32 v144, v144, v145
	v_mov_b32_e32 v145, v144
	s_nop 1
	v_permlane32_swap_b32_e32 v144, v145
	s_nop 0
	v_add_f32_e32 v144, v144, v145
	v_fmamk_f32 v144, v144, 0x3a800000, v3
	v_rsq_f32_e32 v144, v144
	s_nop 0
	v_pk_mul_f32 v[128:129], v[128:129], v[144:145] op_sel_hi:[1,0]
	v_pk_mul_f32 v[130:131], v[130:131], v[144:145] op_sel_hi:[1,0]
	v_pk_mul_f32 v[132:133], v[132:133], v[144:145] op_sel_hi:[1,0]
	v_pk_mul_f32 v[134:135], v[134:135], v[144:145] op_sel_hi:[1,0]
	v_pk_mul_f32 v[136:137], v[136:137], v[144:145] op_sel_hi:[1,0]
	v_pk_mul_f32 v[138:139], v[138:139], v[144:145] op_sel_hi:[1,0]
	v_pk_mul_f32 v[140:141], v[140:141], v[144:145] op_sel_hi:[1,0]
	v_pk_mul_f32 v[142:143], v[142:143], v[144:145] op_sel_hi:[1,0]
	v_pk_mul_f32 v[128:129], v[16:17], v[128:129]
	v_pk_mul_f32 v[130:131], v[18:19], v[130:131]
	v_pk_mul_f32 v[132:133], v[20:21], v[132:133]
	v_pk_mul_f32 v[134:135], v[22:23], v[134:135]
	v_pk_mul_f32 v[136:137], v[24:25], v[136:137]
	v_pk_mul_f32 v[138:139], v[26:27], v[138:139]
	v_pk_mul_f32 v[140:141], v[28:29], v[140:141]
	v_pk_mul_f32 v[142:143], v[30:31], v[142:143]
	v_pk_fma_f32 v[128:129], v[32:33], v[128:129], v[48:49]
	v_pk_fma_f32 v[130:131], v[34:35], v[130:131], v[50:51]
	v_pk_fma_f32 v[132:133], v[36:37], v[132:133], v[52:53]
	v_pk_fma_f32 v[134:135], v[38:39], v[134:135], v[54:55]
	v_pk_fma_f32 v[136:137], v[40:41], v[136:137], v[56:57]
	v_pk_fma_f32 v[138:139], v[42:43], v[138:139], v[58:59]
	v_pk_fma_f32 v[140:141], v[44:45], v[140:141], v[60:61]
	v_pk_fma_f32 v[142:143], v[46:47], v[142:143], v[62:63]
	v_cvt_pk_bf16_f32 v148, v128, v129
	v_cvt_pk_bf16_f32 v149, v130, v131
	v_cvt_pk_bf16_f32 v150, v132, v133
	v_cvt_pk_bf16_f32 v151, v134, v135
	v_cvt_pk_bf16_f32 v152, v136, v137
	v_cvt_pk_bf16_f32 v153, v138, v139
	v_cvt_pk_bf16_f32 v154, v140, v141
	v_cvt_pk_bf16_f32 v155, v142, v143
	global_store_dwordx4 v1, v[148:151], s[10:11] sc1
	global_store_dwordx4 v1, v[152:155], s[10:11] offset:1024 sc1
	s_waitcnt vmcnt(18)
; __device__ __forceinline__ unsigned cvt_pk_bf16(float lo, float hi) { unsigned r; asm("v_cvt_pk_bf16_f32 %0, %1, %2" : "=v"(r) : "v"(lo), "v"(hi)); return r; }
; __device__ __forceinline__ void norm_pass_bf16(const Ctx& X, const bf16_t* xs, const bf16_t* cs, int nrows, const float* gain, const float* modl, int si, bf16_t* HN) {
;     ...
;         u32x4 q[2]; float v[2][8]; float s = 0.f;
; #pragma unroll
;         for (int j = 0; j < 2; ++j) q[j] = *(const u32x4*)(rowp + (X.lane + 64 * j) * 8);
; #pragma unroll
;         for (int j = 0; j < 2; ++j) {
;             v[j][0] = bf2f(q[j].x & 0xffffu); v[j][1] = bf2f(q[j].x >> 16); v[j][2] = bf2f(q[j].y & 0xffffu); v[j][3] = bf2f(q[j].y >> 16);
;             v[j][4] = bf2f(q[j].z & 0xffffu); v[j][5] = bf2f(q[j].z >> 16); v[j][6] = bf2f(q[j].w & 0xffffu); v[j][7] = bf2f(q[j].w >> 16);
; #pragma unroll
;             for (int e = 0; e < 8; ++e) s += v[j][e] * v[j][e]; }
;         const float rstd = rsqrtf(wave_sum(s) * (1.0f / 1024.0f) + 1e-6f);
; #pragma unroll
;         for (int j = 0; j < 2; ++j) { const int c = (X.lane + 64 * j) * 8; float o[8];
; #pragma unroll
;             for (int h = 0; h < 2; ++h) { const f32x4 gn = *(const f32x4*)(gain + c + 4 * h), a = *(const f32x4*)(scl + c + 4 * h), b = *(const f32x4*)(sh + c + 4 * h);
; #pragma unroll
;                 for (int e = 0; e < 4; ++e) o[4 * h + e] = v[j][4 * h + e] * rstd * gn[e] * (a[e] + 1.0f) + b[e]; }
;             u32x4 w; w.x = cvt_pk_bf16(o[0], o[1]); w.y = cvt_pk_bf16(o[2], o[3]); w.z = cvt_pk_bf16(o[4], o[5]); w.w = cvt_pk_bf16(o[6], o[7]); *(u32x4*)(HN + (size_t)r * D + c) = w; }
	v_lshlrev_b32_e32 v128, 16, v104
	v_and_b32_e32 v129, 0xffff0000, v104
	v_lshlrev_b32_e32 v130, 16, v105
	v_and_b32_e32 v131, 0xffff0000, v105
	v_lshlrev_b32_e32 v132, 16, v106
	v_and_b32_e32 v133, 0xffff0000, v106
	v_lshlrev_b32_e32 v134, 16, v107
	v_and_b32_e32 v135, 0xffff0000, v107
	v_lshlrev_b32_e32 v136, 16, v108
	v_and_b32_e32 v137, 0xffff0000, v108
	v_lshlrev_b32_e32 v138, 16, v109
	v_and_b32_e32 v139, 0xffff0000, v109
	v_lshlrev_b32_e32 v140, 16, v110
	v_and_b32_e32 v141, 0xffff0000, v110
	v_lshlrev_b32_e32 v142, 16, v111
	v_and_b32_e32 v143, 0xffff0000, v111
	v_pk_mul_f32 v[144:145], v[128:129], v[128:129]
	v_pk_fma_f32 v[144:145], v[130:131], v[130:131], v[144:145]
	v_pk_fma_f32 v[144:145], v[132:133], v[132:133], v[144:145]
	v_pk_fma_f32 v[144:145], v[134:135], v[134:135], v[144:145]
	v_pk_fma_f32 v[144:145], v[136:137], v[136:137], v[144:145]
	v_pk_fma_f32 v[144:145], v[138:139], v[138:139], v[144:145]
	v_pk_fma_f32 v[144:145], v[140:141], v[140:141], v[144:145]
	v_pk_fma_f32 v[144:145], v[142:143], v[142:143], v[144:145]
	v_add_f32_e32 v144, v144, v145
	s_nop 1
	v_add_f32_dpp v144, v144, v144 quad_perm:[1,0,3,2] row_mask:0xf bank_mask:0xf
	s_nop 1
	v_add_f32_dpp v144, v144, v144 quad_perm:[2,3,0,1] row_mask:0xf bank_mask:0xf
	s_nop 1
	v_add_f32_dpp v144, v144, v144 row_half_mirror row_mask:0xf bank_mask:0xf
	s_nop 1
	v_add_f32_dpp v144, v144, v144 row_mirror row_mask:0xf bank_mask:0xf
	s_nop 0
	v_mov_b32_e32 v145, v144
	s_nop 1
	v_permlane16_swap_b32_e32 v144, v145
	s_nop 0
	v_add_f32_e32 v144, v144, v145
	v_mov_b32_e32 v145, v144
	s_nop 1
	v_permlane32_swap_b32_e32 v144, v145
	s_nop 0
	v_add_f32_e32 v144, v144, v145
	v_fmamk_f32 v144, v144, 0x3a800000, v3
	v_rsq_f32_e32 v144, v144
	s_nop 0
	v_pk_mul_f32 v[128:129], v[128:129], v[144:145] op_sel_hi:[1,0]
	v_pk_mul_f32 v[130:131], v[130:131], v[144:145] op_sel_hi:[1,0]
	v_pk_mul_f32 v[132:133], v[132:133], v[144:145] op_sel_hi:[1,0]
	v_pk_mul_f32 v[134:135], v[134:135], v[144:145] op_sel_hi:[1,0]
	v_pk_mul_f32 v[136:137], v[136:137], v[144:145] op_sel_hi:[1,0]
	v_pk_mul_f32 v[138:139], v[138:139], v[144:145] op_sel_hi:[1,0]
	v_pk_mul_f32 v[140:141], v[140:141], v[144:145] op_sel_hi:[1,0]
	v_pk_mul_f32 v[142:143], v[142:143], v[144:145] op_sel_hi:[1,0]
	v_pk_mul_f32 v[128:129], v[16:17], v[128:129]
	v_pk_mul_f32 v[130:131], v[18:19], v[130:131]
	v_pk_mul_f32 v[132:133], v[20:21], v[132:133]
	v_pk_mul_f32 v[134:135], v[22:23], v[134:135]
	v_pk_mul_f32 v[136:137], v[24:25], v[136:137]
	v_pk_mul_f32 v[138:139], v[26:27], v[138:139]
	v_pk_mul_f32 v[140:141], v[28:29], v[140:141]
	v_pk_mul_f32 v[142:143], v[30:31], v[142:143]
	v_pk_fma_f32 v[128:129], v[32:33], v[128:129], v[48:49]
	v_pk_fma_f32 v[130:131], v[34:35], v[130:131], v[50:51]
	v_pk_fma_f32 v[132:133], v[36:37], v[132:133], v[52:53]
	v_pk_fma_f32 v[134:135], v[38:39], v[134:135], v[54:55]
	v_pk_fma_f32 v[136:137], v[40:41], v[136:137], v[56:57]
	v_pk_fma_f32 v[138:139], v[42:43], v[138:139], v[58:59]
	v_pk_fma_f32 v[140:141], v[44:45], v[140:141], v[60:61]
	v_pk_fma_f32 v[142:143], v[46:47], v[142:143], v[62:63]
	v_cvt_pk_bf16_f32 v148, v128, v129
	v_cvt_pk_bf16_f32 v149, v130, v131
	v_cvt_pk_bf16_f32 v150, v132, v133
	v_cvt_pk_bf16_f32 v151, v134, v135
	v_cvt_pk_bf16_f32 v152, v136, v137
	v_cvt_pk_bf16_f32 v153, v138, v139
	v_cvt_pk_bf16_f32 v154, v140, v141
	v_cvt_pk_bf16_f32 v155, v142, v143
	global_store_dwordx4 v1, v[148:151], s[10:11] offset:2048 sc1
	global_store_dwordx4 v1, v[152:155], s[10:11] offset:3072 sc1
	s_add_u32 s10, s10, 0x1000
	s_addc_u32 s11, s11, 0
	s_waitcnt vmcnt(16)
	v_lshlrev_b32_e32 v128, 16, v112
	v_and_b32_e32 v129, 0xffff0000, v112
	v_lshlrev_b32_e32 v130, 16, v113
	v_and_b32_e32 v131, 0xffff0000, v113
	v_lshlrev_b32_e32 v132, 16, v114
	v_and_b32_e32 v133, 0xffff0000, v114
	v_lshlrev_b32_e32 v134, 16, v115
	v_and_b32_e32 v135, 0xffff0000, v115
	v_lshlrev_b32_e32 v136, 16, v116
	v_and_b32_e32 v137, 0xffff0000, v116
	v_lshlrev_b32_e32 v138, 16, v117
	v_and_b32_e32 v139, 0xffff0000, v117
	v_lshlrev_b32_e32 v140, 16, v118
	v_and_b32_e32 v141, 0xffff0000, v118
	v_lshlrev_b32_e32 v142, 16, v119
	v_and_b32_e32 v143, 0xffff0000, v119
	v_pk_mul_f32 v[144:145], v[128:129], v[128:129]
	v_pk_fma_f32 v[144:145], v[130:131], v[130:131], v[144:145]
	v_pk_fma_f32 v[144:145], v[132:133], v[132:133], v[144:145]
	v_pk_fma_f32 v[144:145], v[134:135], v[134:135], v[144:145]
	v_pk_fma_f32 v[144:145], v[136:137], v[136:137], v[144:145]
	v_pk_fma_f32 v[144:145], v[138:139], v[138:139], v[144:145]
	v_pk_fma_f32 v[144:145], v[140:141], v[140:141], v[144:145]
	v_pk_fma_f32 v[144:145], v[142:143], v[142:143], v[144:145]
	v_add_f32_e32 v144, v144, v145
	s_nop 1
	v_add_f32_dpp v144, v144, v144 quad_perm:[1,0,3,2] row_mask:0xf bank_mask:0xf
	s_nop 1
	v_add_f32_dpp v144, v144, v144 quad_perm:[2,3,0,1] row_mask:0xf bank_mask:0xf
	s_nop 1
	v_add_f32_dpp v144, v144, v144 row_half_mirror row_mask:0xf bank_mask:0xf
	s_nop 1
	v_add_f32_dpp v144, v144, v144 row_mirror row_mask:0xf bank_mask:0xf
	s_nop 0
	v_mov_b32_e32 v145, v144
	s_nop 1
	v_permlane16_swap_b32_e32 v144, v145
	s_nop 0
	v_add_f32_e32 v144, v144, v145
	v_mov_b32_e32 v145, v144
	s_nop 1
	v_permlane32_swap_b32_e32 v144, v145
	s_nop 0
	v_add_f32_e32 v144, v144, v145
	v_fmamk_f32 v144, v144, 0x3a800000, v3
	v_rsq_f32_e32 v144, v144
	s_nop 0
	v_pk_mul_f32 v[128:129], v[128:129], v[144:145] op_sel_hi:[1,0]
; __device__ __forceinline__ unsigned cvt_pk_bf16(float lo, float hi) { unsigned r; asm("v_cvt_pk_bf16_f32 %0, %1, %2" : "=v"(r) : "v"(lo), "v"(hi)); return r; }
; __device__ __forceinline__ void norm_pass_bf16(const Ctx& X, const bf16_t* xs, const bf16_t* cs, int nrows, const float* gain, const float* modl, int si, bf16_t* HN) {
;     for (int r = X.gw; r < nrows; r += X.NGW) {
;     ...
;         for (int j = 0; j < 2; ++j) {
;             v[j][0] = bf2f(q[j].x & 0xffffu); v[j][1] = bf2f(q[j].x >> 16); v[j][2] = bf2f(q[j].y & 0xffffu); v[j][3] = bf2f(q[j].y >> 16);
;             v[j][4] = bf2f(q[j].z & 0xffffu); v[j][5] = bf2f(q[j].z >> 16); v[j][6] = bf2f(q[j].w & 0xffffu); v[j][7] = bf2f(q[j].w >> 16);
; #pragma unroll
;             for (int e = 0; e < 8; ++e) s += v[j][e] * v[j][e]; }
;         const float rstd = rsqrtf(wave_sum(s) * (1.0f / 1024.0f) + 1e-6f);
; #pragma unroll
;         for (int j = 0; j < 2; ++j) { const int c = (X.lane + 64 * j) * 8; float o[8];
; #pragma unroll
;             for (int h = 0; h < 2; ++h) { const f32x4 gn = *(const f32x4*)(gain + c + 4 * h), a = *(const f32x4*)(scl + c + 4 * h), b = *(const f32x4*)(sh + c + 4 * h);
; #pragma unroll
;                 for (int e = 0; e < 4; ++e) o[4 * h + e] = v[j][4 * h + e] * rstd * gn[e] * (a[e] + 1.0f) + b[e]; }
;             u32x4 w; w.x = cvt_pk_bf16(o[0], o[1]); w.y = cvt_pk_bf16(o[2], o[3]); w.z = cvt_pk_bf16(o[4], o[5]); w.w = cvt_pk_bf16(o[6], o[7]); *(u32x4*)(HN + (size_t)r * D + c) = w; }
	v_pk_mul_f32 v[130:131], v[130:131], v[144:145] op_sel_hi:[1,0]
	v_pk_mul_f32 v[132:133], v[132:133], v[144:145] op_sel_hi:[1,0]
	v_pk_mul_f32 v[134:135], v[134:135], v[144:145] op_sel_hi:[1,0]
	v_pk_mul_f32 v[136:137], v[136:137], v[144:145] op_sel_hi:[1,0]
	v_pk_mul_f32 v[138:139], v[138:139], v[144:145] op_sel_hi:[1,0]
	v_pk_mul_f32 v[140:141], v[140:141], v[144:145] op_sel_hi:[1,0]
	v_pk_mul_f32 v[142:143], v[142:143], v[144:145] op_sel_hi:[1,0]
	v_pk_mul_f32 v[128:129], v[16:17], v[128:129]
	v_pk_mul_f32 v[130:131], v[18:19], v[130:131]
	v_pk_mul_f32 v[132:133], v[20:21], v[132:133]
	v_pk_mul_f32 v[134:135], v[22:23], v[134:135]
	v_pk_mul_f32 v[136:137], v[24:25], v[136:137]
	v_pk_mul_f32 v[138:139], v[26:27], v[138:139]
	v_pk_mul_f32 v[140:141], v[28:29], v[140:141]
	v_pk_mul_f32 v[142:143], v[30:31], v[142:143]
	v_pk_fma_f32 v[128:129], v[32:33], v[128:129], v[48:49]
	v_pk_fma_f32 v[130:131], v[34:35], v[130:131], v[50:51]
	v_pk_fma_f32 v[132:133], v[36:37], v[132:133], v[52:53]
	v_pk_fma_f32 v[134:135], v[38:39], v[134:135], v[54:55]
	v_pk_fma_f32 v[136:137], v[40:41], v[136:137], v[56:57]
	v_pk_fma_f32 v[138:139], v[42:43], v[138:139], v[58:59]
	v_pk_fma_f32 v[140:141], v[44:45], v[140:141], v[60:61]
	v_pk_fma_f32 v[142:143], v[46:47], v[142:143], v[62:63]
	v_cvt_pk_bf16_f32 v148, v128, v129
	v_cvt_pk_bf16_f32 v149, v130, v131
	v_cvt_pk_bf16_f32 v150, v132, v133
	v_cvt_pk_bf16_f32 v151, v134, v135
	v_cvt_pk_bf16_f32 v152, v136, v137
	v_cvt_pk_bf16_f32 v153, v138, v139
	v_cvt_pk_bf16_f32 v154, v140, v141
	v_cvt_pk_bf16_f32 v155, v142, v143
	global_store_dwordx4 v1, v[148:151], s[10:11] sc1
	global_store_dwordx4 v1, v[152:155], s[10:11] offset:1024 sc1
	s_waitcnt vmcnt(14)
	v_lshlrev_b32_e32 v128, 16, v120
	v_and_b32_e32 v129, 0xffff0000, v120
	v_lshlrev_b32_e32 v130, 16, v121
	v_and_b32_e32 v131, 0xffff0000, v121
	v_lshlrev_b32_e32 v132, 16, v122
	v_and_b32_e32 v133, 0xffff0000, v122
	v_lshlrev_b32_e32 v134, 16, v123
	v_and_b32_e32 v135, 0xffff0000, v123
	v_lshlrev_b32_e32 v136, 16, v124
	v_and_b32_e32 v137, 0xffff0000, v124
	v_lshlrev_b32_e32 v138, 16, v125
	v_and_b32_e32 v139, 0xffff0000, v125
	v_lshlrev_b32_e32 v140, 16, v126
	v_and_b32_e32 v141, 0xffff0000, v126
	v_lshlrev_b32_e32 v142, 16, v127
	v_and_b32_e32 v143, 0xffff0000, v127
	v_pk_mul_f32 v[144:145], v[128:129], v[128:129]
	v_pk_fma_f32 v[144:145], v[130:131], v[130:131], v[144:145]
	v_pk_fma_f32 v[144:145], v[132:133], v[132:133], v[144:145]
	v_pk_fma_f32 v[144:145], v[134:135], v[134:135], v[144:145]
	v_pk_fma_f32 v[144:145], v[136:137], v[136:137], v[144:145]
	v_pk_fma_f32 v[144:145], v[138:139], v[138:139], v[144:145]
	v_pk_fma_f32 v[144:145], v[140:141], v[140:141], v[144:145]
	v_pk_fma_f32 v[144:145], v[142:143], v[142:143], v[144:145]
	v_add_f32_e32 v144, v144, v145
	s_nop 1
	v_add_f32_dpp v144, v144, v144 quad_perm:[1,0,3,2] row_mask:0xf bank_mask:0xf
	s_nop 1
	v_add_f32_dpp v144, v144, v144 quad_perm:[2,3,0,1] row_mask:0xf bank_mask:0xf
	s_nop 1
	v_add_f32_dpp v144, v144, v144 row_half_mirror row_mask:0xf bank_mask:0xf
	s_nop 1
	v_add_f32_dpp v144, v144, v144 row_mirror row_mask:0xf bank_mask:0xf
	s_nop 0
	v_mov_b32_e32 v145, v144
	s_nop 1
	v_permlane16_swap_b32_e32 v144, v145
	s_nop 0
	v_add_f32_e32 v144, v144, v145
	v_mov_b32_e32 v145, v144
	s_nop 1
	v_permlane32_swap_b32_e32 v144, v145
	s_nop 0
	v_add_f32_e32 v144, v144, v145
	v_fmamk_f32 v144, v144, 0x3a800000, v3
	v_rsq_f32_e32 v144, v144
	s_nop 0
	v_pk_mul_f32 v[128:129], v[128:129], v[144:145] op_sel_hi:[1,0]
	v_pk_mul_f32 v[130:131], v[130:131], v[144:145] op_sel_hi:[1,0]
	v_pk_mul_f32 v[132:133], v[132:133], v[144:145] op_sel_hi:[1,0]
	v_pk_mul_f32 v[134:135], v[134:135], v[144:145] op_sel_hi:[1,0]
	v_pk_mul_f32 v[136:137], v[136:137], v[144:145] op_sel_hi:[1,0]
	v_pk_mul_f32 v[138:139], v[138:139], v[144:145] op_sel_hi:[1,0]
	v_pk_mul_f32 v[140:141], v[140:141], v[144:145] op_sel_hi:[1,0]
	v_pk_mul_f32 v[142:143], v[142:143], v[144:145] op_sel_hi:[1,0]
	v_pk_mul_f32 v[128:129], v[16:17], v[128:129]
	v_pk_mul_f32 v[130:131], v[18:19], v[130:131]
	v_pk_mul_f32 v[132:133], v[20:21], v[132:133]
	v_pk_mul_f32 v[134:135], v[22:23], v[134:135]
	v_pk_mul_f32 v[136:137], v[24:25], v[136:137]
	v_pk_mul_f32 v[138:139], v[26:27], v[138:139]
	v_pk_mul_f32 v[140:141], v[28:29], v[140:141]
	v_pk_mul_f32 v[142:143], v[30:31], v[142:143]
	v_pk_fma_f32 v[128:129], v[32:33], v[128:129], v[48:49]
	v_pk_fma_f32 v[130:131], v[34:35], v[130:131], v[50:51]
	v_pk_fma_f32 v[132:133], v[36:37], v[132:133], v[52:53]
	v_pk_fma_f32 v[134:135], v[38:39], v[134:135], v[54:55]
	v_pk_fma_f32 v[136:137], v[40:41], v[136:137], v[56:57]
	v_pk_fma_f32 v[138:139], v[42:43], v[138:139], v[58:59]
	v_pk_fma_f32 v[140:141], v[44:45], v[140:141], v[60:61]
	v_pk_fma_f32 v[142:143], v[46:47], v[142:143], v[62:63]
	v_cvt_pk_bf16_f32 v148, v128, v129
	v_cvt_pk_bf16_f32 v149, v130, v131
	v_cvt_pk_bf16_f32 v150, v132, v133
	v_cvt_pk_bf16_f32 v151, v134, v135
	v_cvt_pk_bf16_f32 v152, v136, v137
	v_cvt_pk_bf16_f32 v153, v138, v139
	v_cvt_pk_bf16_f32 v154, v140, v141
	v_cvt_pk_bf16_f32 v155, v142, v143
	global_store_dwordx4 v1, v[148:151], s[10:11] offset:2048 sc1
	global_store_dwordx4 v1, v[152:155], s[10:11] offset:3072 sc1
	s_add_u32 s10, s10, 0x1000
	s_addc_u32 s11, s11, 0
	s_add_i32 s12, s12, s20
	s_cmp_lt_i32 s12, 0x800
	s_cbranch_scc0 .LBB0_420
	s_waitcnt vmcnt(0)
	s_branch .Lhn_A_blk

; __device__ __forceinline__ unsigned cvt_pk_bf16(float lo, float hi) { unsigned r; asm("v_cvt_pk_bf16_f32 %0, %1, %2" : "=v"(r) : "v"(lo), "v"(hi)); return r; }
; __device__ __forceinline__ void norm_pass_bf16(const Ctx& X, const bf16_t* xs, const bf16_t* cs, int nrows, const float* gain, const float* modl, int si, bf16_t* HN) {
;     ...
;         const int mb = r < MX ? (r >> 12) : 8;
;         const float* sh = modl + (size_t)mb * 9216 + si * 1024; const float* scl = sh + 1024;
;         const bf16_t* rowp = r < MX ? xs + (size_t)r * D : cs + (size_t)(r - MX) * D;
;         u32x4 q[2]; float v[2][8]; float s = 0.f;
; #pragma unroll
;         for (int j = 0; j < 2; ++j) q[j] = *(const u32x4*)(rowp + (X.lane + 64 * j) * 8);
; #pragma unroll
;         for (int j = 0; j < 2; ++j) {
;             v[j][0] = bf2f(q[j].x & 0xffffu); v[j][1] = bf2f(q[j].x >> 16); v[j][2] = bf2f(q[j].y & 0xffffu); v[j][3] = bf2f(q[j].y >> 16);
;             v[j][4] = bf2f(q[j].z & 0xffffu); v[j][5] = bf2f(q[j].z >> 16); v[j][6] = bf2f(q[j].w & 0xffffu); v[j][7] = bf2f(q[j].w >> 16);
; #pragma unroll
;             for (int e = 0; e < 8; ++e) s += v[j][e] * v[j][e]; }
;         const float rstd = rsqrtf(wave_sum(s) * (1.0f / 1024.0f) + 1e-6f);
; #pragma unroll
;         for (int j = 0; j < 2; ++j) { const int c = (X.lane + 64 * j) * 8; float o[8];
; #pragma unroll
;             for (int h = 0; h < 2; ++h) { const f32x4 gn = *(const f32x4*)(gain + c + 4 * h), a = *(const f32x4*)(scl + c + 4 * h), b = *(const f32x4*)(sh + c + 4 * h);
; #pragma unroll
;                 for (int e = 0; e < 4; ++e) o[4 * h + e] = v[j][4 * h + e] * rstd * gn[e] * (a[e] + 1.0f) + b[e]; }
;             u32x4 w; w.x = cvt_pk_bf16(o[0], o[1]); w.y = cvt_pk_bf16(o[2], o[3]); w.z = cvt_pk_bf16(o[4], o[5]); w.w = cvt_pk_bf16(o[6], o[7]); *(u32x4*)(HN + (size_t)r * D + c) = w; }
.Lhn_B_blk:
	s_add_u32 s6, s48, 0x2000
	s_addc_u32 s7, s49, 0
	global_load_dwordx4 v[16:19], v2, s[6:7]
	global_load_dwordx4 v[20:23], v2, s[6:7] offset:16
	global_load_dwordx4 v[24:27], v2, s[6:7] offset:2048
	global_load_dwordx4 v[28:31], v2, s[6:7] offset:2064
	s_lshr_b32 s5, s12, 8
	s_mul_i32 s5, s5, 0x9000
	s_add_u32 s6, s88, s5
	s_addc_u32 s7, s89, 0
	s_add_u32 s6, s6, 0x6000
	s_addc_u32 s7, s7, 0
	global_load_dwordx4 v[48:51], v2, s[6:7]
	global_load_dwordx4 v[52:55], v2, s[6:7] offset:16
	global_load_dwordx4 v[56:59], v2, s[6:7] offset:2048
	global_load_dwordx4 v[60:63], v2, s[6:7] offset:2064
	s_add_u32 s6, s6, 0x1000
	s_addc_u32 s7, s7, 0
	global_load_dwordx4 v[32:35], v2, s[6:7]
	global_load_dwordx4 v[36:39], v2, s[6:7] offset:16
	global_load_dwordx4 v[40:43], v2, s[6:7] offset:2048
	global_load_dwordx4 v[44:47], v2, s[6:7] offset:2064
	s_lshl_b32 s5, s12, 15
	s_add_u32 s8, s86, s5
	s_addc_u32 s9, s87, 0
	s_add_u32 s10, s88, s5
	s_addc_u32 s11, s89, 0
	s_add_u32 s10, s10, 0x13000000
	s_addc_u32 s11, s11, 0
	global_load_dwordx4 v[64:67], v1, s[8:9]
	global_load_dwordx4 v[68:71], v1, s[8:9] offset:1024
	global_load_dwordx4 v[72:75], v1, s[8:9] offset:2048
	global_load_dwordx4 v[76:79], v1, s[8:9] offset:3072
	s_add_u32 s8, s8, 0x1000
	s_addc_u32 s9, s9, 0
	global_load_dwordx4 v[80:83], v1, s[8:9]
	global_load_dwordx4 v[84:87], v1, s[8:9] offset:1024
	global_load_dwordx4 v[88:91], v1, s[8:9] offset:2048
	global_load_dwordx4 v[92:95], v1, s[8:9] offset:3072
	s_add_u32 s8, s8, 0x1000
	s_addc_u32 s9, s9, 0
	global_load_dwordx4 v[96:99], v1, s[8:9]
	global_load_dwordx4 v[100:103], v1, s[8:9] offset:1024
	global_load_dwordx4 v[104:107], v1, s[8:9] offset:2048
	global_load_dwordx4 v[108:111], v1, s[8:9] offset:3072
	s_add_u32 s8, s8, 0x1000
	s_addc_u32 s9, s9, 0
	global_load_dwordx4 v[112:115], v1, s[8:9]
	global_load_dwordx4 v[116:119], v1, s[8:9] offset:1024
	global_load_dwordx4 v[120:123], v1, s[8:9] offset:2048
	global_load_dwordx4 v[124:127], v1, s[8:9] offset:3072
	s_add_u32 s8, s8, 0x1000
	s_addc_u32 s9, s9, 0
	s_waitcnt vmcnt(16)
	v_pk_add_f32 v[32:33], v[32:33], 1.0 op_sel_hi:[1,0]
	v_pk_add_f32 v[34:35], v[34:35], 1.0 op_sel_hi:[1,0]
	v_pk_add_f32 v[36:37], v[36:37], 1.0 op_sel_hi:[1,0]
	v_pk_add_f32 v[38:39], v[38:39], 1.0 op_sel_hi:[1,0]
	v_pk_add_f32 v[40:41], v[40:41], 1.0 op_sel_hi:[1,0]
	v_pk_add_f32 v[42:43], v[42:43], 1.0 op_sel_hi:[1,0]
	v_pk_add_f32 v[44:45], v[44:45], 1.0 op_sel_hi:[1,0]
	v_pk_add_f32 v[46:47], v[46:47], 1.0 op_sel_hi:[1,0]
	s_waitcnt vmcnt(14)
	v_lshlrev_b32_e32 v128, 16, v64
	v_and_b32_e32 v129, 0xffff0000, v64
	v_lshlrev_b32_e32 v130, 16, v65
	v_and_b32_e32 v131, 0xffff0000, v65
	v_lshlrev_b32_e32 v132, 16, v66
	v_and_b32_e32 v133, 0xffff0000, v66
	v_lshlrev_b32_e32 v134, 16, v67
	v_and_b32_e32 v135, 0xffff0000, v67
	v_lshlrev_b32_e32 v136, 16, v68
	v_and_b32_e32 v137, 0xffff0000, v68
	v_lshlrev_b32_e32 v138, 16, v69
	v_and_b32_e32 v139, 0xffff0000, v69
	v_lshlrev_b32_e32 v140, 16, v70
	v_and_b32_e32 v141, 0xffff0000, v70
	v_lshlrev_b32_e32 v142, 16, v71
	v_and_b32_e32 v143, 0xffff0000, v71
	v_pk_mul_f32 v[144:145], v[128:129], v[128:129]
	v_pk_fma_f32 v[144:145], v[130:131], v[130:131], v[144:145]
	v_pk_fma_f32 v[144:145], v[132:133], v[132:133], v[144:145]
	v_pk_fma_f32 v[144:145], v[134:135], v[134:135], v[144:145]
	v_pk_fma_f32 v[144:145], v[136:137], v[136:137], v[144:145]
	v_pk_fma_f32 v[144:145], v[138:139], v[138:139], v[144:145]
	v_pk_fma_f32 v[144:145], v[140:141], v[140:141], v[144:145]
	v_pk_fma_f32 v[144:145], v[142:143], v[142:143], v[144:145]
	v_add_f32_e32 v144, v144, v145
	s_nop 1
	v_add_f32_dpp v144, v144, v144 quad_perm:[1,0,3,2] row_mask:0xf bank_mask:0xf
	s_nop 1
	v_add_f32_dpp v144, v144, v144 quad_perm:[2,3,0,1] row_mask:0xf bank_mask:0xf
	s_nop 1
	v_add_f32_dpp v144, v144, v144 row_half_mirror row_mask:0xf bank_mask:0xf
	s_nop 1
	v_add_f32_dpp v144, v144, v144 row_mirror row_mask:0xf bank_mask:0xf
	s_nop 0
	v_mov_b32_e32 v145, v144
	s_nop 1
	v_permlane16_swap_b32_e32 v144, v145
	s_nop 0
	v_add_f32_e32 v144, v144, v145
	v_mov_b32_e32 v145, v144
	s_nop 1
	v_permlane32_swap_b32_e32 v144, v145
	s_nop 0
	v_add_f32_e32 v144, v144, v145
	v_fmamk_f32 v144, v144, 0x3a800000, v3
	v_rsq_f32_e32 v144, v144
	s_nop 0
	v_pk_mul_f32 v[128:129], v[128:129], v[144:145] op_sel_hi:[1,0]
	v_pk_mul_f32 v[130:131], v[130:131], v[144:145] op_sel_hi:[1,0]
	v_pk_mul_f32 v[132:133], v[132:133], v[144:145] op_sel_hi:[1,0]
	v_pk_mul_f32 v[134:135], v[134:135], v[144:145] op_sel_hi:[1,0]
	v_pk_mul_f32 v[136:137], v[136:137], v[144:145] op_sel_hi:[1,0]
	v_pk_mul_f32 v[138:139], v[138:139], v[144:145] op_sel_hi:[1,0]
	v_pk_mul_f32 v[140:141], v[140:141], v[144:145] op_sel_hi:[1,0]
	v_pk_mul_f32 v[142:143], v[142:143], v[144:145] op_sel_hi:[1,0]
	v_pk_mul_f32 v[128:129], v[16:17], v[128:129]
	v_pk_mul_f32 v[130:131], v[18:19], v[130:131]
	v_pk_mul_f32 v[132:133], v[20:21], v[132:133]
	v_pk_mul_f32 v[134:135], v[22:23], v[134:135]
	v_pk_mul_f32 v[136:137], v[24:25], v[136:137]
	v_pk_mul_f32 v[138:139], v[26:27], v[138:139]
	v_pk_mul_f32 v[140:141], v[28:29], v[140:141]
	v_pk_mul_f32 v[142:143], v[30:31], v[142:143]
	v_pk_fma_f32 v[128:129], v[32:33], v[128:129], v[48:49]
	v_pk_fma_f32 v[130:131], v[34:35], v[130:131], v[50:51]
	v_pk_fma_f32 v[132:133], v[36:37], v[132:133], v[52:53]
	v_pk_fma_f32 v[134:135], v[38:39], v[134:135], v[54:55]
	v_pk_fma_f32 v[136:137], v[40:41], v[136:137], v[56:57]
	v_pk_fma_f32 v[138:139], v[42:43], v[138:139], v[58:59]
	v_pk_fma_f32 v[140:141], v[44:45], v[140:141], v[60:61]
	v_pk_fma_f32 v[142:143], v[46:47], v[142:143], v[62:63]
	v_cvt_pk_bf16_f32 v148, v128, v129
	v_cvt_pk_bf16_f32 v149, v130, v131
	v_cvt_pk_bf16_f32 v150, v132, v133
	v_cvt_pk_bf16_f32 v151, v134, v135
	v_cvt_pk_bf16_f32 v152, v136, v137
	v_cvt_pk_bf16_f32 v153, v138, v139
	v_cvt_pk_bf16_f32 v154, v140, v141
	v_cvt_pk_bf16_f32 v155, v142, v143
	global_store_dwordx4 v1, v[148:151], s[10:11] sc1
	global_store_dwordx4 v1, v[152:155], s[10:11] offset:1024 sc1
	global_load_dwordx4 v[64:67], v1, s[8:9]
	global_load_dwordx4 v[68:71], v1, s[8:9] offset:1024
	s_waitcnt vmcnt(16)
; __device__ __forceinline__ unsigned cvt_pk_bf16(float lo, float hi) { unsigned r; asm("v_cvt_pk_bf16_f32 %0, %1, %2" : "=v"(r) : "v"(lo), "v"(hi)); return r; }
; __device__ __forceinline__ void norm_pass_bf16(const Ctx& X, const bf16_t* xs, const bf16_t* cs, int nrows, const float* gain, const float* modl, int si, bf16_t* HN) {
;     ...
;         for (int j = 0; j < 2; ++j) {
;             v[j][0] = bf2f(q[j].x & 0xffffu); v[j][1] = bf2f(q[j].x >> 16); v[j][2] = bf2f(q[j].y & 0xffffu); v[j][3] = bf2f(q[j].y >> 16);
;             v[j][4] = bf2f(q[j].z & 0xffffu); v[j][5] = bf2f(q[j].z >> 16); v[j][6] = bf2f(q[j].w & 0xffffu); v[j][7] = bf2f(q[j].w >> 16);
; #pragma unroll
;             for (int e = 0; e < 8; ++e) s += v[j][e] * v[j][e]; }
;         const float rstd = rsqrtf(wave_sum(s) * (1.0f / 1024.0f) + 1e-6f);
; #pragma unroll
;         for (int j = 0; j < 2; ++j) { const int c = (X.lane + 64 * j) * 8; float o[8];
; #pragma unroll
;             for (int h = 0; h < 2; ++h) { const f32x4 gn = *(const f32x4*)(gain + c + 4 * h), a = *(const f32x4*)(scl + c + 4 * h), b = *(const f32x4*)(sh + c + 4 * h);
; #pragma unroll
;                 for (int e = 0; e < 4; ++e) o[4 * h + e] = v[j][4 * h + e] * rstd * gn[e] * (a[e] + 1.0f) + b[e]; }
;             u32x4 w; w.x = cvt_pk_bf16(o[0], o[1]); w.y = cvt_pk_bf16(o[2], o[3]); w.z = cvt_pk_bf16(o[4], o[5]); w.w = cvt_pk_bf16(o[6], o[7]); *(u32x4*)(HN + (size_t)r * D + c) = w; }
	v_lshlrev_b32_e32 v128, 16, v72
	v_and_b32_e32 v129, 0xffff0000, v72
	v_lshlrev_b32_e32 v130, 16, v73
	v_and_b32_e32 v131, 0xffff0000, v73
	v_lshlrev_b32_e32 v132, 16, v74
	v_and_b32_e32 v133, 0xffff0000, v74
	v_lshlrev_b32_e32 v134, 16, v75
	v_and_b32_e32 v135, 0xffff0000, v75
	v_lshlrev_b32_e32 v136, 16, v76
	v_and_b32_e32 v137, 0xffff0000, v76
	v_lshlrev_b32_e32 v138, 16, v77
	v_and_b32_e32 v139, 0xffff0000, v77
	v_lshlrev_b32_e32 v140, 16, v78
	v_and_b32_e32 v141, 0xffff0000, v78
	v_lshlrev_b32_e32 v142, 16, v79
	v_and_b32_e32 v143, 0xffff0000, v79
	v_pk_mul_f32 v[144:145], v[128:129], v[128:129]
	v_pk_fma_f32 v[144:145], v[130:131], v[130:131], v[144:145]
	v_pk_fma_f32 v[144:145], v[132:133], v[132:133], v[144:145]
	v_pk_fma_f32 v[144:145], v[134:135], v[134:135], v[144:145]
	v_pk_fma_f32 v[144:145], v[136:137], v[136:137], v[144:145]
	v_pk_fma_f32 v[144:145], v[138:139], v[138:139], v[144:145]
	v_pk_fma_f32 v[144:145], v[140:141], v[140:141], v[144:145]
	v_pk_fma_f32 v[144:145], v[142:143], v[142:143], v[144:145]
	v_add_f32_e32 v144, v144, v145
	s_nop 1
	v_add_f32_dpp v144, v144, v144 quad_perm:[1,0,3,2] row_mask:0xf bank_mask:0xf
	s_nop 1
	v_add_f32_dpp v144, v144, v144 quad_perm:[2,3,0,1] row_mask:0xf bank_mask:0xf
	s_nop 1
	v_add_f32_dpp v144, v144, v144 row_half_mirror row_mask:0xf bank_mask:0xf
	s_nop 1
	v_add_f32_dpp v144, v144, v144 row_mirror row_mask:0xf bank_mask:0xf
	s_nop 0
	v_mov_b32_e32 v145, v144
	s_nop 1
	v_permlane16_swap_b32_e32 v144, v145
	s_nop 0
	v_add_f32_e32 v144, v144, v145
	v_mov_b32_e32 v145, v144
	s_nop 1
	v_permlane32_swap_b32_e32 v144, v145
	s_nop 0
	v_add_f32_e32 v144, v144, v145
	v_fmamk_f32 v144, v144, 0x3a800000, v3
	v_rsq_f32_e32 v144, v144
	s_nop 0
	v_pk_mul_f32 v[128:129], v[128:129], v[144:145] op_sel_hi:[1,0]
	v_pk_mul_f32 v[130:131], v[130:131], v[144:145] op_sel_hi:[1,0]
	v_pk_mul_f32 v[132:133], v[132:133], v[144:145] op_sel_hi:[1,0]
	v_pk_mul_f32 v[134:135], v[134:135], v[144:145] op_sel_hi:[1,0]
	v_pk_mul_f32 v[136:137], v[136:137], v[144:145] op_sel_hi:[1,0]
	v_pk_mul_f32 v[138:139], v[138:139], v[144:145] op_sel_hi:[1,0]
	v_pk_mul_f32 v[140:141], v[140:141], v[144:145] op_sel_hi:[1,0]
	v_pk_mul_f32 v[142:143], v[142:143], v[144:145] op_sel_hi:[1,0]
	v_pk_mul_f32 v[128:129], v[16:17], v[128:129]
	v_pk_mul_f32 v[130:131], v[18:19], v[130:131]
	v_pk_mul_f32 v[132:133], v[20:21], v[132:133]
	v_pk_mul_f32 v[134:135], v[22:23], v[134:135]
	v_pk_mul_f32 v[136:137], v[24:25], v[136:137]
	v_pk_mul_f32 v[138:139], v[26:27], v[138:139]
	v_pk_mul_f32 v[140:141], v[28:29], v[140:141]
	v_pk_mul_f32 v[142:143], v[30:31], v[142:143]
	v_pk_fma_f32 v[128:129], v[32:33], v[128:129], v[48:49]
	v_pk_fma_f32 v[130:131], v[34:35], v[130:131], v[50:51]
	v_pk_fma_f32 v[132:133], v[36:37], v[132:133], v[52:53]
	v_pk_fma_f32 v[134:135], v[38:39], v[134:135], v[54:55]
	v_pk_fma_f32 v[136:137], v[40:41], v[136:137], v[56:57]
	v_pk_fma_f32 v[138:139], v[42:43], v[138:139], v[58:59]
	v_pk_fma_f32 v[140:141], v[44:45], v[140:141], v[60:61]
	v_pk_fma_f32 v[142:143], v[46:47], v[142:143], v[62:63]
	v_cvt_pk_bf16_f32 v148, v128, v129
	v_cvt_pk_bf16_f32 v149, v130, v131
	v_cvt_pk_bf16_f32 v150, v132, v133
	v_cvt_pk_bf16_f32 v151, v134, v135
	v_cvt_pk_bf16_f32 v152, v136, v137
	v_cvt_pk_bf16_f32 v153, v138, v139
	v_cvt_pk_bf16_f32 v154, v140, v141
	v_cvt_pk_bf16_f32 v155, v142, v143
	global_store_dwordx4 v1, v[148:151], s[10:11] offset:2048 sc1
	global_store_dwordx4 v1, v[152:155], s[10:11] offset:3072 sc1
	s_add_u32 s10, s10, 0x1000
	s_addc_u32 s11, s11, 0
	global_load_dwordx4 v[72:75], v1, s[8:9] offset:2048
	global_load_dwordx4 v[76:79], v1, s[8:9] offset:3072
	s_add_u32 s8, s8, 0x1000
	s_addc_u32 s9, s9, 0
	s_waitcnt vmcnt(18)
	v_lshlrev_b32_e32 v128, 16, v80
	v_and_b32_e32 v129, 0xffff0000, v80
	v_lshlrev_b32_e32 v130, 16, v81
	v_and_b32_e32 v131, 0xffff0000, v81
	v_lshlrev_b32_e32 v132, 16, v82
	v_and_b32_e32 v133, 0xffff0000, v82
	v_lshlrev_b32_e32 v134, 16, v83
	v_and_b32_e32 v135, 0xffff0000, v83
	v_lshlrev_b32_e32 v136, 16, v84
	v_and_b32_e32 v137, 0xffff0000, v84
	v_lshlrev_b32_e32 v138, 16, v85
	v_and_b32_e32 v139, 0xffff0000, v85
	v_lshlrev_b32_e32 v140, 16, v86
	v_and_b32_e32 v141, 0xffff0000, v86
	v_lshlrev_b32_e32 v142, 16, v87
	v_and_b32_e32 v143, 0xffff0000, v87
	v_pk_mul_f32 v[144:145], v[128:129], v[128:129]
	v_pk_fma_f32 v[144:145], v[130:131], v[130:131], v[144:145]
	v_pk_fma_f32 v[144:145], v[132:133], v[132:133], v[144:145]
	v_pk_fma_f32 v[144:145], v[134:135], v[134:135], v[144:145]
	v_pk_fma_f32 v[144:145], v[136:137], v[136:137], v[144:145]
	v_pk_fma_f32 v[144:145], v[138:139], v[138:139], v[144:145]
	v_pk_fma_f32 v[144:145], v[140:141], v[140:141], v[144:145]
	v_pk_fma_f32 v[144:145], v[142:143], v[142:143], v[144:145]
	v_add_f32_e32 v144, v144, v145
	s_nop 1
	v_add_f32_dpp v144, v144, v144 quad_perm:[1,0,3,2] row_mask:0xf bank_mask:0xf
	s_nop 1
	v_add_f32_dpp v144, v144, v144 quad_perm:[2,3,0,1] row_mask:0xf bank_mask:0xf
	s_nop 1
	v_add_f32_dpp v144, v144, v144 row_half_mirror row_mask:0xf bank_mask:0xf
	s_nop 1
	v_add_f32_dpp v144, v144, v144 row_mirror row_mask:0xf bank_mask:0xf
	s_nop 0
	v_mov_b32_e32 v145, v144
	s_nop 1
	v_permlane16_swap_b32_e32 v144, v145
	s_nop 0
	v_add_f32_e32 v144, v144, v145
	v_mov_b32_e32 v145, v144
	s_nop 1
	v_permlane32_swap_b32_e32 v144, v145
	s_nop 0
	v_add_f32_e32 v144, v144, v145
	v_fmamk_f32 v144, v144, 0x3a800000, v3
	v_rsq_f32_e32 v144, v144
	s_nop 0
	v_pk_mul_f32 v[128:129], v[128:129], v[144:145] op_sel_hi:[1,0]
	v_pk_mul_f32 v[130:131], v[130:131], v[144:145] op_sel_hi:[1,0]
	v_pk_mul_f32 v[132:133], v[132:133], v[144:145] op_sel_hi:[1,0]
; __device__ __forceinline__ unsigned cvt_pk_bf16(float lo, float hi) { unsigned r; asm("v_cvt_pk_bf16_f32 %0, %1, %2" : "=v"(r) : "v"(lo), "v"(hi)); return r; }
; __device__ __forceinline__ void norm_pass_bf16(const Ctx& X, const bf16_t* xs, const bf16_t* cs, int nrows, const float* gain, const float* modl, int si, bf16_t* HN) {
;     ...
;         for (int j = 0; j < 2; ++j) {
;             v[j][0] = bf2f(q[j].x & 0xffffu); v[j][1] = bf2f(q[j].x >> 16); v[j][2] = bf2f(q[j].y & 0xffffu); v[j][3] = bf2f(q[j].y >> 16);
;             v[j][4] = bf2f(q[j].z & 0xffffu); v[j][5] = bf2f(q[j].z >> 16); v[j][6] = bf2f(q[j].w & 0xffffu); v[j][7] = bf2f(q[j].w >> 16);
; #pragma unroll
;             for (int e = 0; e < 8; ++e) s += v[j][e] * v[j][e]; }
;         const float rstd = rsqrtf(wave_sum(s) * (1.0f / 1024.0f) + 1e-6f);
; #pragma unroll
;         for (int j = 0; j < 2; ++j) { const int c = (X.lane + 64 * j) * 8; float o[8];
; #pragma unroll
;             for (int h = 0; h < 2; ++h) { const f32x4 gn = *(const f32x4*)(gain + c + 4 * h), a = *(const f32x4*)(scl + c + 4 * h), b = *(const f32x4*)(sh + c + 4 * h);
; #pragma unroll
;                 for (int e = 0; e < 4; ++e) o[4 * h + e] = v[j][4 * h + e] * rstd * gn[e] * (a[e] + 1.0f) + b[e]; }
;             u32x4 w; w.x = cvt_pk_bf16(o[0], o[1]); w.y = cvt_pk_bf16(o[2], o[3]); w.z = cvt_pk_bf16(o[4], o[5]); w.w = cvt_pk_bf16(o[6], o[7]); *(u32x4*)(HN + (size_t)r * D + c) = w; }
	v_pk_mul_f32 v[134:135], v[134:135], v[144:145] op_sel_hi:[1,0]
	v_pk_mul_f32 v[136:137], v[136:137], v[144:145] op_sel_hi:[1,0]
	v_pk_mul_f32 v[138:139], v[138:139], v[144:145] op_sel_hi:[1,0]
	v_pk_mul_f32 v[140:141], v[140:141], v[144:145] op_sel_hi:[1,0]
	v_pk_mul_f32 v[142:143], v[142:143], v[144:145] op_sel_hi:[1,0]
	v_pk_mul_f32 v[128:129], v[16:17], v[128:129]
	v_pk_mul_f32 v[130:131], v[18:19], v[130:131]
	v_pk_mul_f32 v[132:133], v[20:21], v[132:133]
	v_pk_mul_f32 v[134:135], v[22:23], v[134:135]
	v_pk_mul_f32 v[136:137], v[24:25], v[136:137]
	v_pk_mul_f32 v[138:139], v[26:27], v[138:139]
	v_pk_mul_f32 v[140:141], v[28:29], v[140:141]
	v_pk_mul_f32 v[142:143], v[30:31], v[142:143]
	v_pk_fma_f32 v[128:129], v[32:33], v[128:129], v[48:49]
	v_pk_fma_f32 v[130:131], v[34:35], v[130:131], v[50:51]
	v_pk_fma_f32 v[132:133], v[36:37], v[132:133], v[52:53]
	v_pk_fma_f32 v[134:135], v[38:39], v[134:135], v[54:55]
	v_pk_fma_f32 v[136:137], v[40:41], v[136:137], v[56:57]
	v_pk_fma_f32 v[138:139], v[42:43], v[138:139], v[58:59]
	v_pk_fma_f32 v[140:141], v[44:45], v[140:141], v[60:61]
	v_pk_fma_f32 v[142:143], v[46:47], v[142:143], v[62:63]
	v_cvt_pk_bf16_f32 v148, v128, v129
	v_cvt_pk_bf16_f32 v149, v130, v131
	v_cvt_pk_bf16_f32 v150, v132, v133
	v_cvt_pk_bf16_f32 v151, v134, v135
	v_cvt_pk_bf16_f32 v152, v136, v137
	v_cvt_pk_bf16_f32 v153, v138, v139
	v_cvt_pk_bf16_f32 v154, v140, v141
	v_cvt_pk_bf16_f32 v155, v142, v143
	global_store_dwordx4 v1, v[148:151], s[10:11] sc1
	global_store_dwordx4 v1, v[152:155], s[10:11] offset:1024 sc1
	global_load_dwordx4 v[80:83], v1, s[8:9]
	global_load_dwordx4 v[84:87], v1, s[8:9] offset:1024
	s_waitcnt vmcnt(20)
	v_lshlrev_b32_e32 v128, 16, v88
	v_and_b32_e32 v129, 0xffff0000, v88
	v_lshlrev_b32_e32 v130, 16, v89
	v_and_b32_e32 v131, 0xffff0000, v89
	v_lshlrev_b32_e32 v132, 16, v90
	v_and_b32_e32 v133, 0xffff0000, v90
	v_lshlrev_b32_e32 v134, 16, v91
	v_and_b32_e32 v135, 0xffff0000, v91
	v_lshlrev_b32_e32 v136, 16, v92
	v_and_b32_e32 v137, 0xffff0000, v92
	v_lshlrev_b32_e32 v138, 16, v93
	v_and_b32_e32 v139, 0xffff0000, v93
	v_lshlrev_b32_e32 v140, 16, v94
	v_and_b32_e32 v141, 0xffff0000, v94
	v_lshlrev_b32_e32 v142, 16, v95
	v_and_b32_e32 v143, 0xffff0000, v95
	v_pk_mul_f32 v[144:145], v[128:129], v[128:129]
	v_pk_fma_f32 v[144:145], v[130:131], v[130:131], v[144:145]
	v_pk_fma_f32 v[144:145], v[132:133], v[132:133], v[144:145]
	v_pk_fma_f32 v[144:145], v[134:135], v[134:135], v[144:145]
	v_pk_fma_f32 v[144:145], v[136:137], v[136:137], v[144:145]
	v_pk_fma_f32 v[144:145], v[138:139], v[138:139], v[144:145]
	v_pk_fma_f32 v[144:145], v[140:141], v[140:141], v[144:145]
	v_pk_fma_f32 v[144:145], v[142:143], v[142:143], v[144:145]
	v_add_f32_e32 v144, v144, v145
	s_nop 1
	v_add_f32_dpp v144, v144, v144 quad_perm:[1,0,3,2] row_mask:0xf bank_mask:0xf
	s_nop 1
	v_add_f32_dpp v144, v144, v144 quad_perm:[2,3,0,1] row_mask:0xf bank_mask:0xf
	s_nop 1
	v_add_f32_dpp v144, v144, v144 row_half_mirror row_mask:0xf bank_mask:0xf
	s_nop 1
	v_add_f32_dpp v144, v144, v144 row_mirror row_mask:0xf bank_mask:0xf
	s_nop 0
	v_mov_b32_e32 v145, v144
	s_nop 1
	v_permlane16_swap_b32_e32 v144, v145
	s_nop 0
	v_add_f32_e32 v144, v144, v145
	v_mov_b32_e32 v145, v144
	s_nop 1
	v_permlane32_swap_b32_e32 v144, v145
	s_nop 0
	v_add_f32_e32 v144, v144, v145
	v_fmamk_f32 v144, v144, 0x3a800000, v3
	v_rsq_f32_e32 v144, v144
	s_nop 0
	v_pk_mul_f32 v[128:129], v[128:129], v[144:145] op_sel_hi:[1,0]
	v_pk_mul_f32 v[130:131], v[130:131], v[144:145] op_sel_hi:[1,0]
	v_pk_mul_f32 v[132:133], v[132:133], v[144:145] op_sel_hi:[1,0]
	v_pk_mul_f32 v[134:135], v[134:135], v[144:145] op_sel_hi:[1,0]
	v_pk_mul_f32 v[136:137], v[136:137], v[144:145] op_sel_hi:[1,0]
	v_pk_mul_f32 v[138:139], v[138:139], v[144:145] op_sel_hi:[1,0]
	v_pk_mul_f32 v[140:141], v[140:141], v[144:145] op_sel_hi:[1,0]
	v_pk_mul_f32 v[142:143], v[142:143], v[144:145] op_sel_hi:[1,0]
	v_pk_mul_f32 v[128:129], v[16:17], v[128:129]
	v_pk_mul_f32 v[130:131], v[18:19], v[130:131]
	v_pk_mul_f32 v[132:133], v[20:21], v[132:133]
	v_pk_mul_f32 v[134:135], v[22:23], v[134:135]
	v_pk_mul_f32 v[136:137], v[24:25], v[136:137]
	v_pk_mul_f32 v[138:139], v[26:27], v[138:139]
	v_pk_mul_f32 v[140:141], v[28:29], v[140:141]
	v_pk_mul_f32 v[142:143], v[30:31], v[142:143]
	v_pk_fma_f32 v[128:129], v[32:33], v[128:129], v[48:49]
	v_pk_fma_f32 v[130:131], v[34:35], v[130:131], v[50:51]
	v_pk_fma_f32 v[132:133], v[36:37], v[132:133], v[52:53]
	v_pk_fma_f32 v[134:135], v[38:39], v[134:135], v[54:55]
	v_pk_fma_f32 v[136:137], v[40:41], v[136:137], v[56:57]
	v_pk_fma_f32 v[138:139], v[42:43], v[138:139], v[58:59]
	v_pk_fma_f32 v[140:141], v[44:45], v[140:141], v[60:61]
	v_pk_fma_f32 v[142:143], v[46:47], v[142:143], v[62:63]
	v_cvt_pk_bf16_f32 v148, v128, v129
	v_cvt_pk_bf16_f32 v149, v130, v131
	v_cvt_pk_bf16_f32 v150, v132, v133
	v_cvt_pk_bf16_f32 v151, v134, v135
	v_cvt_pk_bf16_f32 v152, v136, v137
	v_cvt_pk_bf16_f32 v153, v138, v139
	v_cvt_pk_bf16_f32 v154, v140, v141
	v_cvt_pk_bf16_f32 v155, v142, v143
	global_store_dwordx4 v1, v[148:151], s[10:11] offset:2048 sc1
	global_store_dwordx4 v1, v[152:155], s[10:11] offset:3072 sc1
	s_add_u32 s10, s10, 0x1000
	s_addc_u32 s11, s11, 0
	global_load_dwordx4 v[88:91], v1, s[8:9] offset:2048
	global_load_dwordx4 v[92:95], v1, s[8:9] offset:3072
	s_add_u32 s8, s8, 0x1000
	s_addc_u32 s9, s9, 0
	s_waitcnt vmcnt(22)
; __device__ __forceinline__ unsigned cvt_pk_bf16(float lo, float hi) { unsigned r; asm("v_cvt_pk_bf16_f32 %0, %1, %2" : "=v"(r) : "v"(lo), "v"(hi)); return r; }
; __device__ __forceinline__ void norm_pass_bf16(const Ctx& X, const bf16_t* xs, const bf16_t* cs, int nrows, const float* gain, const float* modl, int si, bf16_t* HN) {
;     ...
;         for (int j = 0; j < 2; ++j) {
;             v[j][0] = bf2f(q[j].x & 0xffffu); v[j][1] = bf2f(q[j].x >> 16); v[j][2] = bf2f(q[j].y & 0xffffu); v[j][3] = bf2f(q[j].y >> 16);
;             v[j][4] = bf2f(q[j].z & 0xffffu); v[j][5] = bf2f(q[j].z >> 16); v[j][6] = bf2f(q[j].w & 0xffffu); v[j][7] = bf2f(q[j].w >> 16);
; #pragma unroll
;             for (int e = 0; e < 8; ++e) s += v[j][e] * v[j][e]; }
;         const float rstd = rsqrtf(wave_sum(s) * (1.0f / 1024.0f) + 1e-6f);
; #pragma unroll
;         for (int j = 0; j < 2; ++j) { const int c = (X.lane + 64 * j) * 8; float o[8];
; #pragma unroll
;             for (int h = 0; h < 2; ++h) { const f32x4 gn = *(const f32x4*)(gain + c + 4 * h), a = *(const f32x4*)(scl + c + 4 * h), b = *(const f32x4*)(sh + c + 4 * h);
; #pragma unroll
;                 for (int e = 0; e < 4; ++e) o[4 * h + e] = v[j][4 * h + e] * rstd * gn[e] * (a[e] + 1.0f) + b[e]; }
;             u32x4 w; w.x = cvt_pk_bf16(o[0], o[1]); w.y = cvt_pk_bf16(o[2], o[3]); w.z = cvt_pk_bf16(o[4], o[5]); w.w = cvt_pk_bf16(o[6], o[7]); *(u32x4*)(HN + (size_t)r * D + c) = w; }
	v_lshlrev_b32_e32 v128, 16, v96
	v_and_b32_e32 v129, 0xffff0000, v96
	v_lshlrev_b32_e32 v130, 16, v97
	v_and_b32_e32 v131, 0xffff0000, v97
	v_lshlrev_b32_e32 v132, 16, v98
	v_and_b32_e32 v133, 0xffff0000, v98
	v_lshlrev_b32_e32 v134, 16, v99
	v_and_b32_e32 v135, 0xffff0000, v99
	v_lshlrev_b32_e32 v136, 16, v100
	v_and_b32_e32 v137, 0xffff0000, v100
	v_lshlrev_b32_e32 v138, 16, v101
	v_and_b32_e32 v139, 0xffff0000, v101
	v_lshlrev_b32_e32 v140, 16, v102
	v_and_b32_e32 v141, 0xffff0000, v102
	v_lshlrev_b32_e32 v142, 16, v103
	v_and_b32_e32 v143, 0xffff0000, v103
	v_pk_mul_f32 v[144:145], v[128:129], v[128:129]
	v_pk_fma_f32 v[144:145], v[130:131], v[130:131], v[144:145]
	v_pk_fma_f32 v[144:145], v[132:133], v[132:133], v[144:145]
	v_pk_fma_f32 v[144:145], v[134:135], v[134:135], v[144:145]
	v_pk_fma_f32 v[144:145], v[136:137], v[136:137], v[144:145]
	v_pk_fma_f32 v[144:145], v[138:139], v[138:139], v[144:145]
	v_pk_fma_f32 v[144:145], v[140:141], v[140:141], v[144:145]
	v_pk_fma_f32 v[144:145], v[142:143], v[142:143], v[144:145]
	v_add_f32_e32 v144, v144, v145
	s_nop 1
	v_add_f32_dpp v144, v144, v144 quad_perm:[1,0,3,2] row_mask:0xf bank_mask:0xf
	s_nop 1
	v_add_f32_dpp v144, v144, v144 quad_perm:[2,3,0,1] row_mask:0xf bank_mask:0xf
	s_nop 1
	v_add_f32_dpp v144, v144, v144 row_half_mirror row_mask:0xf bank_mask:0xf
	s_nop 1
	v_add_f32_dpp v144, v144, v144 row_mirror row_mask:0xf bank_mask:0xf
	s_nop 0
	v_mov_b32_e32 v145, v144
	s_nop 1
	v_permlane16_swap_b32_e32 v144, v145
	s_nop 0
	v_add_f32_e32 v144, v144, v145
	v_mov_b32_e32 v145, v144
	s_nop 1
	v_permlane32_swap_b32_e32 v144, v145
	s_nop 0
	v_add_f32_e32 v144, v144, v145
	v_fmamk_f32 v144, v144, 0x3a800000, v3
	v_rsq_f32_e32 v144, v144
	s_nop 0
	v_pk_mul_f32 v[128:129], v[128:129], v[144:145] op_sel_hi:[1,0]
	v_pk_mul_f32 v[130:131], v[130:131], v[144:145] op_sel_hi:[1,0]
	v_pk_mul_f32 v[132:133], v[132:133], v[144:145] op_sel_hi:[1,0]
	v_pk_mul_f32 v[134:135], v[134:135], v[144:145] op_sel_hi:[1,0]
	v_pk_mul_f32 v[136:137], v[136:137], v[144:145] op_sel_hi:[1,0]
	v_pk_mul_f32 v[138:139], v[138:139], v[144:145] op_sel_hi:[1,0]
	v_pk_mul_f32 v[140:141], v[140:141], v[144:145] op_sel_hi:[1,0]
	v_pk_mul_f32 v[142:143], v[142:143], v[144:145] op_sel_hi:[1,0]
	v_pk_mul_f32 v[128:129], v[16:17], v[128:129]
	v_pk_mul_f32 v[130:131], v[18:19], v[130:131]
	v_pk_mul_f32 v[132:133], v[20:21], v[132:133]
	v_pk_mul_f32 v[134:135], v[22:23], v[134:135]
	v_pk_mul_f32 v[136:137], v[24:25], v[136:137]
	v_pk_mul_f32 v[138:139], v[26:27], v[138:139]
	v_pk_mul_f32 v[140:141], v[28:29], v[140:141]
	v_pk_mul_f32 v[142:143], v[30:31], v[142:143]
	v_pk_fma_f32 v[128:129], v[32:33], v[128:129], v[48:49]
	v_pk_fma_f32 v[130:131], v[34:35], v[130:131], v[50:51]
	v_pk_fma_f32 v[132:133], v[36:37], v[132:133], v[52:53]
	v_pk_fma_f32 v[134:135], v[38:39], v[134:135], v[54:55]
	v_pk_fma_f32 v[136:137], v[40:41], v[136:137], v[56:57]
	v_pk_fma_f32 v[138:139], v[42:43], v[138:139], v[58:59]
	v_pk_fma_f32 v[140:141], v[44:45], v[140:141], v[60:61]
	v_pk_fma_f32 v[142:143], v[46:47], v[142:143], v[62:63]
	v_cvt_pk_bf16_f32 v148, v128, v129
	v_cvt_pk_bf16_f32 v149, v130, v131
	v_cvt_pk_bf16_f32 v150, v132, v133
	v_cvt_pk_bf16_f32 v151, v134, v135
	v_cvt_pk_bf16_f32 v152, v136, v137
	v_cvt_pk_bf16_f32 v153, v138, v139
	v_cvt_pk_bf16_f32 v154, v140, v141
	v_cvt_pk_bf16_f32 v155, v142, v143
	global_store_dwordx4 v1, v[148:151], s[10:11] sc1
	global_store_dwordx4 v1, v[152:155], s[10:11] offset:1024 sc1
	global_load_dwordx4 v[96:99], v1, s[8:9]
	global_load_dwordx4 v[100:103], v1, s[8:9] offset:1024
	s_waitcnt vmcnt(24)
	v_lshlrev_b32_e32 v128, 16, v104
	v_and_b32_e32 v129, 0xffff0000, v104
	v_lshlrev_b32_e32 v130, 16, v105
	v_and_b32_e32 v131, 0xffff0000, v105
	v_lshlrev_b32_e32 v132, 16, v106
	v_and_b32_e32 v133, 0xffff0000, v106
	v_lshlrev_b32_e32 v134, 16, v107
	v_and_b32_e32 v135, 0xffff0000, v107
	v_lshlrev_b32_e32 v136, 16, v108
	v_and_b32_e32 v137, 0xffff0000, v108
	v_lshlrev_b32_e32 v138, 16, v109
	v_and_b32_e32 v139, 0xffff0000, v109
	v_lshlrev_b32_e32 v140, 16, v110
	v_and_b32_e32 v141, 0xffff0000, v110
	v_lshlrev_b32_e32 v142, 16, v111
	v_and_b32_e32 v143, 0xffff0000, v111
	v_pk_mul_f32 v[144:145], v[128:129], v[128:129]
	v_pk_fma_f32 v[144:145], v[130:131], v[130:131], v[144:145]
	v_pk_fma_f32 v[144:145], v[132:133], v[132:133], v[144:145]
	v_pk_fma_f32 v[144:145], v[134:135], v[134:135], v[144:145]
	v_pk_fma_f32 v[144:145], v[136:137], v[136:137], v[144:145]
	v_pk_fma_f32 v[144:145], v[138:139], v[138:139], v[144:145]
	v_pk_fma_f32 v[144:145], v[140:141], v[140:141], v[144:145]
	v_pk_fma_f32 v[144:145], v[142:143], v[142:143], v[144:145]
	v_add_f32_e32 v144, v144, v145
	s_nop 1
	v_add_f32_dpp v144, v144, v144 quad_perm:[1,0,3,2] row_mask:0xf bank_mask:0xf
	s_nop 1
	v_add_f32_dpp v144, v144, v144 quad_perm:[2,3,0,1] row_mask:0xf bank_mask:0xf
	s_nop 1
	v_add_f32_dpp v144, v144, v144 row_half_mirror row_mask:0xf bank_mask:0xf
	s_nop 1
	v_add_f32_dpp v144, v144, v144 row_mirror row_mask:0xf bank_mask:0xf
	s_nop 0
	v_mov_b32_e32 v145, v144
	s_nop 1
	v_permlane16_swap_b32_e32 v144, v145
	s_nop 0
	v_add_f32_e32 v144, v144, v145
	v_mov_b32_e32 v145, v144
	s_nop 1
	v_permlane32_swap_b32_e32 v144, v145
	s_nop 0
	v_add_f32_e32 v144, v144, v145
	v_fmamk_f32 v144, v144, 0x3a800000, v3
	v_rsq_f32_e32 v144, v144
	s_nop 0
	v_pk_mul_f32 v[128:129], v[128:129], v[144:145] op_sel_hi:[1,0]
	v_pk_mul_f32 v[130:131], v[130:131], v[144:145] op_sel_hi:[1,0]
	v_pk_mul_f32 v[132:133], v[132:133], v[144:145] op_sel_hi:[1,0]
	v_pk_mul_f32 v[134:135], v[134:135], v[144:145] op_sel_hi:[1,0]
	v_pk_mul_f32 v[136:137], v[136:137], v[144:145] op_sel_hi:[1,0]
; __device__ __forceinline__ unsigned cvt_pk_bf16(float lo, float hi) { unsigned r; asm("v_cvt_pk_bf16_f32 %0, %1, %2" : "=v"(r) : "v"(lo), "v"(hi)); return r; }
; __device__ __forceinline__ void norm_pass_bf16(const Ctx& X, const bf16_t* xs, const bf16_t* cs, int nrows, const float* gain, const float* modl, int si, bf16_t* HN) {
;     ...
;         for (int j = 0; j < 2; ++j) {
;             v[j][0] = bf2f(q[j].x & 0xffffu); v[j][1] = bf2f(q[j].x >> 16); v[j][2] = bf2f(q[j].y & 0xffffu); v[j][3] = bf2f(q[j].y >> 16);
;             v[j][4] = bf2f(q[j].z & 0xffffu); v[j][5] = bf2f(q[j].z >> 16); v[j][6] = bf2f(q[j].w & 0xffffu); v[j][7] = bf2f(q[j].w >> 16);
; #pragma unroll
;             for (int e = 0; e < 8; ++e) s += v[j][e] * v[j][e]; }
;         const float rstd = rsqrtf(wave_sum(s) * (1.0f / 1024.0f) + 1e-6f);
; #pragma unroll
;         for (int j = 0; j < 2; ++j) { const int c = (X.lane + 64 * j) * 8; float o[8];
; #pragma unroll
;             for (int h = 0; h < 2; ++h) { const f32x4 gn = *(const f32x4*)(gain + c + 4 * h), a = *(const f32x4*)(scl + c + 4 * h), b = *(const f32x4*)(sh + c + 4 * h);
; #pragma unroll
;                 for (int e = 0; e < 4; ++e) o[4 * h + e] = v[j][4 * h + e] * rstd * gn[e] * (a[e] + 1.0f) + b[e]; }
;             u32x4 w; w.x = cvt_pk_bf16(o[0], o[1]); w.y = cvt_pk_bf16(o[2], o[3]); w.z = cvt_pk_bf16(o[4], o[5]); w.w = cvt_pk_bf16(o[6], o[7]); *(u32x4*)(HN + (size_t)r * D + c) = w; }
	v_pk_mul_f32 v[138:139], v[138:139], v[144:145] op_sel_hi:[1,0]
	v_pk_mul_f32 v[140:141], v[140:141], v[144:145] op_sel_hi:[1,0]
	v_pk_mul_f32 v[142:143], v[142:143], v[144:145] op_sel_hi:[1,0]
	v_pk_mul_f32 v[128:129], v[16:17], v[128:129]
	v_pk_mul_f32 v[130:131], v[18:19], v[130:131]
	v_pk_mul_f32 v[132:133], v[20:21], v[132:133]
	v_pk_mul_f32 v[134:135], v[22:23], v[134:135]
	v_pk_mul_f32 v[136:137], v[24:25], v[136:137]
	v_pk_mul_f32 v[138:139], v[26:27], v[138:139]
	v_pk_mul_f32 v[140:141], v[28:29], v[140:141]
	v_pk_mul_f32 v[142:143], v[30:31], v[142:143]
	v_pk_fma_f32 v[128:129], v[32:33], v[128:129], v[48:49]
	v_pk_fma_f32 v[130:131], v[34:35], v[130:131], v[50:51]
	v_pk_fma_f32 v[132:133], v[36:37], v[132:133], v[52:53]
	v_pk_fma_f32 v[134:135], v[38:39], v[134:135], v[54:55]
	v_pk_fma_f32 v[136:137], v[40:41], v[136:137], v[56:57]
	v_pk_fma_f32 v[138:139], v[42:43], v[138:139], v[58:59]
	v_pk_fma_f32 v[140:141], v[44:45], v[140:141], v[60:61]
	v_pk_fma_f32 v[142:143], v[46:47], v[142:143], v[62:63]
	v_cvt_pk_bf16_f32 v148, v128, v129
	v_cvt_pk_bf16_f32 v149, v130, v131
	v_cvt_pk_bf16_f32 v150, v132, v133
	v_cvt_pk_bf16_f32 v151, v134, v135
	v_cvt_pk_bf16_f32 v152, v136, v137
	v_cvt_pk_bf16_f32 v153, v138, v139
	v_cvt_pk_bf16_f32 v154, v140, v141
	v_cvt_pk_bf16_f32 v155, v142, v143
	global_store_dwordx4 v1, v[148:151], s[10:11] offset:2048 sc1
	global_store_dwordx4 v1, v[152:155], s[10:11] offset:3072 sc1
	s_add_u32 s10, s10, 0x1000
	s_addc_u32 s11, s11, 0
	global_load_dwordx4 v[104:107], v1, s[8:9] offset:2048
	global_load_dwordx4 v[108:111], v1, s[8:9] offset:3072
	s_add_u32 s8, s8, 0x1000
	s_addc_u32 s9, s9, 0
	s_waitcnt vmcnt(26)
	v_lshlrev_b32_e32 v128, 16, v112
	v_and_b32_e32 v129, 0xffff0000, v112
	v_lshlrev_b32_e32 v130, 16, v113
	v_and_b32_e32 v131, 0xffff0000, v113
	v_lshlrev_b32_e32 v132, 16, v114
	v_and_b32_e32 v133, 0xffff0000, v114
	v_lshlrev_b32_e32 v134, 16, v115
	v_and_b32_e32 v135, 0xffff0000, v115
	v_lshlrev_b32_e32 v136, 16, v116
	v_and_b32_e32 v137, 0xffff0000, v116
	v_lshlrev_b32_e32 v138, 16, v117
	v_and_b32_e32 v139, 0xffff0000, v117
	v_lshlrev_b32_e32 v140, 16, v118
	v_and_b32_e32 v141, 0xffff0000, v118
	v_lshlrev_b32_e32 v142, 16, v119
	v_and_b32_e32 v143, 0xffff0000, v119
	v_pk_mul_f32 v[144:145], v[128:129], v[128:129]
	v_pk_fma_f32 v[144:145], v[130:131], v[130:131], v[144:145]
	v_pk_fma_f32 v[144:145], v[132:133], v[132:133], v[144:145]
	v_pk_fma_f32 v[144:145], v[134:135], v[134:135], v[144:145]
	v_pk_fma_f32 v[144:145], v[136:137], v[136:137], v[144:145]
	v_pk_fma_f32 v[144:145], v[138:139], v[138:139], v[144:145]
	v_pk_fma_f32 v[144:145], v[140:141], v[140:141], v[144:145]
	v_pk_fma_f32 v[144:145], v[142:143], v[142:143], v[144:145]
	v_add_f32_e32 v144, v144, v145
	s_nop 1
	v_add_f32_dpp v144, v144, v144 quad_perm:[1,0,3,2] row_mask:0xf bank_mask:0xf
	s_nop 1
	v_add_f32_dpp v144, v144, v144 quad_perm:[2,3,0,1] row_mask:0xf bank_mask:0xf
	s_nop 1
	v_add_f32_dpp v144, v144, v144 row_half_mirror row_mask:0xf bank_mask:0xf
	s_nop 1
	v_add_f32_dpp v144, v144, v144 row_mirror row_mask:0xf bank_mask:0xf
	s_nop 0
	v_mov_b32_e32 v145, v144
	s_nop 1
	v_permlane16_swap_b32_e32 v144, v145
	s_nop 0
	v_add_f32_e32 v144, v144, v145
	v_mov_b32_e32 v145, v144
	s_nop 1
	v_permlane32_swap_b32_e32 v144, v145
	s_nop 0
	v_add_f32_e32 v144, v144, v145
	v_fmamk_f32 v144, v144, 0x3a800000, v3
	v_rsq_f32_e32 v144, v144
	s_nop 0
	v_pk_mul_f32 v[128:129], v[128:129], v[144:145] op_sel_hi:[1,0]
	v_pk_mul_f32 v[130:131], v[130:131], v[144:145] op_sel_hi:[1,0]
	v_pk_mul_f32 v[132:133], v[132:133], v[144:145] op_sel_hi:[1,0]
	v_pk_mul_f32 v[134:135], v[134:135], v[144:145] op_sel_hi:[1,0]
	v_pk_mul_f32 v[136:137], v[136:137], v[144:145] op_sel_hi:[1,0]
	v_pk_mul_f32 v[138:139], v[138:139], v[144:145] op_sel_hi:[1,0]
	v_pk_mul_f32 v[140:141], v[140:141], v[144:145] op_sel_hi:[1,0]
	v_pk_mul_f32 v[142:143], v[142:143], v[144:145] op_sel_hi:[1,0]
	v_pk_mul_f32 v[128:129], v[16:17], v[128:129]
	v_pk_mul_f32 v[130:131], v[18:19], v[130:131]
	v_pk_mul_f32 v[132:133], v[20:21], v[132:133]
	v_pk_mul_f32 v[134:135], v[22:23], v[134:135]
	v_pk_mul_f32 v[136:137], v[24:25], v[136:137]
	v_pk_mul_f32 v[138:139], v[26:27], v[138:139]
	v_pk_mul_f32 v[140:141], v[28:29], v[140:141]
	v_pk_mul_f32 v[142:143], v[30:31], v[142:143]
	v_pk_fma_f32 v[128:129], v[32:33], v[128:129], v[48:49]
	v_pk_fma_f32 v[130:131], v[34:35], v[130:131], v[50:51]
	v_pk_fma_f32 v[132:133], v[36:37], v[132:133], v[52:53]
	v_pk_fma_f32 v[134:135], v[38:39], v[134:135], v[54:55]
	v_pk_fma_f32 v[136:137], v[40:41], v[136:137], v[56:57]
	v_pk_fma_f32 v[138:139], v[42:43], v[138:139], v[58:59]
	v_pk_fma_f32 v[140:141], v[44:45], v[140:141], v[60:61]
	v_pk_fma_f32 v[142:143], v[46:47], v[142:143], v[62:63]
	v_cvt_pk_bf16_f32 v148, v128, v129
	v_cvt_pk_bf16_f32 v149, v130, v131
	v_cvt_pk_bf16_f32 v150, v132, v133
	v_cvt_pk_bf16_f32 v151, v134, v135
	v_cvt_pk_bf16_f32 v152, v136, v137
	v_cvt_pk_bf16_f32 v153, v138, v139
	v_cvt_pk_bf16_f32 v154, v140, v141
	v_cvt_pk_bf16_f32 v155, v142, v143
	global_store_dwordx4 v1, v[148:151], s[10:11] sc1
	global_store_dwordx4 v1, v[152:155], s[10:11] offset:1024 sc1
	global_load_dwordx4 v[112:115], v1, s[8:9]
	global_load_dwordx4 v[116:119], v1, s[8:9] offset:1024
	s_waitcnt vmcnt(28)
; __device__ __forceinline__ unsigned cvt_pk_bf16(float lo, float hi) { unsigned r; asm("v_cvt_pk_bf16_f32 %0, %1, %2" : "=v"(r) : "v"(lo), "v"(hi)); return r; }
; __device__ __forceinline__ void norm_pass_bf16(const Ctx& X, const bf16_t* xs, const bf16_t* cs, int nrows, const float* gain, const float* modl, int si, bf16_t* HN) {
;     ...
;         for (int j = 0; j < 2; ++j) {
;             v[j][0] = bf2f(q[j].x & 0xffffu); v[j][1] = bf2f(q[j].x >> 16); v[j][2] = bf2f(q[j].y & 0xffffu); v[j][3] = bf2f(q[j].y >> 16);
;             v[j][4] = bf2f(q[j].z & 0xffffu); v[j][5] = bf2f(q[j].z >> 16); v[j][6] = bf2f(q[j].w & 0xffffu); v[j][7] = bf2f(q[j].w >> 16);
; #pragma unroll
;             for (int e = 0; e < 8; ++e) s += v[j][e] * v[j][e]; }
;         const float rstd = rsqrtf(wave_sum(s) * (1.0f / 1024.0f) + 1e-6f);
; #pragma unroll
;         for (int j = 0; j < 2; ++j) { const int c = (X.lane + 64 * j) * 8; float o[8];
; #pragma unroll
;             for (int h = 0; h < 2; ++h) { const f32x4 gn = *(const f32x4*)(gain + c + 4 * h), a = *(const f32x4*)(scl + c + 4 * h), b = *(const f32x4*)(sh + c + 4 * h);
; #pragma unroll
;                 for (int e = 0; e < 4; ++e) o[4 * h + e] = v[j][4 * h + e] * rstd * gn[e] * (a[e] + 1.0f) + b[e]; }
;             u32x4 w; w.x = cvt_pk_bf16(o[0], o[1]); w.y = cvt_pk_bf16(o[2], o[3]); w.z = cvt_pk_bf16(o[4], o[5]); w.w = cvt_pk_bf16(o[6], o[7]); *(u32x4*)(HN + (size_t)r * D + c) = w; }
	v_lshlrev_b32_e32 v128, 16, v120
	v_and_b32_e32 v129, 0xffff0000, v120
	v_lshlrev_b32_e32 v130, 16, v121
	v_and_b32_e32 v131, 0xffff0000, v121
	v_lshlrev_b32_e32 v132, 16, v122
	v_and_b32_e32 v133, 0xffff0000, v122
	v_lshlrev_b32_e32 v134, 16, v123
	v_and_b32_e32 v135, 0xffff0000, v123
	v_lshlrev_b32_e32 v136, 16, v124
	v_and_b32_e32 v137, 0xffff0000, v124
	v_lshlrev_b32_e32 v138, 16, v125
	v_and_b32_e32 v139, 0xffff0000, v125
	v_lshlrev_b32_e32 v140, 16, v126
	v_and_b32_e32 v141, 0xffff0000, v126
	v_lshlrev_b32_e32 v142, 16, v127
	v_and_b32_e32 v143, 0xffff0000, v127
	v_pk_mul_f32 v[144:145], v[128:129], v[128:129]
	v_pk_fma_f32 v[144:145], v[130:131], v[130:131], v[144:145]
	v_pk_fma_f32 v[144:145], v[132:133], v[132:133], v[144:145]
	v_pk_fma_f32 v[144:145], v[134:135], v[134:135], v[144:145]
	v_pk_fma_f32 v[144:145], v[136:137], v[136:137], v[144:145]
	v_pk_fma_f32 v[144:145], v[138:139], v[138:139], v[144:145]
	v_pk_fma_f32 v[144:145], v[140:141], v[140:141], v[144:145]
	v_pk_fma_f32 v[144:145], v[142:143], v[142:143], v[144:145]
	v_add_f32_e32 v144, v144, v145
	s_nop 1
	v_add_f32_dpp v144, v144, v144 quad_perm:[1,0,3,2] row_mask:0xf bank_mask:0xf
	s_nop 1
	v_add_f32_dpp v144, v144, v144 quad_perm:[2,3,0,1] row_mask:0xf bank_mask:0xf
	s_nop 1
	v_add_f32_dpp v144, v144, v144 row_half_mirror row_mask:0xf bank_mask:0xf
	s_nop 1
	v_add_f32_dpp v144, v144, v144 row_mirror row_mask:0xf bank_mask:0xf
	s_nop 0
	v_mov_b32_e32 v145, v144
	s_nop 1
	v_permlane16_swap_b32_e32 v144, v145
	s_nop 0
	v_add_f32_e32 v144, v144, v145
	v_mov_b32_e32 v145, v144
	s_nop 1
	v_permlane32_swap_b32_e32 v144, v145
	s_nop 0
	v_add_f32_e32 v144, v144, v145
	v_fmamk_f32 v144, v144, 0x3a800000, v3
	v_rsq_f32_e32 v144, v144
	s_nop 0
	v_pk_mul_f32 v[128:129], v[128:129], v[144:145] op_sel_hi:[1,0]
	v_pk_mul_f32 v[130:131], v[130:131], v[144:145] op_sel_hi:[1,0]
	v_pk_mul_f32 v[132:133], v[132:133], v[144:145] op_sel_hi:[1,0]
	v_pk_mul_f32 v[134:135], v[134:135], v[144:145] op_sel_hi:[1,0]
	v_pk_mul_f32 v[136:137], v[136:137], v[144:145] op_sel_hi:[1,0]
	v_pk_mul_f32 v[138:139], v[138:139], v[144:145] op_sel_hi:[1,0]
	v_pk_mul_f32 v[140:141], v[140:141], v[144:145] op_sel_hi:[1,0]
	v_pk_mul_f32 v[142:143], v[142:143], v[144:145] op_sel_hi:[1,0]
	v_pk_mul_f32 v[128:129], v[16:17], v[128:129]
	v_pk_mul_f32 v[130:131], v[18:19], v[130:131]
	v_pk_mul_f32 v[132:133], v[20:21], v[132:133]
	v_pk_mul_f32 v[134:135], v[22:23], v[134:135]
	v_pk_mul_f32 v[136:137], v[24:25], v[136:137]
	v_pk_mul_f32 v[138:139], v[26:27], v[138:139]
	v_pk_mul_f32 v[140:141], v[28:29], v[140:141]
	v_pk_mul_f32 v[142:143], v[30:31], v[142:143]
	v_pk_fma_f32 v[128:129], v[32:33], v[128:129], v[48:49]
	v_pk_fma_f32 v[130:131], v[34:35], v[130:131], v[50:51]
	v_pk_fma_f32 v[132:133], v[36:37], v[132:133], v[52:53]
	v_pk_fma_f32 v[134:135], v[38:39], v[134:135], v[54:55]
	v_pk_fma_f32 v[136:137], v[40:41], v[136:137], v[56:57]
	v_pk_fma_f32 v[138:139], v[42:43], v[138:139], v[58:59]
	v_pk_fma_f32 v[140:141], v[44:45], v[140:141], v[60:61]
	v_pk_fma_f32 v[142:143], v[46:47], v[142:143], v[62:63]
	v_cvt_pk_bf16_f32 v148, v128, v129
	v_cvt_pk_bf16_f32 v149, v130, v131
	v_cvt_pk_bf16_f32 v150, v132, v133
	v_cvt_pk_bf16_f32 v151, v134, v135
	v_cvt_pk_bf16_f32 v152, v136, v137
	v_cvt_pk_bf16_f32 v153, v138, v139
	v_cvt_pk_bf16_f32 v154, v140, v141
	v_cvt_pk_bf16_f32 v155, v142, v143
	global_store_dwordx4 v1, v[148:151], s[10:11] offset:2048 sc1
	global_store_dwordx4 v1, v[152:155], s[10:11] offset:3072 sc1
	s_add_u32 s10, s10, 0x1000
	s_addc_u32 s11, s11, 0
	global_load_dwordx4 v[120:123], v1, s[8:9] offset:2048
	global_load_dwordx4 v[124:127], v1, s[8:9] offset:3072
	s_add_u32 s8, s8, 0x1000
	s_addc_u32 s9, s9, 0
	s_waitcnt vmcnt(28)
	v_lshlrev_b32_e32 v128, 16, v64
	v_and_b32_e32 v129, 0xffff0000, v64
	v_lshlrev_b32_e32 v130, 16, v65
	v_and_b32_e32 v131, 0xffff0000, v65
	v_lshlrev_b32_e32 v132, 16, v66
	v_and_b32_e32 v133, 0xffff0000, v66
	v_lshlrev_b32_e32 v134, 16, v67
	v_and_b32_e32 v135, 0xffff0000, v67
	v_lshlrev_b32_e32 v136, 16, v68
	v_and_b32_e32 v137, 0xffff0000, v68
	v_lshlrev_b32_e32 v138, 16, v69
	v_and_b32_e32 v139, 0xffff0000, v69
	v_lshlrev_b32_e32 v140, 16, v70
	v_and_b32_e32 v141, 0xffff0000, v70
	v_lshlrev_b32_e32 v142, 16, v71
	v_and_b32_e32 v143, 0xffff0000, v71
	v_pk_mul_f32 v[144:145], v[128:129], v[128:129]
	v_pk_fma_f32 v[144:145], v[130:131], v[130:131], v[144:145]
	v_pk_fma_f32 v[144:145], v[132:133], v[132:133], v[144:145]
	v_pk_fma_f32 v[144:145], v[134:135], v[134:135], v[144:145]
	v_pk_fma_f32 v[144:145], v[136:137], v[136:137], v[144:145]
	v_pk_fma_f32 v[144:145], v[138:139], v[138:139], v[144:145]
	v_pk_fma_f32 v[144:145], v[140:141], v[140:141], v[144:145]
	v_pk_fma_f32 v[144:145], v[142:143], v[142:143], v[144:145]
	v_add_f32_e32 v144, v144, v145
	s_nop 1
	v_add_f32_dpp v144, v144, v144 quad_perm:[1,0,3,2] row_mask:0xf bank_mask:0xf
	s_nop 1
	v_add_f32_dpp v144, v144, v144 quad_perm:[2,3,0,1] row_mask:0xf bank_mask:0xf
	s_nop 1
	v_add_f32_dpp v144, v144, v144 row_half_mirror row_mask:0xf bank_mask:0xf
	s_nop 1
	v_add_f32_dpp v144, v144, v144 row_mirror row_mask:0xf bank_mask:0xf
	s_nop 0
	v_mov_b32_e32 v145, v144
	s_nop 1
	v_permlane16_swap_b32_e32 v144, v145
	s_nop 0
	v_add_f32_e32 v144, v144, v145
	v_mov_b32_e32 v145, v144
	s_nop 1
	v_permlane32_swap_b32_e32 v144, v145
	s_nop 0
	v_add_f32_e32 v144, v144, v145
	v_fmamk_f32 v144, v144, 0x3a800000, v3
	v_rsq_f32_e32 v144, v144
	s_nop 0
	v_pk_mul_f32 v[128:129], v[128:129], v[144:145] op_sel_hi:[1,0]
	v_pk_mul_f32 v[130:131], v[130:131], v[144:145] op_sel_hi:[1,0]
	v_pk_mul_f32 v[132:133], v[132:133], v[144:145] op_sel_hi:[1,0]
; __device__ __forceinline__ unsigned cvt_pk_bf16(float lo, float hi) { unsigned r; asm("v_cvt_pk_bf16_f32 %0, %1, %2" : "=v"(r) : "v"(lo), "v"(hi)); return r; }
; __device__ __forceinline__ void norm_pass_bf16(const Ctx& X, const bf16_t* xs, const bf16_t* cs, int nrows, const float* gain, const float* modl, int si, bf16_t* HN) {
;     ...
;         for (int j = 0; j < 2; ++j) {
;             v[j][0] = bf2f(q[j].x & 0xffffu); v[j][1] = bf2f(q[j].x >> 16); v[j][2] = bf2f(q[j].y & 0xffffu); v[j][3] = bf2f(q[j].y >> 16);
;             v[j][4] = bf2f(q[j].z & 0xffffu); v[j][5] = bf2f(q[j].z >> 16); v[j][6] = bf2f(q[j].w & 0xffffu); v[j][7] = bf2f(q[j].w >> 16);
; #pragma unroll
;             for (int e = 0; e < 8; ++e) s += v[j][e] * v[j][e]; }
;         const float rstd = rsqrtf(wave_sum(s) * (1.0f / 1024.0f) + 1e-6f);
; #pragma unroll
;         for (int j = 0; j < 2; ++j) { const int c = (X.lane + 64 * j) * 8; float o[8];
; #pragma unroll
;             for (int h = 0; h < 2; ++h) { const f32x4 gn = *(const f32x4*)(gain + c + 4 * h), a = *(const f32x4*)(scl + c + 4 * h), b = *(const f32x4*)(sh + c + 4 * h);
; #pragma unroll
;                 for (int e = 0; e < 4; ++e) o[4 * h + e] = v[j][4 * h + e] * rstd * gn[e] * (a[e] + 1.0f) + b[e]; }
;             u32x4 w; w.x = cvt_pk_bf16(o[0], o[1]); w.y = cvt_pk_bf16(o[2], o[3]); w.z = cvt_pk_bf16(o[4], o[5]); w.w = cvt_pk_bf16(o[6], o[7]); *(u32x4*)(HN + (size_t)r * D + c) = w; }
	v_pk_mul_f32 v[134:135], v[134:135], v[144:145] op_sel_hi:[1,0]
	v_pk_mul_f32 v[136:137], v[136:137], v[144:145] op_sel_hi:[1,0]
	v_pk_mul_f32 v[138:139], v[138:139], v[144:145] op_sel_hi:[1,0]
	v_pk_mul_f32 v[140:141], v[140:141], v[144:145] op_sel_hi:[1,0]
	v_pk_mul_f32 v[142:143], v[142:143], v[144:145] op_sel_hi:[1,0]
	v_pk_mul_f32 v[128:129], v[16:17], v[128:129]
	v_pk_mul_f32 v[130:131], v[18:19], v[130:131]
	v_pk_mul_f32 v[132:133], v[20:21], v[132:133]
	v_pk_mul_f32 v[134:135], v[22:23], v[134:135]
	v_pk_mul_f32 v[136:137], v[24:25], v[136:137]
	v_pk_mul_f32 v[138:139], v[26:27], v[138:139]
	v_pk_mul_f32 v[140:141], v[28:29], v[140:141]
	v_pk_mul_f32 v[142:143], v[30:31], v[142:143]
	v_pk_fma_f32 v[128:129], v[32:33], v[128:129], v[48:49]
	v_pk_fma_f32 v[130:131], v[34:35], v[130:131], v[50:51]
	v_pk_fma_f32 v[132:133], v[36:37], v[132:133], v[52:53]
	v_pk_fma_f32 v[134:135], v[38:39], v[134:135], v[54:55]
	v_pk_fma_f32 v[136:137], v[40:41], v[136:137], v[56:57]
	v_pk_fma_f32 v[138:139], v[42:43], v[138:139], v[58:59]
	v_pk_fma_f32 v[140:141], v[44:45], v[140:141], v[60:61]
	v_pk_fma_f32 v[142:143], v[46:47], v[142:143], v[62:63]
	v_cvt_pk_bf16_f32 v148, v128, v129
	v_cvt_pk_bf16_f32 v149, v130, v131
	v_cvt_pk_bf16_f32 v150, v132, v133
	v_cvt_pk_bf16_f32 v151, v134, v135
	v_cvt_pk_bf16_f32 v152, v136, v137
	v_cvt_pk_bf16_f32 v153, v138, v139
	v_cvt_pk_bf16_f32 v154, v140, v141
	v_cvt_pk_bf16_f32 v155, v142, v143
	global_store_dwordx4 v1, v[148:151], s[10:11] sc1
	global_store_dwordx4 v1, v[152:155], s[10:11] offset:1024 sc1
	s_waitcnt vmcnt(26)
	v_lshlrev_b32_e32 v128, 16, v72
	v_and_b32_e32 v129, 0xffff0000, v72
	v_lshlrev_b32_e32 v130, 16, v73
	v_and_b32_e32 v131, 0xffff0000, v73
	v_lshlrev_b32_e32 v132, 16, v74
	v_and_b32_e32 v133, 0xffff0000, v74
	v_lshlrev_b32_e32 v134, 16, v75
	v_and_b32_e32 v135, 0xffff0000, v75
	v_lshlrev_b32_e32 v136, 16, v76
	v_and_b32_e32 v137, 0xffff0000, v76
	v_lshlrev_b32_e32 v138, 16, v77
	v_and_b32_e32 v139, 0xffff0000, v77
	v_lshlrev_b32_e32 v140, 16, v78
	v_and_b32_e32 v141, 0xffff0000, v78
	v_lshlrev_b32_e32 v142, 16, v79
	v_and_b32_e32 v143, 0xffff0000, v79
	v_pk_mul_f32 v[144:145], v[128:129], v[128:129]
	v_pk_fma_f32 v[144:145], v[130:131], v[130:131], v[144:145]
	v_pk_fma_f32 v[144:145], v[132:133], v[132:133], v[144:145]
	v_pk_fma_f32 v[144:145], v[134:135], v[134:135], v[144:145]
	v_pk_fma_f32 v[144:145], v[136:137], v[136:137], v[144:145]
	v_pk_fma_f32 v[144:145], v[138:139], v[138:139], v[144:145]
	v_pk_fma_f32 v[144:145], v[140:141], v[140:141], v[144:145]
	v_pk_fma_f32 v[144:145], v[142:143], v[142:143], v[144:145]
	v_add_f32_e32 v144, v144, v145
	s_nop 1
	v_add_f32_dpp v144, v144, v144 quad_perm:[1,0,3,2] row_mask:0xf bank_mask:0xf
	s_nop 1
	v_add_f32_dpp v144, v144, v144 quad_perm:[2,3,0,1] row_mask:0xf bank_mask:0xf
	s_nop 1
	v_add_f32_dpp v144, v144, v144 row_half_mirror row_mask:0xf bank_mask:0xf
	s_nop 1
	v_add_f32_dpp v144, v144, v144 row_mirror row_mask:0xf bank_mask:0xf
	s_nop 0
	v_mov_b32_e32 v145, v144
	s_nop 1
	v_permlane16_swap_b32_e32 v144, v145
	s_nop 0
	v_add_f32_e32 v144, v144, v145
	v_mov_b32_e32 v145, v144
	s_nop 1
	v_permlane32_swap_b32_e32 v144, v145
	s_nop 0
	v_add_f32_e32 v144, v144, v145
	v_fmamk_f32 v144, v144, 0x3a800000, v3
	v_rsq_f32_e32 v144, v144
	s_nop 0
	v_pk_mul_f32 v[128:129], v[128:129], v[144:145] op_sel_hi:[1,0]
	v_pk_mul_f32 v[130:131], v[130:131], v[144:145] op_sel_hi:[1,0]
	v_pk_mul_f32 v[132:133], v[132:133], v[144:145] op_sel_hi:[1,0]
	v_pk_mul_f32 v[134:135], v[134:135], v[144:145] op_sel_hi:[1,0]
	v_pk_mul_f32 v[136:137], v[136:137], v[144:145] op_sel_hi:[1,0]
	v_pk_mul_f32 v[138:139], v[138:139], v[144:145] op_sel_hi:[1,0]
	v_pk_mul_f32 v[140:141], v[140:141], v[144:145] op_sel_hi:[1,0]
	v_pk_mul_f32 v[142:143], v[142:143], v[144:145] op_sel_hi:[1,0]
	v_pk_mul_f32 v[128:129], v[16:17], v[128:129]
	v_pk_mul_f32 v[130:131], v[18:19], v[130:131]
	v_pk_mul_f32 v[132:133], v[20:21], v[132:133]
	v_pk_mul_f32 v[134:135], v[22:23], v[134:135]
	v_pk_mul_f32 v[136:137], v[24:25], v[136:137]
	v_pk_mul_f32 v[138:139], v[26:27], v[138:139]
	v_pk_mul_f32 v[140:141], v[28:29], v[140:141]
	v_pk_mul_f32 v[142:143], v[30:31], v[142:143]
	v_pk_fma_f32 v[128:129], v[32:33], v[128:129], v[48:49]
	v_pk_fma_f32 v[130:131], v[34:35], v[130:131], v[50:51]
	v_pk_fma_f32 v[132:133], v[36:37], v[132:133], v[52:53]
	v_pk_fma_f32 v[134:135], v[38:39], v[134:135], v[54:55]
	v_pk_fma_f32 v[136:137], v[40:41], v[136:137], v[56:57]
	v_pk_fma_f32 v[138:139], v[42:43], v[138:139], v[58:59]
	v_pk_fma_f32 v[140:141], v[44:45], v[140:141], v[60:61]
	v_pk_fma_f32 v[142:143], v[46:47], v[142:143], v[62:63]
	v_cvt_pk_bf16_f32 v148, v128, v129
	v_cvt_pk_bf16_f32 v149, v130, v131
	v_cvt_pk_bf16_f32 v150, v132, v133
	v_cvt_pk_bf16_f32 v151, v134, v135
	v_cvt_pk_bf16_f32 v152, v136, v137
	v_cvt_pk_bf16_f32 v153, v138, v139
	v_cvt_pk_bf16_f32 v154, v140, v141
	v_cvt_pk_bf16_f32 v155, v142, v143
	global_store_dwordx4 v1, v[148:151], s[10:11] offset:2048 sc1
	global_store_dwordx4 v1, v[152:155], s[10:11] offset:3072 sc1
	s_add_u32 s10, s10, 0x1000
	s_addc_u32 s11, s11, 0
	s_waitcnt vmcnt(24)
; __device__ __forceinline__ unsigned cvt_pk_bf16(float lo, float hi) { unsigned r; asm("v_cvt_pk_bf16_f32 %0, %1, %2" : "=v"(r) : "v"(lo), "v"(hi)); return r; }
; __device__ __forceinline__ void norm_pass_bf16(const Ctx& X, const bf16_t* xs, const bf16_t* cs, int nrows, const float* gain, const float* modl, int si, bf16_t* HN) {
;     ...
;         for (int j = 0; j < 2; ++j) {
;             v[j][0] = bf2f(q[j].x & 0xffffu); v[j][1] = bf2f(q[j].x >> 16); v[j][2] = bf2f(q[j].y & 0xffffu); v[j][3] = bf2f(q[j].y >> 16);
;             v[j][4] = bf2f(q[j].z & 0xffffu); v[j][5] = bf2f(q[j].z >> 16); v[j][6] = bf2f(q[j].w & 0xffffu); v[j][7] = bf2f(q[j].w >> 16);
; #pragma unroll
;             for (int e = 0; e < 8; ++e) s += v[j][e] * v[j][e]; }
;         const float rstd = rsqrtf(wave_sum(s) * (1.0f / 1024.0f) + 1e-6f);
; #pragma unroll
;         for (int j = 0; j < 2; ++j) { const int c = (X.lane + 64 * j) * 8; float o[8];
; #pragma unroll
;             for (int h = 0; h < 2; ++h) { const f32x4 gn = *(const f32x4*)(gain + c + 4 * h), a = *(const f32x4*)(scl + c + 4 * h), b = *(const f32x4*)(sh + c + 4 * h);
; #pragma unroll
;                 for (int e = 0; e < 4; ++e) o[4 * h + e] = v[j][4 * h + e] * rstd * gn[e] * (a[e] + 1.0f) + b[e]; }
;             u32x4 w; w.x = cvt_pk_bf16(o[0], o[1]); w.y = cvt_pk_bf16(o[2], o[3]); w.z = cvt_pk_bf16(o[4], o[5]); w.w = cvt_pk_bf16(o[6], o[7]); *(u32x4*)(HN + (size_t)r * D + c) = w; }
	v_lshlrev_b32_e32 v128, 16, v80
	v_and_b32_e32 v129, 0xffff0000, v80
	v_lshlrev_b32_e32 v130, 16, v81
	v_and_b32_e32 v131, 0xffff0000, v81
	v_lshlrev_b32_e32 v132, 16, v82
	v_and_b32_e32 v133, 0xffff0000, v82
	v_lshlrev_b32_e32 v134, 16, v83
	v_and_b32_e32 v135, 0xffff0000, v83
	v_lshlrev_b32_e32 v136, 16, v84
	v_and_b32_e32 v137, 0xffff0000, v84
	v_lshlrev_b32_e32 v138, 16, v85
	v_and_b32_e32 v139, 0xffff0000, v85
	v_lshlrev_b32_e32 v140, 16, v86
	v_and_b32_e32 v141, 0xffff0000, v86
	v_lshlrev_b32_e32 v142, 16, v87
	v_and_b32_e32 v143, 0xffff0000, v87
	v_pk_mul_f32 v[144:145], v[128:129], v[128:129]
	v_pk_fma_f32 v[144:145], v[130:131], v[130:131], v[144:145]
	v_pk_fma_f32 v[144:145], v[132:133], v[132:133], v[144:145]
	v_pk_fma_f32 v[144:145], v[134:135], v[134:135], v[144:145]
	v_pk_fma_f32 v[144:145], v[136:137], v[136:137], v[144:145]
	v_pk_fma_f32 v[144:145], v[138:139], v[138:139], v[144:145]
	v_pk_fma_f32 v[144:145], v[140:141], v[140:141], v[144:145]
	v_pk_fma_f32 v[144:145], v[142:143], v[142:143], v[144:145]
	v_add_f32_e32 v144, v144, v145
	s_nop 1
	v_add_f32_dpp v144, v144, v144 quad_perm:[1,0,3,2] row_mask:0xf bank_mask:0xf
	s_nop 1
	v_add_f32_dpp v144, v144, v144 quad_perm:[2,3,0,1] row_mask:0xf bank_mask:0xf
	s_nop 1
	v_add_f32_dpp v144, v144, v144 row_half_mirror row_mask:0xf bank_mask:0xf
	s_nop 1
	v_add_f32_dpp v144, v144, v144 row_mirror row_mask:0xf bank_mask:0xf
	s_nop 0
	v_mov_b32_e32 v145, v144
	s_nop 1
	v_permlane16_swap_b32_e32 v144, v145
	s_nop 0
	v_add_f32_e32 v144, v144, v145
	v_mov_b32_e32 v145, v144
	s_nop 1
	v_permlane32_swap_b32_e32 v144, v145
	s_nop 0
	v_add_f32_e32 v144, v144, v145
	v_fmamk_f32 v144, v144, 0x3a800000, v3
	v_rsq_f32_e32 v144, v144
	s_nop 0
	v_pk_mul_f32 v[128:129], v[128:129], v[144:145] op_sel_hi:[1,0]
	v_pk_mul_f32 v[130:131], v[130:131], v[144:145] op_sel_hi:[1,0]
	v_pk_mul_f32 v[132:133], v[132:133], v[144:145] op_sel_hi:[1,0]
	v_pk_mul_f32 v[134:135], v[134:135], v[144:145] op_sel_hi:[1,0]
	v_pk_mul_f32 v[136:137], v[136:137], v[144:145] op_sel_hi:[1,0]
	v_pk_mul_f32 v[138:139], v[138:139], v[144:145] op_sel_hi:[1,0]
	v_pk_mul_f32 v[140:141], v[140:141], v[144:145] op_sel_hi:[1,0]
	v_pk_mul_f32 v[142:143], v[142:143], v[144:145] op_sel_hi:[1,0]
	v_pk_mul_f32 v[128:129], v[16:17], v[128:129]
	v_pk_mul_f32 v[130:131], v[18:19], v[130:131]
	v_pk_mul_f32 v[132:133], v[20:21], v[132:133]
	v_pk_mul_f32 v[134:135], v[22:23], v[134:135]
	v_pk_mul_f32 v[136:137], v[24:25], v[136:137]
	v_pk_mul_f32 v[138:139], v[26:27], v[138:139]
	v_pk_mul_f32 v[140:141], v[28:29], v[140:141]
	v_pk_mul_f32 v[142:143], v[30:31], v[142:143]
	v_pk_fma_f32 v[128:129], v[32:33], v[128:129], v[48:49]
	v_pk_fma_f32 v[130:131], v[34:35], v[130:131], v[50:51]
	v_pk_fma_f32 v[132:133], v[36:37], v[132:133], v[52:53]
	v_pk_fma_f32 v[134:135], v[38:39], v[134:135], v[54:55]
	v_pk_fma_f32 v[136:137], v[40:41], v[136:137], v[56:57]
	v_pk_fma_f32 v[138:139], v[42:43], v[138:139], v[58:59]
	v_pk_fma_f32 v[140:141], v[44:45], v[140:141], v[60:61]
	v_pk_fma_f32 v[142:143], v[46:47], v[142:143], v[62:63]
	v_cvt_pk_bf16_f32 v148, v128, v129
	v_cvt_pk_bf16_f32 v149, v130, v131
	v_cvt_pk_bf16_f32 v150, v132, v133
	v_cvt_pk_bf16_f32 v151, v134, v135
	v_cvt_pk_bf16_f32 v152, v136, v137
	v_cvt_pk_bf16_f32 v153, v138, v139
	v_cvt_pk_bf16_f32 v154, v140, v141
	v_cvt_pk_bf16_f32 v155, v142, v143
	global_store_dwordx4 v1, v[148:151], s[10:11] sc1
	global_store_dwordx4 v1, v[152:155], s[10:11] offset:1024 sc1
	s_waitcnt vmcnt(22)
	v_lshlrev_b32_e32 v128, 16, v88
	v_and_b32_e32 v129, 0xffff0000, v88
	v_lshlrev_b32_e32 v130, 16, v89
	v_and_b32_e32 v131, 0xffff0000, v89
	v_lshlrev_b32_e32 v132, 16, v90
	v_and_b32_e32 v133, 0xffff0000, v90
	v_lshlrev_b32_e32 v134, 16, v91
	v_and_b32_e32 v135, 0xffff0000, v91
	v_lshlrev_b32_e32 v136, 16, v92
	v_and_b32_e32 v137, 0xffff0000, v92
	v_lshlrev_b32_e32 v138, 16, v93
	v_and_b32_e32 v139, 0xffff0000, v93
	v_lshlrev_b32_e32 v140, 16, v94
	v_and_b32_e32 v141, 0xffff0000, v94
	v_lshlrev_b32_e32 v142, 16, v95
	v_and_b32_e32 v143, 0xffff0000, v95
	v_pk_mul_f32 v[144:145], v[128:129], v[128:129]
	v_pk_fma_f32 v[144:145], v[130:131], v[130:131], v[144:145]
	v_pk_fma_f32 v[144:145], v[132:133], v[132:133], v[144:145]
	v_pk_fma_f32 v[144:145], v[134:135], v[134:135], v[144:145]
	v_pk_fma_f32 v[144:145], v[136:137], v[136:137], v[144:145]
	v_pk_fma_f32 v[144:145], v[138:139], v[138:139], v[144:145]
	v_pk_fma_f32 v[144:145], v[140:141], v[140:141], v[144:145]
	v_pk_fma_f32 v[144:145], v[142:143], v[142:143], v[144:145]
	v_add_f32_e32 v144, v144, v145
	s_nop 1
	v_add_f32_dpp v144, v144, v144 quad_perm:[1,0,3,2] row_mask:0xf bank_mask:0xf
	s_nop 1
	v_add_f32_dpp v144, v144, v144 quad_perm:[2,3,0,1] row_mask:0xf bank_mask:0xf
	s_nop 1
	v_add_f32_dpp v144, v144, v144 row_half_mirror row_mask:0xf bank_mask:0xf
	s_nop 1
	v_add_f32_dpp v144, v144, v144 row_mirror row_mask:0xf bank_mask:0xf
	s_nop 0
	v_mov_b32_e32 v145, v144
	s_nop 1
	v_permlane16_swap_b32_e32 v144, v145
	s_nop 0
	v_add_f32_e32 v144, v144, v145
	v_mov_b32_e32 v145, v144
	s_nop 1
	v_permlane32_swap_b32_e32 v144, v145
	s_nop 0
	v_add_f32_e32 v144, v144, v145
	v_fmamk_f32 v144, v144, 0x3a800000, v3
	v_rsq_f32_e32 v144, v144
	s_nop 0
	v_pk_mul_f32 v[128:129], v[128:129], v[144:145] op_sel_hi:[1,0]
	v_pk_mul_f32 v[130:131], v[130:131], v[144:145] op_sel_hi:[1,0]
	v_pk_mul_f32 v[132:133], v[132:133], v[144:145] op_sel_hi:[1,0]
	v_pk_mul_f32 v[134:135], v[134:135], v[144:145] op_sel_hi:[1,0]
	v_pk_mul_f32 v[136:137], v[136:137], v[144:145] op_sel_hi:[1,0]
	v_pk_mul_f32 v[138:139], v[138:139], v[144:145] op_sel_hi:[1,0]
	v_pk_mul_f32 v[140:141], v[140:141], v[144:145] op_sel_hi:[1,0]
; __device__ __forceinline__ unsigned cvt_pk_bf16(float lo, float hi) { unsigned r; asm("v_cvt_pk_bf16_f32 %0, %1, %2" : "=v"(r) : "v"(lo), "v"(hi)); return r; }
; __device__ __forceinline__ void norm_pass_bf16(const Ctx& X, const bf16_t* xs, const bf16_t* cs, int nrows, const float* gain, const float* modl, int si, bf16_t* HN) {
;     ...
;         for (int j = 0; j < 2; ++j) {
;             v[j][0] = bf2f(q[j].x & 0xffffu); v[j][1] = bf2f(q[j].x >> 16); v[j][2] = bf2f(q[j].y & 0xffffu); v[j][3] = bf2f(q[j].y >> 16);
;             v[j][4] = bf2f(q[j].z & 0xffffu); v[j][5] = bf2f(q[j].z >> 16); v[j][6] = bf2f(q[j].w & 0xffffu); v[j][7] = bf2f(q[j].w >> 16);
; #pragma unroll
;             for (int e = 0; e < 8; ++e) s += v[j][e] * v[j][e]; }
;         const float rstd = rsqrtf(wave_sum(s) * (1.0f / 1024.0f) + 1e-6f);
; #pragma unroll
;         for (int j = 0; j < 2; ++j) { const int c = (X.lane + 64 * j) * 8; float o[8];
; #pragma unroll
;             for (int h = 0; h < 2; ++h) { const f32x4 gn = *(const f32x4*)(gain + c + 4 * h), a = *(const f32x4*)(scl + c + 4 * h), b = *(const f32x4*)(sh + c + 4 * h);
; #pragma unroll
;                 for (int e = 0; e < 4; ++e) o[4 * h + e] = v[j][4 * h + e] * rstd * gn[e] * (a[e] + 1.0f) + b[e]; }
;             u32x4 w; w.x = cvt_pk_bf16(o[0], o[1]); w.y = cvt_pk_bf16(o[2], o[3]); w.z = cvt_pk_bf16(o[4], o[5]); w.w = cvt_pk_bf16(o[6], o[7]); *(u32x4*)(HN + (size_t)r * D + c) = w; }
	v_pk_mul_f32 v[142:143], v[142:143], v[144:145] op_sel_hi:[1,0]
	v_pk_mul_f32 v[128:129], v[16:17], v[128:129]
	v_pk_mul_f32 v[130:131], v[18:19], v[130:131]
	v_pk_mul_f32 v[132:133], v[20:21], v[132:133]
	v_pk_mul_f32 v[134:135], v[22:23], v[134:135]
	v_pk_mul_f32 v[136:137], v[24:25], v[136:137]
	v_pk_mul_f32 v[138:139], v[26:27], v[138:139]
	v_pk_mul_f32 v[140:141], v[28:29], v[140:141]
	v_pk_mul_f32 v[142:143], v[30:31], v[142:143]
	v_pk_fma_f32 v[128:129], v[32:33], v[128:129], v[48:49]
	v_pk_fma_f32 v[130:131], v[34:35], v[130:131], v[50:51]
	v_pk_fma_f32 v[132:133], v[36:37], v[132:133], v[52:53]
	v_pk_fma_f32 v[134:135], v[38:39], v[134:135], v[54:55]
	v_pk_fma_f32 v[136:137], v[40:41], v[136:137], v[56:57]
	v_pk_fma_f32 v[138:139], v[42:43], v[138:139], v[58:59]
	v_pk_fma_f32 v[140:141], v[44:45], v[140:141], v[60:61]
	v_pk_fma_f32 v[142:143], v[46:47], v[142:143], v[62:63]
	v_cvt_pk_bf16_f32 v148, v128, v129
	v_cvt_pk_bf16_f32 v149, v130, v131
	v_cvt_pk_bf16_f32 v150, v132, v133
	v_cvt_pk_bf16_f32 v151, v134, v135
	v_cvt_pk_bf16_f32 v152, v136, v137
	v_cvt_pk_bf16_f32 v153, v138, v139
	v_cvt_pk_bf16_f32 v154, v140, v141
	v_cvt_pk_bf16_f32 v155, v142, v143
	global_store_dwordx4 v1, v[148:151], s[10:11] offset:2048 sc1
	global_store_dwordx4 v1, v[152:155], s[10:11] offset:3072 sc1
	s_add_u32 s10, s10, 0x1000
	s_addc_u32 s11, s11, 0
	s_waitcnt vmcnt(20)
	v_lshlrev_b32_e32 v128, 16, v96
	v_and_b32_e32 v129, 0xffff0000, v96
	v_lshlrev_b32_e32 v130, 16, v97
	v_and_b32_e32 v131, 0xffff0000, v97
	v_lshlrev_b32_e32 v132, 16, v98
	v_and_b32_e32 v133, 0xffff0000, v98
	v_lshlrev_b32_e32 v134, 16, v99
	v_and_b32_e32 v135, 0xffff0000, v99
	v_lshlrev_b32_e32 v136, 16, v100
	v_and_b32_e32 v137, 0xffff0000, v100
	v_lshlrev_b32_e32 v138, 16, v101
	v_and_b32_e32 v139, 0xffff0000, v101
	v_lshlrev_b32_e32 v140, 16, v102
	v_and_b32_e32 v141, 0xffff0000, v102
	v_lshlrev_b32_e32 v142, 16, v103
	v_and_b32_e32 v143, 0xffff0000, v103
	v_pk_mul_f32 v[144:145], v[128:129], v[128:129]
	v_pk_fma_f32 v[144:145], v[130:131], v[130:131], v[144:145]
	v_pk_fma_f32 v[144:145], v[132:133], v[132:133], v[144:145]
	v_pk_fma_f32 v[144:145], v[134:135], v[134:135], v[144:145]
	v_pk_fma_f32 v[144:145], v[136:137], v[136:137], v[144:145]
	v_pk_fma_f32 v[144:145], v[138:139], v[138:139], v[144:145]
	v_pk_fma_f32 v[144:145], v[140:141], v[140:141], v[144:145]
	v_pk_fma_f32 v[144:145], v[142:143], v[142:143], v[144:145]
	v_add_f32_e32 v144, v144, v145
	s_nop 1
	v_add_f32_dpp v144, v144, v144 quad_perm:[1,0,3,2] row_mask:0xf bank_mask:0xf
	s_nop 1
	v_add_f32_dpp v144, v144, v144 quad_perm:[2,3,0,1] row_mask:0xf bank_mask:0xf
	s_nop 1
	v_add_f32_dpp v144, v144, v144 row_half_mirror row_mask:0xf bank_mask:0xf
	s_nop 1
	v_add_f32_dpp v144, v144, v144 row_mirror row_mask:0xf bank_mask:0xf
	s_nop 0
	v_mov_b32_e32 v145, v144
	s_nop 1
	v_permlane16_swap_b32_e32 v144, v145
	s_nop 0
	v_add_f32_e32 v144, v144, v145
	v_mov_b32_e32 v145, v144
	s_nop 1
	v_permlane32_swap_b32_e32 v144, v145
	s_nop 0
	v_add_f32_e32 v144, v144, v145
	v_fmamk_f32 v144, v144, 0x3a800000, v3
	v_rsq_f32_e32 v144, v144
	s_nop 0
	v_pk_mul_f32 v[128:129], v[128:129], v[144:145] op_sel_hi:[1,0]
	v_pk_mul_f32 v[130:131], v[130:131], v[144:145] op_sel_hi:[1,0]
	v_pk_mul_f32 v[132:133], v[132:133], v[144:145] op_sel_hi:[1,0]
	v_pk_mul_f32 v[134:135], v[134:135], v[144:145] op_sel_hi:[1,0]
	v_pk_mul_f32 v[136:137], v[136:137], v[144:145] op_sel_hi:[1,0]
	v_pk_mul_f32 v[138:139], v[138:139], v[144:145] op_sel_hi:[1,0]
	v_pk_mul_f32 v[140:141], v[140:141], v[144:145] op_sel_hi:[1,0]
	v_pk_mul_f32 v[142:143], v[142:143], v[144:145] op_sel_hi:[1,0]
	v_pk_mul_f32 v[128:129], v[16:17], v[128:129]
	v_pk_mul_f32 v[130:131], v[18:19], v[130:131]
	v_pk_mul_f32 v[132:133], v[20:21], v[132:133]
	v_pk_mul_f32 v[134:135], v[22:23], v[134:135]
	v_pk_mul_f32 v[136:137], v[24:25], v[136:137]
	v_pk_mul_f32 v[138:139], v[26:27], v[138:139]
	v_pk_mul_f32 v[140:141], v[28:29], v[140:141]
	v_pk_mul_f32 v[142:143], v[30:31], v[142:143]
	v_pk_fma_f32 v[128:129], v[32:33], v[128:129], v[48:49]
	v_pk_fma_f32 v[130:131], v[34:35], v[130:131], v[50:51]
	v_pk_fma_f32 v[132:133], v[36:37], v[132:133], v[52:53]
	v_pk_fma_f32 v[134:135], v[38:39], v[134:135], v[54:55]
	v_pk_fma_f32 v[136:137], v[40:41], v[136:137], v[56:57]
	v_pk_fma_f32 v[138:139], v[42:43], v[138:139], v[58:59]
	v_pk_fma_f32 v[140:141], v[44:45], v[140:141], v[60:61]
	v_pk_fma_f32 v[142:143], v[46:47], v[142:143], v[62:63]
	v_cvt_pk_bf16_f32 v148, v128, v129
	v_cvt_pk_bf16_f32 v149, v130, v131
	v_cvt_pk_bf16_f32 v150, v132, v133
	v_cvt_pk_bf16_f32 v151, v134, v135
	v_cvt_pk_bf16_f32 v152, v136, v137
	v_cvt_pk_bf16_f32 v153, v138, v139
	v_cvt_pk_bf16_f32 v154, v140, v141
	v_cvt_pk_bf16_f32 v155, v142, v143
	global_store_dwordx4 v1, v[148:151], s[10:11] sc1
	global_store_dwordx4 v1, v[152:155], s[10:11] offset:1024 sc1
	s_waitcnt vmcnt(18)
; __device__ __forceinline__ unsigned cvt_pk_bf16(float lo, float hi) { unsigned r; asm("v_cvt_pk_bf16_f32 %0, %1, %2" : "=v"(r) : "v"(lo), "v"(hi)); return r; }
; __device__ __forceinline__ void norm_pass_bf16(const Ctx& X, const bf16_t* xs, const bf16_t* cs, int nrows, const float* gain, const float* modl, int si, bf16_t* HN) {
;     ...
;         for (int j = 0; j < 2; ++j) {
;             v[j][0] = bf2f(q[j].x & 0xffffu); v[j][1] = bf2f(q[j].x >> 16); v[j][2] = bf2f(q[j].y & 0xffffu); v[j][3] = bf2f(q[j].y >> 16);
;             v[j][4] = bf2f(q[j].z & 0xffffu); v[j][5] = bf2f(q[j].z >> 16); v[j][6] = bf2f(q[j].w & 0xffffu); v[j][7] = bf2f(q[j].w >> 16);
; #pragma unroll
;             for (int e = 0; e < 8; ++e) s += v[j][e] * v[j][e]; }
;         const float rstd = rsqrtf(wave_sum(s) * (1.0f / 1024.0f) + 1e-6f);
; #pragma unroll
;         for (int j = 0; j < 2; ++j) { const int c = (X.lane + 64 * j) * 8; float o[8];
; #pragma unroll
;             for (int h = 0; h < 2; ++h) { const f32x4 gn = *(const f32x4*)(gain + c + 4 * h), a = *(const f32x4*)(scl + c + 4 * h), b = *(const f32x4*)(sh + c + 4 * h);
; #pragma unroll
;                 for (int e = 0; e < 4; ++e) o[4 * h + e] = v[j][4 * h + e] * rstd * gn[e] * (a[e] + 1.0f) + b[e]; }
;             u32x4 w; w.x = cvt_pk_bf16(o[0], o[1]); w.y = cvt_pk_bf16(o[2], o[3]); w.z = cvt_pk_bf16(o[4], o[5]); w.w = cvt_pk_bf16(o[6], o[7]); *(u32x4*)(HN + (size_t)r * D + c) = w; }
	v_lshlrev_b32_e32 v128, 16, v104
	v_and_b32_e32 v129, 0xffff0000, v104
	v_lshlrev_b32_e32 v130, 16, v105
	v_and_b32_e32 v131, 0xffff0000, v105
	v_lshlrev_b32_e32 v132, 16, v106
	v_and_b32_e32 v133, 0xffff0000, v106
	v_lshlrev_b32_e32 v134, 16, v107
	v_and_b32_e32 v135, 0xffff0000, v107
	v_lshlrev_b32_e32 v136, 16, v108
	v_and_b32_e32 v137, 0xffff0000, v108
	v_lshlrev_b32_e32 v138, 16, v109
	v_and_b32_e32 v139, 0xffff0000, v109
	v_lshlrev_b32_e32 v140, 16, v110
	v_and_b32_e32 v141, 0xffff0000, v110
	v_lshlrev_b32_e32 v142, 16, v111
	v_and_b32_e32 v143, 0xffff0000, v111
	v_pk_mul_f32 v[144:145], v[128:129], v[128:129]
	v_pk_fma_f32 v[144:145], v[130:131], v[130:131], v[144:145]
	v_pk_fma_f32 v[144:145], v[132:133], v[132:133], v[144:145]
	v_pk_fma_f32 v[144:145], v[134:135], v[134:135], v[144:145]
	v_pk_fma_f32 v[144:145], v[136:137], v[136:137], v[144:145]
	v_pk_fma_f32 v[144:145], v[138:139], v[138:139], v[144:145]
	v_pk_fma_f32 v[144:145], v[140:141], v[140:141], v[144:145]
	v_pk_fma_f32 v[144:145], v[142:143], v[142:143], v[144:145]
	v_add_f32_e32 v144, v144, v145
	s_nop 1
	v_add_f32_dpp v144, v144, v144 quad_perm:[1,0,3,2] row_mask:0xf bank_mask:0xf
	s_nop 1
	v_add_f32_dpp v144, v144, v144 quad_perm:[2,3,0,1] row_mask:0xf bank_mask:0xf
	s_nop 1
	v_add_f32_dpp v144, v144, v144 row_half_mirror row_mask:0xf bank_mask:0xf
	s_nop 1
	v_add_f32_dpp v144, v144, v144 row_mirror row_mask:0xf bank_mask:0xf
	s_nop 0
	v_mov_b32_e32 v145, v144
	s_nop 1
	v_permlane16_swap_b32_e32 v144, v145
	s_nop 0
	v_add_f32_e32 v144, v144, v145
	v_mov_b32_e32 v145, v144
	s_nop 1
	v_permlane32_swap_b32_e32 v144, v145
	s_nop 0
	v_add_f32_e32 v144, v144, v145
	v_fmamk_f32 v144, v144, 0x3a800000, v3
	v_rsq_f32_e32 v144, v144
	s_nop 0
	v_pk_mul_f32 v[128:129], v[128:129], v[144:145] op_sel_hi:[1,0]
	v_pk_mul_f32 v[130:131], v[130:131], v[144:145] op_sel_hi:[1,0]
	v_pk_mul_f32 v[132:133], v[132:133], v[144:145] op_sel_hi:[1,0]
	v_pk_mul_f32 v[134:135], v[134:135], v[144:145] op_sel_hi:[1,0]
	v_pk_mul_f32 v[136:137], v[136:137], v[144:145] op_sel_hi:[1,0]
	v_pk_mul_f32 v[138:139], v[138:139], v[144:145] op_sel_hi:[1,0]
	v_pk_mul_f32 v[140:141], v[140:141], v[144:145] op_sel_hi:[1,0]
	v_pk_mul_f32 v[142:143], v[142:143], v[144:145] op_sel_hi:[1,0]
	v_pk_mul_f32 v[128:129], v[16:17], v[128:129]
	v_pk_mul_f32 v[130:131], v[18:19], v[130:131]
	v_pk_mul_f32 v[132:133], v[20:21], v[132:133]
	v_pk_mul_f32 v[134:135], v[22:23], v[134:135]
	v_pk_mul_f32 v[136:137], v[24:25], v[136:137]
	v_pk_mul_f32 v[138:139], v[26:27], v[138:139]
	v_pk_mul_f32 v[140:141], v[28:29], v[140:141]
	v_pk_mul_f32 v[142:143], v[30:31], v[142:143]
	v_pk_fma_f32 v[128:129], v[32:33], v[128:129], v[48:49]
	v_pk_fma_f32 v[130:131], v[34:35], v[130:131], v[50:51]
	v_pk_fma_f32 v[132:133], v[36:37], v[132:133], v[52:53]
	v_pk_fma_f32 v[134:135], v[38:39], v[134:135], v[54:55]
	v_pk_fma_f32 v[136:137], v[40:41], v[136:137], v[56:57]
	v_pk_fma_f32 v[138:139], v[42:43], v[138:139], v[58:59]
	v_pk_fma_f32 v[140:141], v[44:45], v[140:141], v[60:61]
	v_pk_fma_f32 v[142:143], v[46:47], v[142:143], v[62:63]
	v_cvt_pk_bf16_f32 v148, v128, v129
	v_cvt_pk_bf16_f32 v149, v130, v131
	v_cvt_pk_bf16_f32 v150, v132, v133
	v_cvt_pk_bf16_f32 v151, v134, v135
	v_cvt_pk_bf16_f32 v152, v136, v137
	v_cvt_pk_bf16_f32 v153, v138, v139
	v_cvt_pk_bf16_f32 v154, v140, v141
	v_cvt_pk_bf16_f32 v155, v142, v143
	global_store_dwordx4 v1, v[148:151], s[10:11] offset:2048 sc1
	global_store_dwordx4 v1, v[152:155], s[10:11] offset:3072 sc1
	s_add_u32 s10, s10, 0x1000
	s_addc_u32 s11, s11, 0
	s_waitcnt vmcnt(16)
	v_lshlrev_b32_e32 v128, 16, v112
	v_and_b32_e32 v129, 0xffff0000, v112
	v_lshlrev_b32_e32 v130, 16, v113
	v_and_b32_e32 v131, 0xffff0000, v113
	v_lshlrev_b32_e32 v132, 16, v114
	v_and_b32_e32 v133, 0xffff0000, v114
	v_lshlrev_b32_e32 v134, 16, v115
	v_and_b32_e32 v135, 0xffff0000, v115
	v_lshlrev_b32_e32 v136, 16, v116
	v_and_b32_e32 v137, 0xffff0000, v116
	v_lshlrev_b32_e32 v138, 16, v117
	v_and_b32_e32 v139, 0xffff0000, v117
	v_lshlrev_b32_e32 v140, 16, v118
	v_and_b32_e32 v141, 0xffff0000, v118
	v_lshlrev_b32_e32 v142, 16, v119
	v_and_b32_e32 v143, 0xffff0000, v119
	v_pk_mul_f32 v[144:145], v[128:129], v[128:129]
	v_pk_fma_f32 v[144:145], v[130:131], v[130:131], v[144:145]
	v_pk_fma_f32 v[144:145], v[132:133], v[132:133], v[144:145]
	v_pk_fma_f32 v[144:145], v[134:135], v[134:135], v[144:145]
	v_pk_fma_f32 v[144:145], v[136:137], v[136:137], v[144:145]
	v_pk_fma_f32 v[144:145], v[138:139], v[138:139], v[144:145]
	v_pk_fma_f32 v[144:145], v[140:141], v[140:141], v[144:145]
	v_pk_fma_f32 v[144:145], v[142:143], v[142:143], v[144:145]
	v_add_f32_e32 v144, v144, v145
	s_nop 1
	v_add_f32_dpp v144, v144, v144 quad_perm:[1,0,3,2] row_mask:0xf bank_mask:0xf
	s_nop 1
	v_add_f32_dpp v144, v144, v144 quad_perm:[2,3,0,1] row_mask:0xf bank_mask:0xf
	s_nop 1
	v_add_f32_dpp v144, v144, v144 row_half_mirror row_mask:0xf bank_mask:0xf
	s_nop 1
	v_add_f32_dpp v144, v144, v144 row_mirror row_mask:0xf bank_mask:0xf
	s_nop 0
	v_mov_b32_e32 v145, v144
	s_nop 1
	v_permlane16_swap_b32_e32 v144, v145
	s_nop 0
	v_add_f32_e32 v144, v144, v145
	v_mov_b32_e32 v145, v144
	s_nop 1
	v_permlane32_swap_b32_e32 v144, v145
	s_nop 0
	v_add_f32_e32 v144, v144, v145
	v_fmamk_f32 v144, v144, 0x3a800000, v3
	v_rsq_f32_e32 v144, v144
	s_nop 0
	v_pk_mul_f32 v[128:129], v[128:129], v[144:145] op_sel_hi:[1,0]
; __device__ __forceinline__ unsigned cvt_pk_bf16(float lo, float hi) { unsigned r; asm("v_cvt_pk_bf16_f32 %0, %1, %2" : "=v"(r) : "v"(lo), "v"(hi)); return r; }
; __device__ __forceinline__ void norm_pass_bf16(const Ctx& X, const bf16_t* xs, const bf16_t* cs, int nrows, const float* gain, const float* modl, int si, bf16_t* HN) {
;     for (int r = X.gw; r < nrows; r += X.NGW) {
;     ...
;         for (int j = 0; j < 2; ++j) {
;             v[j][0] = bf2f(q[j].x & 0xffffu); v[j][1] = bf2f(q[j].x >> 16); v[j][2] = bf2f(q[j].y & 0xffffu); v[j][3] = bf2f(q[j].y >> 16);
;             v[j][4] = bf2f(q[j].z & 0xffffu); v[j][5] = bf2f(q[j].z >> 16); v[j][6] = bf2f(q[j].w & 0xffffu); v[j][7] = bf2f(q[j].w >> 16);
; #pragma unroll
;             for (int e = 0; e < 8; ++e) s += v[j][e] * v[j][e]; }
;         const float rstd = rsqrtf(wave_sum(s) * (1.0f / 1024.0f) + 1e-6f);
; #pragma unroll
;         for (int j = 0; j < 2; ++j) { const int c = (X.lane + 64 * j) * 8; float o[8];
; #pragma unroll
;             for (int h = 0; h < 2; ++h) { const f32x4 gn = *(const f32x4*)(gain + c + 4 * h), a = *(const f32x4*)(scl + c + 4 * h), b = *(const f32x4*)(sh + c + 4 * h);
; #pragma unroll
;                 for (int e = 0; e < 4; ++e) o[4 * h + e] = v[j][4 * h + e] * rstd * gn[e] * (a[e] + 1.0f) + b[e]; }
;             u32x4 w; w.x = cvt_pk_bf16(o[0], o[1]); w.y = cvt_pk_bf16(o[2], o[3]); w.z = cvt_pk_bf16(o[4], o[5]); w.w = cvt_pk_bf16(o[6], o[7]); *(u32x4*)(HN + (size_t)r * D + c) = w; }
	v_pk_mul_f32 v[130:131], v[130:131], v[144:145] op_sel_hi:[1,0]
	v_pk_mul_f32 v[132:133], v[132:133], v[144:145] op_sel_hi:[1,0]
	v_pk_mul_f32 v[134:135], v[134:135], v[144:145] op_sel_hi:[1,0]
	v_pk_mul_f32 v[136:137], v[136:137], v[144:145] op_sel_hi:[1,0]
	v_pk_mul_f32 v[138:139], v[138:139], v[144:145] op_sel_hi:[1,0]
	v_pk_mul_f32 v[140:141], v[140:141], v[144:145] op_sel_hi:[1,0]
	v_pk_mul_f32 v[142:143], v[142:143], v[144:145] op_sel_hi:[1,0]
	v_pk_mul_f32 v[128:129], v[16:17], v[128:129]
	v_pk_mul_f32 v[130:131], v[18:19], v[130:131]
	v_pk_mul_f32 v[132:133], v[20:21], v[132:133]
	v_pk_mul_f32 v[134:135], v[22:23], v[134:135]
	v_pk_mul_f32 v[136:137], v[24:25], v[136:137]
	v_pk_mul_f32 v[138:139], v[26:27], v[138:139]
	v_pk_mul_f32 v[140:141], v[28:29], v[140:141]
	v_pk_mul_f32 v[142:143], v[30:31], v[142:143]
	v_pk_fma_f32 v[128:129], v[32:33], v[128:129], v[48:49]
	v_pk_fma_f32 v[130:131], v[34:35], v[130:131], v[50:51]
	v_pk_fma_f32 v[132:133], v[36:37], v[132:133], v[52:53]
	v_pk_fma_f32 v[134:135], v[38:39], v[134:135], v[54:55]
	v_pk_fma_f32 v[136:137], v[40:41], v[136:137], v[56:57]
	v_pk_fma_f32 v[138:139], v[42:43], v[138:139], v[58:59]
	v_pk_fma_f32 v[140:141], v[44:45], v[140:141], v[60:61]
	v_pk_fma_f32 v[142:143], v[46:47], v[142:143], v[62:63]
	v_cvt_pk_bf16_f32 v148, v128, v129
	v_cvt_pk_bf16_f32 v149, v130, v131
	v_cvt_pk_bf16_f32 v150, v132, v133
	v_cvt_pk_bf16_f32 v151, v134, v135
	v_cvt_pk_bf16_f32 v152, v136, v137
	v_cvt_pk_bf16_f32 v153, v138, v139
	v_cvt_pk_bf16_f32 v154, v140, v141
	v_cvt_pk_bf16_f32 v155, v142, v143
	global_store_dwordx4 v1, v[148:151], s[10:11] sc1
	global_store_dwordx4 v1, v[152:155], s[10:11] offset:1024 sc1
	s_waitcnt vmcnt(14)
	v_lshlrev_b32_e32 v128, 16, v120
	v_and_b32_e32 v129, 0xffff0000, v120
	v_lshlrev_b32_e32 v130, 16, v121
	v_and_b32_e32 v131, 0xffff0000, v121
	v_lshlrev_b32_e32 v132, 16, v122
	v_and_b32_e32 v133, 0xffff0000, v122
	v_lshlrev_b32_e32 v134, 16, v123
	v_and_b32_e32 v135, 0xffff0000, v123
	v_lshlrev_b32_e32 v136, 16, v124
	v_and_b32_e32 v137, 0xffff0000, v124
	v_lshlrev_b32_e32 v138, 16, v125
	v_and_b32_e32 v139, 0xffff0000, v125
	v_lshlrev_b32_e32 v140, 16, v126
	v_and_b32_e32 v141, 0xffff0000, v126
	v_lshlrev_b32_e32 v142, 16, v127
	v_and_b32_e32 v143, 0xffff0000, v127
	v_pk_mul_f32 v[144:145], v[128:129], v[128:129]
	v_pk_fma_f32 v[144:145], v[130:131], v[130:131], v[144:145]
	v_pk_fma_f32 v[144:145], v[132:133], v[132:133], v[144:145]
	v_pk_fma_f32 v[144:145], v[134:135], v[134:135], v[144:145]
	v_pk_fma_f32 v[144:145], v[136:137], v[136:137], v[144:145]
	v_pk_fma_f32 v[144:145], v[138:139], v[138:139], v[144:145]
	v_pk_fma_f32 v[144:145], v[140:141], v[140:141], v[144:145]
	v_pk_fma_f32 v[144:145], v[142:143], v[142:143], v[144:145]
	v_add_f32_e32 v144, v144, v145
	s_nop 1
	v_add_f32_dpp v144, v144, v144 quad_perm:[1,0,3,2] row_mask:0xf bank_mask:0xf
	s_nop 1
	v_add_f32_dpp v144, v144, v144 quad_perm:[2,3,0,1] row_mask:0xf bank_mask:0xf
	s_nop 1
	v_add_f32_dpp v144, v144, v144 row_half_mirror row_mask:0xf bank_mask:0xf
	s_nop 1
	v_add_f32_dpp v144, v144, v144 row_mirror row_mask:0xf bank_mask:0xf
	s_nop 0
	v_mov_b32_e32 v145, v144
	s_nop 1
	v_permlane16_swap_b32_e32 v144, v145
	s_nop 0
	v_add_f32_e32 v144, v144, v145
	v_mov_b32_e32 v145, v144
	s_nop 1
	v_permlane32_swap_b32_e32 v144, v145
	s_nop 0
	v_add_f32_e32 v144, v144, v145
	v_fmamk_f32 v144, v144, 0x3a800000, v3
	v_rsq_f32_e32 v144, v144
	s_nop 0
	v_pk_mul_f32 v[128:129], v[128:129], v[144:145] op_sel_hi:[1,0]
	v_pk_mul_f32 v[130:131], v[130:131], v[144:145] op_sel_hi:[1,0]
	v_pk_mul_f32 v[132:133], v[132:133], v[144:145] op_sel_hi:[1,0]
	v_pk_mul_f32 v[134:135], v[134:135], v[144:145] op_sel_hi:[1,0]
	v_pk_mul_f32 v[136:137], v[136:137], v[144:145] op_sel_hi:[1,0]
	v_pk_mul_f32 v[138:139], v[138:139], v[144:145] op_sel_hi:[1,0]
	v_pk_mul_f32 v[140:141], v[140:141], v[144:145] op_sel_hi:[1,0]
	v_pk_mul_f32 v[142:143], v[142:143], v[144:145] op_sel_hi:[1,0]
	v_pk_mul_f32 v[128:129], v[16:17], v[128:129]
	v_pk_mul_f32 v[130:131], v[18:19], v[130:131]
	v_pk_mul_f32 v[132:133], v[20:21], v[132:133]
	v_pk_mul_f32 v[134:135], v[22:23], v[134:135]
	v_pk_mul_f32 v[136:137], v[24:25], v[136:137]
	v_pk_mul_f32 v[138:139], v[26:27], v[138:139]
	v_pk_mul_f32 v[140:141], v[28:29], v[140:141]
	v_pk_mul_f32 v[142:143], v[30:31], v[142:143]
	v_pk_fma_f32 v[128:129], v[32:33], v[128:129], v[48:49]
	v_pk_fma_f32 v[130:131], v[34:35], v[130:131], v[50:51]
	v_pk_fma_f32 v[132:133], v[36:37], v[132:133], v[52:53]
	v_pk_fma_f32 v[134:135], v[38:39], v[134:135], v[54:55]
	v_pk_fma_f32 v[136:137], v[40:41], v[136:137], v[56:57]
	v_pk_fma_f32 v[138:139], v[42:43], v[138:139], v[58:59]
	v_pk_fma_f32 v[140:141], v[44:45], v[140:141], v[60:61]
	v_pk_fma_f32 v[142:143], v[46:47], v[142:143], v[62:63]
	v_cvt_pk_bf16_f32 v148, v128, v129
	v_cvt_pk_bf16_f32 v149, v130, v131
	v_cvt_pk_bf16_f32 v150, v132, v133
	v_cvt_pk_bf16_f32 v151, v134, v135
	v_cvt_pk_bf16_f32 v152, v136, v137
	v_cvt_pk_bf16_f32 v153, v138, v139
	v_cvt_pk_bf16_f32 v154, v140, v141
	v_cvt_pk_bf16_f32 v155, v142, v143
	global_store_dwordx4 v1, v[148:151], s[10:11] offset:2048 sc1
	global_store_dwordx4 v1, v[152:155], s[10:11] offset:3072 sc1
	s_add_u32 s10, s10, 0x1000
	s_addc_u32 s11, s11, 0
	s_add_i32 s12, s12, s20
	s_cmp_lt_i32 s12, 0x800
	s_cbranch_scc0 .LBB0_982
	s_waitcnt vmcnt(0)
	s_branch .Lhn_B_blk

; __device__ __forceinline__ unsigned cvt_pk_bf16(float lo, float hi) { unsigned r; asm("v_cvt_pk_bf16_f32 %0, %1, %2" : "=v"(r) : "v"(lo), "v"(hi)); return r; }
; __device__ __forceinline__ void norm_pass_bf16(const Ctx& X, const bf16_t* xs, const bf16_t* cs, int nrows, const float* gain, const float* modl, int si, bf16_t* HN) {
;     ...
;         const int mb = r < MX ? (r >> 12) : 8;
;         const float* sh = modl + (size_t)mb * 9216 + si * 1024; const float* scl = sh + 1024;
;         const bf16_t* rowp = r < MX ? xs + (size_t)r * D : cs + (size_t)(r - MX) * D;
;         u32x4 q[2]; float v[2][8]; float s = 0.f;
; #pragma unroll
;         for (int j = 0; j < 2; ++j) q[j] = *(const u32x4*)(rowp + (X.lane + 64 * j) * 8);
; #pragma unroll
;         for (int j = 0; j < 2; ++j) {
;             v[j][0] = bf2f(q[j].x & 0xffffu); v[j][1] = bf2f(q[j].x >> 16); v[j][2] = bf2f(q[j].y & 0xffffu); v[j][3] = bf2f(q[j].y >> 16);
;             v[j][4] = bf2f(q[j].z & 0xffffu); v[j][5] = bf2f(q[j].z >> 16); v[j][6] = bf2f(q[j].w & 0xffffu); v[j][7] = bf2f(q[j].w >> 16);
; #pragma unroll
;             for (int e = 0; e < 8; ++e) s += v[j][e] * v[j][e]; }
;         const float rstd = rsqrtf(wave_sum(s) * (1.0f / 1024.0f) + 1e-6f);
; #pragma unroll
;         for (int j = 0; j < 2; ++j) { const int c = (X.lane + 64 * j) * 8; float o[8];
; #pragma unroll
;             for (int h = 0; h < 2; ++h) { const f32x4 gn = *(const f32x4*)(gain + c + 4 * h), a = *(const f32x4*)(scl + c + 4 * h), b = *(const f32x4*)(sh + c + 4 * h);
; #pragma unroll
;                 for (int e = 0; e < 4; ++e) o[4 * h + e] = v[j][4 * h + e] * rstd * gn[e] * (a[e] + 1.0f) + b[e]; }
;             u32x4 w; w.x = cvt_pk_bf16(o[0], o[1]); w.y = cvt_pk_bf16(o[2], o[3]); w.z = cvt_pk_bf16(o[4], o[5]); w.w = cvt_pk_bf16(o[6], o[7]); *(u32x4*)(HN + (size_t)r * D + c) = w; }
.Lhn_C_blk:
	s_add_u32 s6, s48, 0x3000
	s_addc_u32 s7, s49, 0
	global_load_dwordx4 v[16:19], v2, s[6:7]
	global_load_dwordx4 v[20:23], v2, s[6:7] offset:16
	global_load_dwordx4 v[24:27], v2, s[6:7] offset:2048
	global_load_dwordx4 v[28:31], v2, s[6:7] offset:2064
	s_lshr_b32 s1, s21, 8
	s_mul_i32 s1, s1, 0x9000
	s_add_u32 s6, s88, s1
	s_addc_u32 s7, s89, 0
	s_add_u32 s6, s6, 0x51000
	s_addc_u32 s7, s7, 0
	global_load_dwordx4 v[48:51], v2, s[6:7]
	global_load_dwordx4 v[52:55], v2, s[6:7] offset:16
	global_load_dwordx4 v[56:59], v2, s[6:7] offset:2048
	global_load_dwordx4 v[60:63], v2, s[6:7] offset:2064
	s_add_u32 s6, s6, 0x1000
	s_addc_u32 s7, s7, 0
	global_load_dwordx4 v[32:35], v2, s[6:7]
	global_load_dwordx4 v[36:39], v2, s[6:7] offset:16
	global_load_dwordx4 v[40:43], v2, s[6:7] offset:2048
	global_load_dwordx4 v[44:47], v2, s[6:7] offset:2064
	s_lshl_b32 s1, s21, 15
	s_add_u32 s8, s86, s1
	s_addc_u32 s9, s87, 0
	s_add_u32 s12, s88, s1
	s_addc_u32 s13, s89, 0
	s_add_u32 s12, s12, 0x13000000
	s_addc_u32 s13, s13, 0
	global_load_dwordx4 v[64:67], v1, s[8:9]
	global_load_dwordx4 v[68:71], v1, s[8:9] offset:1024
	global_load_dwordx4 v[72:75], v1, s[8:9] offset:2048
	global_load_dwordx4 v[76:79], v1, s[8:9] offset:3072
	s_add_u32 s8, s8, 0x1000
	s_addc_u32 s9, s9, 0
	global_load_dwordx4 v[80:83], v1, s[8:9]
	global_load_dwordx4 v[84:87], v1, s[8:9] offset:1024
	global_load_dwordx4 v[88:91], v1, s[8:9] offset:2048
	global_load_dwordx4 v[92:95], v1, s[8:9] offset:3072
	s_add_u32 s8, s8, 0x1000
	s_addc_u32 s9, s9, 0
	global_load_dwordx4 v[96:99], v1, s[8:9]
	global_load_dwordx4 v[100:103], v1, s[8:9] offset:1024
	global_load_dwordx4 v[104:107], v1, s[8:9] offset:2048
	global_load_dwordx4 v[108:111], v1, s[8:9] offset:3072
	s_add_u32 s8, s8, 0x1000
	s_addc_u32 s9, s9, 0
	global_load_dwordx4 v[112:115], v1, s[8:9]
	global_load_dwordx4 v[116:119], v1, s[8:9] offset:1024
	global_load_dwordx4 v[120:123], v1, s[8:9] offset:2048
	global_load_dwordx4 v[124:127], v1, s[8:9] offset:3072
	s_add_u32 s8, s8, 0x1000
	s_addc_u32 s9, s9, 0
	s_waitcnt vmcnt(16)
	v_pk_add_f32 v[32:33], v[32:33], 1.0 op_sel_hi:[1,0]
	v_pk_add_f32 v[34:35], v[34:35], 1.0 op_sel_hi:[1,0]
	v_pk_add_f32 v[36:37], v[36:37], 1.0 op_sel_hi:[1,0]
	v_pk_add_f32 v[38:39], v[38:39], 1.0 op_sel_hi:[1,0]
	v_pk_add_f32 v[40:41], v[40:41], 1.0 op_sel_hi:[1,0]
	v_pk_add_f32 v[42:43], v[42:43], 1.0 op_sel_hi:[1,0]
	v_pk_add_f32 v[44:45], v[44:45], 1.0 op_sel_hi:[1,0]
	v_pk_add_f32 v[46:47], v[46:47], 1.0 op_sel_hi:[1,0]
	s_waitcnt vmcnt(14)
	v_lshlrev_b32_e32 v128, 16, v64
	v_and_b32_e32 v129, 0xffff0000, v64
	v_lshlrev_b32_e32 v130, 16, v65
	v_and_b32_e32 v131, 0xffff0000, v65
	v_lshlrev_b32_e32 v132, 16, v66
	v_and_b32_e32 v133, 0xffff0000, v66
	v_lshlrev_b32_e32 v134, 16, v67
	v_and_b32_e32 v135, 0xffff0000, v67
	v_lshlrev_b32_e32 v136, 16, v68
	v_and_b32_e32 v137, 0xffff0000, v68
	v_lshlrev_b32_e32 v138, 16, v69
	v_and_b32_e32 v139, 0xffff0000, v69
	v_lshlrev_b32_e32 v140, 16, v70
	v_and_b32_e32 v141, 0xffff0000, v70
	v_lshlrev_b32_e32 v142, 16, v71
	v_and_b32_e32 v143, 0xffff0000, v71
	v_pk_mul_f32 v[144:145], v[128:129], v[128:129]
	v_pk_fma_f32 v[144:145], v[130:131], v[130:131], v[144:145]
	v_pk_fma_f32 v[144:145], v[132:133], v[132:133], v[144:145]
	v_pk_fma_f32 v[144:145], v[134:135], v[134:135], v[144:145]
	v_pk_fma_f32 v[144:145], v[136:137], v[136:137], v[144:145]
	v_pk_fma_f32 v[144:145], v[138:139], v[138:139], v[144:145]
	v_pk_fma_f32 v[144:145], v[140:141], v[140:141], v[144:145]
	v_pk_fma_f32 v[144:145], v[142:143], v[142:143], v[144:145]
	v_add_f32_e32 v144, v144, v145
	s_nop 1
	v_add_f32_dpp v144, v144, v144 quad_perm:[1,0,3,2] row_mask:0xf bank_mask:0xf
	s_nop 1
	v_add_f32_dpp v144, v144, v144 quad_perm:[2,3,0,1] row_mask:0xf bank_mask:0xf
	s_nop 1
	v_add_f32_dpp v144, v144, v144 row_half_mirror row_mask:0xf bank_mask:0xf
	s_nop 1
	v_add_f32_dpp v144, v144, v144 row_mirror row_mask:0xf bank_mask:0xf
	s_nop 0
	v_mov_b32_e32 v145, v144
	s_nop 1
	v_permlane16_swap_b32_e32 v144, v145
	s_nop 0
	v_add_f32_e32 v144, v144, v145
	v_mov_b32_e32 v145, v144
	s_nop 1
	v_permlane32_swap_b32_e32 v144, v145
	s_nop 0
	v_add_f32_e32 v144, v144, v145
	v_fmamk_f32 v144, v144, 0x3a800000, v3
	v_rsq_f32_e32 v144, v144
	s_nop 0
	v_pk_mul_f32 v[128:129], v[128:129], v[144:145] op_sel_hi:[1,0]
	v_pk_mul_f32 v[130:131], v[130:131], v[144:145] op_sel_hi:[1,0]
	v_pk_mul_f32 v[132:133], v[132:133], v[144:145] op_sel_hi:[1,0]
	v_pk_mul_f32 v[134:135], v[134:135], v[144:145] op_sel_hi:[1,0]
	v_pk_mul_f32 v[136:137], v[136:137], v[144:145] op_sel_hi:[1,0]
	v_pk_mul_f32 v[138:139], v[138:139], v[144:145] op_sel_hi:[1,0]
	v_pk_mul_f32 v[140:141], v[140:141], v[144:145] op_sel_hi:[1,0]
	v_pk_mul_f32 v[142:143], v[142:143], v[144:145] op_sel_hi:[1,0]
	v_pk_mul_f32 v[128:129], v[16:17], v[128:129]
	v_pk_mul_f32 v[130:131], v[18:19], v[130:131]
	v_pk_mul_f32 v[132:133], v[20:21], v[132:133]
	v_pk_mul_f32 v[134:135], v[22:23], v[134:135]
	v_pk_mul_f32 v[136:137], v[24:25], v[136:137]
	v_pk_mul_f32 v[138:139], v[26:27], v[138:139]
	v_pk_mul_f32 v[140:141], v[28:29], v[140:141]
	v_pk_mul_f32 v[142:143], v[30:31], v[142:143]
	v_pk_fma_f32 v[128:129], v[32:33], v[128:129], v[48:49]
	v_pk_fma_f32 v[130:131], v[34:35], v[130:131], v[50:51]
	v_pk_fma_f32 v[132:133], v[36:37], v[132:133], v[52:53]
	v_pk_fma_f32 v[134:135], v[38:39], v[134:135], v[54:55]
	v_pk_fma_f32 v[136:137], v[40:41], v[136:137], v[56:57]
	v_pk_fma_f32 v[138:139], v[42:43], v[138:139], v[58:59]
	v_pk_fma_f32 v[140:141], v[44:45], v[140:141], v[60:61]
	v_pk_fma_f32 v[142:143], v[46:47], v[142:143], v[62:63]
	v_cvt_pk_bf16_f32 v148, v128, v129
	v_cvt_pk_bf16_f32 v149, v130, v131
	v_cvt_pk_bf16_f32 v150, v132, v133
	v_cvt_pk_bf16_f32 v151, v134, v135
	v_cvt_pk_bf16_f32 v152, v136, v137
	v_cvt_pk_bf16_f32 v153, v138, v139
	v_cvt_pk_bf16_f32 v154, v140, v141
	v_cvt_pk_bf16_f32 v155, v142, v143
	global_store_dwordx4 v1, v[148:151], s[12:13] sc1
	global_store_dwordx4 v1, v[152:155], s[12:13] offset:1024 sc1
	global_load_dwordx4 v[64:67], v1, s[8:9]
	global_load_dwordx4 v[68:71], v1, s[8:9] offset:1024
	s_waitcnt vmcnt(16)
; __device__ __forceinline__ unsigned cvt_pk_bf16(float lo, float hi) { unsigned r; asm("v_cvt_pk_bf16_f32 %0, %1, %2" : "=v"(r) : "v"(lo), "v"(hi)); return r; }
; __device__ __forceinline__ void norm_pass_bf16(const Ctx& X, const bf16_t* xs, const bf16_t* cs, int nrows, const float* gain, const float* modl, int si, bf16_t* HN) {
;     ...
;         for (int j = 0; j < 2; ++j) {
;             v[j][0] = bf2f(q[j].x & 0xffffu); v[j][1] = bf2f(q[j].x >> 16); v[j][2] = bf2f(q[j].y & 0xffffu); v[j][3] = bf2f(q[j].y >> 16);
;             v[j][4] = bf2f(q[j].z & 0xffffu); v[j][5] = bf2f(q[j].z >> 16); v[j][6] = bf2f(q[j].w & 0xffffu); v[j][7] = bf2f(q[j].w >> 16);
; #pragma unroll
;             for (int e = 0; e < 8; ++e) s += v[j][e] * v[j][e]; }
;         const float rstd = rsqrtf(wave_sum(s) * (1.0f / 1024.0f) + 1e-6f);
; #pragma unroll
;         for (int j = 0; j < 2; ++j) { const int c = (X.lane + 64 * j) * 8; float o[8];
; #pragma unroll
;             for (int h = 0; h < 2; ++h) { const f32x4 gn = *(const f32x4*)(gain + c + 4 * h), a = *(const f32x4*)(scl + c + 4 * h), b = *(const f32x4*)(sh + c + 4 * h);
; #pragma unroll
;                 for (int e = 0; e < 4; ++e) o[4 * h + e] = v[j][4 * h + e] * rstd * gn[e] * (a[e] + 1.0f) + b[e]; }
;             u32x4 w; w.x = cvt_pk_bf16(o[0], o[1]); w.y = cvt_pk_bf16(o[2], o[3]); w.z = cvt_pk_bf16(o[4], o[5]); w.w = cvt_pk_bf16(o[6], o[7]); *(u32x4*)(HN + (size_t)r * D + c) = w; }
	v_lshlrev_b32_e32 v128, 16, v72
	v_and_b32_e32 v129, 0xffff0000, v72
	v_lshlrev_b32_e32 v130, 16, v73
	v_and_b32_e32 v131, 0xffff0000, v73
	v_lshlrev_b32_e32 v132, 16, v74
	v_and_b32_e32 v133, 0xffff0000, v74
	v_lshlrev_b32_e32 v134, 16, v75
	v_and_b32_e32 v135, 0xffff0000, v75
	v_lshlrev_b32_e32 v136, 16, v76
	v_and_b32_e32 v137, 0xffff0000, v76
	v_lshlrev_b32_e32 v138, 16, v77
	v_and_b32_e32 v139, 0xffff0000, v77
	v_lshlrev_b32_e32 v140, 16, v78
	v_and_b32_e32 v141, 0xffff0000, v78
	v_lshlrev_b32_e32 v142, 16, v79
	v_and_b32_e32 v143, 0xffff0000, v79
	v_pk_mul_f32 v[144:145], v[128:129], v[128:129]
	v_pk_fma_f32 v[144:145], v[130:131], v[130:131], v[144:145]
	v_pk_fma_f32 v[144:145], v[132:133], v[132:133], v[144:145]
	v_pk_fma_f32 v[144:145], v[134:135], v[134:135], v[144:145]
	v_pk_fma_f32 v[144:145], v[136:137], v[136:137], v[144:145]
	v_pk_fma_f32 v[144:145], v[138:139], v[138:139], v[144:145]
	v_pk_fma_f32 v[144:145], v[140:141], v[140:141], v[144:145]
	v_pk_fma_f32 v[144:145], v[142:143], v[142:143], v[144:145]
	v_add_f32_e32 v144, v144, v145
	s_nop 1
	v_add_f32_dpp v144, v144, v144 quad_perm:[1,0,3,2] row_mask:0xf bank_mask:0xf
	s_nop 1
	v_add_f32_dpp v144, v144, v144 quad_perm:[2,3,0,1] row_mask:0xf bank_mask:0xf
	s_nop 1
	v_add_f32_dpp v144, v144, v144 row_half_mirror row_mask:0xf bank_mask:0xf
	s_nop 1
	v_add_f32_dpp v144, v144, v144 row_mirror row_mask:0xf bank_mask:0xf
	s_nop 0
	v_mov_b32_e32 v145, v144
	s_nop 1
	v_permlane16_swap_b32_e32 v144, v145
	s_nop 0
	v_add_f32_e32 v144, v144, v145
	v_mov_b32_e32 v145, v144
	s_nop 1
	v_permlane32_swap_b32_e32 v144, v145
	s_nop 0
	v_add_f32_e32 v144, v144, v145
	v_fmamk_f32 v144, v144, 0x3a800000, v3
	v_rsq_f32_e32 v144, v144
	s_nop 0
	v_pk_mul_f32 v[128:129], v[128:129], v[144:145] op_sel_hi:[1,0]
	v_pk_mul_f32 v[130:131], v[130:131], v[144:145] op_sel_hi:[1,0]
	v_pk_mul_f32 v[132:133], v[132:133], v[144:145] op_sel_hi:[1,0]
	v_pk_mul_f32 v[134:135], v[134:135], v[144:145] op_sel_hi:[1,0]
	v_pk_mul_f32 v[136:137], v[136:137], v[144:145] op_sel_hi:[1,0]
	v_pk_mul_f32 v[138:139], v[138:139], v[144:145] op_sel_hi:[1,0]
	v_pk_mul_f32 v[140:141], v[140:141], v[144:145] op_sel_hi:[1,0]
	v_pk_mul_f32 v[142:143], v[142:143], v[144:145] op_sel_hi:[1,0]
	v_pk_mul_f32 v[128:129], v[16:17], v[128:129]
	v_pk_mul_f32 v[130:131], v[18:19], v[130:131]
	v_pk_mul_f32 v[132:133], v[20:21], v[132:133]
	v_pk_mul_f32 v[134:135], v[22:23], v[134:135]
	v_pk_mul_f32 v[136:137], v[24:25], v[136:137]
	v_pk_mul_f32 v[138:139], v[26:27], v[138:139]
	v_pk_mul_f32 v[140:141], v[28:29], v[140:141]
	v_pk_mul_f32 v[142:143], v[30:31], v[142:143]
	v_pk_fma_f32 v[128:129], v[32:33], v[128:129], v[48:49]
	v_pk_fma_f32 v[130:131], v[34:35], v[130:131], v[50:51]
	v_pk_fma_f32 v[132:133], v[36:37], v[132:133], v[52:53]
	v_pk_fma_f32 v[134:135], v[38:39], v[134:135], v[54:55]
	v_pk_fma_f32 v[136:137], v[40:41], v[136:137], v[56:57]
	v_pk_fma_f32 v[138:139], v[42:43], v[138:139], v[58:59]
	v_pk_fma_f32 v[140:141], v[44:45], v[140:141], v[60:61]
	v_pk_fma_f32 v[142:143], v[46:47], v[142:143], v[62:63]
	v_cvt_pk_bf16_f32 v148, v128, v129
	v_cvt_pk_bf16_f32 v149, v130, v131
	v_cvt_pk_bf16_f32 v150, v132, v133
	v_cvt_pk_bf16_f32 v151, v134, v135
	v_cvt_pk_bf16_f32 v152, v136, v137
	v_cvt_pk_bf16_f32 v153, v138, v139
	v_cvt_pk_bf16_f32 v154, v140, v141
	v_cvt_pk_bf16_f32 v155, v142, v143
	global_store_dwordx4 v1, v[148:151], s[12:13] offset:2048 sc1
	global_store_dwordx4 v1, v[152:155], s[12:13] offset:3072 sc1
	s_add_u32 s12, s12, 0x1000
	s_addc_u32 s13, s13, 0
	global_load_dwordx4 v[72:75], v1, s[8:9] offset:2048
	global_load_dwordx4 v[76:79], v1, s[8:9] offset:3072
	s_add_u32 s8, s8, 0x1000
	s_addc_u32 s9, s9, 0
	s_waitcnt vmcnt(18)
	v_lshlrev_b32_e32 v128, 16, v80
	v_and_b32_e32 v129, 0xffff0000, v80
	v_lshlrev_b32_e32 v130, 16, v81
	v_and_b32_e32 v131, 0xffff0000, v81
	v_lshlrev_b32_e32 v132, 16, v82
	v_and_b32_e32 v133, 0xffff0000, v82
	v_lshlrev_b32_e32 v134, 16, v83
	v_and_b32_e32 v135, 0xffff0000, v83
	v_lshlrev_b32_e32 v136, 16, v84
	v_and_b32_e32 v137, 0xffff0000, v84
	v_lshlrev_b32_e32 v138, 16, v85
	v_and_b32_e32 v139, 0xffff0000, v85
	v_lshlrev_b32_e32 v140, 16, v86
	v_and_b32_e32 v141, 0xffff0000, v86
	v_lshlrev_b32_e32 v142, 16, v87
	v_and_b32_e32 v143, 0xffff0000, v87
	v_pk_mul_f32 v[144:145], v[128:129], v[128:129]
	v_pk_fma_f32 v[144:145], v[130:131], v[130:131], v[144:145]
	v_pk_fma_f32 v[144:145], v[132:133], v[132:133], v[144:145]
	v_pk_fma_f32 v[144:145], v[134:135], v[134:135], v[144:145]
	v_pk_fma_f32 v[144:145], v[136:137], v[136:137], v[144:145]
	v_pk_fma_f32 v[144:145], v[138:139], v[138:139], v[144:145]
	v_pk_fma_f32 v[144:145], v[140:141], v[140:141], v[144:145]
	v_pk_fma_f32 v[144:145], v[142:143], v[142:143], v[144:145]
	v_add_f32_e32 v144, v144, v145
	s_nop 1
	v_add_f32_dpp v144, v144, v144 quad_perm:[1,0,3,2] row_mask:0xf bank_mask:0xf
	s_nop 1
	v_add_f32_dpp v144, v144, v144 quad_perm:[2,3,0,1] row_mask:0xf bank_mask:0xf
	s_nop 1
	v_add_f32_dpp v144, v144, v144 row_half_mirror row_mask:0xf bank_mask:0xf
	s_nop 1
	v_add_f32_dpp v144, v144, v144 row_mirror row_mask:0xf bank_mask:0xf
	s_nop 0
	v_mov_b32_e32 v145, v144
	s_nop 1
	v_permlane16_swap_b32_e32 v144, v145
	s_nop 0
	v_add_f32_e32 v144, v144, v145
	v_mov_b32_e32 v145, v144
	s_nop 1
	v_permlane32_swap_b32_e32 v144, v145
	s_nop 0
	v_add_f32_e32 v144, v144, v145
	v_fmamk_f32 v144, v144, 0x3a800000, v3
	v_rsq_f32_e32 v144, v144
	s_nop 0
	v_pk_mul_f32 v[128:129], v[128:129], v[144:145] op_sel_hi:[1,0]
	v_pk_mul_f32 v[130:131], v[130:131], v[144:145] op_sel_hi:[1,0]
	v_pk_mul_f32 v[132:133], v[132:133], v[144:145] op_sel_hi:[1,0]
; __device__ __forceinline__ unsigned cvt_pk_bf16(float lo, float hi) { unsigned r; asm("v_cvt_pk_bf16_f32 %0, %1, %2" : "=v"(r) : "v"(lo), "v"(hi)); return r; }
; __device__ __forceinline__ void norm_pass_bf16(const Ctx& X, const bf16_t* xs, const bf16_t* cs, int nrows, const float* gain, const float* modl, int si, bf16_t* HN) {
;     ...
;         for (int j = 0; j < 2; ++j) {
;             v[j][0] = bf2f(q[j].x & 0xffffu); v[j][1] = bf2f(q[j].x >> 16); v[j][2] = bf2f(q[j].y & 0xffffu); v[j][3] = bf2f(q[j].y >> 16);
;             v[j][4] = bf2f(q[j].z & 0xffffu); v[j][5] = bf2f(q[j].z >> 16); v[j][6] = bf2f(q[j].w & 0xffffu); v[j][7] = bf2f(q[j].w >> 16);
; #pragma unroll
;             for (int e = 0; e < 8; ++e) s += v[j][e] * v[j][e]; }
;         const float rstd = rsqrtf(wave_sum(s) * (1.0f / 1024.0f) + 1e-6f);
; #pragma unroll
;         for (int j = 0; j < 2; ++j) { const int c = (X.lane + 64 * j) * 8; float o[8];
; #pragma unroll
;             for (int h = 0; h < 2; ++h) { const f32x4 gn = *(const f32x4*)(gain + c + 4 * h), a = *(const f32x4*)(scl + c + 4 * h), b = *(const f32x4*)(sh + c + 4 * h);
; #pragma unroll
;                 for (int e = 0; e < 4; ++e) o[4 * h + e] = v[j][4 * h + e] * rstd * gn[e] * (a[e] + 1.0f) + b[e]; }
;             u32x4 w; w.x = cvt_pk_bf16(o[0], o[1]); w.y = cvt_pk_bf16(o[2], o[3]); w.z = cvt_pk_bf16(o[4], o[5]); w.w = cvt_pk_bf16(o[6], o[7]); *(u32x4*)(HN + (size_t)r * D + c) = w; }
	v_pk_mul_f32 v[134:135], v[134:135], v[144:145] op_sel_hi:[1,0]
	v_pk_mul_f32 v[136:137], v[136:137], v[144:145] op_sel_hi:[1,0]
	v_pk_mul_f32 v[138:139], v[138:139], v[144:145] op_sel_hi:[1,0]
	v_pk_mul_f32 v[140:141], v[140:141], v[144:145] op_sel_hi:[1,0]
	v_pk_mul_f32 v[142:143], v[142:143], v[144:145] op_sel_hi:[1,0]
	v_pk_mul_f32 v[128:129], v[16:17], v[128:129]
	v_pk_mul_f32 v[130:131], v[18:19], v[130:131]
	v_pk_mul_f32 v[132:133], v[20:21], v[132:133]
	v_pk_mul_f32 v[134:135], v[22:23], v[134:135]
	v_pk_mul_f32 v[136:137], v[24:25], v[136:137]
	v_pk_mul_f32 v[138:139], v[26:27], v[138:139]
	v_pk_mul_f32 v[140:141], v[28:29], v[140:141]
	v_pk_mul_f32 v[142:143], v[30:31], v[142:143]
	v_pk_fma_f32 v[128:129], v[32:33], v[128:129], v[48:49]
	v_pk_fma_f32 v[130:131], v[34:35], v[130:131], v[50:51]
	v_pk_fma_f32 v[132:133], v[36:37], v[132:133], v[52:53]
	v_pk_fma_f32 v[134:135], v[38:39], v[134:135], v[54:55]
	v_pk_fma_f32 v[136:137], v[40:41], v[136:137], v[56:57]
	v_pk_fma_f32 v[138:139], v[42:43], v[138:139], v[58:59]
	v_pk_fma_f32 v[140:141], v[44:45], v[140:141], v[60:61]
	v_pk_fma_f32 v[142:143], v[46:47], v[142:143], v[62:63]
	v_cvt_pk_bf16_f32 v148, v128, v129
	v_cvt_pk_bf16_f32 v149, v130, v131
	v_cvt_pk_bf16_f32 v150, v132, v133
	v_cvt_pk_bf16_f32 v151, v134, v135
	v_cvt_pk_bf16_f32 v152, v136, v137
	v_cvt_pk_bf16_f32 v153, v138, v139
	v_cvt_pk_bf16_f32 v154, v140, v141
	v_cvt_pk_bf16_f32 v155, v142, v143
	global_store_dwordx4 v1, v[148:151], s[12:13] sc1
	global_store_dwordx4 v1, v[152:155], s[12:13] offset:1024 sc1
	global_load_dwordx4 v[80:83], v1, s[8:9]
	global_load_dwordx4 v[84:87], v1, s[8:9] offset:1024
	s_waitcnt vmcnt(20)
	v_lshlrev_b32_e32 v128, 16, v88
	v_and_b32_e32 v129, 0xffff0000, v88
	v_lshlrev_b32_e32 v130, 16, v89
	v_and_b32_e32 v131, 0xffff0000, v89
	v_lshlrev_b32_e32 v132, 16, v90
	v_and_b32_e32 v133, 0xffff0000, v90
	v_lshlrev_b32_e32 v134, 16, v91
	v_and_b32_e32 v135, 0xffff0000, v91
	v_lshlrev_b32_e32 v136, 16, v92
	v_and_b32_e32 v137, 0xffff0000, v92
	v_lshlrev_b32_e32 v138, 16, v93
	v_and_b32_e32 v139, 0xffff0000, v93
	v_lshlrev_b32_e32 v140, 16, v94
	v_and_b32_e32 v141, 0xffff0000, v94
	v_lshlrev_b32_e32 v142, 16, v95
	v_and_b32_e32 v143, 0xffff0000, v95
	v_pk_mul_f32 v[144:145], v[128:129], v[128:129]
	v_pk_fma_f32 v[144:145], v[130:131], v[130:131], v[144:145]
	v_pk_fma_f32 v[144:145], v[132:133], v[132:133], v[144:145]
	v_pk_fma_f32 v[144:145], v[134:135], v[134:135], v[144:145]
	v_pk_fma_f32 v[144:145], v[136:137], v[136:137], v[144:145]
	v_pk_fma_f32 v[144:145], v[138:139], v[138:139], v[144:145]
	v_pk_fma_f32 v[144:145], v[140:141], v[140:141], v[144:145]
	v_pk_fma_f32 v[144:145], v[142:143], v[142:143], v[144:145]
	v_add_f32_e32 v144, v144, v145
	s_nop 1
	v_add_f32_dpp v144, v144, v144 quad_perm:[1,0,3,2] row_mask:0xf bank_mask:0xf
	s_nop 1
	v_add_f32_dpp v144, v144, v144 quad_perm:[2,3,0,1] row_mask:0xf bank_mask:0xf
	s_nop 1
	v_add_f32_dpp v144, v144, v144 row_half_mirror row_mask:0xf bank_mask:0xf
	s_nop 1
	v_add_f32_dpp v144, v144, v144 row_mirror row_mask:0xf bank_mask:0xf
	s_nop 0
	v_mov_b32_e32 v145, v144
	s_nop 1
	v_permlane16_swap_b32_e32 v144, v145
	s_nop 0
	v_add_f32_e32 v144, v144, v145
	v_mov_b32_e32 v145, v144
	s_nop 1
	v_permlane32_swap_b32_e32 v144, v145
	s_nop 0
	v_add_f32_e32 v144, v144, v145
	v_fmamk_f32 v144, v144, 0x3a800000, v3
	v_rsq_f32_e32 v144, v144
	s_nop 0
	v_pk_mul_f32 v[128:129], v[128:129], v[144:145] op_sel_hi:[1,0]
	v_pk_mul_f32 v[130:131], v[130:131], v[144:145] op_sel_hi:[1,0]
	v_pk_mul_f32 v[132:133], v[132:133], v[144:145] op_sel_hi:[1,0]
	v_pk_mul_f32 v[134:135], v[134:135], v[144:145] op_sel_hi:[1,0]
	v_pk_mul_f32 v[136:137], v[136:137], v[144:145] op_sel_hi:[1,0]
	v_pk_mul_f32 v[138:139], v[138:139], v[144:145] op_sel_hi:[1,0]
	v_pk_mul_f32 v[140:141], v[140:141], v[144:145] op_sel_hi:[1,0]
	v_pk_mul_f32 v[142:143], v[142:143], v[144:145] op_sel_hi:[1,0]
	v_pk_mul_f32 v[128:129], v[16:17], v[128:129]
	v_pk_mul_f32 v[130:131], v[18:19], v[130:131]
	v_pk_mul_f32 v[132:133], v[20:21], v[132:133]
	v_pk_mul_f32 v[134:135], v[22:23], v[134:135]
	v_pk_mul_f32 v[136:137], v[24:25], v[136:137]
	v_pk_mul_f32 v[138:139], v[26:27], v[138:139]
	v_pk_mul_f32 v[140:141], v[28:29], v[140:141]
	v_pk_mul_f32 v[142:143], v[30:31], v[142:143]
	v_pk_fma_f32 v[128:129], v[32:33], v[128:129], v[48:49]
	v_pk_fma_f32 v[130:131], v[34:35], v[130:131], v[50:51]
	v_pk_fma_f32 v[132:133], v[36:37], v[132:133], v[52:53]
	v_pk_fma_f32 v[134:135], v[38:39], v[134:135], v[54:55]
	v_pk_fma_f32 v[136:137], v[40:41], v[136:137], v[56:57]
	v_pk_fma_f32 v[138:139], v[42:43], v[138:139], v[58:59]
	v_pk_fma_f32 v[140:141], v[44:45], v[140:141], v[60:61]
	v_pk_fma_f32 v[142:143], v[46:47], v[142:143], v[62:63]
	v_cvt_pk_bf16_f32 v148, v128, v129
	v_cvt_pk_bf16_f32 v149, v130, v131
	v_cvt_pk_bf16_f32 v150, v132, v133
	v_cvt_pk_bf16_f32 v151, v134, v135
	v_cvt_pk_bf16_f32 v152, v136, v137
	v_cvt_pk_bf16_f32 v153, v138, v139
	v_cvt_pk_bf16_f32 v154, v140, v141
	v_cvt_pk_bf16_f32 v155, v142, v143
	global_store_dwordx4 v1, v[148:151], s[12:13] offset:2048 sc1
	global_store_dwordx4 v1, v[152:155], s[12:13] offset:3072 sc1
	s_add_u32 s12, s12, 0x1000
	s_addc_u32 s13, s13, 0
	global_load_dwordx4 v[88:91], v1, s[8:9] offset:2048
	global_load_dwordx4 v[92:95], v1, s[8:9] offset:3072
	s_add_u32 s8, s8, 0x1000
	s_addc_u32 s9, s9, 0
	s_waitcnt vmcnt(22)
; __device__ __forceinline__ unsigned cvt_pk_bf16(float lo, float hi) { unsigned r; asm("v_cvt_pk_bf16_f32 %0, %1, %2" : "=v"(r) : "v"(lo), "v"(hi)); return r; }
; __device__ __forceinline__ void norm_pass_bf16(const Ctx& X, const bf16_t* xs, const bf16_t* cs, int nrows, const float* gain, const float* modl, int si, bf16_t* HN) {
;     ...
;         for (int j = 0; j < 2; ++j) {
;             v[j][0] = bf2f(q[j].x & 0xffffu); v[j][1] = bf2f(q[j].x >> 16); v[j][2] = bf2f(q[j].y & 0xffffu); v[j][3] = bf2f(q[j].y >> 16);
;             v[j][4] = bf2f(q[j].z & 0xffffu); v[j][5] = bf2f(q[j].z >> 16); v[j][6] = bf2f(q[j].w & 0xffffu); v[j][7] = bf2f(q[j].w >> 16);
; #pragma unroll
;             for (int e = 0; e < 8; ++e) s += v[j][e] * v[j][e]; }
;         const float rstd = rsqrtf(wave_sum(s) * (1.0f / 1024.0f) + 1e-6f);
; #pragma unroll
;         for (int j = 0; j < 2; ++j) { const int c = (X.lane + 64 * j) * 8; float o[8];
; #pragma unroll
;             for (int h = 0; h < 2; ++h) { const f32x4 gn = *(const f32x4*)(gain + c + 4 * h), a = *(const f32x4*)(scl + c + 4 * h), b = *(const f32x4*)(sh + c + 4 * h);
; #pragma unroll
;                 for (int e = 0; e < 4; ++e) o[4 * h + e] = v[j][4 * h + e] * rstd * gn[e] * (a[e] + 1.0f) + b[e]; }
;             u32x4 w; w.x = cvt_pk_bf16(o[0], o[1]); w.y = cvt_pk_bf16(o[2], o[3]); w.z = cvt_pk_bf16(o[4], o[5]); w.w = cvt_pk_bf16(o[6], o[7]); *(u32x4*)(HN + (size_t)r * D + c) = w; }
	v_lshlrev_b32_e32 v128, 16, v96
	v_and_b32_e32 v129, 0xffff0000, v96
	v_lshlrev_b32_e32 v130, 16, v97
	v_and_b32_e32 v131, 0xffff0000, v97
	v_lshlrev_b32_e32 v132, 16, v98
	v_and_b32_e32 v133, 0xffff0000, v98
	v_lshlrev_b32_e32 v134, 16, v99
	v_and_b32_e32 v135, 0xffff0000, v99
	v_lshlrev_b32_e32 v136, 16, v100
	v_and_b32_e32 v137, 0xffff0000, v100
	v_lshlrev_b32_e32 v138, 16, v101
	v_and_b32_e32 v139, 0xffff0000, v101
	v_lshlrev_b32_e32 v140, 16, v102
	v_and_b32_e32 v141, 0xffff0000, v102
	v_lshlrev_b32_e32 v142, 16, v103
	v_and_b32_e32 v143, 0xffff0000, v103
	v_pk_mul_f32 v[144:145], v[128:129], v[128:129]
	v_pk_fma_f32 v[144:145], v[130:131], v[130:131], v[144:145]
	v_pk_fma_f32 v[144:145], v[132:133], v[132:133], v[144:145]
	v_pk_fma_f32 v[144:145], v[134:135], v[134:135], v[144:145]
	v_pk_fma_f32 v[144:145], v[136:137], v[136:137], v[144:145]
	v_pk_fma_f32 v[144:145], v[138:139], v[138:139], v[144:145]
	v_pk_fma_f32 v[144:145], v[140:141], v[140:141], v[144:145]
	v_pk_fma_f32 v[144:145], v[142:143], v[142:143], v[144:145]
	v_add_f32_e32 v144, v144, v145
	s_nop 1
	v_add_f32_dpp v144, v144, v144 quad_perm:[1,0,3,2] row_mask:0xf bank_mask:0xf
	s_nop 1
	v_add_f32_dpp v144, v144, v144 quad_perm:[2,3,0,1] row_mask:0xf bank_mask:0xf
	s_nop 1
	v_add_f32_dpp v144, v144, v144 row_half_mirror row_mask:0xf bank_mask:0xf
	s_nop 1
	v_add_f32_dpp v144, v144, v144 row_mirror row_mask:0xf bank_mask:0xf
	s_nop 0
	v_mov_b32_e32 v145, v144
	s_nop 1
	v_permlane16_swap_b32_e32 v144, v145
	s_nop 0
	v_add_f32_e32 v144, v144, v145
	v_mov_b32_e32 v145, v144
	s_nop 1
	v_permlane32_swap_b32_e32 v144, v145
	s_nop 0
	v_add_f32_e32 v144, v144, v145
	v_fmamk_f32 v144, v144, 0x3a800000, v3
	v_rsq_f32_e32 v144, v144
	s_nop 0
	v_pk_mul_f32 v[128:129], v[128:129], v[144:145] op_sel_hi:[1,0]
	v_pk_mul_f32 v[130:131], v[130:131], v[144:145] op_sel_hi:[1,0]
	v_pk_mul_f32 v[132:133], v[132:133], v[144:145] op_sel_hi:[1,0]
	v_pk_mul_f32 v[134:135], v[134:135], v[144:145] op_sel_hi:[1,0]
	v_pk_mul_f32 v[136:137], v[136:137], v[144:145] op_sel_hi:[1,0]
	v_pk_mul_f32 v[138:139], v[138:139], v[144:145] op_sel_hi:[1,0]
	v_pk_mul_f32 v[140:141], v[140:141], v[144:145] op_sel_hi:[1,0]
	v_pk_mul_f32 v[142:143], v[142:143], v[144:145] op_sel_hi:[1,0]
	v_pk_mul_f32 v[128:129], v[16:17], v[128:129]
	v_pk_mul_f32 v[130:131], v[18:19], v[130:131]
	v_pk_mul_f32 v[132:133], v[20:21], v[132:133]
	v_pk_mul_f32 v[134:135], v[22:23], v[134:135]
	v_pk_mul_f32 v[136:137], v[24:25], v[136:137]
	v_pk_mul_f32 v[138:139], v[26:27], v[138:139]
	v_pk_mul_f32 v[140:141], v[28:29], v[140:141]
	v_pk_mul_f32 v[142:143], v[30:31], v[142:143]
	v_pk_fma_f32 v[128:129], v[32:33], v[128:129], v[48:49]
	v_pk_fma_f32 v[130:131], v[34:35], v[130:131], v[50:51]
	v_pk_fma_f32 v[132:133], v[36:37], v[132:133], v[52:53]
	v_pk_fma_f32 v[134:135], v[38:39], v[134:135], v[54:55]
	v_pk_fma_f32 v[136:137], v[40:41], v[136:137], v[56:57]
	v_pk_fma_f32 v[138:139], v[42:43], v[138:139], v[58:59]
	v_pk_fma_f32 v[140:141], v[44:45], v[140:141], v[60:61]
	v_pk_fma_f32 v[142:143], v[46:47], v[142:143], v[62:63]
	v_cvt_pk_bf16_f32 v148, v128, v129
	v_cvt_pk_bf16_f32 v149, v130, v131
	v_cvt_pk_bf16_f32 v150, v132, v133
	v_cvt_pk_bf16_f32 v151, v134, v135
	v_cvt_pk_bf16_f32 v152, v136, v137
	v_cvt_pk_bf16_f32 v153, v138, v139
	v_cvt_pk_bf16_f32 v154, v140, v141
	v_cvt_pk_bf16_f32 v155, v142, v143
	global_store_dwordx4 v1, v[148:151], s[12:13] sc1
	global_store_dwordx4 v1, v[152:155], s[12:13] offset:1024 sc1
	global_load_dwordx4 v[96:99], v1, s[8:9]
	global_load_dwordx4 v[100:103], v1, s[8:9] offset:1024
	s_waitcnt vmcnt(24)
	v_lshlrev_b32_e32 v128, 16, v104
	v_and_b32_e32 v129, 0xffff0000, v104
	v_lshlrev_b32_e32 v130, 16, v105
	v_and_b32_e32 v131, 0xffff0000, v105
	v_lshlrev_b32_e32 v132, 16, v106
	v_and_b32_e32 v133, 0xffff0000, v106
	v_lshlrev_b32_e32 v134, 16, v107
	v_and_b32_e32 v135, 0xffff0000, v107
	v_lshlrev_b32_e32 v136, 16, v108
	v_and_b32_e32 v137, 0xffff0000, v108
	v_lshlrev_b32_e32 v138, 16, v109
	v_and_b32_e32 v139, 0xffff0000, v109
	v_lshlrev_b32_e32 v140, 16, v110
	v_and_b32_e32 v141, 0xffff0000, v110
	v_lshlrev_b32_e32 v142, 16, v111
	v_and_b32_e32 v143, 0xffff0000, v111
	v_pk_mul_f32 v[144:145], v[128:129], v[128:129]
	v_pk_fma_f32 v[144:145], v[130:131], v[130:131], v[144:145]
	v_pk_fma_f32 v[144:145], v[132:133], v[132:133], v[144:145]
	v_pk_fma_f32 v[144:145], v[134:135], v[134:135], v[144:145]
	v_pk_fma_f32 v[144:145], v[136:137], v[136:137], v[144:145]
	v_pk_fma_f32 v[144:145], v[138:139], v[138:139], v[144:145]
	v_pk_fma_f32 v[144:145], v[140:141], v[140:141], v[144:145]
	v_pk_fma_f32 v[144:145], v[142:143], v[142:143], v[144:145]
	v_add_f32_e32 v144, v144, v145
	s_nop 1
	v_add_f32_dpp v144, v144, v144 quad_perm:[1,0,3,2] row_mask:0xf bank_mask:0xf
	s_nop 1
	v_add_f32_dpp v144, v144, v144 quad_perm:[2,3,0,1] row_mask:0xf bank_mask:0xf
	s_nop 1
	v_add_f32_dpp v144, v144, v144 row_half_mirror row_mask:0xf bank_mask:0xf
	s_nop 1
	v_add_f32_dpp v144, v144, v144 row_mirror row_mask:0xf bank_mask:0xf
	s_nop 0
	v_mov_b32_e32 v145, v144
	s_nop 1
	v_permlane16_swap_b32_e32 v144, v145
	s_nop 0
	v_add_f32_e32 v144, v144, v145
	v_mov_b32_e32 v145, v144
	s_nop 1
	v_permlane32_swap_b32_e32 v144, v145
	s_nop 0
	v_add_f32_e32 v144, v144, v145
	v_fmamk_f32 v144, v144, 0x3a800000, v3
	v_rsq_f32_e32 v144, v144
	s_nop 0
	v_pk_mul_f32 v[128:129], v[128:129], v[144:145] op_sel_hi:[1,0]
	v_pk_mul_f32 v[130:131], v[130:131], v[144:145] op_sel_hi:[1,0]
	v_pk_mul_f32 v[132:133], v[132:133], v[144:145] op_sel_hi:[1,0]
	v_pk_mul_f32 v[134:135], v[134:135], v[144:145] op_sel_hi:[1,0]
	v_pk_mul_f32 v[136:137], v[136:137], v[144:145] op_sel_hi:[1,0]
; __device__ __forceinline__ unsigned cvt_pk_bf16(float lo, float hi) { unsigned r; asm("v_cvt_pk_bf16_f32 %0, %1, %2" : "=v"(r) : "v"(lo), "v"(hi)); return r; }
; __device__ __forceinline__ void norm_pass_bf16(const Ctx& X, const bf16_t* xs, const bf16_t* cs, int nrows, const float* gain, const float* modl, int si, bf16_t* HN) {
;     ...
;         for (int j = 0; j < 2; ++j) {
;             v[j][0] = bf2f(q[j].x & 0xffffu); v[j][1] = bf2f(q[j].x >> 16); v[j][2] = bf2f(q[j].y & 0xffffu); v[j][3] = bf2f(q[j].y >> 16);
;             v[j][4] = bf2f(q[j].z & 0xffffu); v[j][5] = bf2f(q[j].z >> 16); v[j][6] = bf2f(q[j].w & 0xffffu); v[j][7] = bf2f(q[j].w >> 16);
; #pragma unroll
;             for (int e = 0; e < 8; ++e) s += v[j][e] * v[j][e]; }
;         const float rstd = rsqrtf(wave_sum(s) * (1.0f / 1024.0f) + 1e-6f);
; #pragma unroll
;         for (int j = 0; j < 2; ++j) { const int c = (X.lane + 64 * j) * 8; float o[8];
; #pragma unroll
;             for (int h = 0; h < 2; ++h) { const f32x4 gn = *(const f32x4*)(gain + c + 4 * h), a = *(const f32x4*)(scl + c + 4 * h), b = *(const f32x4*)(sh + c + 4 * h);
; #pragma unroll
;                 for (int e = 0; e < 4; ++e) o[4 * h + e] = v[j][4 * h + e] * rstd * gn[e] * (a[e] + 1.0f) + b[e]; }
;             u32x4 w; w.x = cvt_pk_bf16(o[0], o[1]); w.y = cvt_pk_bf16(o[2], o[3]); w.z = cvt_pk_bf16(o[4], o[5]); w.w = cvt_pk_bf16(o[6], o[7]); *(u32x4*)(HN + (size_t)r * D + c) = w; }
	v_pk_mul_f32 v[138:139], v[138:139], v[144:145] op_sel_hi:[1,0]
	v_pk_mul_f32 v[140:141], v[140:141], v[144:145] op_sel_hi:[1,0]
	v_pk_mul_f32 v[142:143], v[142:143], v[144:145] op_sel_hi:[1,0]
	v_pk_mul_f32 v[128:129], v[16:17], v[128:129]
	v_pk_mul_f32 v[130:131], v[18:19], v[130:131]
	v_pk_mul_f32 v[132:133], v[20:21], v[132:133]
	v_pk_mul_f32 v[134:135], v[22:23], v[134:135]
	v_pk_mul_f32 v[136:137], v[24:25], v[136:137]
	v_pk_mul_f32 v[138:139], v[26:27], v[138:139]
	v_pk_mul_f32 v[140:141], v[28:29], v[140:141]
	v_pk_mul_f32 v[142:143], v[30:31], v[142:143]
	v_pk_fma_f32 v[128:129], v[32:33], v[128:129], v[48:49]
	v_pk_fma_f32 v[130:131], v[34:35], v[130:131], v[50:51]
	v_pk_fma_f32 v[132:133], v[36:37], v[132:133], v[52:53]
	v_pk_fma_f32 v[134:135], v[38:39], v[134:135], v[54:55]
	v_pk_fma_f32 v[136:137], v[40:41], v[136:137], v[56:57]
	v_pk_fma_f32 v[138:139], v[42:43], v[138:139], v[58:59]
	v_pk_fma_f32 v[140:141], v[44:45], v[140:141], v[60:61]
	v_pk_fma_f32 v[142:143], v[46:47], v[142:143], v[62:63]
	v_cvt_pk_bf16_f32 v148, v128, v129
	v_cvt_pk_bf16_f32 v149, v130, v131
	v_cvt_pk_bf16_f32 v150, v132, v133
	v_cvt_pk_bf16_f32 v151, v134, v135
	v_cvt_pk_bf16_f32 v152, v136, v137
	v_cvt_pk_bf16_f32 v153, v138, v139
	v_cvt_pk_bf16_f32 v154, v140, v141
	v_cvt_pk_bf16_f32 v155, v142, v143
	global_store_dwordx4 v1, v[148:151], s[12:13] offset:2048 sc1
	global_store_dwordx4 v1, v[152:155], s[12:13] offset:3072 sc1
	s_add_u32 s12, s12, 0x1000
	s_addc_u32 s13, s13, 0
	global_load_dwordx4 v[104:107], v1, s[8:9] offset:2048
	global_load_dwordx4 v[108:111], v1, s[8:9] offset:3072
	s_add_u32 s8, s8, 0x1000
	s_addc_u32 s9, s9, 0
	s_waitcnt vmcnt(26)
	v_lshlrev_b32_e32 v128, 16, v112
	v_and_b32_e32 v129, 0xffff0000, v112
	v_lshlrev_b32_e32 v130, 16, v113
	v_and_b32_e32 v131, 0xffff0000, v113
	v_lshlrev_b32_e32 v132, 16, v114
	v_and_b32_e32 v133, 0xffff0000, v114
	v_lshlrev_b32_e32 v134, 16, v115
	v_and_b32_e32 v135, 0xffff0000, v115
	v_lshlrev_b32_e32 v136, 16, v116
	v_and_b32_e32 v137, 0xffff0000, v116
	v_lshlrev_b32_e32 v138, 16, v117
	v_and_b32_e32 v139, 0xffff0000, v117
	v_lshlrev_b32_e32 v140, 16, v118
	v_and_b32_e32 v141, 0xffff0000, v118
	v_lshlrev_b32_e32 v142, 16, v119
	v_and_b32_e32 v143, 0xffff0000, v119
	v_pk_mul_f32 v[144:145], v[128:129], v[128:129]
	v_pk_fma_f32 v[144:145], v[130:131], v[130:131], v[144:145]
	v_pk_fma_f32 v[144:145], v[132:133], v[132:133], v[144:145]
	v_pk_fma_f32 v[144:145], v[134:135], v[134:135], v[144:145]
	v_pk_fma_f32 v[144:145], v[136:137], v[136:137], v[144:145]
	v_pk_fma_f32 v[144:145], v[138:139], v[138:139], v[144:145]
	v_pk_fma_f32 v[144:145], v[140:141], v[140:141], v[144:145]
	v_pk_fma_f32 v[144:145], v[142:143], v[142:143], v[144:145]
	v_add_f32_e32 v144, v144, v145
	s_nop 1
	v_add_f32_dpp v144, v144, v144 quad_perm:[1,0,3,2] row_mask:0xf bank_mask:0xf
	s_nop 1
	v_add_f32_dpp v144, v144, v144 quad_perm:[2,3,0,1] row_mask:0xf bank_mask:0xf
	s_nop 1
	v_add_f32_dpp v144, v144, v144 row_half_mirror row_mask:0xf bank_mask:0xf
	s_nop 1
	v_add_f32_dpp v144, v144, v144 row_mirror row_mask:0xf bank_mask:0xf
	s_nop 0
	v_mov_b32_e32 v145, v144
	s_nop 1
	v_permlane16_swap_b32_e32 v144, v145
	s_nop 0
	v_add_f32_e32 v144, v144, v145
	v_mov_b32_e32 v145, v144
	s_nop 1
	v_permlane32_swap_b32_e32 v144, v145
	s_nop 0
	v_add_f32_e32 v144, v144, v145
	v_fmamk_f32 v144, v144, 0x3a800000, v3
	v_rsq_f32_e32 v144, v144
	s_nop 0
	v_pk_mul_f32 v[128:129], v[128:129], v[144:145] op_sel_hi:[1,0]
	v_pk_mul_f32 v[130:131], v[130:131], v[144:145] op_sel_hi:[1,0]
	v_pk_mul_f32 v[132:133], v[132:133], v[144:145] op_sel_hi:[1,0]
	v_pk_mul_f32 v[134:135], v[134:135], v[144:145] op_sel_hi:[1,0]
	v_pk_mul_f32 v[136:137], v[136:137], v[144:145] op_sel_hi:[1,0]
	v_pk_mul_f32 v[138:139], v[138:139], v[144:145] op_sel_hi:[1,0]
	v_pk_mul_f32 v[140:141], v[140:141], v[144:145] op_sel_hi:[1,0]
	v_pk_mul_f32 v[142:143], v[142:143], v[144:145] op_sel_hi:[1,0]
	v_pk_mul_f32 v[128:129], v[16:17], v[128:129]
	v_pk_mul_f32 v[130:131], v[18:19], v[130:131]
	v_pk_mul_f32 v[132:133], v[20:21], v[132:133]
	v_pk_mul_f32 v[134:135], v[22:23], v[134:135]
	v_pk_mul_f32 v[136:137], v[24:25], v[136:137]
	v_pk_mul_f32 v[138:139], v[26:27], v[138:139]
	v_pk_mul_f32 v[140:141], v[28:29], v[140:141]
	v_pk_mul_f32 v[142:143], v[30:31], v[142:143]
	v_pk_fma_f32 v[128:129], v[32:33], v[128:129], v[48:49]
	v_pk_fma_f32 v[130:131], v[34:35], v[130:131], v[50:51]
	v_pk_fma_f32 v[132:133], v[36:37], v[132:133], v[52:53]
	v_pk_fma_f32 v[134:135], v[38:39], v[134:135], v[54:55]
	v_pk_fma_f32 v[136:137], v[40:41], v[136:137], v[56:57]
	v_pk_fma_f32 v[138:139], v[42:43], v[138:139], v[58:59]
	v_pk_fma_f32 v[140:141], v[44:45], v[140:141], v[60:61]
	v_pk_fma_f32 v[142:143], v[46:47], v[142:143], v[62:63]
	v_cvt_pk_bf16_f32 v148, v128, v129
	v_cvt_pk_bf16_f32 v149, v130, v131
	v_cvt_pk_bf16_f32 v150, v132, v133
	v_cvt_pk_bf16_f32 v151, v134, v135
	v_cvt_pk_bf16_f32 v152, v136, v137
	v_cvt_pk_bf16_f32 v153, v138, v139
	v_cvt_pk_bf16_f32 v154, v140, v141
	v_cvt_pk_bf16_f32 v155, v142, v143
	global_store_dwordx4 v1, v[148:151], s[12:13] sc1
	global_store_dwordx4 v1, v[152:155], s[12:13] offset:1024 sc1
	global_load_dwordx4 v[112:115], v1, s[8:9]
	global_load_dwordx4 v[116:119], v1, s[8:9] offset:1024
	s_waitcnt vmcnt(28)
; __device__ __forceinline__ unsigned cvt_pk_bf16(float lo, float hi) { unsigned r; asm("v_cvt_pk_bf16_f32 %0, %1, %2" : "=v"(r) : "v"(lo), "v"(hi)); return r; }
; __device__ __forceinline__ void norm_pass_bf16(const Ctx& X, const bf16_t* xs, const bf16_t* cs, int nrows, const float* gain, const float* modl, int si, bf16_t* HN) {
;     ...
;         for (int j = 0; j < 2; ++j) {
;             v[j][0] = bf2f(q[j].x & 0xffffu); v[j][1] = bf2f(q[j].x >> 16); v[j][2] = bf2f(q[j].y & 0xffffu); v[j][3] = bf2f(q[j].y >> 16);
;             v[j][4] = bf2f(q[j].z & 0xffffu); v[j][5] = bf2f(q[j].z >> 16); v[j][6] = bf2f(q[j].w & 0xffffu); v[j][7] = bf2f(q[j].w >> 16);
; #pragma unroll
;             for (int e = 0; e < 8; ++e) s += v[j][e] * v[j][e]; }
;         const float rstd = rsqrtf(wave_sum(s) * (1.0f / 1024.0f) + 1e-6f);
; #pragma unroll
;         for (int j = 0; j < 2; ++j) { const int c = (X.lane + 64 * j) * 8; float o[8];
; #pragma unroll
;             for (int h = 0; h < 2; ++h) { const f32x4 gn = *(const f32x4*)(gain + c + 4 * h), a = *(const f32x4*)(scl + c + 4 * h), b = *(const f32x4*)(sh + c + 4 * h);
; #pragma unroll
;                 for (int e = 0; e < 4; ++e) o[4 * h + e] = v[j][4 * h + e] * rstd * gn[e] * (a[e] + 1.0f) + b[e]; }
;             u32x4 w; w.x = cvt_pk_bf16(o[0], o[1]); w.y = cvt_pk_bf16(o[2], o[3]); w.z = cvt_pk_bf16(o[4], o[5]); w.w = cvt_pk_bf16(o[6], o[7]); *(u32x4*)(HN + (size_t)r * D + c) = w; }
	v_lshlrev_b32_e32 v128, 16, v120
	v_and_b32_e32 v129, 0xffff0000, v120
	v_lshlrev_b32_e32 v130, 16, v121
	v_and_b32_e32 v131, 0xffff0000, v121
	v_lshlrev_b32_e32 v132, 16, v122
	v_and_b32_e32 v133, 0xffff0000, v122
	v_lshlrev_b32_e32 v134, 16, v123
	v_and_b32_e32 v135, 0xffff0000, v123
	v_lshlrev_b32_e32 v136, 16, v124
	v_and_b32_e32 v137, 0xffff0000, v124
	v_lshlrev_b32_e32 v138, 16, v125
	v_and_b32_e32 v139, 0xffff0000, v125
	v_lshlrev_b32_e32 v140, 16, v126
	v_and_b32_e32 v141, 0xffff0000, v126
	v_lshlrev_b32_e32 v142, 16, v127
	v_and_b32_e32 v143, 0xffff0000, v127
	v_pk_mul_f32 v[144:145], v[128:129], v[128:129]
	v_pk_fma_f32 v[144:145], v[130:131], v[130:131], v[144:145]
	v_pk_fma_f32 v[144:145], v[132:133], v[132:133], v[144:145]
	v_pk_fma_f32 v[144:145], v[134:135], v[134:135], v[144:145]
	v_pk_fma_f32 v[144:145], v[136:137], v[136:137], v[144:145]
	v_pk_fma_f32 v[144:145], v[138:139], v[138:139], v[144:145]
	v_pk_fma_f32 v[144:145], v[140:141], v[140:141], v[144:145]
	v_pk_fma_f32 v[144:145], v[142:143], v[142:143], v[144:145]
	v_add_f32_e32 v144, v144, v145
	s_nop 1
	v_add_f32_dpp v144, v144, v144 quad_perm:[1,0,3,2] row_mask:0xf bank_mask:0xf
	s_nop 1
	v_add_f32_dpp v144, v144, v144 quad_perm:[2,3,0,1] row_mask:0xf bank_mask:0xf
	s_nop 1
	v_add_f32_dpp v144, v144, v144 row_half_mirror row_mask:0xf bank_mask:0xf
	s_nop 1
	v_add_f32_dpp v144, v144, v144 row_mirror row_mask:0xf bank_mask:0xf
	s_nop 0
	v_mov_b32_e32 v145, v144
	s_nop 1
	v_permlane16_swap_b32_e32 v144, v145
	s_nop 0
	v_add_f32_e32 v144, v144, v145
	v_mov_b32_e32 v145, v144
	s_nop 1
	v_permlane32_swap_b32_e32 v144, v145
	s_nop 0
	v_add_f32_e32 v144, v144, v145
	v_fmamk_f32 v144, v144, 0x3a800000, v3
	v_rsq_f32_e32 v144, v144
	s_nop 0
	v_pk_mul_f32 v[128:129], v[128:129], v[144:145] op_sel_hi:[1,0]
	v_pk_mul_f32 v[130:131], v[130:131], v[144:145] op_sel_hi:[1,0]
	v_pk_mul_f32 v[132:133], v[132:133], v[144:145] op_sel_hi:[1,0]
	v_pk_mul_f32 v[134:135], v[134:135], v[144:145] op_sel_hi:[1,0]
	v_pk_mul_f32 v[136:137], v[136:137], v[144:145] op_sel_hi:[1,0]
	v_pk_mul_f32 v[138:139], v[138:139], v[144:145] op_sel_hi:[1,0]
	v_pk_mul_f32 v[140:141], v[140:141], v[144:145] op_sel_hi:[1,0]
	v_pk_mul_f32 v[142:143], v[142:143], v[144:145] op_sel_hi:[1,0]
	v_pk_mul_f32 v[128:129], v[16:17], v[128:129]
	v_pk_mul_f32 v[130:131], v[18:19], v[130:131]
	v_pk_mul_f32 v[132:133], v[20:21], v[132:133]
	v_pk_mul_f32 v[134:135], v[22:23], v[134:135]
	v_pk_mul_f32 v[136:137], v[24:25], v[136:137]
	v_pk_mul_f32 v[138:139], v[26:27], v[138:139]
	v_pk_mul_f32 v[140:141], v[28:29], v[140:141]
	v_pk_mul_f32 v[142:143], v[30:31], v[142:143]
	v_pk_fma_f32 v[128:129], v[32:33], v[128:129], v[48:49]
	v_pk_fma_f32 v[130:131], v[34:35], v[130:131], v[50:51]
	v_pk_fma_f32 v[132:133], v[36:37], v[132:133], v[52:53]
	v_pk_fma_f32 v[134:135], v[38:39], v[134:135], v[54:55]
	v_pk_fma_f32 v[136:137], v[40:41], v[136:137], v[56:57]
	v_pk_fma_f32 v[138:139], v[42:43], v[138:139], v[58:59]
	v_pk_fma_f32 v[140:141], v[44:45], v[140:141], v[60:61]
	v_pk_fma_f32 v[142:143], v[46:47], v[142:143], v[62:63]
	v_cvt_pk_bf16_f32 v148, v128, v129
	v_cvt_pk_bf16_f32 v149, v130, v131
	v_cvt_pk_bf16_f32 v150, v132, v133
	v_cvt_pk_bf16_f32 v151, v134, v135
	v_cvt_pk_bf16_f32 v152, v136, v137
	v_cvt_pk_bf16_f32 v153, v138, v139
	v_cvt_pk_bf16_f32 v154, v140, v141
	v_cvt_pk_bf16_f32 v155, v142, v143
	global_store_dwordx4 v1, v[148:151], s[12:13] offset:2048 sc1
	global_store_dwordx4 v1, v[152:155], s[12:13] offset:3072 sc1
	s_add_u32 s12, s12, 0x1000
	s_addc_u32 s13, s13, 0
	global_load_dwordx4 v[120:123], v1, s[8:9] offset:2048
	global_load_dwordx4 v[124:127], v1, s[8:9] offset:3072
	s_add_u32 s8, s8, 0x1000
	s_addc_u32 s9, s9, 0
	s_waitcnt vmcnt(28)
	v_lshlrev_b32_e32 v128, 16, v64
	v_and_b32_e32 v129, 0xffff0000, v64
	v_lshlrev_b32_e32 v130, 16, v65
	v_and_b32_e32 v131, 0xffff0000, v65
	v_lshlrev_b32_e32 v132, 16, v66
	v_and_b32_e32 v133, 0xffff0000, v66
	v_lshlrev_b32_e32 v134, 16, v67
	v_and_b32_e32 v135, 0xffff0000, v67
	v_lshlrev_b32_e32 v136, 16, v68
	v_and_b32_e32 v137, 0xffff0000, v68
	v_lshlrev_b32_e32 v138, 16, v69
	v_and_b32_e32 v139, 0xffff0000, v69
	v_lshlrev_b32_e32 v140, 16, v70
	v_and_b32_e32 v141, 0xffff0000, v70
	v_lshlrev_b32_e32 v142, 16, v71
	v_and_b32_e32 v143, 0xffff0000, v71
	v_pk_mul_f32 v[144:145], v[128:129], v[128:129]
	v_pk_fma_f32 v[144:145], v[130:131], v[130:131], v[144:145]
	v_pk_fma_f32 v[144:145], v[132:133], v[132:133], v[144:145]
	v_pk_fma_f32 v[144:145], v[134:135], v[134:135], v[144:145]
	v_pk_fma_f32 v[144:145], v[136:137], v[136:137], v[144:145]
	v_pk_fma_f32 v[144:145], v[138:139], v[138:139], v[144:145]
	v_pk_fma_f32 v[144:145], v[140:141], v[140:141], v[144:145]
	v_pk_fma_f32 v[144:145], v[142:143], v[142:143], v[144:145]
	v_add_f32_e32 v144, v144, v145
	s_nop 1
	v_add_f32_dpp v144, v144, v144 quad_perm:[1,0,3,2] row_mask:0xf bank_mask:0xf
	s_nop 1
	v_add_f32_dpp v144, v144, v144 quad_perm:[2,3,0,1] row_mask:0xf bank_mask:0xf
	s_nop 1
	v_add_f32_dpp v144, v144, v144 row_half_mirror row_mask:0xf bank_mask:0xf
	s_nop 1
	v_add_f32_dpp v144, v144, v144 row_mirror row_mask:0xf bank_mask:0xf
	s_nop 0
	v_mov_b32_e32 v145, v144
	s_nop 1
	v_permlane16_swap_b32_e32 v144, v145
	s_nop 0
	v_add_f32_e32 v144, v144, v145
	v_mov_b32_e32 v145, v144
	s_nop 1
	v_permlane32_swap_b32_e32 v144, v145
	s_nop 0
	v_add_f32_e32 v144, v144, v145
	v_fmamk_f32 v144, v144, 0x3a800000, v3
	v_rsq_f32_e32 v144, v144
	s_nop 0
	v_pk_mul_f32 v[128:129], v[128:129], v[144:145] op_sel_hi:[1,0]
	v_pk_mul_f32 v[130:131], v[130:131], v[144:145] op_sel_hi:[1,0]
	v_pk_mul_f32 v[132:133], v[132:133], v[144:145] op_sel_hi:[1,0]
; __device__ __forceinline__ unsigned cvt_pk_bf16(float lo, float hi) { unsigned r; asm("v_cvt_pk_bf16_f32 %0, %1, %2" : "=v"(r) : "v"(lo), "v"(hi)); return r; }
; __device__ __forceinline__ void norm_pass_bf16(const Ctx& X, const bf16_t* xs, const bf16_t* cs, int nrows, const float* gain, const float* modl, int si, bf16_t* HN) {
;     ...
;         for (int j = 0; j < 2; ++j) {
;             v[j][0] = bf2f(q[j].x & 0xffffu); v[j][1] = bf2f(q[j].x >> 16); v[j][2] = bf2f(q[j].y & 0xffffu); v[j][3] = bf2f(q[j].y >> 16);
;             v[j][4] = bf2f(q[j].z & 0xffffu); v[j][5] = bf2f(q[j].z >> 16); v[j][6] = bf2f(q[j].w & 0xffffu); v[j][7] = bf2f(q[j].w >> 16);
; #pragma unroll
;             for (int e = 0; e < 8; ++e) s += v[j][e] * v[j][e]; }
;         const float rstd = rsqrtf(wave_sum(s) * (1.0f / 1024.0f) + 1e-6f);
; #pragma unroll
;         for (int j = 0; j < 2; ++j) { const int c = (X.lane + 64 * j) * 8; float o[8];
; #pragma unroll
;             for (int h = 0; h < 2; ++h) { const f32x4 gn = *(const f32x4*)(gain + c + 4 * h), a = *(const f32x4*)(scl + c + 4 * h), b = *(const f32x4*)(sh + c + 4 * h);
; #pragma unroll
;                 for (int e = 0; e < 4; ++e) o[4 * h + e] = v[j][4 * h + e] * rstd * gn[e] * (a[e] + 1.0f) + b[e]; }
;             u32x4 w; w.x = cvt_pk_bf16(o[0], o[1]); w.y = cvt_pk_bf16(o[2], o[3]); w.z = cvt_pk_bf16(o[4], o[5]); w.w = cvt_pk_bf16(o[6], o[7]); *(u32x4*)(HN + (size_t)r * D + c) = w; }
	v_pk_mul_f32 v[134:135], v[134:135], v[144:145] op_sel_hi:[1,0]
	v_pk_mul_f32 v[136:137], v[136:137], v[144:145] op_sel_hi:[1,0]
	v_pk_mul_f32 v[138:139], v[138:139], v[144:145] op_sel_hi:[1,0]
	v_pk_mul_f32 v[140:141], v[140:141], v[144:145] op_sel_hi:[1,0]
	v_pk_mul_f32 v[142:143], v[142:143], v[144:145] op_sel_hi:[1,0]
	v_pk_mul_f32 v[128:129], v[16:17], v[128:129]
	v_pk_mul_f32 v[130:131], v[18:19], v[130:131]
	v_pk_mul_f32 v[132:133], v[20:21], v[132:133]
	v_pk_mul_f32 v[134:135], v[22:23], v[134:135]
	v_pk_mul_f32 v[136:137], v[24:25], v[136:137]
	v_pk_mul_f32 v[138:139], v[26:27], v[138:139]
	v_pk_mul_f32 v[140:141], v[28:29], v[140:141]
	v_pk_mul_f32 v[142:143], v[30:31], v[142:143]
	v_pk_fma_f32 v[128:129], v[32:33], v[128:129], v[48:49]
	v_pk_fma_f32 v[130:131], v[34:35], v[130:131], v[50:51]
	v_pk_fma_f32 v[132:133], v[36:37], v[132:133], v[52:53]
	v_pk_fma_f32 v[134:135], v[38:39], v[134:135], v[54:55]
	v_pk_fma_f32 v[136:137], v[40:41], v[136:137], v[56:57]
	v_pk_fma_f32 v[138:139], v[42:43], v[138:139], v[58:59]
	v_pk_fma_f32 v[140:141], v[44:45], v[140:141], v[60:61]
	v_pk_fma_f32 v[142:143], v[46:47], v[142:143], v[62:63]
	v_cvt_pk_bf16_f32 v148, v128, v129
	v_cvt_pk_bf16_f32 v149, v130, v131
	v_cvt_pk_bf16_f32 v150, v132, v133
	v_cvt_pk_bf16_f32 v151, v134, v135
	v_cvt_pk_bf16_f32 v152, v136, v137
	v_cvt_pk_bf16_f32 v153, v138, v139
	v_cvt_pk_bf16_f32 v154, v140, v141
	v_cvt_pk_bf16_f32 v155, v142, v143
	global_store_dwordx4 v1, v[148:151], s[12:13] sc1
	global_store_dwordx4 v1, v[152:155], s[12:13] offset:1024 sc1
	s_waitcnt vmcnt(26)
	v_lshlrev_b32_e32 v128, 16, v72
	v_and_b32_e32 v129, 0xffff0000, v72
	v_lshlrev_b32_e32 v130, 16, v73
	v_and_b32_e32 v131, 0xffff0000, v73
	v_lshlrev_b32_e32 v132, 16, v74
	v_and_b32_e32 v133, 0xffff0000, v74
	v_lshlrev_b32_e32 v134, 16, v75
	v_and_b32_e32 v135, 0xffff0000, v75
	v_lshlrev_b32_e32 v136, 16, v76
	v_and_b32_e32 v137, 0xffff0000, v76
	v_lshlrev_b32_e32 v138, 16, v77
	v_and_b32_e32 v139, 0xffff0000, v77
	v_lshlrev_b32_e32 v140, 16, v78
	v_and_b32_e32 v141, 0xffff0000, v78
	v_lshlrev_b32_e32 v142, 16, v79
	v_and_b32_e32 v143, 0xffff0000, v79
	v_pk_mul_f32 v[144:145], v[128:129], v[128:129]
	v_pk_fma_f32 v[144:145], v[130:131], v[130:131], v[144:145]
	v_pk_fma_f32 v[144:145], v[132:133], v[132:133], v[144:145]
	v_pk_fma_f32 v[144:145], v[134:135], v[134:135], v[144:145]
	v_pk_fma_f32 v[144:145], v[136:137], v[136:137], v[144:145]
	v_pk_fma_f32 v[144:145], v[138:139], v[138:139], v[144:145]
	v_pk_fma_f32 v[144:145], v[140:141], v[140:141], v[144:145]
	v_pk_fma_f32 v[144:145], v[142:143], v[142:143], v[144:145]
	v_add_f32_e32 v144, v144, v145
	s_nop 1
	v_add_f32_dpp v144, v144, v144 quad_perm:[1,0,3,2] row_mask:0xf bank_mask:0xf
	s_nop 1
	v_add_f32_dpp v144, v144, v144 quad_perm:[2,3,0,1] row_mask:0xf bank_mask:0xf
	s_nop 1
	v_add_f32_dpp v144, v144, v144 row_half_mirror row_mask:0xf bank_mask:0xf
	s_nop 1
	v_add_f32_dpp v144, v144, v144 row_mirror row_mask:0xf bank_mask:0xf
	s_nop 0
	v_mov_b32_e32 v145, v144
	s_nop 1
	v_permlane16_swap_b32_e32 v144, v145
	s_nop 0
	v_add_f32_e32 v144, v144, v145
	v_mov_b32_e32 v145, v144
	s_nop 1
	v_permlane32_swap_b32_e32 v144, v145
	s_nop 0
	v_add_f32_e32 v144, v144, v145
	v_fmamk_f32 v144, v144, 0x3a800000, v3
	v_rsq_f32_e32 v144, v144
	s_nop 0
	v_pk_mul_f32 v[128:129], v[128:129], v[144:145] op_sel_hi:[1,0]
	v_pk_mul_f32 v[130:131], v[130:131], v[144:145] op_sel_hi:[1,0]
	v_pk_mul_f32 v[132:133], v[132:133], v[144:145] op_sel_hi:[1,0]
	v_pk_mul_f32 v[134:135], v[134:135], v[144:145] op_sel_hi:[1,0]
	v_pk_mul_f32 v[136:137], v[136:137], v[144:145] op_sel_hi:[1,0]
	v_pk_mul_f32 v[138:139], v[138:139], v[144:145] op_sel_hi:[1,0]
	v_pk_mul_f32 v[140:141], v[140:141], v[144:145] op_sel_hi:[1,0]
	v_pk_mul_f32 v[142:143], v[142:143], v[144:145] op_sel_hi:[1,0]
	v_pk_mul_f32 v[128:129], v[16:17], v[128:129]
	v_pk_mul_f32 v[130:131], v[18:19], v[130:131]
	v_pk_mul_f32 v[132:133], v[20:21], v[132:133]
	v_pk_mul_f32 v[134:135], v[22:23], v[134:135]
	v_pk_mul_f32 v[136:137], v[24:25], v[136:137]
	v_pk_mul_f32 v[138:139], v[26:27], v[138:139]
	v_pk_mul_f32 v[140:141], v[28:29], v[140:141]
	v_pk_mul_f32 v[142:143], v[30:31], v[142:143]
	v_pk_fma_f32 v[128:129], v[32:33], v[128:129], v[48:49]
	v_pk_fma_f32 v[130:131], v[34:35], v[130:131], v[50:51]
	v_pk_fma_f32 v[132:133], v[36:37], v[132:133], v[52:53]
	v_pk_fma_f32 v[134:135], v[38:39], v[134:135], v[54:55]
	v_pk_fma_f32 v[136:137], v[40:41], v[136:137], v[56:57]
	v_pk_fma_f32 v[138:139], v[42:43], v[138:139], v[58:59]
	v_pk_fma_f32 v[140:141], v[44:45], v[140:141], v[60:61]
	v_pk_fma_f32 v[142:143], v[46:47], v[142:143], v[62:63]
	v_cvt_pk_bf16_f32 v148, v128, v129
	v_cvt_pk_bf16_f32 v149, v130, v131
	v_cvt_pk_bf16_f32 v150, v132, v133
	v_cvt_pk_bf16_f32 v151, v134, v135
	v_cvt_pk_bf16_f32 v152, v136, v137
	v_cvt_pk_bf16_f32 v153, v138, v139
	v_cvt_pk_bf16_f32 v154, v140, v141
	v_cvt_pk_bf16_f32 v155, v142, v143
	global_store_dwordx4 v1, v[148:151], s[12:13] offset:2048 sc1
	global_store_dwordx4 v1, v[152:155], s[12:13] offset:3072 sc1
	s_add_u32 s12, s12, 0x1000
	s_addc_u32 s13, s13, 0
	s_waitcnt vmcnt(24)
; __device__ __forceinline__ unsigned cvt_pk_bf16(float lo, float hi) { unsigned r; asm("v_cvt_pk_bf16_f32 %0, %1, %2" : "=v"(r) : "v"(lo), "v"(hi)); return r; }
; __device__ __forceinline__ void norm_pass_bf16(const Ctx& X, const bf16_t* xs, const bf16_t* cs, int nrows, const float* gain, const float* modl, int si, bf16_t* HN) {
;     ...
;         for (int j = 0; j < 2; ++j) {
;             v[j][0] = bf2f(q[j].x & 0xffffu); v[j][1] = bf2f(q[j].x >> 16); v[j][2] = bf2f(q[j].y & 0xffffu); v[j][3] = bf2f(q[j].y >> 16);
;             v[j][4] = bf2f(q[j].z & 0xffffu); v[j][5] = bf2f(q[j].z >> 16); v[j][6] = bf2f(q[j].w & 0xffffu); v[j][7] = bf2f(q[j].w >> 16);
; #pragma unroll
;             for (int e = 0; e < 8; ++e) s += v[j][e] * v[j][e]; }
;         const float rstd = rsqrtf(wave_sum(s) * (1.0f / 1024.0f) + 1e-6f);
; #pragma unroll
;         for (int j = 0; j < 2; ++j) { const int c = (X.lane + 64 * j) * 8; float o[8];
; #pragma unroll
;             for (int h = 0; h < 2; ++h) { const f32x4 gn = *(const f32x4*)(gain + c + 4 * h), a = *(const f32x4*)(scl + c + 4 * h), b = *(const f32x4*)(sh + c + 4 * h);
; #pragma unroll
;                 for (int e = 0; e < 4; ++e) o[4 * h + e] = v[j][4 * h + e] * rstd * gn[e] * (a[e] + 1.0f) + b[e]; }
;             u32x4 w; w.x = cvt_pk_bf16(o[0], o[1]); w.y = cvt_pk_bf16(o[2], o[3]); w.z = cvt_pk_bf16(o[4], o[5]); w.w = cvt_pk_bf16(o[6], o[7]); *(u32x4*)(HN + (size_t)r * D + c) = w; }
	v_lshlrev_b32_e32 v128, 16, v80
	v_and_b32_e32 v129, 0xffff0000, v80
	v_lshlrev_b32_e32 v130, 16, v81
	v_and_b32_e32 v131, 0xffff0000, v81
	v_lshlrev_b32_e32 v132, 16, v82
	v_and_b32_e32 v133, 0xffff0000, v82
	v_lshlrev_b32_e32 v134, 16, v83
	v_and_b32_e32 v135, 0xffff0000, v83
	v_lshlrev_b32_e32 v136, 16, v84
	v_and_b32_e32 v137, 0xffff0000, v84
	v_lshlrev_b32_e32 v138, 16, v85
	v_and_b32_e32 v139, 0xffff0000, v85
	v_lshlrev_b32_e32 v140, 16, v86
	v_and_b32_e32 v141, 0xffff0000, v86
	v_lshlrev_b32_e32 v142, 16, v87
	v_and_b32_e32 v143, 0xffff0000, v87
	v_pk_mul_f32 v[144:145], v[128:129], v[128:129]
	v_pk_fma_f32 v[144:145], v[130:131], v[130:131], v[144:145]
	v_pk_fma_f32 v[144:145], v[132:133], v[132:133], v[144:145]
	v_pk_fma_f32 v[144:145], v[134:135], v[134:135], v[144:145]
	v_pk_fma_f32 v[144:145], v[136:137], v[136:137], v[144:145]
	v_pk_fma_f32 v[144:145], v[138:139], v[138:139], v[144:145]
	v_pk_fma_f32 v[144:145], v[140:141], v[140:141], v[144:145]
	v_pk_fma_f32 v[144:145], v[142:143], v[142:143], v[144:145]
	v_add_f32_e32 v144, v144, v145
	s_nop 1
	v_add_f32_dpp v144, v144, v144 quad_perm:[1,0,3,2] row_mask:0xf bank_mask:0xf
	s_nop 1
	v_add_f32_dpp v144, v144, v144 quad_perm:[2,3,0,1] row_mask:0xf bank_mask:0xf
	s_nop 1
	v_add_f32_dpp v144, v144, v144 row_half_mirror row_mask:0xf bank_mask:0xf
	s_nop 1
	v_add_f32_dpp v144, v144, v144 row_mirror row_mask:0xf bank_mask:0xf
	s_nop 0
	v_mov_b32_e32 v145, v144
	s_nop 1
	v_permlane16_swap_b32_e32 v144, v145
	s_nop 0
	v_add_f32_e32 v144, v144, v145
	v_mov_b32_e32 v145, v144
	s_nop 1
	v_permlane32_swap_b32_e32 v144, v145
	s_nop 0
	v_add_f32_e32 v144, v144, v145
	v_fmamk_f32 v144, v144, 0x3a800000, v3
	v_rsq_f32_e32 v144, v144
	s_nop 0
	v_pk_mul_f32 v[128:129], v[128:129], v[144:145] op_sel_hi:[1,0]
	v_pk_mul_f32 v[130:131], v[130:131], v[144:145] op_sel_hi:[1,0]
	v_pk_mul_f32 v[132:133], v[132:133], v[144:145] op_sel_hi:[1,0]
	v_pk_mul_f32 v[134:135], v[134:135], v[144:145] op_sel_hi:[1,0]
	v_pk_mul_f32 v[136:137], v[136:137], v[144:145] op_sel_hi:[1,0]
	v_pk_mul_f32 v[138:139], v[138:139], v[144:145] op_sel_hi:[1,0]
	v_pk_mul_f32 v[140:141], v[140:141], v[144:145] op_sel_hi:[1,0]
	v_pk_mul_f32 v[142:143], v[142:143], v[144:145] op_sel_hi:[1,0]
	v_pk_mul_f32 v[128:129], v[16:17], v[128:129]
	v_pk_mul_f32 v[130:131], v[18:19], v[130:131]
	v_pk_mul_f32 v[132:133], v[20:21], v[132:133]
	v_pk_mul_f32 v[134:135], v[22:23], v[134:135]
	v_pk_mul_f32 v[136:137], v[24:25], v[136:137]
	v_pk_mul_f32 v[138:139], v[26:27], v[138:139]
	v_pk_mul_f32 v[140:141], v[28:29], v[140:141]
	v_pk_mul_f32 v[142:143], v[30:31], v[142:143]
	v_pk_fma_f32 v[128:129], v[32:33], v[128:129], v[48:49]
	v_pk_fma_f32 v[130:131], v[34:35], v[130:131], v[50:51]
	v_pk_fma_f32 v[132:133], v[36:37], v[132:133], v[52:53]
	v_pk_fma_f32 v[134:135], v[38:39], v[134:135], v[54:55]
	v_pk_fma_f32 v[136:137], v[40:41], v[136:137], v[56:57]
	v_pk_fma_f32 v[138:139], v[42:43], v[138:139], v[58:59]
	v_pk_fma_f32 v[140:141], v[44:45], v[140:141], v[60:61]
	v_pk_fma_f32 v[142:143], v[46:47], v[142:143], v[62:63]
	v_cvt_pk_bf16_f32 v148, v128, v129
	v_cvt_pk_bf16_f32 v149, v130, v131
	v_cvt_pk_bf16_f32 v150, v132, v133
	v_cvt_pk_bf16_f32 v151, v134, v135
	v_cvt_pk_bf16_f32 v152, v136, v137
	v_cvt_pk_bf16_f32 v153, v138, v139
	v_cvt_pk_bf16_f32 v154, v140, v141
	v_cvt_pk_bf16_f32 v155, v142, v143
	global_store_dwordx4 v1, v[148:151], s[12:13] sc1
	global_store_dwordx4 v1, v[152:155], s[12:13] offset:1024 sc1
	s_waitcnt vmcnt(22)
	v_lshlrev_b32_e32 v128, 16, v88
	v_and_b32_e32 v129, 0xffff0000, v88
	v_lshlrev_b32_e32 v130, 16, v89
	v_and_b32_e32 v131, 0xffff0000, v89
	v_lshlrev_b32_e32 v132, 16, v90
	v_and_b32_e32 v133, 0xffff0000, v90
	v_lshlrev_b32_e32 v134, 16, v91
	v_and_b32_e32 v135, 0xffff0000, v91
	v_lshlrev_b32_e32 v136, 16, v92
	v_and_b32_e32 v137, 0xffff0000, v92
	v_lshlrev_b32_e32 v138, 16, v93
	v_and_b32_e32 v139, 0xffff0000, v93
	v_lshlrev_b32_e32 v140, 16, v94
	v_and_b32_e32 v141, 0xffff0000, v94
	v_lshlrev_b32_e32 v142, 16, v95
	v_and_b32_e32 v143, 0xffff0000, v95
	v_pk_mul_f32 v[144:145], v[128:129], v[128:129]
	v_pk_fma_f32 v[144:145], v[130:131], v[130:131], v[144:145]
	v_pk_fma_f32 v[144:145], v[132:133], v[132:133], v[144:145]
	v_pk_fma_f32 v[144:145], v[134:135], v[134:135], v[144:145]
	v_pk_fma_f32 v[144:145], v[136:137], v[136:137], v[144:145]
	v_pk_fma_f32 v[144:145], v[138:139], v[138:139], v[144:145]
	v_pk_fma_f32 v[144:145], v[140:141], v[140:141], v[144:145]
	v_pk_fma_f32 v[144:145], v[142:143], v[142:143], v[144:145]
	v_add_f32_e32 v144, v144, v145
	s_nop 1
	v_add_f32_dpp v144, v144, v144 quad_perm:[1,0,3,2] row_mask:0xf bank_mask:0xf
	s_nop 1
	v_add_f32_dpp v144, v144, v144 quad_perm:[2,3,0,1] row_mask:0xf bank_mask:0xf
	s_nop 1
	v_add_f32_dpp v144, v144, v144 row_half_mirror row_mask:0xf bank_mask:0xf
	s_nop 1
	v_add_f32_dpp v144, v144, v144 row_mirror row_mask:0xf bank_mask:0xf
	s_nop 0
	v_mov_b32_e32 v145, v144
	s_nop 1
	v_permlane16_swap_b32_e32 v144, v145
	s_nop 0
	v_add_f32_e32 v144, v144, v145
	v_mov_b32_e32 v145, v144
	s_nop 1
	v_permlane32_swap_b32_e32 v144, v145
	s_nop 0
	v_add_f32_e32 v144, v144, v145
	v_fmamk_f32 v144, v144, 0x3a800000, v3
	v_rsq_f32_e32 v144, v144
	s_nop 0
	v_pk_mul_f32 v[128:129], v[128:129], v[144:145] op_sel_hi:[1,0]
	v_pk_mul_f32 v[130:131], v[130:131], v[144:145] op_sel_hi:[1,0]
	v_pk_mul_f32 v[132:133], v[132:133], v[144:145] op_sel_hi:[1,0]
	v_pk_mul_f32 v[134:135], v[134:135], v[144:145] op_sel_hi:[1,0]
	v_pk_mul_f32 v[136:137], v[136:137], v[144:145] op_sel_hi:[1,0]
	v_pk_mul_f32 v[138:139], v[138:139], v[144:145] op_sel_hi:[1,0]
	v_pk_mul_f32 v[140:141], v[140:141], v[144:145] op_sel_hi:[1,0]
; __device__ __forceinline__ unsigned cvt_pk_bf16(float lo, float hi) { unsigned r; asm("v_cvt_pk_bf16_f32 %0, %1, %2" : "=v"(r) : "v"(lo), "v"(hi)); return r; }
; __device__ __forceinline__ void norm_pass_bf16(const Ctx& X, const bf16_t* xs, const bf16_t* cs, int nrows, const float* gain, const float* modl, int si, bf16_t* HN) {
;     ...
;         for (int j = 0; j < 2; ++j) {
;             v[j][0] = bf2f(q[j].x & 0xffffu); v[j][1] = bf2f(q[j].x >> 16); v[j][2] = bf2f(q[j].y & 0xffffu); v[j][3] = bf2f(q[j].y >> 16);
;             v[j][4] = bf2f(q[j].z & 0xffffu); v[j][5] = bf2f(q[j].z >> 16); v[j][6] = bf2f(q[j].w & 0xffffu); v[j][7] = bf2f(q[j].w >> 16);
; #pragma unroll
;             for (int e = 0; e < 8; ++e) s += v[j][e] * v[j][e]; }
;         const float rstd = rsqrtf(wave_sum(s) * (1.0f / 1024.0f) + 1e-6f);
; #pragma unroll
;         for (int j = 0; j < 2; ++j) { const int c = (X.lane + 64 * j) * 8; float o[8];
; #pragma unroll
;             for (int h = 0; h < 2; ++h) { const f32x4 gn = *(const f32x4*)(gain + c + 4 * h), a = *(const f32x4*)(scl + c + 4 * h), b = *(const f32x4*)(sh + c + 4 * h);
; #pragma unroll
;                 for (int e = 0; e < 4; ++e) o[4 * h + e] = v[j][4 * h + e] * rstd * gn[e] * (a[e] + 1.0f) + b[e]; }
;             u32x4 w; w.x = cvt_pk_bf16(o[0], o[1]); w.y = cvt_pk_bf16(o[2], o[3]); w.z = cvt_pk_bf16(o[4], o[5]); w.w = cvt_pk_bf16(o[6], o[7]); *(u32x4*)(HN + (size_t)r * D + c) = w; }
	v_pk_mul_f32 v[142:143], v[142:143], v[144:145] op_sel_hi:[1,0]
	v_pk_mul_f32 v[128:129], v[16:17], v[128:129]
	v_pk_mul_f32 v[130:131], v[18:19], v[130:131]
	v_pk_mul_f32 v[132:133], v[20:21], v[132:133]
	v_pk_mul_f32 v[134:135], v[22:23], v[134:135]
	v_pk_mul_f32 v[136:137], v[24:25], v[136:137]
	v_pk_mul_f32 v[138:139], v[26:27], v[138:139]
	v_pk_mul_f32 v[140:141], v[28:29], v[140:141]
	v_pk_mul_f32 v[142:143], v[30:31], v[142:143]
	v_pk_fma_f32 v[128:129], v[32:33], v[128:129], v[48:49]
	v_pk_fma_f32 v[130:131], v[34:35], v[130:131], v[50:51]
	v_pk_fma_f32 v[132:133], v[36:37], v[132:133], v[52:53]
	v_pk_fma_f32 v[134:135], v[38:39], v[134:135], v[54:55]
	v_pk_fma_f32 v[136:137], v[40:41], v[136:137], v[56:57]
	v_pk_fma_f32 v[138:139], v[42:43], v[138:139], v[58:59]
	v_pk_fma_f32 v[140:141], v[44:45], v[140:141], v[60:61]
	v_pk_fma_f32 v[142:143], v[46:47], v[142:143], v[62:63]
	v_cvt_pk_bf16_f32 v148, v128, v129
	v_cvt_pk_bf16_f32 v149, v130, v131
	v_cvt_pk_bf16_f32 v150, v132, v133
	v_cvt_pk_bf16_f32 v151, v134, v135
	v_cvt_pk_bf16_f32 v152, v136, v137
	v_cvt_pk_bf16_f32 v153, v138, v139
	v_cvt_pk_bf16_f32 v154, v140, v141
	v_cvt_pk_bf16_f32 v155, v142, v143
	global_store_dwordx4 v1, v[148:151], s[12:13] offset:2048 sc1
	global_store_dwordx4 v1, v[152:155], s[12:13] offset:3072 sc1
	s_add_u32 s12, s12, 0x1000
	s_addc_u32 s13, s13, 0
	s_waitcnt vmcnt(20)
	v_lshlrev_b32_e32 v128, 16, v96
	v_and_b32_e32 v129, 0xffff0000, v96
	v_lshlrev_b32_e32 v130, 16, v97
	v_and_b32_e32 v131, 0xffff0000, v97
	v_lshlrev_b32_e32 v132, 16, v98
	v_and_b32_e32 v133, 0xffff0000, v98
	v_lshlrev_b32_e32 v134, 16, v99
	v_and_b32_e32 v135, 0xffff0000, v99
	v_lshlrev_b32_e32 v136, 16, v100
	v_and_b32_e32 v137, 0xffff0000, v100
	v_lshlrev_b32_e32 v138, 16, v101
	v_and_b32_e32 v139, 0xffff0000, v101
	v_lshlrev_b32_e32 v140, 16, v102
	v_and_b32_e32 v141, 0xffff0000, v102
	v_lshlrev_b32_e32 v142, 16, v103
	v_and_b32_e32 v143, 0xffff0000, v103
	v_pk_mul_f32 v[144:145], v[128:129], v[128:129]
	v_pk_fma_f32 v[144:145], v[130:131], v[130:131], v[144:145]
	v_pk_fma_f32 v[144:145], v[132:133], v[132:133], v[144:145]
	v_pk_fma_f32 v[144:145], v[134:135], v[134:135], v[144:145]
	v_pk_fma_f32 v[144:145], v[136:137], v[136:137], v[144:145]
	v_pk_fma_f32 v[144:145], v[138:139], v[138:139], v[144:145]
	v_pk_fma_f32 v[144:145], v[140:141], v[140:141], v[144:145]
	v_pk_fma_f32 v[144:145], v[142:143], v[142:143], v[144:145]
	v_add_f32_e32 v144, v144, v145
	s_nop 1
	v_add_f32_dpp v144, v144, v144 quad_perm:[1,0,3,2] row_mask:0xf bank_mask:0xf
	s_nop 1
	v_add_f32_dpp v144, v144, v144 quad_perm:[2,3,0,1] row_mask:0xf bank_mask:0xf
	s_nop 1
	v_add_f32_dpp v144, v144, v144 row_half_mirror row_mask:0xf bank_mask:0xf
	s_nop 1
	v_add_f32_dpp v144, v144, v144 row_mirror row_mask:0xf bank_mask:0xf
	s_nop 0
	v_mov_b32_e32 v145, v144
	s_nop 1
	v_permlane16_swap_b32_e32 v144, v145
	s_nop 0
	v_add_f32_e32 v144, v144, v145
	v_mov_b32_e32 v145, v144
	s_nop 1
	v_permlane32_swap_b32_e32 v144, v145
	s_nop 0
	v_add_f32_e32 v144, v144, v145
	v_fmamk_f32 v144, v144, 0x3a800000, v3
	v_rsq_f32_e32 v144, v144
	s_nop 0
	v_pk_mul_f32 v[128:129], v[128:129], v[144:145] op_sel_hi:[1,0]
	v_pk_mul_f32 v[130:131], v[130:131], v[144:145] op_sel_hi:[1,0]
	v_pk_mul_f32 v[132:133], v[132:133], v[144:145] op_sel_hi:[1,0]
	v_pk_mul_f32 v[134:135], v[134:135], v[144:145] op_sel_hi:[1,0]
	v_pk_mul_f32 v[136:137], v[136:137], v[144:145] op_sel_hi:[1,0]
	v_pk_mul_f32 v[138:139], v[138:139], v[144:145] op_sel_hi:[1,0]
	v_pk_mul_f32 v[140:141], v[140:141], v[144:145] op_sel_hi:[1,0]
	v_pk_mul_f32 v[142:143], v[142:143], v[144:145] op_sel_hi:[1,0]
	v_pk_mul_f32 v[128:129], v[16:17], v[128:129]
	v_pk_mul_f32 v[130:131], v[18:19], v[130:131]
	v_pk_mul_f32 v[132:133], v[20:21], v[132:133]
	v_pk_mul_f32 v[134:135], v[22:23], v[134:135]
	v_pk_mul_f32 v[136:137], v[24:25], v[136:137]
	v_pk_mul_f32 v[138:139], v[26:27], v[138:139]
	v_pk_mul_f32 v[140:141], v[28:29], v[140:141]
	v_pk_mul_f32 v[142:143], v[30:31], v[142:143]
	v_pk_fma_f32 v[128:129], v[32:33], v[128:129], v[48:49]
	v_pk_fma_f32 v[130:131], v[34:35], v[130:131], v[50:51]
	v_pk_fma_f32 v[132:133], v[36:37], v[132:133], v[52:53]
	v_pk_fma_f32 v[134:135], v[38:39], v[134:135], v[54:55]
	v_pk_fma_f32 v[136:137], v[40:41], v[136:137], v[56:57]
	v_pk_fma_f32 v[138:139], v[42:43], v[138:139], v[58:59]
	v_pk_fma_f32 v[140:141], v[44:45], v[140:141], v[60:61]
	v_pk_fma_f32 v[142:143], v[46:47], v[142:143], v[62:63]
	v_cvt_pk_bf16_f32 v148, v128, v129
	v_cvt_pk_bf16_f32 v149, v130, v131
	v_cvt_pk_bf16_f32 v150, v132, v133
	v_cvt_pk_bf16_f32 v151, v134, v135
	v_cvt_pk_bf16_f32 v152, v136, v137
	v_cvt_pk_bf16_f32 v153, v138, v139
	v_cvt_pk_bf16_f32 v154, v140, v141
	v_cvt_pk_bf16_f32 v155, v142, v143
	global_store_dwordx4 v1, v[148:151], s[12:13] sc1
	global_store_dwordx4 v1, v[152:155], s[12:13] offset:1024 sc1
	s_waitcnt vmcnt(18)
; __device__ __forceinline__ unsigned cvt_pk_bf16(float lo, float hi) { unsigned r; asm("v_cvt_pk_bf16_f32 %0, %1, %2" : "=v"(r) : "v"(lo), "v"(hi)); return r; }
; __device__ __forceinline__ void norm_pass_bf16(const Ctx& X, const bf16_t* xs, const bf16_t* cs, int nrows, const float* gain, const float* modl, int si, bf16_t* HN) {
;     ...
;         for (int j = 0; j < 2; ++j) {
;             v[j][0] = bf2f(q[j].x & 0xffffu); v[j][1] = bf2f(q[j].x >> 16); v[j][2] = bf2f(q[j].y & 0xffffu); v[j][3] = bf2f(q[j].y >> 16);
;             v[j][4] = bf2f(q[j].z & 0xffffu); v[j][5] = bf2f(q[j].z >> 16); v[j][6] = bf2f(q[j].w & 0xffffu); v[j][7] = bf2f(q[j].w >> 16);
; #pragma unroll
;             for (int e = 0; e < 8; ++e) s += v[j][e] * v[j][e]; }
;         const float rstd = rsqrtf(wave_sum(s) * (1.0f / 1024.0f) + 1e-6f);
; #pragma unroll
;         for (int j = 0; j < 2; ++j) { const int c = (X.lane + 64 * j) * 8; float o[8];
; #pragma unroll
;             for (int h = 0; h < 2; ++h) { const f32x4 gn = *(const f32x4*)(gain + c + 4 * h), a = *(const f32x4*)(scl + c + 4 * h), b = *(const f32x4*)(sh + c + 4 * h);
; #pragma unroll
;                 for (int e = 0; e < 4; ++e) o[4 * h + e] = v[j][4 * h + e] * rstd * gn[e] * (a[e] + 1.0f) + b[e]; }
;             u32x4 w; w.x = cvt_pk_bf16(o[0], o[1]); w.y = cvt_pk_bf16(o[2], o[3]); w.z = cvt_pk_bf16(o[4], o[5]); w.w = cvt_pk_bf16(o[6], o[7]); *(u32x4*)(HN + (size_t)r * D + c) = w; }
	v_lshlrev_b32_e32 v128, 16, v104
	v_and_b32_e32 v129, 0xffff0000, v104
	v_lshlrev_b32_e32 v130, 16, v105
	v_and_b32_e32 v131, 0xffff0000, v105
	v_lshlrev_b32_e32 v132, 16, v106
	v_and_b32_e32 v133, 0xffff0000, v106
	v_lshlrev_b32_e32 v134, 16, v107
	v_and_b32_e32 v135, 0xffff0000, v107
	v_lshlrev_b32_e32 v136, 16, v108
	v_and_b32_e32 v137, 0xffff0000, v108
	v_lshlrev_b32_e32 v138, 16, v109
	v_and_b32_e32 v139, 0xffff0000, v109
	v_lshlrev_b32_e32 v140, 16, v110
	v_and_b32_e32 v141, 0xffff0000, v110
	v_lshlrev_b32_e32 v142, 16, v111
	v_and_b32_e32 v143, 0xffff0000, v111
	v_pk_mul_f32 v[144:145], v[128:129], v[128:129]
	v_pk_fma_f32 v[144:145], v[130:131], v[130:131], v[144:145]
	v_pk_fma_f32 v[144:145], v[132:133], v[132:133], v[144:145]
	v_pk_fma_f32 v[144:145], v[134:135], v[134:135], v[144:145]
	v_pk_fma_f32 v[144:145], v[136:137], v[136:137], v[144:145]
	v_pk_fma_f32 v[144:145], v[138:139], v[138:139], v[144:145]
	v_pk_fma_f32 v[144:145], v[140:141], v[140:141], v[144:145]
	v_pk_fma_f32 v[144:145], v[142:143], v[142:143], v[144:145]
	v_add_f32_e32 v144, v144, v145
	s_nop 1
	v_add_f32_dpp v144, v144, v144 quad_perm:[1,0,3,2] row_mask:0xf bank_mask:0xf
	s_nop 1
	v_add_f32_dpp v144, v144, v144 quad_perm:[2,3,0,1] row_mask:0xf bank_mask:0xf
	s_nop 1
	v_add_f32_dpp v144, v144, v144 row_half_mirror row_mask:0xf bank_mask:0xf
	s_nop 1
	v_add_f32_dpp v144, v144, v144 row_mirror row_mask:0xf bank_mask:0xf
	s_nop 0
	v_mov_b32_e32 v145, v144
	s_nop 1
	v_permlane16_swap_b32_e32 v144, v145
	s_nop 0
	v_add_f32_e32 v144, v144, v145
	v_mov_b32_e32 v145, v144
	s_nop 1
	v_permlane32_swap_b32_e32 v144, v145
	s_nop 0
	v_add_f32_e32 v144, v144, v145
	v_fmamk_f32 v144, v144, 0x3a800000, v3
	v_rsq_f32_e32 v144, v144
	s_nop 0
	v_pk_mul_f32 v[128:129], v[128:129], v[144:145] op_sel_hi:[1,0]
	v_pk_mul_f32 v[130:131], v[130:131], v[144:145] op_sel_hi:[1,0]
	v_pk_mul_f32 v[132:133], v[132:133], v[144:145] op_sel_hi:[1,0]
	v_pk_mul_f32 v[134:135], v[134:135], v[144:145] op_sel_hi:[1,0]
	v_pk_mul_f32 v[136:137], v[136:137], v[144:145] op_sel_hi:[1,0]
	v_pk_mul_f32 v[138:139], v[138:139], v[144:145] op_sel_hi:[1,0]
	v_pk_mul_f32 v[140:141], v[140:141], v[144:145] op_sel_hi:[1,0]
	v_pk_mul_f32 v[142:143], v[142:143], v[144:145] op_sel_hi:[1,0]
	v_pk_mul_f32 v[128:129], v[16:17], v[128:129]
	v_pk_mul_f32 v[130:131], v[18:19], v[130:131]
	v_pk_mul_f32 v[132:133], v[20:21], v[132:133]
	v_pk_mul_f32 v[134:135], v[22:23], v[134:135]
	v_pk_mul_f32 v[136:137], v[24:25], v[136:137]
	v_pk_mul_f32 v[138:139], v[26:27], v[138:139]
	v_pk_mul_f32 v[140:141], v[28:29], v[140:141]
	v_pk_mul_f32 v[142:143], v[30:31], v[142:143]
	v_pk_fma_f32 v[128:129], v[32:33], v[128:129], v[48:49]
	v_pk_fma_f32 v[130:131], v[34:35], v[130:131], v[50:51]
	v_pk_fma_f32 v[132:133], v[36:37], v[132:133], v[52:53]
	v_pk_fma_f32 v[134:135], v[38:39], v[134:135], v[54:55]
	v_pk_fma_f32 v[136:137], v[40:41], v[136:137], v[56:57]
	v_pk_fma_f32 v[138:139], v[42:43], v[138:139], v[58:59]
	v_pk_fma_f32 v[140:141], v[44:45], v[140:141], v[60:61]
	v_pk_fma_f32 v[142:143], v[46:47], v[142:143], v[62:63]
	v_cvt_pk_bf16_f32 v148, v128, v129
	v_cvt_pk_bf16_f32 v149, v130, v131
	v_cvt_pk_bf16_f32 v150, v132, v133
	v_cvt_pk_bf16_f32 v151, v134, v135
	v_cvt_pk_bf16_f32 v152, v136, v137
	v_cvt_pk_bf16_f32 v153, v138, v139
	v_cvt_pk_bf16_f32 v154, v140, v141
	v_cvt_pk_bf16_f32 v155, v142, v143
	global_store_dwordx4 v1, v[148:151], s[12:13] offset:2048 sc1
	global_store_dwordx4 v1, v[152:155], s[12:13] offset:3072 sc1
	s_add_u32 s12, s12, 0x1000
	s_addc_u32 s13, s13, 0
	s_waitcnt vmcnt(16)
	v_lshlrev_b32_e32 v128, 16, v112
	v_and_b32_e32 v129, 0xffff0000, v112
	v_lshlrev_b32_e32 v130, 16, v113
	v_and_b32_e32 v131, 0xffff0000, v113
	v_lshlrev_b32_e32 v132, 16, v114
	v_and_b32_e32 v133, 0xffff0000, v114
	v_lshlrev_b32_e32 v134, 16, v115
	v_and_b32_e32 v135, 0xffff0000, v115
	v_lshlrev_b32_e32 v136, 16, v116
	v_and_b32_e32 v137, 0xffff0000, v116
	v_lshlrev_b32_e32 v138, 16, v117
	v_and_b32_e32 v139, 0xffff0000, v117
	v_lshlrev_b32_e32 v140, 16, v118
	v_and_b32_e32 v141, 0xffff0000, v118
	v_lshlrev_b32_e32 v142, 16, v119
	v_and_b32_e32 v143, 0xffff0000, v119
	v_pk_mul_f32 v[144:145], v[128:129], v[128:129]
	v_pk_fma_f32 v[144:145], v[130:131], v[130:131], v[144:145]
	v_pk_fma_f32 v[144:145], v[132:133], v[132:133], v[144:145]
	v_pk_fma_f32 v[144:145], v[134:135], v[134:135], v[144:145]
	v_pk_fma_f32 v[144:145], v[136:137], v[136:137], v[144:145]
	v_pk_fma_f32 v[144:145], v[138:139], v[138:139], v[144:145]
	v_pk_fma_f32 v[144:145], v[140:141], v[140:141], v[144:145]
	v_pk_fma_f32 v[144:145], v[142:143], v[142:143], v[144:145]
	v_add_f32_e32 v144, v144, v145
	s_nop 1
	v_add_f32_dpp v144, v144, v144 quad_perm:[1,0,3,2] row_mask:0xf bank_mask:0xf
	s_nop 1
	v_add_f32_dpp v144, v144, v144 quad_perm:[2,3,0,1] row_mask:0xf bank_mask:0xf
	s_nop 1
	v_add_f32_dpp v144, v144, v144 row_half_mirror row_mask:0xf bank_mask:0xf
	s_nop 1
	v_add_f32_dpp v144, v144, v144 row_mirror row_mask:0xf bank_mask:0xf
	s_nop 0
	v_mov_b32_e32 v145, v144
	s_nop 1
	v_permlane16_swap_b32_e32 v144, v145
	s_nop 0
	v_add_f32_e32 v144, v144, v145
	v_mov_b32_e32 v145, v144
	s_nop 1
	v_permlane32_swap_b32_e32 v144, v145
	s_nop 0
	v_add_f32_e32 v144, v144, v145
	v_fmamk_f32 v144, v144, 0x3a800000, v3
	v_rsq_f32_e32 v144, v144
	s_nop 0
	v_pk_mul_f32 v[128:129], v[128:129], v[144:145] op_sel_hi:[1,0]
; __device__ __forceinline__ unsigned cvt_pk_bf16(float lo, float hi) { unsigned r; asm("v_cvt_pk_bf16_f32 %0, %1, %2" : "=v"(r) : "v"(lo), "v"(hi)); return r; }
; __device__ __forceinline__ void norm_pass_bf16(const Ctx& X, const bf16_t* xs, const bf16_t* cs, int nrows, const float* gain, const float* modl, int si, bf16_t* HN) {
;     ...
;         for (int j = 0; j < 2; ++j) {
;             v[j][0] = bf2f(q[j].x & 0xffffu); v[j][1] = bf2f(q[j].x >> 16); v[j][2] = bf2f(q[j].y & 0xffffu); v[j][3] = bf2f(q[j].y >> 16);
;             v[j][4] = bf2f(q[j].z & 0xffffu); v[j][5] = bf2f(q[j].z >> 16); v[j][6] = bf2f(q[j].w & 0xffffu); v[j][7] = bf2f(q[j].w >> 16);
; #pragma unroll
;             for (int e = 0; e < 8; ++e) s += v[j][e] * v[j][e]; }
;         const float rstd = rsqrtf(wave_sum(s) * (1.0f / 1024.0f) + 1e-6f);
; #pragma unroll
;         for (int j = 0; j < 2; ++j) { const int c = (X.lane + 64 * j) * 8; float o[8];
; #pragma unroll
;             for (int h = 0; h < 2; ++h) { const f32x4 gn = *(const f32x4*)(gain + c + 4 * h), a = *(const f32x4*)(scl + c + 4 * h), b = *(const f32x4*)(sh + c + 4 * h);
; #pragma unroll
;                 for (int e = 0; e < 4; ++e) o[4 * h + e] = v[j][4 * h + e] * rstd * gn[e] * (a[e] + 1.0f) + b[e]; }
;             u32x4 w; w.x = cvt_pk_bf16(o[0], o[1]); w.y = cvt_pk_bf16(o[2], o[3]); w.z = cvt_pk_bf16(o[4], o[5]); w.w = cvt_pk_bf16(o[6], o[7]); *(u32x4*)(HN + (size_t)r * D + c) = w; }
	v_pk_mul_f32 v[130:131], v[130:131], v[144:145] op_sel_hi:[1,0]
	v_pk_mul_f32 v[132:133], v[132:133], v[144:145] op_sel_hi:[1,0]
	v_pk_mul_f32 v[134:135], v[134:135], v[144:145] op_sel_hi:[1,0]
	v_pk_mul_f32 v[136:137], v[136:137], v[144:145] op_sel_hi:[1,0]
	v_pk_mul_f32 v[138:139], v[138:139], v[144:145] op_sel_hi:[1,0]
	v_pk_mul_f32 v[140:141], v[140:141], v[144:145] op_sel_hi:[1,0]
	v_pk_mul_f32 v[142:143], v[142:143], v[144:145] op_sel_hi:[1,0]
	v_pk_mul_f32 v[128:129], v[16:17], v[128:129]
	v_pk_mul_f32 v[130:131], v[18:19], v[130:131]
	v_pk_mul_f32 v[132:133], v[20:21], v[132:133]
	v_pk_mul_f32 v[134:135], v[22:23], v[134:135]
	v_pk_mul_f32 v[136:137], v[24:25], v[136:137]
	v_pk_mul_f32 v[138:139], v[26:27], v[138:139]
	v_pk_mul_f32 v[140:141], v[28:29], v[140:141]
	v_pk_mul_f32 v[142:143], v[30:31], v[142:143]
	v_pk_fma_f32 v[128:129], v[32:33], v[128:129], v[48:49]
	v_pk_fma_f32 v[130:131], v[34:35], v[130:131], v[50:51]
	v_pk_fma_f32 v[132:133], v[36:37], v[132:133], v[52:53]
	v_pk_fma_f32 v[134:135], v[38:39], v[134:135], v[54:55]
	v_pk_fma_f32 v[136:137], v[40:41], v[136:137], v[56:57]
	v_pk_fma_f32 v[138:139], v[42:43], v[138:139], v[58:59]
	v_pk_fma_f32 v[140:141], v[44:45], v[140:141], v[60:61]
	v_pk_fma_f32 v[142:143], v[46:47], v[142:143], v[62:63]
	v_cvt_pk_bf16_f32 v148, v128, v129
	v_cvt_pk_bf16_f32 v149, v130, v131
	v_cvt_pk_bf16_f32 v150, v132, v133
	v_cvt_pk_bf16_f32 v151, v134, v135
	v_cvt_pk_bf16_f32 v152, v136, v137
	v_cvt_pk_bf16_f32 v153, v138, v139
	v_cvt_pk_bf16_f32 v154, v140, v141
	v_cvt_pk_bf16_f32 v155, v142, v143
	global_store_dwordx4 v1, v[148:151], s[12:13] sc1
	global_store_dwordx4 v1, v[152:155], s[12:13] offset:1024 sc1
	s_waitcnt vmcnt(14)
	v_lshlrev_b32_e32 v128, 16, v120
	v_and_b32_e32 v129, 0xffff0000, v120
	v_lshlrev_b32_e32 v130, 16, v121
	v_and_b32_e32 v131, 0xffff0000, v121
	v_lshlrev_b32_e32 v132, 16, v122
	v_and_b32_e32 v133, 0xffff0000, v122
	v_lshlrev_b32_e32 v134, 16, v123
	v_and_b32_e32 v135, 0xffff0000, v123
	v_lshlrev_b32_e32 v136, 16, v124
	v_and_b32_e32 v137, 0xffff0000, v124
	v_lshlrev_b32_e32 v138, 16, v125
	v_and_b32_e32 v139, 0xffff0000, v125
	v_lshlrev_b32_e32 v140, 16, v126
	v_and_b32_e32 v141, 0xffff0000, v126
	v_lshlrev_b32_e32 v142, 16, v127
	v_and_b32_e32 v143, 0xffff0000, v127
	v_pk_mul_f32 v[144:145], v[128:129], v[128:129]
	v_pk_fma_f32 v[144:145], v[130:131], v[130:131], v[144:145]
	v_pk_fma_f32 v[144:145], v[132:133], v[132:133], v[144:145]
	v_pk_fma_f32 v[144:145], v[134:135], v[134:135], v[144:145]
	v_pk_fma_f32 v[144:145], v[136:137], v[136:137], v[144:145]
	v_pk_fma_f32 v[144:145], v[138:139], v[138:139], v[144:145]
	v_pk_fma_f32 v[144:145], v[140:141], v[140:141], v[144:145]
	v_pk_fma_f32 v[144:145], v[142:143], v[142:143], v[144:145]
	v_add_f32_e32 v144, v144, v145
	s_nop 1
	v_add_f32_dpp v144, v144, v144 quad_perm:[1,0,3,2] row_mask:0xf bank_mask:0xf
	s_nop 1
	v_add_f32_dpp v144, v144, v144 quad_perm:[2,3,0,1] row_mask:0xf bank_mask:0xf
	s_nop 1
	v_add_f32_dpp v144, v144, v144 row_half_mirror row_mask:0xf bank_mask:0xf
	s_nop 1
	v_add_f32_dpp v144, v144, v144 row_mirror row_mask:0xf bank_mask:0xf
	s_nop 0
	v_mov_b32_e32 v145, v144
	s_nop 1
	v_permlane16_swap_b32_e32 v144, v145
	s_nop 0
	v_add_f32_e32 v144, v144, v145
	v_mov_b32_e32 v145, v144
	s_nop 1
	v_permlane32_swap_b32_e32 v144, v145
	s_nop 0
	v_add_f32_e32 v144, v144, v145
	v_fmamk_f32 v144, v144, 0x3a800000, v3
	v_rsq_f32_e32 v144, v144
	s_nop 0
	v_pk_mul_f32 v[128:129], v[128:129], v[144:145] op_sel_hi:[1,0]
	v_pk_mul_f32 v[130:131], v[130:131], v[144:145] op_sel_hi:[1,0]
	v_pk_mul_f32 v[132:133], v[132:133], v[144:145] op_sel_hi:[1,0]
	v_pk_mul_f32 v[134:135], v[134:135], v[144:145] op_sel_hi:[1,0]
	v_pk_mul_f32 v[136:137], v[136:137], v[144:145] op_sel_hi:[1,0]
	v_pk_mul_f32 v[138:139], v[138:139], v[144:145] op_sel_hi:[1,0]
	v_pk_mul_f32 v[140:141], v[140:141], v[144:145] op_sel_hi:[1,0]
	v_pk_mul_f32 v[142:143], v[142:143], v[144:145] op_sel_hi:[1,0]
	v_pk_mul_f32 v[128:129], v[16:17], v[128:129]
	v_pk_mul_f32 v[130:131], v[18:19], v[130:131]
	v_pk_mul_f32 v[132:133], v[20:21], v[132:133]
	v_pk_mul_f32 v[134:135], v[22:23], v[134:135]
	v_pk_mul_f32 v[136:137], v[24:25], v[136:137]
	v_pk_mul_f32 v[138:139], v[26:27], v[138:139]
	v_pk_mul_f32 v[140:141], v[28:29], v[140:141]
	v_pk_mul_f32 v[142:143], v[30:31], v[142:143]
	v_pk_fma_f32 v[128:129], v[32:33], v[128:129], v[48:49]
	v_pk_fma_f32 v[130:131], v[34:35], v[130:131], v[50:51]
	v_pk_fma_f32 v[132:133], v[36:37], v[132:133], v[52:53]
	v_pk_fma_f32 v[134:135], v[38:39], v[134:135], v[54:55]
	v_pk_fma_f32 v[136:137], v[40:41], v[136:137], v[56:57]
	v_pk_fma_f32 v[138:139], v[42:43], v[138:139], v[58:59]
	v_pk_fma_f32 v[140:141], v[44:45], v[140:141], v[60:61]
	v_pk_fma_f32 v[142:143], v[46:47], v[142:143], v[62:63]
	v_cvt_pk_bf16_f32 v148, v128, v129
	v_cvt_pk_bf16_f32 v149, v130, v131
	v_cvt_pk_bf16_f32 v150, v132, v133
	v_cvt_pk_bf16_f32 v151, v134, v135
	v_cvt_pk_bf16_f32 v152, v136, v137
	v_cvt_pk_bf16_f32 v153, v138, v139
	v_cvt_pk_bf16_f32 v154, v140, v141
	v_cvt_pk_bf16_f32 v155, v142, v143
	global_store_dwordx4 v1, v[148:151], s[12:13] offset:2048 sc1
	global_store_dwordx4 v1, v[152:155], s[12:13] offset:3072 sc1
	s_add_u32 s12, s12, 0x1000
	s_addc_u32 s13, s13, 0
	s_add_i32 s21, s21, s20
	s_cmp_lt_i32 s21, 0x800
	s_cbranch_scc0 .LBB0_1185
	s_waitcnt vmcnt(0)
	s_branch .Lhn_C_blk

; __device__ __forceinline__ unsigned cvt_pk_bf16(float lo, float hi) { unsigned r; asm("v_cvt_pk_bf16_f32 %0, %1, %2" : "=v"(r) : "v"(lo), "v"(hi)); return r; }
; __device__ __forceinline__ void norm_pass_bf16(const Ctx& X, const bf16_t* xs, const bf16_t* cs, int nrows, const float* gain, const float* modl, int si, bf16_t* HN) {
;     for (int r = X.gw; r < nrows; r += X.NGW) {
;         const int mb = r < MX ? (r >> 12) : 8;
;         const float* sh = modl + (size_t)mb * 9216 + si * 1024; const float* scl = sh + 1024;
;         const bf16_t* rowp = r < MX ? xs + (size_t)r * D : cs + (size_t)(r - MX) * D;
;         u32x4 q[2]; float v[2][8]; float s = 0.f;
; #pragma unroll
;         for (int j = 0; j < 2; ++j) q[j] = *(const u32x4*)(rowp + (X.lane + 64 * j) * 8);
; #pragma unroll
;         for (int j = 0; j < 2; ++j) {
;             v[j][0] = bf2f(q[j].x & 0xffffu); v[j][1] = bf2f(q[j].x >> 16); v[j][2] = bf2f(q[j].y & 0xffffu); v[j][3] = bf2f(q[j].y >> 16);
;             v[j][4] = bf2f(q[j].z & 0xffffu); v[j][5] = bf2f(q[j].z >> 16); v[j][6] = bf2f(q[j].w & 0xffffu); v[j][7] = bf2f(q[j].w >> 16);
; #pragma unroll
;             for (int e = 0; e < 8; ++e) s += v[j][e] * v[j][e]; }
;         const float rstd = rsqrtf(wave_sum(s) * (1.0f / 1024.0f) + 1e-6f);
; #pragma unroll
;         for (int j = 0; j < 2; ++j) { const int c = (X.lane + 64 * j) * 8; float o[8];
; #pragma unroll
;             for (int h = 0; h < 2; ++h) { const f32x4 gn = *(const f32x4*)(gain + c + 4 * h), a = *(const f32x4*)(scl + c + 4 * h), b = *(const f32x4*)(sh + c + 4 * h);
; #pragma unroll
;                 for (int e = 0; e < 4; ++e) o[4 * h + e] = v[j][4 * h + e] * rstd * gn[e] * (a[e] + 1.0f) + b[e]; }
;             u32x4 w; w.x = cvt_pk_bf16(o[0], o[1]); w.y = cvt_pk_bf16(o[2], o[3]); w.z = cvt_pk_bf16(o[4], o[5]); w.w = cvt_pk_bf16(o[6], o[7]); *(u32x4*)(HN + (size_t)r * D + c) = w; }
.Lhn_D_blk:
	s_add_u32 s6, s48, 0x4000
	s_addc_u32 s7, s49, 0
	global_load_dwordx4 v[16:19], v2, s[6:7]
	global_load_dwordx4 v[20:23], v2, s[6:7] offset:16
	global_load_dwordx4 v[24:27], v2, s[6:7] offset:2048
	global_load_dwordx4 v[28:31], v2, s[6:7] offset:2064
	s_lshr_b32 s1, s21, 8
	s_mul_i32 s1, s1, 0x9000
	s_add_u32 s6, s88, s1
	s_addc_u32 s7, s89, 0
	s_add_u32 s6, s6, 0x54000
	s_addc_u32 s7, s7, 0
	global_load_dwordx4 v[48:51], v2, s[6:7]
	global_load_dwordx4 v[52:55], v2, s[6:7] offset:16
	global_load_dwordx4 v[56:59], v2, s[6:7] offset:2048
	global_load_dwordx4 v[60:63], v2, s[6:7] offset:2064
	s_add_u32 s6, s6, 0x1000
	s_addc_u32 s7, s7, 0
	global_load_dwordx4 v[32:35], v2, s[6:7]
	global_load_dwordx4 v[36:39], v2, s[6:7] offset:16
	global_load_dwordx4 v[40:43], v2, s[6:7] offset:2048
	global_load_dwordx4 v[44:47], v2, s[6:7] offset:2064
	s_lshl_b32 s1, s21, 15
	s_add_u32 s8, s86, s1
	s_addc_u32 s9, s87, 0
	s_add_u32 s12, s88, s1
	s_addc_u32 s13, s89, 0
	s_add_u32 s12, s12, 0x13000000
	s_addc_u32 s13, s13, 0
	global_load_dwordx4 v[64:67], v1, s[8:9]
	global_load_dwordx4 v[68:71], v1, s[8:9] offset:1024
	global_load_dwordx4 v[72:75], v1, s[8:9] offset:2048
	global_load_dwordx4 v[76:79], v1, s[8:9] offset:3072
	s_add_u32 s8, s8, 0x1000
	s_addc_u32 s9, s9, 0
	global_load_dwordx4 v[80:83], v1, s[8:9]
	global_load_dwordx4 v[84:87], v1, s[8:9] offset:1024
	global_load_dwordx4 v[88:91], v1, s[8:9] offset:2048
	global_load_dwordx4 v[92:95], v1, s[8:9] offset:3072
	s_add_u32 s8, s8, 0x1000
	s_addc_u32 s9, s9, 0
	global_load_dwordx4 v[96:99], v1, s[8:9]
	global_load_dwordx4 v[100:103], v1, s[8:9] offset:1024
	global_load_dwordx4 v[104:107], v1, s[8:9] offset:2048
	global_load_dwordx4 v[108:111], v1, s[8:9] offset:3072
	s_add_u32 s8, s8, 0x1000
	s_addc_u32 s9, s9, 0
	global_load_dwordx4 v[112:115], v1, s[8:9]
	global_load_dwordx4 v[116:119], v1, s[8:9] offset:1024
	global_load_dwordx4 v[120:123], v1, s[8:9] offset:2048
	global_load_dwordx4 v[124:127], v1, s[8:9] offset:3072
	s_add_u32 s8, s8, 0x1000
	s_addc_u32 s9, s9, 0
	s_waitcnt vmcnt(16)
	v_pk_add_f32 v[32:33], v[32:33], 1.0 op_sel_hi:[1,0]
	v_pk_add_f32 v[34:35], v[34:35], 1.0 op_sel_hi:[1,0]
	v_pk_add_f32 v[36:37], v[36:37], 1.0 op_sel_hi:[1,0]
	v_pk_add_f32 v[38:39], v[38:39], 1.0 op_sel_hi:[1,0]
	v_pk_add_f32 v[40:41], v[40:41], 1.0 op_sel_hi:[1,0]
	v_pk_add_f32 v[42:43], v[42:43], 1.0 op_sel_hi:[1,0]
	v_pk_add_f32 v[44:45], v[44:45], 1.0 op_sel_hi:[1,0]
	v_pk_add_f32 v[46:47], v[46:47], 1.0 op_sel_hi:[1,0]
	s_waitcnt vmcnt(14)
	v_lshlrev_b32_e32 v128, 16, v64
	v_and_b32_e32 v129, 0xffff0000, v64
	v_lshlrev_b32_e32 v130, 16, v65
	v_and_b32_e32 v131, 0xffff0000, v65
	v_lshlrev_b32_e32 v132, 16, v66
	v_and_b32_e32 v133, 0xffff0000, v66
	v_lshlrev_b32_e32 v134, 16, v67
	v_and_b32_e32 v135, 0xffff0000, v67
	v_lshlrev_b32_e32 v136, 16, v68
	v_and_b32_e32 v137, 0xffff0000, v68
	v_lshlrev_b32_e32 v138, 16, v69
	v_and_b32_e32 v139, 0xffff0000, v69
	v_lshlrev_b32_e32 v140, 16, v70
	v_and_b32_e32 v141, 0xffff0000, v70
	v_lshlrev_b32_e32 v142, 16, v71
	v_and_b32_e32 v143, 0xffff0000, v71
	v_pk_mul_f32 v[144:145], v[128:129], v[128:129]
	v_pk_fma_f32 v[144:145], v[130:131], v[130:131], v[144:145]
	v_pk_fma_f32 v[144:145], v[132:133], v[132:133], v[144:145]
	v_pk_fma_f32 v[144:145], v[134:135], v[134:135], v[144:145]
	v_pk_fma_f32 v[144:145], v[136:137], v[136:137], v[144:145]
	v_pk_fma_f32 v[144:145], v[138:139], v[138:139], v[144:145]
	v_pk_fma_f32 v[144:145], v[140:141], v[140:141], v[144:145]
	v_pk_fma_f32 v[144:145], v[142:143], v[142:143], v[144:145]
	v_add_f32_e32 v144, v144, v145
	s_nop 1
	v_add_f32_dpp v144, v144, v144 quad_perm:[1,0,3,2] row_mask:0xf bank_mask:0xf
	s_nop 1
	v_add_f32_dpp v144, v144, v144 quad_perm:[2,3,0,1] row_mask:0xf bank_mask:0xf
	s_nop 1
	v_add_f32_dpp v144, v144, v144 row_half_mirror row_mask:0xf bank_mask:0xf
	s_nop 1
	v_add_f32_dpp v144, v144, v144 row_mirror row_mask:0xf bank_mask:0xf
	s_nop 0
	v_mov_b32_e32 v145, v144
	s_nop 1
	v_permlane16_swap_b32_e32 v144, v145
	s_nop 0
	v_add_f32_e32 v144, v144, v145
	v_mov_b32_e32 v145, v144
	s_nop 1
	v_permlane32_swap_b32_e32 v144, v145
	s_nop 0
	v_add_f32_e32 v144, v144, v145
	v_fmamk_f32 v144, v144, 0x3a800000, v3
	v_rsq_f32_e32 v144, v144
	s_nop 0
	v_pk_mul_f32 v[128:129], v[128:129], v[144:145] op_sel_hi:[1,0]
	v_pk_mul_f32 v[130:131], v[130:131], v[144:145] op_sel_hi:[1,0]
	v_pk_mul_f32 v[132:133], v[132:133], v[144:145] op_sel_hi:[1,0]
	v_pk_mul_f32 v[134:135], v[134:135], v[144:145] op_sel_hi:[1,0]
	v_pk_mul_f32 v[136:137], v[136:137], v[144:145] op_sel_hi:[1,0]
	v_pk_mul_f32 v[138:139], v[138:139], v[144:145] op_sel_hi:[1,0]
	v_pk_mul_f32 v[140:141], v[140:141], v[144:145] op_sel_hi:[1,0]
	v_pk_mul_f32 v[142:143], v[142:143], v[144:145] op_sel_hi:[1,0]
	v_pk_mul_f32 v[128:129], v[16:17], v[128:129]
	v_pk_mul_f32 v[130:131], v[18:19], v[130:131]
	v_pk_mul_f32 v[132:133], v[20:21], v[132:133]
	v_pk_mul_f32 v[134:135], v[22:23], v[134:135]
	v_pk_mul_f32 v[136:137], v[24:25], v[136:137]
	v_pk_mul_f32 v[138:139], v[26:27], v[138:139]
	v_pk_mul_f32 v[140:141], v[28:29], v[140:141]
	v_pk_mul_f32 v[142:143], v[30:31], v[142:143]
	v_pk_fma_f32 v[128:129], v[32:33], v[128:129], v[48:49]
	v_pk_fma_f32 v[130:131], v[34:35], v[130:131], v[50:51]
	v_pk_fma_f32 v[132:133], v[36:37], v[132:133], v[52:53]
	v_pk_fma_f32 v[134:135], v[38:39], v[134:135], v[54:55]
	v_pk_fma_f32 v[136:137], v[40:41], v[136:137], v[56:57]
	v_pk_fma_f32 v[138:139], v[42:43], v[138:139], v[58:59]
	v_pk_fma_f32 v[140:141], v[44:45], v[140:141], v[60:61]
	v_pk_fma_f32 v[142:143], v[46:47], v[142:143], v[62:63]
	v_cvt_pk_bf16_f32 v148, v128, v129
	v_cvt_pk_bf16_f32 v149, v130, v131
	v_cvt_pk_bf16_f32 v150, v132, v133
	v_cvt_pk_bf16_f32 v151, v134, v135
	v_cvt_pk_bf16_f32 v152, v136, v137
	v_cvt_pk_bf16_f32 v153, v138, v139
	v_cvt_pk_bf16_f32 v154, v140, v141
	v_cvt_pk_bf16_f32 v155, v142, v143
	global_store_dwordx4 v1, v[148:151], s[12:13] sc1
	global_store_dwordx4 v1, v[152:155], s[12:13] offset:1024 sc1
	global_load_dwordx4 v[64:67], v1, s[8:9]
	global_load_dwordx4 v[68:71], v1, s[8:9] offset:1024
	s_waitcnt vmcnt(16)
; __device__ __forceinline__ unsigned cvt_pk_bf16(float lo, float hi) { unsigned r; asm("v_cvt_pk_bf16_f32 %0, %1, %2" : "=v"(r) : "v"(lo), "v"(hi)); return r; }
; __device__ __forceinline__ void norm_pass_bf16(const Ctx& X, const bf16_t* xs, const bf16_t* cs, int nrows, const float* gain, const float* modl, int si, bf16_t* HN) {
;     ...
;         for (int j = 0; j < 2; ++j) {
;             v[j][0] = bf2f(q[j].x & 0xffffu); v[j][1] = bf2f(q[j].x >> 16); v[j][2] = bf2f(q[j].y & 0xffffu); v[j][3] = bf2f(q[j].y >> 16);
;             v[j][4] = bf2f(q[j].z & 0xffffu); v[j][5] = bf2f(q[j].z >> 16); v[j][6] = bf2f(q[j].w & 0xffffu); v[j][7] = bf2f(q[j].w >> 16);
; #pragma unroll
;             for (int e = 0; e < 8; ++e) s += v[j][e] * v[j][e]; }
;         const float rstd = rsqrtf(wave_sum(s) * (1.0f / 1024.0f) + 1e-6f);
; #pragma unroll
;         for (int j = 0; j < 2; ++j) { const int c = (X.lane + 64 * j) * 8; float o[8];
; #pragma unroll
;             for (int h = 0; h < 2; ++h) { const f32x4 gn = *(const f32x4*)(gain + c + 4 * h), a = *(const f32x4*)(scl + c + 4 * h), b = *(const f32x4*)(sh + c + 4 * h);
; #pragma unroll
;                 for (int e = 0; e < 4; ++e) o[4 * h + e] = v[j][4 * h + e] * rstd * gn[e] * (a[e] + 1.0f) + b[e]; }
;             u32x4 w; w.x = cvt_pk_bf16(o[0], o[1]); w.y = cvt_pk_bf16(o[2], o[3]); w.z = cvt_pk_bf16(o[4], o[5]); w.w = cvt_pk_bf16(o[6], o[7]); *(u32x4*)(HN + (size_t)r * D + c) = w; }
	v_lshlrev_b32_e32 v128, 16, v72
	v_and_b32_e32 v129, 0xffff0000, v72
	v_lshlrev_b32_e32 v130, 16, v73
	v_and_b32_e32 v131, 0xffff0000, v73
	v_lshlrev_b32_e32 v132, 16, v74
	v_and_b32_e32 v133, 0xffff0000, v74
	v_lshlrev_b32_e32 v134, 16, v75
	v_and_b32_e32 v135, 0xffff0000, v75
	v_lshlrev_b32_e32 v136, 16, v76
	v_and_b32_e32 v137, 0xffff0000, v76
	v_lshlrev_b32_e32 v138, 16, v77
	v_and_b32_e32 v139, 0xffff0000, v77
	v_lshlrev_b32_e32 v140, 16, v78
	v_and_b32_e32 v141, 0xffff0000, v78
	v_lshlrev_b32_e32 v142, 16, v79
	v_and_b32_e32 v143, 0xffff0000, v79
	v_pk_mul_f32 v[144:145], v[128:129], v[128:129]
	v_pk_fma_f32 v[144:145], v[130:131], v[130:131], v[144:145]
	v_pk_fma_f32 v[144:145], v[132:133], v[132:133], v[144:145]
	v_pk_fma_f32 v[144:145], v[134:135], v[134:135], v[144:145]
	v_pk_fma_f32 v[144:145], v[136:137], v[136:137], v[144:145]
	v_pk_fma_f32 v[144:145], v[138:139], v[138:139], v[144:145]
	v_pk_fma_f32 v[144:145], v[140:141], v[140:141], v[144:145]
	v_pk_fma_f32 v[144:145], v[142:143], v[142:143], v[144:145]
	v_add_f32_e32 v144, v144, v145
	s_nop 1
	v_add_f32_dpp v144, v144, v144 quad_perm:[1,0,3,2] row_mask:0xf bank_mask:0xf
	s_nop 1
	v_add_f32_dpp v144, v144, v144 quad_perm:[2,3,0,1] row_mask:0xf bank_mask:0xf
	s_nop 1
	v_add_f32_dpp v144, v144, v144 row_half_mirror row_mask:0xf bank_mask:0xf
	s_nop 1
	v_add_f32_dpp v144, v144, v144 row_mirror row_mask:0xf bank_mask:0xf
	s_nop 0
	v_mov_b32_e32 v145, v144
	s_nop 1
	v_permlane16_swap_b32_e32 v144, v145
	s_nop 0
	v_add_f32_e32 v144, v144, v145
	v_mov_b32_e32 v145, v144
	s_nop 1
	v_permlane32_swap_b32_e32 v144, v145
	s_nop 0
	v_add_f32_e32 v144, v144, v145
	v_fmamk_f32 v144, v144, 0x3a800000, v3
	v_rsq_f32_e32 v144, v144
	s_nop 0
	v_pk_mul_f32 v[128:129], v[128:129], v[144:145] op_sel_hi:[1,0]
	v_pk_mul_f32 v[130:131], v[130:131], v[144:145] op_sel_hi:[1,0]
	v_pk_mul_f32 v[132:133], v[132:133], v[144:145] op_sel_hi:[1,0]
	v_pk_mul_f32 v[134:135], v[134:135], v[144:145] op_sel_hi:[1,0]
	v_pk_mul_f32 v[136:137], v[136:137], v[144:145] op_sel_hi:[1,0]
	v_pk_mul_f32 v[138:139], v[138:139], v[144:145] op_sel_hi:[1,0]
	v_pk_mul_f32 v[140:141], v[140:141], v[144:145] op_sel_hi:[1,0]
	v_pk_mul_f32 v[142:143], v[142:143], v[144:145] op_sel_hi:[1,0]
	v_pk_mul_f32 v[128:129], v[16:17], v[128:129]
	v_pk_mul_f32 v[130:131], v[18:19], v[130:131]
	v_pk_mul_f32 v[132:133], v[20:21], v[132:133]
	v_pk_mul_f32 v[134:135], v[22:23], v[134:135]
	v_pk_mul_f32 v[136:137], v[24:25], v[136:137]
	v_pk_mul_f32 v[138:139], v[26:27], v[138:139]
	v_pk_mul_f32 v[140:141], v[28:29], v[140:141]
	v_pk_mul_f32 v[142:143], v[30:31], v[142:143]
	v_pk_fma_f32 v[128:129], v[32:33], v[128:129], v[48:49]
	v_pk_fma_f32 v[130:131], v[34:35], v[130:131], v[50:51]
	v_pk_fma_f32 v[132:133], v[36:37], v[132:133], v[52:53]
	v_pk_fma_f32 v[134:135], v[38:39], v[134:135], v[54:55]
	v_pk_fma_f32 v[136:137], v[40:41], v[136:137], v[56:57]
	v_pk_fma_f32 v[138:139], v[42:43], v[138:139], v[58:59]
	v_pk_fma_f32 v[140:141], v[44:45], v[140:141], v[60:61]
	v_pk_fma_f32 v[142:143], v[46:47], v[142:143], v[62:63]
	v_cvt_pk_bf16_f32 v148, v128, v129
	v_cvt_pk_bf16_f32 v149, v130, v131
	v_cvt_pk_bf16_f32 v150, v132, v133
	v_cvt_pk_bf16_f32 v151, v134, v135
	v_cvt_pk_bf16_f32 v152, v136, v137
	v_cvt_pk_bf16_f32 v153, v138, v139
	v_cvt_pk_bf16_f32 v154, v140, v141
	v_cvt_pk_bf16_f32 v155, v142, v143
	global_store_dwordx4 v1, v[148:151], s[12:13] offset:2048 sc1
	global_store_dwordx4 v1, v[152:155], s[12:13] offset:3072 sc1
	s_add_u32 s12, s12, 0x1000
	s_addc_u32 s13, s13, 0
	global_load_dwordx4 v[72:75], v1, s[8:9] offset:2048
	global_load_dwordx4 v[76:79], v1, s[8:9] offset:3072
	s_add_u32 s8, s8, 0x1000
	s_addc_u32 s9, s9, 0
	s_waitcnt vmcnt(18)
	v_lshlrev_b32_e32 v128, 16, v80
	v_and_b32_e32 v129, 0xffff0000, v80
	v_lshlrev_b32_e32 v130, 16, v81
	v_and_b32_e32 v131, 0xffff0000, v81
	v_lshlrev_b32_e32 v132, 16, v82
	v_and_b32_e32 v133, 0xffff0000, v82
	v_lshlrev_b32_e32 v134, 16, v83
	v_and_b32_e32 v135, 0xffff0000, v83
	v_lshlrev_b32_e32 v136, 16, v84
	v_and_b32_e32 v137, 0xffff0000, v84
	v_lshlrev_b32_e32 v138, 16, v85
	v_and_b32_e32 v139, 0xffff0000, v85
	v_lshlrev_b32_e32 v140, 16, v86
	v_and_b32_e32 v141, 0xffff0000, v86
	v_lshlrev_b32_e32 v142, 16, v87
	v_and_b32_e32 v143, 0xffff0000, v87
	v_pk_mul_f32 v[144:145], v[128:129], v[128:129]
	v_pk_fma_f32 v[144:145], v[130:131], v[130:131], v[144:145]
	v_pk_fma_f32 v[144:145], v[132:133], v[132:133], v[144:145]
	v_pk_fma_f32 v[144:145], v[134:135], v[134:135], v[144:145]
	v_pk_fma_f32 v[144:145], v[136:137], v[136:137], v[144:145]
	v_pk_fma_f32 v[144:145], v[138:139], v[138:139], v[144:145]
	v_pk_fma_f32 v[144:145], v[140:141], v[140:141], v[144:145]
	v_pk_fma_f32 v[144:145], v[142:143], v[142:143], v[144:145]
	v_add_f32_e32 v144, v144, v145
	s_nop 1
	v_add_f32_dpp v144, v144, v144 quad_perm:[1,0,3,2] row_mask:0xf bank_mask:0xf
	s_nop 1
	v_add_f32_dpp v144, v144, v144 quad_perm:[2,3,0,1] row_mask:0xf bank_mask:0xf
	s_nop 1
	v_add_f32_dpp v144, v144, v144 row_half_mirror row_mask:0xf bank_mask:0xf
	s_nop 1
	v_add_f32_dpp v144, v144, v144 row_mirror row_mask:0xf bank_mask:0xf
	s_nop 0
	v_mov_b32_e32 v145, v144
	s_nop 1
	v_permlane16_swap_b32_e32 v144, v145
	s_nop 0
	v_add_f32_e32 v144, v144, v145
	v_mov_b32_e32 v145, v144
	s_nop 1
	v_permlane32_swap_b32_e32 v144, v145
	s_nop 0
	v_add_f32_e32 v144, v144, v145
	v_fmamk_f32 v144, v144, 0x3a800000, v3
	v_rsq_f32_e32 v144, v144
	s_nop 0
	v_pk_mul_f32 v[128:129], v[128:129], v[144:145] op_sel_hi:[1,0]
	v_pk_mul_f32 v[130:131], v[130:131], v[144:145] op_sel_hi:[1,0]
	v_pk_mul_f32 v[132:133], v[132:133], v[144:145] op_sel_hi:[1,0]
; __device__ __forceinline__ unsigned cvt_pk_bf16(float lo, float hi) { unsigned r; asm("v_cvt_pk_bf16_f32 %0, %1, %2" : "=v"(r) : "v"(lo), "v"(hi)); return r; }
; __device__ __forceinline__ void norm_pass_bf16(const Ctx& X, const bf16_t* xs, const bf16_t* cs, int nrows, const float* gain, const float* modl, int si, bf16_t* HN) {
;     ...
;         for (int j = 0; j < 2; ++j) {
;             v[j][0] = bf2f(q[j].x & 0xffffu); v[j][1] = bf2f(q[j].x >> 16); v[j][2] = bf2f(q[j].y & 0xffffu); v[j][3] = bf2f(q[j].y >> 16);
;             v[j][4] = bf2f(q[j].z & 0xffffu); v[j][5] = bf2f(q[j].z >> 16); v[j][6] = bf2f(q[j].w & 0xffffu); v[j][7] = bf2f(q[j].w >> 16);
; #pragma unroll
;             for (int e = 0; e < 8; ++e) s += v[j][e] * v[j][e]; }
;         const float rstd = rsqrtf(wave_sum(s) * (1.0f / 1024.0f) + 1e-6f);
; #pragma unroll
;         for (int j = 0; j < 2; ++j) { const int c = (X.lane + 64 * j) * 8; float o[8];
; #pragma unroll
;             for (int h = 0; h < 2; ++h) { const f32x4 gn = *(const f32x4*)(gain + c + 4 * h), a = *(const f32x4*)(scl + c + 4 * h), b = *(const f32x4*)(sh + c + 4 * h);
; #pragma unroll
;                 for (int e = 0; e < 4; ++e) o[4 * h + e] = v[j][4 * h + e] * rstd * gn[e] * (a[e] + 1.0f) + b[e]; }
;             u32x4 w; w.x = cvt_pk_bf16(o[0], o[1]); w.y = cvt_pk_bf16(o[2], o[3]); w.z = cvt_pk_bf16(o[4], o[5]); w.w = cvt_pk_bf16(o[6], o[7]); *(u32x4*)(HN + (size_t)r * D + c) = w; }
	v_pk_mul_f32 v[134:135], v[134:135], v[144:145] op_sel_hi:[1,0]
	v_pk_mul_f32 v[136:137], v[136:137], v[144:145] op_sel_hi:[1,0]
	v_pk_mul_f32 v[138:139], v[138:139], v[144:145] op_sel_hi:[1,0]
	v_pk_mul_f32 v[140:141], v[140:141], v[144:145] op_sel_hi:[1,0]
	v_pk_mul_f32 v[142:143], v[142:143], v[144:145] op_sel_hi:[1,0]
	v_pk_mul_f32 v[128:129], v[16:17], v[128:129]
	v_pk_mul_f32 v[130:131], v[18:19], v[130:131]
	v_pk_mul_f32 v[132:133], v[20:21], v[132:133]
	v_pk_mul_f32 v[134:135], v[22:23], v[134:135]
	v_pk_mul_f32 v[136:137], v[24:25], v[136:137]
	v_pk_mul_f32 v[138:139], v[26:27], v[138:139]
	v_pk_mul_f32 v[140:141], v[28:29], v[140:141]
	v_pk_mul_f32 v[142:143], v[30:31], v[142:143]
	v_pk_fma_f32 v[128:129], v[32:33], v[128:129], v[48:49]
	v_pk_fma_f32 v[130:131], v[34:35], v[130:131], v[50:51]
	v_pk_fma_f32 v[132:133], v[36:37], v[132:133], v[52:53]
	v_pk_fma_f32 v[134:135], v[38:39], v[134:135], v[54:55]
	v_pk_fma_f32 v[136:137], v[40:41], v[136:137], v[56:57]
	v_pk_fma_f32 v[138:139], v[42:43], v[138:139], v[58:59]
	v_pk_fma_f32 v[140:141], v[44:45], v[140:141], v[60:61]
	v_pk_fma_f32 v[142:143], v[46:47], v[142:143], v[62:63]
	v_cvt_pk_bf16_f32 v148, v128, v129
	v_cvt_pk_bf16_f32 v149, v130, v131
	v_cvt_pk_bf16_f32 v150, v132, v133
	v_cvt_pk_bf16_f32 v151, v134, v135
	v_cvt_pk_bf16_f32 v152, v136, v137
	v_cvt_pk_bf16_f32 v153, v138, v139
	v_cvt_pk_bf16_f32 v154, v140, v141
	v_cvt_pk_bf16_f32 v155, v142, v143
	global_store_dwordx4 v1, v[148:151], s[12:13] sc1
	global_store_dwordx4 v1, v[152:155], s[12:13] offset:1024 sc1
	global_load_dwordx4 v[80:83], v1, s[8:9]
	global_load_dwordx4 v[84:87], v1, s[8:9] offset:1024
	s_waitcnt vmcnt(20)
	v_lshlrev_b32_e32 v128, 16, v88
	v_and_b32_e32 v129, 0xffff0000, v88
	v_lshlrev_b32_e32 v130, 16, v89
	v_and_b32_e32 v131, 0xffff0000, v89
	v_lshlrev_b32_e32 v132, 16, v90
	v_and_b32_e32 v133, 0xffff0000, v90
	v_lshlrev_b32_e32 v134, 16, v91
	v_and_b32_e32 v135, 0xffff0000, v91
	v_lshlrev_b32_e32 v136, 16, v92
	v_and_b32_e32 v137, 0xffff0000, v92
	v_lshlrev_b32_e32 v138, 16, v93
	v_and_b32_e32 v139, 0xffff0000, v93
	v_lshlrev_b32_e32 v140, 16, v94
	v_and_b32_e32 v141, 0xffff0000, v94
	v_lshlrev_b32_e32 v142, 16, v95
	v_and_b32_e32 v143, 0xffff0000, v95
	v_pk_mul_f32 v[144:145], v[128:129], v[128:129]
	v_pk_fma_f32 v[144:145], v[130:131], v[130:131], v[144:145]
	v_pk_fma_f32 v[144:145], v[132:133], v[132:133], v[144:145]
	v_pk_fma_f32 v[144:145], v[134:135], v[134:135], v[144:145]
	v_pk_fma_f32 v[144:145], v[136:137], v[136:137], v[144:145]
	v_pk_fma_f32 v[144:145], v[138:139], v[138:139], v[144:145]
	v_pk_fma_f32 v[144:145], v[140:141], v[140:141], v[144:145]
	v_pk_fma_f32 v[144:145], v[142:143], v[142:143], v[144:145]
	v_add_f32_e32 v144, v144, v145
	s_nop 1
	v_add_f32_dpp v144, v144, v144 quad_perm:[1,0,3,2] row_mask:0xf bank_mask:0xf
	s_nop 1
	v_add_f32_dpp v144, v144, v144 quad_perm:[2,3,0,1] row_mask:0xf bank_mask:0xf
	s_nop 1
	v_add_f32_dpp v144, v144, v144 row_half_mirror row_mask:0xf bank_mask:0xf
	s_nop 1
	v_add_f32_dpp v144, v144, v144 row_mirror row_mask:0xf bank_mask:0xf
	s_nop 0
	v_mov_b32_e32 v145, v144
	s_nop 1
	v_permlane16_swap_b32_e32 v144, v145
	s_nop 0
	v_add_f32_e32 v144, v144, v145
	v_mov_b32_e32 v145, v144
	s_nop 1
	v_permlane32_swap_b32_e32 v144, v145
	s_nop 0
	v_add_f32_e32 v144, v144, v145
	v_fmamk_f32 v144, v144, 0x3a800000, v3
	v_rsq_f32_e32 v144, v144
	s_nop 0
	v_pk_mul_f32 v[128:129], v[128:129], v[144:145] op_sel_hi:[1,0]
	v_pk_mul_f32 v[130:131], v[130:131], v[144:145] op_sel_hi:[1,0]
	v_pk_mul_f32 v[132:133], v[132:133], v[144:145] op_sel_hi:[1,0]
	v_pk_mul_f32 v[134:135], v[134:135], v[144:145] op_sel_hi:[1,0]
	v_pk_mul_f32 v[136:137], v[136:137], v[144:145] op_sel_hi:[1,0]
	v_pk_mul_f32 v[138:139], v[138:139], v[144:145] op_sel_hi:[1,0]
	v_pk_mul_f32 v[140:141], v[140:141], v[144:145] op_sel_hi:[1,0]
	v_pk_mul_f32 v[142:143], v[142:143], v[144:145] op_sel_hi:[1,0]
	v_pk_mul_f32 v[128:129], v[16:17], v[128:129]
	v_pk_mul_f32 v[130:131], v[18:19], v[130:131]
	v_pk_mul_f32 v[132:133], v[20:21], v[132:133]
	v_pk_mul_f32 v[134:135], v[22:23], v[134:135]
	v_pk_mul_f32 v[136:137], v[24:25], v[136:137]
	v_pk_mul_f32 v[138:139], v[26:27], v[138:139]
	v_pk_mul_f32 v[140:141], v[28:29], v[140:141]
	v_pk_mul_f32 v[142:143], v[30:31], v[142:143]
	v_pk_fma_f32 v[128:129], v[32:33], v[128:129], v[48:49]
	v_pk_fma_f32 v[130:131], v[34:35], v[130:131], v[50:51]
	v_pk_fma_f32 v[132:133], v[36:37], v[132:133], v[52:53]
	v_pk_fma_f32 v[134:135], v[38:39], v[134:135], v[54:55]
	v_pk_fma_f32 v[136:137], v[40:41], v[136:137], v[56:57]
	v_pk_fma_f32 v[138:139], v[42:43], v[138:139], v[58:59]
	v_pk_fma_f32 v[140:141], v[44:45], v[140:141], v[60:61]
	v_pk_fma_f32 v[142:143], v[46:47], v[142:143], v[62:63]
	v_cvt_pk_bf16_f32 v148, v128, v129
	v_cvt_pk_bf16_f32 v149, v130, v131
	v_cvt_pk_bf16_f32 v150, v132, v133
	v_cvt_pk_bf16_f32 v151, v134, v135
	v_cvt_pk_bf16_f32 v152, v136, v137
	v_cvt_pk_bf16_f32 v153, v138, v139
	v_cvt_pk_bf16_f32 v154, v140, v141
	v_cvt_pk_bf16_f32 v155, v142, v143
	global_store_dwordx4 v1, v[148:151], s[12:13] offset:2048 sc1
	global_store_dwordx4 v1, v[152:155], s[12:13] offset:3072 sc1
	s_add_u32 s12, s12, 0x1000
	s_addc_u32 s13, s13, 0
	global_load_dwordx4 v[88:91], v1, s[8:9] offset:2048
	global_load_dwordx4 v[92:95], v1, s[8:9] offset:3072
	s_add_u32 s8, s8, 0x1000
	s_addc_u32 s9, s9, 0
	s_waitcnt vmcnt(22)
; __device__ __forceinline__ unsigned cvt_pk_bf16(float lo, float hi) { unsigned r; asm("v_cvt_pk_bf16_f32 %0, %1, %2" : "=v"(r) : "v"(lo), "v"(hi)); return r; }
; __device__ __forceinline__ void norm_pass_bf16(const Ctx& X, const bf16_t* xs, const bf16_t* cs, int nrows, const float* gain, const float* modl, int si, bf16_t* HN) {
;     ...
;         for (int j = 0; j < 2; ++j) {
;             v[j][0] = bf2f(q[j].x & 0xffffu); v[j][1] = bf2f(q[j].x >> 16); v[j][2] = bf2f(q[j].y & 0xffffu); v[j][3] = bf2f(q[j].y >> 16);
;             v[j][4] = bf2f(q[j].z & 0xffffu); v[j][5] = bf2f(q[j].z >> 16); v[j][6] = bf2f(q[j].w & 0xffffu); v[j][7] = bf2f(q[j].w >> 16);
; #pragma unroll
;             for (int e = 0; e < 8; ++e) s += v[j][e] * v[j][e]; }
;         const float rstd = rsqrtf(wave_sum(s) * (1.0f / 1024.0f) + 1e-6f);
; #pragma unroll
;         for (int j = 0; j < 2; ++j) { const int c = (X.lane + 64 * j) * 8; float o[8];
; #pragma unroll
;             for (int h = 0; h < 2; ++h) { const f32x4 gn = *(const f32x4*)(gain + c + 4 * h), a = *(const f32x4*)(scl + c + 4 * h), b = *(const f32x4*)(sh + c + 4 * h);
; #pragma unroll
;                 for (int e = 0; e < 4; ++e) o[4 * h + e] = v[j][4 * h + e] * rstd * gn[e] * (a[e] + 1.0f) + b[e]; }
;             u32x4 w; w.x = cvt_pk_bf16(o[0], o[1]); w.y = cvt_pk_bf16(o[2], o[3]); w.z = cvt_pk_bf16(o[4], o[5]); w.w = cvt_pk_bf16(o[6], o[7]); *(u32x4*)(HN + (size_t)r * D + c) = w; }
	v_lshlrev_b32_e32 v128, 16, v96
	v_and_b32_e32 v129, 0xffff0000, v96
	v_lshlrev_b32_e32 v130, 16, v97
	v_and_b32_e32 v131, 0xffff0000, v97
	v_lshlrev_b32_e32 v132, 16, v98
	v_and_b32_e32 v133, 0xffff0000, v98
	v_lshlrev_b32_e32 v134, 16, v99
	v_and_b32_e32 v135, 0xffff0000, v99
	v_lshlrev_b32_e32 v136, 16, v100
	v_and_b32_e32 v137, 0xffff0000, v100
	v_lshlrev_b32_e32 v138, 16, v101
	v_and_b32_e32 v139, 0xffff0000, v101
	v_lshlrev_b32_e32 v140, 16, v102
	v_and_b32_e32 v141, 0xffff0000, v102
	v_lshlrev_b32_e32 v142, 16, v103
	v_and_b32_e32 v143, 0xffff0000, v103
	v_pk_mul_f32 v[144:145], v[128:129], v[128:129]
	v_pk_fma_f32 v[144:145], v[130:131], v[130:131], v[144:145]
	v_pk_fma_f32 v[144:145], v[132:133], v[132:133], v[144:145]
	v_pk_fma_f32 v[144:145], v[134:135], v[134:135], v[144:145]
	v_pk_fma_f32 v[144:145], v[136:137], v[136:137], v[144:145]
	v_pk_fma_f32 v[144:145], v[138:139], v[138:139], v[144:145]
	v_pk_fma_f32 v[144:145], v[140:141], v[140:141], v[144:145]
	v_pk_fma_f32 v[144:145], v[142:143], v[142:143], v[144:145]
	v_add_f32_e32 v144, v144, v145
	s_nop 1
	v_add_f32_dpp v144, v144, v144 quad_perm:[1,0,3,2] row_mask:0xf bank_mask:0xf
	s_nop 1
	v_add_f32_dpp v144, v144, v144 quad_perm:[2,3,0,1] row_mask:0xf bank_mask:0xf
	s_nop 1
	v_add_f32_dpp v144, v144, v144 row_half_mirror row_mask:0xf bank_mask:0xf
	s_nop 1
	v_add_f32_dpp v144, v144, v144 row_mirror row_mask:0xf bank_mask:0xf
	s_nop 0
	v_mov_b32_e32 v145, v144
	s_nop 1
	v_permlane16_swap_b32_e32 v144, v145
	s_nop 0
	v_add_f32_e32 v144, v144, v145
	v_mov_b32_e32 v145, v144
	s_nop 1
	v_permlane32_swap_b32_e32 v144, v145
	s_nop 0
	v_add_f32_e32 v144, v144, v145
	v_fmamk_f32 v144, v144, 0x3a800000, v3
	v_rsq_f32_e32 v144, v144
	s_nop 0
	v_pk_mul_f32 v[128:129], v[128:129], v[144:145] op_sel_hi:[1,0]
	v_pk_mul_f32 v[130:131], v[130:131], v[144:145] op_sel_hi:[1,0]
	v_pk_mul_f32 v[132:133], v[132:133], v[144:145] op_sel_hi:[1,0]
	v_pk_mul_f32 v[134:135], v[134:135], v[144:145] op_sel_hi:[1,0]
	v_pk_mul_f32 v[136:137], v[136:137], v[144:145] op_sel_hi:[1,0]
	v_pk_mul_f32 v[138:139], v[138:139], v[144:145] op_sel_hi:[1,0]
	v_pk_mul_f32 v[140:141], v[140:141], v[144:145] op_sel_hi:[1,0]
	v_pk_mul_f32 v[142:143], v[142:143], v[144:145] op_sel_hi:[1,0]
	v_pk_mul_f32 v[128:129], v[16:17], v[128:129]
	v_pk_mul_f32 v[130:131], v[18:19], v[130:131]
	v_pk_mul_f32 v[132:133], v[20:21], v[132:133]
	v_pk_mul_f32 v[134:135], v[22:23], v[134:135]
	v_pk_mul_f32 v[136:137], v[24:25], v[136:137]
	v_pk_mul_f32 v[138:139], v[26:27], v[138:139]
	v_pk_mul_f32 v[140:141], v[28:29], v[140:141]
	v_pk_mul_f32 v[142:143], v[30:31], v[142:143]
	v_pk_fma_f32 v[128:129], v[32:33], v[128:129], v[48:49]
	v_pk_fma_f32 v[130:131], v[34:35], v[130:131], v[50:51]
	v_pk_fma_f32 v[132:133], v[36:37], v[132:133], v[52:53]
	v_pk_fma_f32 v[134:135], v[38:39], v[134:135], v[54:55]
	v_pk_fma_f32 v[136:137], v[40:41], v[136:137], v[56:57]
	v_pk_fma_f32 v[138:139], v[42:43], v[138:139], v[58:59]
	v_pk_fma_f32 v[140:141], v[44:45], v[140:141], v[60:61]
	v_pk_fma_f32 v[142:143], v[46:47], v[142:143], v[62:63]
	v_cvt_pk_bf16_f32 v148, v128, v129
	v_cvt_pk_bf16_f32 v149, v130, v131
	v_cvt_pk_bf16_f32 v150, v132, v133
	v_cvt_pk_bf16_f32 v151, v134, v135
	v_cvt_pk_bf16_f32 v152, v136, v137
	v_cvt_pk_bf16_f32 v153, v138, v139
	v_cvt_pk_bf16_f32 v154, v140, v141
	v_cvt_pk_bf16_f32 v155, v142, v143
	global_store_dwordx4 v1, v[148:151], s[12:13] sc1
	global_store_dwordx4 v1, v[152:155], s[12:13] offset:1024 sc1
	global_load_dwordx4 v[96:99], v1, s[8:9]
	global_load_dwordx4 v[100:103], v1, s[8:9] offset:1024
	s_waitcnt vmcnt(24)
	v_lshlrev_b32_e32 v128, 16, v104
	v_and_b32_e32 v129, 0xffff0000, v104
	v_lshlrev_b32_e32 v130, 16, v105
	v_and_b32_e32 v131, 0xffff0000, v105
	v_lshlrev_b32_e32 v132, 16, v106
	v_and_b32_e32 v133, 0xffff0000, v106
	v_lshlrev_b32_e32 v134, 16, v107
	v_and_b32_e32 v135, 0xffff0000, v107
	v_lshlrev_b32_e32 v136, 16, v108
	v_and_b32_e32 v137, 0xffff0000, v108
	v_lshlrev_b32_e32 v138, 16, v109
	v_and_b32_e32 v139, 0xffff0000, v109
	v_lshlrev_b32_e32 v140, 16, v110
	v_and_b32_e32 v141, 0xffff0000, v110
	v_lshlrev_b32_e32 v142, 16, v111
	v_and_b32_e32 v143, 0xffff0000, v111
	v_pk_mul_f32 v[144:145], v[128:129], v[128:129]
	v_pk_fma_f32 v[144:145], v[130:131], v[130:131], v[144:145]
	v_pk_fma_f32 v[144:145], v[132:133], v[132:133], v[144:145]
	v_pk_fma_f32 v[144:145], v[134:135], v[134:135], v[144:145]
	v_pk_fma_f32 v[144:145], v[136:137], v[136:137], v[144:145]
	v_pk_fma_f32 v[144:145], v[138:139], v[138:139], v[144:145]
	v_pk_fma_f32 v[144:145], v[140:141], v[140:141], v[144:145]
	v_pk_fma_f32 v[144:145], v[142:143], v[142:143], v[144:145]
	v_add_f32_e32 v144, v144, v145
	s_nop 1
	v_add_f32_dpp v144, v144, v144 quad_perm:[1,0,3,2] row_mask:0xf bank_mask:0xf
	s_nop 1
	v_add_f32_dpp v144, v144, v144 quad_perm:[2,3,0,1] row_mask:0xf bank_mask:0xf
	s_nop 1
	v_add_f32_dpp v144, v144, v144 row_half_mirror row_mask:0xf bank_mask:0xf
	s_nop 1
	v_add_f32_dpp v144, v144, v144 row_mirror row_mask:0xf bank_mask:0xf
	s_nop 0
	v_mov_b32_e32 v145, v144
	s_nop 1
	v_permlane16_swap_b32_e32 v144, v145
	s_nop 0
	v_add_f32_e32 v144, v144, v145
	v_mov_b32_e32 v145, v144
	s_nop 1
	v_permlane32_swap_b32_e32 v144, v145
	s_nop 0
	v_add_f32_e32 v144, v144, v145
	v_fmamk_f32 v144, v144, 0x3a800000, v3
	v_rsq_f32_e32 v144, v144
	s_nop 0
	v_pk_mul_f32 v[128:129], v[128:129], v[144:145] op_sel_hi:[1,0]
	v_pk_mul_f32 v[130:131], v[130:131], v[144:145] op_sel_hi:[1,0]
	v_pk_mul_f32 v[132:133], v[132:133], v[144:145] op_sel_hi:[1,0]
	v_pk_mul_f32 v[134:135], v[134:135], v[144:145] op_sel_hi:[1,0]
	v_pk_mul_f32 v[136:137], v[136:137], v[144:145] op_sel_hi:[1,0]
; __device__ __forceinline__ unsigned cvt_pk_bf16(float lo, float hi) { unsigned r; asm("v_cvt_pk_bf16_f32 %0, %1, %2" : "=v"(r) : "v"(lo), "v"(hi)); return r; }
; __device__ __forceinline__ void norm_pass_bf16(const Ctx& X, const bf16_t* xs, const bf16_t* cs, int nrows, const float* gain, const float* modl, int si, bf16_t* HN) {
;     ...
;         for (int j = 0; j < 2; ++j) {
;             v[j][0] = bf2f(q[j].x & 0xffffu); v[j][1] = bf2f(q[j].x >> 16); v[j][2] = bf2f(q[j].y & 0xffffu); v[j][3] = bf2f(q[j].y >> 16);
;             v[j][4] = bf2f(q[j].z & 0xffffu); v[j][5] = bf2f(q[j].z >> 16); v[j][6] = bf2f(q[j].w & 0xffffu); v[j][7] = bf2f(q[j].w >> 16);
; #pragma unroll
;             for (int e = 0; e < 8; ++e) s += v[j][e] * v[j][e]; }
;         const float rstd = rsqrtf(wave_sum(s) * (1.0f / 1024.0f) + 1e-6f);
; #pragma unroll
;         for (int j = 0; j < 2; ++j) { const int c = (X.lane + 64 * j) * 8; float o[8];
; #pragma unroll
;             for (int h = 0; h < 2; ++h) { const f32x4 gn = *(const f32x4*)(gain + c + 4 * h), a = *(const f32x4*)(scl + c + 4 * h), b = *(const f32x4*)(sh + c + 4 * h);
; #pragma unroll
;                 for (int e = 0; e < 4; ++e) o[4 * h + e] = v[j][4 * h + e] * rstd * gn[e] * (a[e] + 1.0f) + b[e]; }
;             u32x4 w; w.x = cvt_pk_bf16(o[0], o[1]); w.y = cvt_pk_bf16(o[2], o[3]); w.z = cvt_pk_bf16(o[4], o[5]); w.w = cvt_pk_bf16(o[6], o[7]); *(u32x4*)(HN + (size_t)r * D + c) = w; }
	v_pk_mul_f32 v[138:139], v[138:139], v[144:145] op_sel_hi:[1,0]
	v_pk_mul_f32 v[140:141], v[140:141], v[144:145] op_sel_hi:[1,0]
	v_pk_mul_f32 v[142:143], v[142:143], v[144:145] op_sel_hi:[1,0]
	v_pk_mul_f32 v[128:129], v[16:17], v[128:129]
	v_pk_mul_f32 v[130:131], v[18:19], v[130:131]
	v_pk_mul_f32 v[132:133], v[20:21], v[132:133]
	v_pk_mul_f32 v[134:135], v[22:23], v[134:135]
	v_pk_mul_f32 v[136:137], v[24:25], v[136:137]
	v_pk_mul_f32 v[138:139], v[26:27], v[138:139]
	v_pk_mul_f32 v[140:141], v[28:29], v[140:141]
	v_pk_mul_f32 v[142:143], v[30:31], v[142:143]
	v_pk_fma_f32 v[128:129], v[32:33], v[128:129], v[48:49]
	v_pk_fma_f32 v[130:131], v[34:35], v[130:131], v[50:51]
	v_pk_fma_f32 v[132:133], v[36:37], v[132:133], v[52:53]
	v_pk_fma_f32 v[134:135], v[38:39], v[134:135], v[54:55]
	v_pk_fma_f32 v[136:137], v[40:41], v[136:137], v[56:57]
	v_pk_fma_f32 v[138:139], v[42:43], v[138:139], v[58:59]
	v_pk_fma_f32 v[140:141], v[44:45], v[140:141], v[60:61]
	v_pk_fma_f32 v[142:143], v[46:47], v[142:143], v[62:63]
	v_cvt_pk_bf16_f32 v148, v128, v129
	v_cvt_pk_bf16_f32 v149, v130, v131
	v_cvt_pk_bf16_f32 v150, v132, v133
	v_cvt_pk_bf16_f32 v151, v134, v135
	v_cvt_pk_bf16_f32 v152, v136, v137
	v_cvt_pk_bf16_f32 v153, v138, v139
	v_cvt_pk_bf16_f32 v154, v140, v141
	v_cvt_pk_bf16_f32 v155, v142, v143
	global_store_dwordx4 v1, v[148:151], s[12:13] offset:2048 sc1
	global_store_dwordx4 v1, v[152:155], s[12:13] offset:3072 sc1
	s_add_u32 s12, s12, 0x1000
	s_addc_u32 s13, s13, 0
	global_load_dwordx4 v[104:107], v1, s[8:9] offset:2048
	global_load_dwordx4 v[108:111], v1, s[8:9] offset:3072
	s_add_u32 s8, s8, 0x1000
	s_addc_u32 s9, s9, 0
	s_waitcnt vmcnt(26)
	v_lshlrev_b32_e32 v128, 16, v112
	v_and_b32_e32 v129, 0xffff0000, v112
	v_lshlrev_b32_e32 v130, 16, v113
	v_and_b32_e32 v131, 0xffff0000, v113
	v_lshlrev_b32_e32 v132, 16, v114
	v_and_b32_e32 v133, 0xffff0000, v114
	v_lshlrev_b32_e32 v134, 16, v115
	v_and_b32_e32 v135, 0xffff0000, v115
	v_lshlrev_b32_e32 v136, 16, v116
	v_and_b32_e32 v137, 0xffff0000, v116
	v_lshlrev_b32_e32 v138, 16, v117
	v_and_b32_e32 v139, 0xffff0000, v117
	v_lshlrev_b32_e32 v140, 16, v118
	v_and_b32_e32 v141, 0xffff0000, v118
	v_lshlrev_b32_e32 v142, 16, v119
	v_and_b32_e32 v143, 0xffff0000, v119
	v_pk_mul_f32 v[144:145], v[128:129], v[128:129]
	v_pk_fma_f32 v[144:145], v[130:131], v[130:131], v[144:145]
	v_pk_fma_f32 v[144:145], v[132:133], v[132:133], v[144:145]
	v_pk_fma_f32 v[144:145], v[134:135], v[134:135], v[144:145]
	v_pk_fma_f32 v[144:145], v[136:137], v[136:137], v[144:145]
	v_pk_fma_f32 v[144:145], v[138:139], v[138:139], v[144:145]
	v_pk_fma_f32 v[144:145], v[140:141], v[140:141], v[144:145]
	v_pk_fma_f32 v[144:145], v[142:143], v[142:143], v[144:145]
	v_add_f32_e32 v144, v144, v145
	s_nop 1
	v_add_f32_dpp v144, v144, v144 quad_perm:[1,0,3,2] row_mask:0xf bank_mask:0xf
	s_nop 1
	v_add_f32_dpp v144, v144, v144 quad_perm:[2,3,0,1] row_mask:0xf bank_mask:0xf
	s_nop 1
	v_add_f32_dpp v144, v144, v144 row_half_mirror row_mask:0xf bank_mask:0xf
	s_nop 1
	v_add_f32_dpp v144, v144, v144 row_mirror row_mask:0xf bank_mask:0xf
	s_nop 0
	v_mov_b32_e32 v145, v144
	s_nop 1
	v_permlane16_swap_b32_e32 v144, v145
	s_nop 0
	v_add_f32_e32 v144, v144, v145
	v_mov_b32_e32 v145, v144
	s_nop 1
	v_permlane32_swap_b32_e32 v144, v145
	s_nop 0
	v_add_f32_e32 v144, v144, v145
	v_fmamk_f32 v144, v144, 0x3a800000, v3
	v_rsq_f32_e32 v144, v144
	s_nop 0
	v_pk_mul_f32 v[128:129], v[128:129], v[144:145] op_sel_hi:[1,0]
	v_pk_mul_f32 v[130:131], v[130:131], v[144:145] op_sel_hi:[1,0]
	v_pk_mul_f32 v[132:133], v[132:133], v[144:145] op_sel_hi:[1,0]
	v_pk_mul_f32 v[134:135], v[134:135], v[144:145] op_sel_hi:[1,0]
	v_pk_mul_f32 v[136:137], v[136:137], v[144:145] op_sel_hi:[1,0]
	v_pk_mul_f32 v[138:139], v[138:139], v[144:145] op_sel_hi:[1,0]
	v_pk_mul_f32 v[140:141], v[140:141], v[144:145] op_sel_hi:[1,0]
	v_pk_mul_f32 v[142:143], v[142:143], v[144:145] op_sel_hi:[1,0]
	v_pk_mul_f32 v[128:129], v[16:17], v[128:129]
	v_pk_mul_f32 v[130:131], v[18:19], v[130:131]
	v_pk_mul_f32 v[132:133], v[20:21], v[132:133]
	v_pk_mul_f32 v[134:135], v[22:23], v[134:135]
	v_pk_mul_f32 v[136:137], v[24:25], v[136:137]
	v_pk_mul_f32 v[138:139], v[26:27], v[138:139]
	v_pk_mul_f32 v[140:141], v[28:29], v[140:141]
	v_pk_mul_f32 v[142:143], v[30:31], v[142:143]
	v_pk_fma_f32 v[128:129], v[32:33], v[128:129], v[48:49]
	v_pk_fma_f32 v[130:131], v[34:35], v[130:131], v[50:51]
	v_pk_fma_f32 v[132:133], v[36:37], v[132:133], v[52:53]
	v_pk_fma_f32 v[134:135], v[38:39], v[134:135], v[54:55]
	v_pk_fma_f32 v[136:137], v[40:41], v[136:137], v[56:57]
	v_pk_fma_f32 v[138:139], v[42:43], v[138:139], v[58:59]
	v_pk_fma_f32 v[140:141], v[44:45], v[140:141], v[60:61]
	v_pk_fma_f32 v[142:143], v[46:47], v[142:143], v[62:63]
	v_cvt_pk_bf16_f32 v148, v128, v129
	v_cvt_pk_bf16_f32 v149, v130, v131
	v_cvt_pk_bf16_f32 v150, v132, v133
	v_cvt_pk_bf16_f32 v151, v134, v135
	v_cvt_pk_bf16_f32 v152, v136, v137
	v_cvt_pk_bf16_f32 v153, v138, v139
	v_cvt_pk_bf16_f32 v154, v140, v141
	v_cvt_pk_bf16_f32 v155, v142, v143
	global_store_dwordx4 v1, v[148:151], s[12:13] sc1
	global_store_dwordx4 v1, v[152:155], s[12:13] offset:1024 sc1
	global_load_dwordx4 v[112:115], v1, s[8:9]
	global_load_dwordx4 v[116:119], v1, s[8:9] offset:1024
	s_waitcnt vmcnt(28)
; __device__ __forceinline__ unsigned cvt_pk_bf16(float lo, float hi) { unsigned r; asm("v_cvt_pk_bf16_f32 %0, %1, %2" : "=v"(r) : "v"(lo), "v"(hi)); return r; }
; __device__ __forceinline__ void norm_pass_bf16(const Ctx& X, const bf16_t* xs, const bf16_t* cs, int nrows, const float* gain, const float* modl, int si, bf16_t* HN) {
;     ...
;         for (int j = 0; j < 2; ++j) {
;             v[j][0] = bf2f(q[j].x & 0xffffu); v[j][1] = bf2f(q[j].x >> 16); v[j][2] = bf2f(q[j].y & 0xffffu); v[j][3] = bf2f(q[j].y >> 16);
;             v[j][4] = bf2f(q[j].z & 0xffffu); v[j][5] = bf2f(q[j].z >> 16); v[j][6] = bf2f(q[j].w & 0xffffu); v[j][7] = bf2f(q[j].w >> 16);
; #pragma unroll
;             for (int e = 0; e < 8; ++e) s += v[j][e] * v[j][e]; }
;         const float rstd = rsqrtf(wave_sum(s) * (1.0f / 1024.0f) + 1e-6f);
; #pragma unroll
;         for (int j = 0; j < 2; ++j) { const int c = (X.lane + 64 * j) * 8; float o[8];
; #pragma unroll
;             for (int h = 0; h < 2; ++h) { const f32x4 gn = *(const f32x4*)(gain + c + 4 * h), a = *(const f32x4*)(scl + c + 4 * h), b = *(const f32x4*)(sh + c + 4 * h);
; #pragma unroll
;                 for (int e = 0; e < 4; ++e) o[4 * h + e] = v[j][4 * h + e] * rstd * gn[e] * (a[e] + 1.0f) + b[e]; }
;             u32x4 w; w.x = cvt_pk_bf16(o[0], o[1]); w.y = cvt_pk_bf16(o[2], o[3]); w.z = cvt_pk_bf16(o[4], o[5]); w.w = cvt_pk_bf16(o[6], o[7]); *(u32x4*)(HN + (size_t)r * D + c) = w; }
	v_lshlrev_b32_e32 v128, 16, v120
	v_and_b32_e32 v129, 0xffff0000, v120
	v_lshlrev_b32_e32 v130, 16, v121
	v_and_b32_e32 v131, 0xffff0000, v121
	v_lshlrev_b32_e32 v132, 16, v122
	v_and_b32_e32 v133, 0xffff0000, v122
	v_lshlrev_b32_e32 v134, 16, v123
	v_and_b32_e32 v135, 0xffff0000, v123
	v_lshlrev_b32_e32 v136, 16, v124
	v_and_b32_e32 v137, 0xffff0000, v124
	v_lshlrev_b32_e32 v138, 16, v125
	v_and_b32_e32 v139, 0xffff0000, v125
	v_lshlrev_b32_e32 v140, 16, v126
	v_and_b32_e32 v141, 0xffff0000, v126
	v_lshlrev_b32_e32 v142, 16, v127
	v_and_b32_e32 v143, 0xffff0000, v127
	v_pk_mul_f32 v[144:145], v[128:129], v[128:129]
	v_pk_fma_f32 v[144:145], v[130:131], v[130:131], v[144:145]
	v_pk_fma_f32 v[144:145], v[132:133], v[132:133], v[144:145]
	v_pk_fma_f32 v[144:145], v[134:135], v[134:135], v[144:145]
	v_pk_fma_f32 v[144:145], v[136:137], v[136:137], v[144:145]
	v_pk_fma_f32 v[144:145], v[138:139], v[138:139], v[144:145]
	v_pk_fma_f32 v[144:145], v[140:141], v[140:141], v[144:145]
	v_pk_fma_f32 v[144:145], v[142:143], v[142:143], v[144:145]
	v_add_f32_e32 v144, v144, v145
	s_nop 1
	v_add_f32_dpp v144, v144, v144 quad_perm:[1,0,3,2] row_mask:0xf bank_mask:0xf
	s_nop 1
	v_add_f32_dpp v144, v144, v144 quad_perm:[2,3,0,1] row_mask:0xf bank_mask:0xf
	s_nop 1
	v_add_f32_dpp v144, v144, v144 row_half_mirror row_mask:0xf bank_mask:0xf
	s_nop 1
	v_add_f32_dpp v144, v144, v144 row_mirror row_mask:0xf bank_mask:0xf
	s_nop 0
	v_mov_b32_e32 v145, v144
	s_nop 1
	v_permlane16_swap_b32_e32 v144, v145
	s_nop 0
	v_add_f32_e32 v144, v144, v145
	v_mov_b32_e32 v145, v144
	s_nop 1
	v_permlane32_swap_b32_e32 v144, v145
	s_nop 0
	v_add_f32_e32 v144, v144, v145
	v_fmamk_f32 v144, v144, 0x3a800000, v3
	v_rsq_f32_e32 v144, v144
	s_nop 0
	v_pk_mul_f32 v[128:129], v[128:129], v[144:145] op_sel_hi:[1,0]
	v_pk_mul_f32 v[130:131], v[130:131], v[144:145] op_sel_hi:[1,0]
	v_pk_mul_f32 v[132:133], v[132:133], v[144:145] op_sel_hi:[1,0]
	v_pk_mul_f32 v[134:135], v[134:135], v[144:145] op_sel_hi:[1,0]
	v_pk_mul_f32 v[136:137], v[136:137], v[144:145] op_sel_hi:[1,0]
	v_pk_mul_f32 v[138:139], v[138:139], v[144:145] op_sel_hi:[1,0]
	v_pk_mul_f32 v[140:141], v[140:141], v[144:145] op_sel_hi:[1,0]
	v_pk_mul_f32 v[142:143], v[142:143], v[144:145] op_sel_hi:[1,0]
	v_pk_mul_f32 v[128:129], v[16:17], v[128:129]
	v_pk_mul_f32 v[130:131], v[18:19], v[130:131]
	v_pk_mul_f32 v[132:133], v[20:21], v[132:133]
	v_pk_mul_f32 v[134:135], v[22:23], v[134:135]
	v_pk_mul_f32 v[136:137], v[24:25], v[136:137]
	v_pk_mul_f32 v[138:139], v[26:27], v[138:139]
	v_pk_mul_f32 v[140:141], v[28:29], v[140:141]
	v_pk_mul_f32 v[142:143], v[30:31], v[142:143]
	v_pk_fma_f32 v[128:129], v[32:33], v[128:129], v[48:49]
	v_pk_fma_f32 v[130:131], v[34:35], v[130:131], v[50:51]
	v_pk_fma_f32 v[132:133], v[36:37], v[132:133], v[52:53]
	v_pk_fma_f32 v[134:135], v[38:39], v[134:135], v[54:55]
	v_pk_fma_f32 v[136:137], v[40:41], v[136:137], v[56:57]
	v_pk_fma_f32 v[138:139], v[42:43], v[138:139], v[58:59]
	v_pk_fma_f32 v[140:141], v[44:45], v[140:141], v[60:61]
	v_pk_fma_f32 v[142:143], v[46:47], v[142:143], v[62:63]
	v_cvt_pk_bf16_f32 v148, v128, v129
	v_cvt_pk_bf16_f32 v149, v130, v131
	v_cvt_pk_bf16_f32 v150, v132, v133
	v_cvt_pk_bf16_f32 v151, v134, v135
	v_cvt_pk_bf16_f32 v152, v136, v137
	v_cvt_pk_bf16_f32 v153, v138, v139
	v_cvt_pk_bf16_f32 v154, v140, v141
	v_cvt_pk_bf16_f32 v155, v142, v143
	global_store_dwordx4 v1, v[148:151], s[12:13] offset:2048 sc1
	global_store_dwordx4 v1, v[152:155], s[12:13] offset:3072 sc1
	s_add_u32 s12, s12, 0x1000
	s_addc_u32 s13, s13, 0
	global_load_dwordx4 v[120:123], v1, s[8:9] offset:2048
	global_load_dwordx4 v[124:127], v1, s[8:9] offset:3072
	s_add_u32 s8, s8, 0x1000
	s_addc_u32 s9, s9, 0
	s_waitcnt vmcnt(28)
	v_lshlrev_b32_e32 v128, 16, v64
	v_and_b32_e32 v129, 0xffff0000, v64
	v_lshlrev_b32_e32 v130, 16, v65
	v_and_b32_e32 v131, 0xffff0000, v65
	v_lshlrev_b32_e32 v132, 16, v66
	v_and_b32_e32 v133, 0xffff0000, v66
	v_lshlrev_b32_e32 v134, 16, v67
	v_and_b32_e32 v135, 0xffff0000, v67
	v_lshlrev_b32_e32 v136, 16, v68
	v_and_b32_e32 v137, 0xffff0000, v68
	v_lshlrev_b32_e32 v138, 16, v69
	v_and_b32_e32 v139, 0xffff0000, v69
	v_lshlrev_b32_e32 v140, 16, v70
	v_and_b32_e32 v141, 0xffff0000, v70
	v_lshlrev_b32_e32 v142, 16, v71
	v_and_b32_e32 v143, 0xffff0000, v71
	v_pk_mul_f32 v[144:145], v[128:129], v[128:129]
	v_pk_fma_f32 v[144:145], v[130:131], v[130:131], v[144:145]
	v_pk_fma_f32 v[144:145], v[132:133], v[132:133], v[144:145]
	v_pk_fma_f32 v[144:145], v[134:135], v[134:135], v[144:145]
	v_pk_fma_f32 v[144:145], v[136:137], v[136:137], v[144:145]
	v_pk_fma_f32 v[144:145], v[138:139], v[138:139], v[144:145]
	v_pk_fma_f32 v[144:145], v[140:141], v[140:141], v[144:145]
	v_pk_fma_f32 v[144:145], v[142:143], v[142:143], v[144:145]
	v_add_f32_e32 v144, v144, v145
	s_nop 1
	v_add_f32_dpp v144, v144, v144 quad_perm:[1,0,3,2] row_mask:0xf bank_mask:0xf
	s_nop 1
	v_add_f32_dpp v144, v144, v144 quad_perm:[2,3,0,1] row_mask:0xf bank_mask:0xf
	s_nop 1
	v_add_f32_dpp v144, v144, v144 row_half_mirror row_mask:0xf bank_mask:0xf
	s_nop 1
	v_add_f32_dpp v144, v144, v144 row_mirror row_mask:0xf bank_mask:0xf
	s_nop 0
	v_mov_b32_e32 v145, v144
	s_nop 1
	v_permlane16_swap_b32_e32 v144, v145
	s_nop 0
	v_add_f32_e32 v144, v144, v145
	v_mov_b32_e32 v145, v144
	s_nop 1
	v_permlane32_swap_b32_e32 v144, v145
	s_nop 0
	v_add_f32_e32 v144, v144, v145
	v_fmamk_f32 v144, v144, 0x3a800000, v3
	v_rsq_f32_e32 v144, v144
	s_nop 0
	v_pk_mul_f32 v[128:129], v[128:129], v[144:145] op_sel_hi:[1,0]
	v_pk_mul_f32 v[130:131], v[130:131], v[144:145] op_sel_hi:[1,0]
	v_pk_mul_f32 v[132:133], v[132:133], v[144:145] op_sel_hi:[1,0]
; __device__ __forceinline__ unsigned cvt_pk_bf16(float lo, float hi) { unsigned r; asm("v_cvt_pk_bf16_f32 %0, %1, %2" : "=v"(r) : "v"(lo), "v"(hi)); return r; }
; __device__ __forceinline__ void norm_pass_bf16(const Ctx& X, const bf16_t* xs, const bf16_t* cs, int nrows, const float* gain, const float* modl, int si, bf16_t* HN) {
;     ...
;         for (int j = 0; j < 2; ++j) {
;             v[j][0] = bf2f(q[j].x & 0xffffu); v[j][1] = bf2f(q[j].x >> 16); v[j][2] = bf2f(q[j].y & 0xffffu); v[j][3] = bf2f(q[j].y >> 16);
;             v[j][4] = bf2f(q[j].z & 0xffffu); v[j][5] = bf2f(q[j].z >> 16); v[j][6] = bf2f(q[j].w & 0xffffu); v[j][7] = bf2f(q[j].w >> 16);
; #pragma unroll
;             for (int e = 0; e < 8; ++e) s += v[j][e] * v[j][e]; }
;         const float rstd = rsqrtf(wave_sum(s) * (1.0f / 1024.0f) + 1e-6f);
; #pragma unroll
;         for (int j = 0; j < 2; ++j) { const int c = (X.lane + 64 * j) * 8; float o[8];
; #pragma unroll
;             for (int h = 0; h < 2; ++h) { const f32x4 gn = *(const f32x4*)(gain + c + 4 * h), a = *(const f32x4*)(scl + c + 4 * h), b = *(const f32x4*)(sh + c + 4 * h);
; #pragma unroll
;                 for (int e = 0; e < 4; ++e) o[4 * h + e] = v[j][4 * h + e] * rstd * gn[e] * (a[e] + 1.0f) + b[e]; }
;             u32x4 w; w.x = cvt_pk_bf16(o[0], o[1]); w.y = cvt_pk_bf16(o[2], o[3]); w.z = cvt_pk_bf16(o[4], o[5]); w.w = cvt_pk_bf16(o[6], o[7]); *(u32x4*)(HN + (size_t)r * D + c) = w; }
	v_pk_mul_f32 v[134:135], v[134:135], v[144:145] op_sel_hi:[1,0]
	v_pk_mul_f32 v[136:137], v[136:137], v[144:145] op_sel_hi:[1,0]
	v_pk_mul_f32 v[138:139], v[138:139], v[144:145] op_sel_hi:[1,0]
	v_pk_mul_f32 v[140:141], v[140:141], v[144:145] op_sel_hi:[1,0]
	v_pk_mul_f32 v[142:143], v[142:143], v[144:145] op_sel_hi:[1,0]
	v_pk_mul_f32 v[128:129], v[16:17], v[128:129]
	v_pk_mul_f32 v[130:131], v[18:19], v[130:131]
	v_pk_mul_f32 v[132:133], v[20:21], v[132:133]
	v_pk_mul_f32 v[134:135], v[22:23], v[134:135]
	v_pk_mul_f32 v[136:137], v[24:25], v[136:137]
	v_pk_mul_f32 v[138:139], v[26:27], v[138:139]
	v_pk_mul_f32 v[140:141], v[28:29], v[140:141]
	v_pk_mul_f32 v[142:143], v[30:31], v[142:143]
	v_pk_fma_f32 v[128:129], v[32:33], v[128:129], v[48:49]
	v_pk_fma_f32 v[130:131], v[34:35], v[130:131], v[50:51]
	v_pk_fma_f32 v[132:133], v[36:37], v[132:133], v[52:53]
	v_pk_fma_f32 v[134:135], v[38:39], v[134:135], v[54:55]
	v_pk_fma_f32 v[136:137], v[40:41], v[136:137], v[56:57]
	v_pk_fma_f32 v[138:139], v[42:43], v[138:139], v[58:59]
	v_pk_fma_f32 v[140:141], v[44:45], v[140:141], v[60:61]
	v_pk_fma_f32 v[142:143], v[46:47], v[142:143], v[62:63]
	v_cvt_pk_bf16_f32 v148, v128, v129
	v_cvt_pk_bf16_f32 v149, v130, v131
	v_cvt_pk_bf16_f32 v150, v132, v133
	v_cvt_pk_bf16_f32 v151, v134, v135
	v_cvt_pk_bf16_f32 v152, v136, v137
	v_cvt_pk_bf16_f32 v153, v138, v139
	v_cvt_pk_bf16_f32 v154, v140, v141
	v_cvt_pk_bf16_f32 v155, v142, v143
	global_store_dwordx4 v1, v[148:151], s[12:13] sc1
	global_store_dwordx4 v1, v[152:155], s[12:13] offset:1024 sc1
	s_waitcnt vmcnt(26)
	v_lshlrev_b32_e32 v128, 16, v72
	v_and_b32_e32 v129, 0xffff0000, v72
	v_lshlrev_b32_e32 v130, 16, v73
	v_and_b32_e32 v131, 0xffff0000, v73
	v_lshlrev_b32_e32 v132, 16, v74
	v_and_b32_e32 v133, 0xffff0000, v74
	v_lshlrev_b32_e32 v134, 16, v75
	v_and_b32_e32 v135, 0xffff0000, v75
	v_lshlrev_b32_e32 v136, 16, v76
	v_and_b32_e32 v137, 0xffff0000, v76
	v_lshlrev_b32_e32 v138, 16, v77
	v_and_b32_e32 v139, 0xffff0000, v77
	v_lshlrev_b32_e32 v140, 16, v78
	v_and_b32_e32 v141, 0xffff0000, v78
	v_lshlrev_b32_e32 v142, 16, v79
	v_and_b32_e32 v143, 0xffff0000, v79
	v_pk_mul_f32 v[144:145], v[128:129], v[128:129]
	v_pk_fma_f32 v[144:145], v[130:131], v[130:131], v[144:145]
	v_pk_fma_f32 v[144:145], v[132:133], v[132:133], v[144:145]
	v_pk_fma_f32 v[144:145], v[134:135], v[134:135], v[144:145]
	v_pk_fma_f32 v[144:145], v[136:137], v[136:137], v[144:145]
	v_pk_fma_f32 v[144:145], v[138:139], v[138:139], v[144:145]
	v_pk_fma_f32 v[144:145], v[140:141], v[140:141], v[144:145]
	v_pk_fma_f32 v[144:145], v[142:143], v[142:143], v[144:145]
	v_add_f32_e32 v144, v144, v145
	s_nop 1
	v_add_f32_dpp v144, v144, v144 quad_perm:[1,0,3,2] row_mask:0xf bank_mask:0xf
	s_nop 1
	v_add_f32_dpp v144, v144, v144 quad_perm:[2,3,0,1] row_mask:0xf bank_mask:0xf
	s_nop 1
	v_add_f32_dpp v144, v144, v144 row_half_mirror row_mask:0xf bank_mask:0xf
	s_nop 1
	v_add_f32_dpp v144, v144, v144 row_mirror row_mask:0xf bank_mask:0xf
	s_nop 0
	v_mov_b32_e32 v145, v144
	s_nop 1
	v_permlane16_swap_b32_e32 v144, v145
	s_nop 0
	v_add_f32_e32 v144, v144, v145
	v_mov_b32_e32 v145, v144
	s_nop 1
	v_permlane32_swap_b32_e32 v144, v145
	s_nop 0
	v_add_f32_e32 v144, v144, v145
	v_fmamk_f32 v144, v144, 0x3a800000, v3
	v_rsq_f32_e32 v144, v144
	s_nop 0
	v_pk_mul_f32 v[128:129], v[128:129], v[144:145] op_sel_hi:[1,0]
	v_pk_mul_f32 v[130:131], v[130:131], v[144:145] op_sel_hi:[1,0]
	v_pk_mul_f32 v[132:133], v[132:133], v[144:145] op_sel_hi:[1,0]
	v_pk_mul_f32 v[134:135], v[134:135], v[144:145] op_sel_hi:[1,0]
	v_pk_mul_f32 v[136:137], v[136:137], v[144:145] op_sel_hi:[1,0]
	v_pk_mul_f32 v[138:139], v[138:139], v[144:145] op_sel_hi:[1,0]
	v_pk_mul_f32 v[140:141], v[140:141], v[144:145] op_sel_hi:[1,0]
	v_pk_mul_f32 v[142:143], v[142:143], v[144:145] op_sel_hi:[1,0]
	v_pk_mul_f32 v[128:129], v[16:17], v[128:129]
	v_pk_mul_f32 v[130:131], v[18:19], v[130:131]
	v_pk_mul_f32 v[132:133], v[20:21], v[132:133]
	v_pk_mul_f32 v[134:135], v[22:23], v[134:135]
	v_pk_mul_f32 v[136:137], v[24:25], v[136:137]
	v_pk_mul_f32 v[138:139], v[26:27], v[138:139]
	v_pk_mul_f32 v[140:141], v[28:29], v[140:141]
	v_pk_mul_f32 v[142:143], v[30:31], v[142:143]
	v_pk_fma_f32 v[128:129], v[32:33], v[128:129], v[48:49]
	v_pk_fma_f32 v[130:131], v[34:35], v[130:131], v[50:51]
	v_pk_fma_f32 v[132:133], v[36:37], v[132:133], v[52:53]
	v_pk_fma_f32 v[134:135], v[38:39], v[134:135], v[54:55]
	v_pk_fma_f32 v[136:137], v[40:41], v[136:137], v[56:57]
	v_pk_fma_f32 v[138:139], v[42:43], v[138:139], v[58:59]
	v_pk_fma_f32 v[140:141], v[44:45], v[140:141], v[60:61]
	v_pk_fma_f32 v[142:143], v[46:47], v[142:143], v[62:63]
	v_cvt_pk_bf16_f32 v148, v128, v129
	v_cvt_pk_bf16_f32 v149, v130, v131
	v_cvt_pk_bf16_f32 v150, v132, v133
	v_cvt_pk_bf16_f32 v151, v134, v135
	v_cvt_pk_bf16_f32 v152, v136, v137
	v_cvt_pk_bf16_f32 v153, v138, v139
	v_cvt_pk_bf16_f32 v154, v140, v141
	v_cvt_pk_bf16_f32 v155, v142, v143
	global_store_dwordx4 v1, v[148:151], s[12:13] offset:2048 sc1
	global_store_dwordx4 v1, v[152:155], s[12:13] offset:3072 sc1
	s_add_u32 s12, s12, 0x1000
	s_addc_u32 s13, s13, 0
	s_waitcnt vmcnt(24)
; __device__ __forceinline__ unsigned cvt_pk_bf16(float lo, float hi) { unsigned r; asm("v_cvt_pk_bf16_f32 %0, %1, %2" : "=v"(r) : "v"(lo), "v"(hi)); return r; }
; __device__ __forceinline__ void norm_pass_bf16(const Ctx& X, const bf16_t* xs, const bf16_t* cs, int nrows, const float* gain, const float* modl, int si, bf16_t* HN) {
;     ...
;         for (int j = 0; j < 2; ++j) {
;             v[j][0] = bf2f(q[j].x & 0xffffu); v[j][1] = bf2f(q[j].x >> 16); v[j][2] = bf2f(q[j].y & 0xffffu); v[j][3] = bf2f(q[j].y >> 16);
;             v[j][4] = bf2f(q[j].z & 0xffffu); v[j][5] = bf2f(q[j].z >> 16); v[j][6] = bf2f(q[j].w & 0xffffu); v[j][7] = bf2f(q[j].w >> 16);
; #pragma unroll
;             for (int e = 0; e < 8; ++e) s += v[j][e] * v[j][e]; }
;         const float rstd = rsqrtf(wave_sum(s) * (1.0f / 1024.0f) + 1e-6f);
; #pragma unroll
;         for (int j = 0; j < 2; ++j) { const int c = (X.lane + 64 * j) * 8; float o[8];
; #pragma unroll
;             for (int h = 0; h < 2; ++h) { const f32x4 gn = *(const f32x4*)(gain + c + 4 * h), a = *(const f32x4*)(scl + c + 4 * h), b = *(const f32x4*)(sh + c + 4 * h);
; #pragma unroll
;                 for (int e = 0; e < 4; ++e) o[4 * h + e] = v[j][4 * h + e] * rstd * gn[e] * (a[e] + 1.0f) + b[e]; }
;             u32x4 w; w.x = cvt_pk_bf16(o[0], o[1]); w.y = cvt_pk_bf16(o[2], o[3]); w.z = cvt_pk_bf16(o[4], o[5]); w.w = cvt_pk_bf16(o[6], o[7]); *(u32x4*)(HN + (size_t)r * D + c) = w; }
	v_lshlrev_b32_e32 v128, 16, v80
	v_and_b32_e32 v129, 0xffff0000, v80
	v_lshlrev_b32_e32 v130, 16, v81
	v_and_b32_e32 v131, 0xffff0000, v81
	v_lshlrev_b32_e32 v132, 16, v82
	v_and_b32_e32 v133, 0xffff0000, v82
	v_lshlrev_b32_e32 v134, 16, v83
	v_and_b32_e32 v135, 0xffff0000, v83
	v_lshlrev_b32_e32 v136, 16, v84
	v_and_b32_e32 v137, 0xffff0000, v84
	v_lshlrev_b32_e32 v138, 16, v85
	v_and_b32_e32 v139, 0xffff0000, v85
	v_lshlrev_b32_e32 v140, 16, v86
	v_and_b32_e32 v141, 0xffff0000, v86
	v_lshlrev_b32_e32 v142, 16, v87
	v_and_b32_e32 v143, 0xffff0000, v87
	v_pk_mul_f32 v[144:145], v[128:129], v[128:129]
	v_pk_fma_f32 v[144:145], v[130:131], v[130:131], v[144:145]
	v_pk_fma_f32 v[144:145], v[132:133], v[132:133], v[144:145]
	v_pk_fma_f32 v[144:145], v[134:135], v[134:135], v[144:145]
	v_pk_fma_f32 v[144:145], v[136:137], v[136:137], v[144:145]
	v_pk_fma_f32 v[144:145], v[138:139], v[138:139], v[144:145]
	v_pk_fma_f32 v[144:145], v[140:141], v[140:141], v[144:145]
	v_pk_fma_f32 v[144:145], v[142:143], v[142:143], v[144:145]
	v_add_f32_e32 v144, v144, v145
	s_nop 1
	v_add_f32_dpp v144, v144, v144 quad_perm:[1,0,3,2] row_mask:0xf bank_mask:0xf
	s_nop 1
	v_add_f32_dpp v144, v144, v144 quad_perm:[2,3,0,1] row_mask:0xf bank_mask:0xf
	s_nop 1
	v_add_f32_dpp v144, v144, v144 row_half_mirror row_mask:0xf bank_mask:0xf
	s_nop 1
	v_add_f32_dpp v144, v144, v144 row_mirror row_mask:0xf bank_mask:0xf
	s_nop 0
	v_mov_b32_e32 v145, v144
	s_nop 1
	v_permlane16_swap_b32_e32 v144, v145
	s_nop 0
	v_add_f32_e32 v144, v144, v145
	v_mov_b32_e32 v145, v144
	s_nop 1
	v_permlane32_swap_b32_e32 v144, v145
	s_nop 0
	v_add_f32_e32 v144, v144, v145
	v_fmamk_f32 v144, v144, 0x3a800000, v3
	v_rsq_f32_e32 v144, v144
	s_nop 0
	v_pk_mul_f32 v[128:129], v[128:129], v[144:145] op_sel_hi:[1,0]
	v_pk_mul_f32 v[130:131], v[130:131], v[144:145] op_sel_hi:[1,0]
	v_pk_mul_f32 v[132:133], v[132:133], v[144:145] op_sel_hi:[1,0]
	v_pk_mul_f32 v[134:135], v[134:135], v[144:145] op_sel_hi:[1,0]
	v_pk_mul_f32 v[136:137], v[136:137], v[144:145] op_sel_hi:[1,0]
	v_pk_mul_f32 v[138:139], v[138:139], v[144:145] op_sel_hi:[1,0]
	v_pk_mul_f32 v[140:141], v[140:141], v[144:145] op_sel_hi:[1,0]
	v_pk_mul_f32 v[142:143], v[142:143], v[144:145] op_sel_hi:[1,0]
	v_pk_mul_f32 v[128:129], v[16:17], v[128:129]
	v_pk_mul_f32 v[130:131], v[18:19], v[130:131]
	v_pk_mul_f32 v[132:133], v[20:21], v[132:133]
	v_pk_mul_f32 v[134:135], v[22:23], v[134:135]
	v_pk_mul_f32 v[136:137], v[24:25], v[136:137]
	v_pk_mul_f32 v[138:139], v[26:27], v[138:139]
	v_pk_mul_f32 v[140:141], v[28:29], v[140:141]
	v_pk_mul_f32 v[142:143], v[30:31], v[142:143]
	v_pk_fma_f32 v[128:129], v[32:33], v[128:129], v[48:49]
	v_pk_fma_f32 v[130:131], v[34:35], v[130:131], v[50:51]
	v_pk_fma_f32 v[132:133], v[36:37], v[132:133], v[52:53]
	v_pk_fma_f32 v[134:135], v[38:39], v[134:135], v[54:55]
	v_pk_fma_f32 v[136:137], v[40:41], v[136:137], v[56:57]
	v_pk_fma_f32 v[138:139], v[42:43], v[138:139], v[58:59]
	v_pk_fma_f32 v[140:141], v[44:45], v[140:141], v[60:61]
	v_pk_fma_f32 v[142:143], v[46:47], v[142:143], v[62:63]
	v_cvt_pk_bf16_f32 v148, v128, v129
	v_cvt_pk_bf16_f32 v149, v130, v131
	v_cvt_pk_bf16_f32 v150, v132, v133
	v_cvt_pk_bf16_f32 v151, v134, v135
	v_cvt_pk_bf16_f32 v152, v136, v137
	v_cvt_pk_bf16_f32 v153, v138, v139
	v_cvt_pk_bf16_f32 v154, v140, v141
	v_cvt_pk_bf16_f32 v155, v142, v143
	global_store_dwordx4 v1, v[148:151], s[12:13] sc1
	global_store_dwordx4 v1, v[152:155], s[12:13] offset:1024 sc1
	s_waitcnt vmcnt(22)
	v_lshlrev_b32_e32 v128, 16, v88
	v_and_b32_e32 v129, 0xffff0000, v88
	v_lshlrev_b32_e32 v130, 16, v89
	v_and_b32_e32 v131, 0xffff0000, v89
	v_lshlrev_b32_e32 v132, 16, v90
	v_and_b32_e32 v133, 0xffff0000, v90
	v_lshlrev_b32_e32 v134, 16, v91
	v_and_b32_e32 v135, 0xffff0000, v91
	v_lshlrev_b32_e32 v136, 16, v92
	v_and_b32_e32 v137, 0xffff0000, v92
	v_lshlrev_b32_e32 v138, 16, v93
	v_and_b32_e32 v139, 0xffff0000, v93
	v_lshlrev_b32_e32 v140, 16, v94
	v_and_b32_e32 v141, 0xffff0000, v94
	v_lshlrev_b32_e32 v142, 16, v95
	v_and_b32_e32 v143, 0xffff0000, v95
	v_pk_mul_f32 v[144:145], v[128:129], v[128:129]
	v_pk_fma_f32 v[144:145], v[130:131], v[130:131], v[144:145]
	v_pk_fma_f32 v[144:145], v[132:133], v[132:133], v[144:145]
	v_pk_fma_f32 v[144:145], v[134:135], v[134:135], v[144:145]
	v_pk_fma_f32 v[144:145], v[136:137], v[136:137], v[144:145]
	v_pk_fma_f32 v[144:145], v[138:139], v[138:139], v[144:145]
	v_pk_fma_f32 v[144:145], v[140:141], v[140:141], v[144:145]
	v_pk_fma_f32 v[144:145], v[142:143], v[142:143], v[144:145]
	v_add_f32_e32 v144, v144, v145
	s_nop 1
	v_add_f32_dpp v144, v144, v144 quad_perm:[1,0,3,2] row_mask:0xf bank_mask:0xf
	s_nop 1
	v_add_f32_dpp v144, v144, v144 quad_perm:[2,3,0,1] row_mask:0xf bank_mask:0xf
	s_nop 1
	v_add_f32_dpp v144, v144, v144 row_half_mirror row_mask:0xf bank_mask:0xf
	s_nop 1
	v_add_f32_dpp v144, v144, v144 row_mirror row_mask:0xf bank_mask:0xf
	s_nop 0
	v_mov_b32_e32 v145, v144
	s_nop 1
	v_permlane16_swap_b32_e32 v144, v145
	s_nop 0
	v_add_f32_e32 v144, v144, v145
	v_mov_b32_e32 v145, v144
	s_nop 1
	v_permlane32_swap_b32_e32 v144, v145
	s_nop 0
	v_add_f32_e32 v144, v144, v145
	v_fmamk_f32 v144, v144, 0x3a800000, v3
	v_rsq_f32_e32 v144, v144
	s_nop 0
	v_pk_mul_f32 v[128:129], v[128:129], v[144:145] op_sel_hi:[1,0]
	v_pk_mul_f32 v[130:131], v[130:131], v[144:145] op_sel_hi:[1,0]
	v_pk_mul_f32 v[132:133], v[132:133], v[144:145] op_sel_hi:[1,0]
	v_pk_mul_f32 v[134:135], v[134:135], v[144:145] op_sel_hi:[1,0]
	v_pk_mul_f32 v[136:137], v[136:137], v[144:145] op_sel_hi:[1,0]
	v_pk_mul_f32 v[138:139], v[138:139], v[144:145] op_sel_hi:[1,0]
	v_pk_mul_f32 v[140:141], v[140:141], v[144:145] op_sel_hi:[1,0]
; __device__ __forceinline__ unsigned cvt_pk_bf16(float lo, float hi) { unsigned r; asm("v_cvt_pk_bf16_f32 %0, %1, %2" : "=v"(r) : "v"(lo), "v"(hi)); return r; }
; __device__ __forceinline__ void norm_pass_bf16(const Ctx& X, const bf16_t* xs, const bf16_t* cs, int nrows, const float* gain, const float* modl, int si, bf16_t* HN) {
;     ...
;         for (int j = 0; j < 2; ++j) {
;             v[j][0] = bf2f(q[j].x & 0xffffu); v[j][1] = bf2f(q[j].x >> 16); v[j][2] = bf2f(q[j].y & 0xffffu); v[j][3] = bf2f(q[j].y >> 16);
;             v[j][4] = bf2f(q[j].z & 0xffffu); v[j][5] = bf2f(q[j].z >> 16); v[j][6] = bf2f(q[j].w & 0xffffu); v[j][7] = bf2f(q[j].w >> 16);
; #pragma unroll
;             for (int e = 0; e < 8; ++e) s += v[j][e] * v[j][e]; }
;         const float rstd = rsqrtf(wave_sum(s) * (1.0f / 1024.0f) + 1e-6f);
; #pragma unroll
;         for (int j = 0; j < 2; ++j) { const int c = (X.lane + 64 * j) * 8; float o[8];
; #pragma unroll
;             for (int h = 0; h < 2; ++h) { const f32x4 gn = *(const f32x4*)(gain + c + 4 * h), a = *(const f32x4*)(scl + c + 4 * h), b = *(const f32x4*)(sh + c + 4 * h);
; #pragma unroll
;                 for (int e = 0; e < 4; ++e) o[4 * h + e] = v[j][4 * h + e] * rstd * gn[e] * (a[e] + 1.0f) + b[e]; }
;             u32x4 w; w.x = cvt_pk_bf16(o[0], o[1]); w.y = cvt_pk_bf16(o[2], o[3]); w.z = cvt_pk_bf16(o[4], o[5]); w.w = cvt_pk_bf16(o[6], o[7]); *(u32x4*)(HN + (size_t)r * D + c) = w; }
	v_pk_mul_f32 v[142:143], v[142:143], v[144:145] op_sel_hi:[1,0]
	v_pk_mul_f32 v[128:129], v[16:17], v[128:129]
	v_pk_mul_f32 v[130:131], v[18:19], v[130:131]
	v_pk_mul_f32 v[132:133], v[20:21], v[132:133]
	v_pk_mul_f32 v[134:135], v[22:23], v[134:135]
	v_pk_mul_f32 v[136:137], v[24:25], v[136:137]
	v_pk_mul_f32 v[138:139], v[26:27], v[138:139]
	v_pk_mul_f32 v[140:141], v[28:29], v[140:141]
	v_pk_mul_f32 v[142:143], v[30:31], v[142:143]
	v_pk_fma_f32 v[128:129], v[32:33], v[128:129], v[48:49]
	v_pk_fma_f32 v[130:131], v[34:35], v[130:131], v[50:51]
	v_pk_fma_f32 v[132:133], v[36:37], v[132:133], v[52:53]
	v_pk_fma_f32 v[134:135], v[38:39], v[134:135], v[54:55]
	v_pk_fma_f32 v[136:137], v[40:41], v[136:137], v[56:57]
	v_pk_fma_f32 v[138:139], v[42:43], v[138:139], v[58:59]
	v_pk_fma_f32 v[140:141], v[44:45], v[140:141], v[60:61]
	v_pk_fma_f32 v[142:143], v[46:47], v[142:143], v[62:63]
	v_cvt_pk_bf16_f32 v148, v128, v129
	v_cvt_pk_bf16_f32 v149, v130, v131
	v_cvt_pk_bf16_f32 v150, v132, v133
	v_cvt_pk_bf16_f32 v151, v134, v135
	v_cvt_pk_bf16_f32 v152, v136, v137
	v_cvt_pk_bf16_f32 v153, v138, v139
	v_cvt_pk_bf16_f32 v154, v140, v141
	v_cvt_pk_bf16_f32 v155, v142, v143
	global_store_dwordx4 v1, v[148:151], s[12:13] offset:2048 sc1
	global_store_dwordx4 v1, v[152:155], s[12:13] offset:3072 sc1
	s_add_u32 s12, s12, 0x1000
	s_addc_u32 s13, s13, 0
	s_waitcnt vmcnt(20)
	v_lshlrev_b32_e32 v128, 16, v96
	v_and_b32_e32 v129, 0xffff0000, v96
	v_lshlrev_b32_e32 v130, 16, v97
	v_and_b32_e32 v131, 0xffff0000, v97
	v_lshlrev_b32_e32 v132, 16, v98
	v_and_b32_e32 v133, 0xffff0000, v98
	v_lshlrev_b32_e32 v134, 16, v99
	v_and_b32_e32 v135, 0xffff0000, v99
	v_lshlrev_b32_e32 v136, 16, v100
	v_and_b32_e32 v137, 0xffff0000, v100
	v_lshlrev_b32_e32 v138, 16, v101
	v_and_b32_e32 v139, 0xffff0000, v101
	v_lshlrev_b32_e32 v140, 16, v102
	v_and_b32_e32 v141, 0xffff0000, v102
	v_lshlrev_b32_e32 v142, 16, v103
	v_and_b32_e32 v143, 0xffff0000, v103
	v_pk_mul_f32 v[144:145], v[128:129], v[128:129]
	v_pk_fma_f32 v[144:145], v[130:131], v[130:131], v[144:145]
	v_pk_fma_f32 v[144:145], v[132:133], v[132:133], v[144:145]
	v_pk_fma_f32 v[144:145], v[134:135], v[134:135], v[144:145]
	v_pk_fma_f32 v[144:145], v[136:137], v[136:137], v[144:145]
	v_pk_fma_f32 v[144:145], v[138:139], v[138:139], v[144:145]
	v_pk_fma_f32 v[144:145], v[140:141], v[140:141], v[144:145]
	v_pk_fma_f32 v[144:145], v[142:143], v[142:143], v[144:145]
	v_add_f32_e32 v144, v144, v145
	s_nop 1
	v_add_f32_dpp v144, v144, v144 quad_perm:[1,0,3,2] row_mask:0xf bank_mask:0xf
	s_nop 1
	v_add_f32_dpp v144, v144, v144 quad_perm:[2,3,0,1] row_mask:0xf bank_mask:0xf
	s_nop 1
	v_add_f32_dpp v144, v144, v144 row_half_mirror row_mask:0xf bank_mask:0xf
	s_nop 1
	v_add_f32_dpp v144, v144, v144 row_mirror row_mask:0xf bank_mask:0xf
	s_nop 0
	v_mov_b32_e32 v145, v144
	s_nop 1
	v_permlane16_swap_b32_e32 v144, v145
	s_nop 0
	v_add_f32_e32 v144, v144, v145
	v_mov_b32_e32 v145, v144
	s_nop 1
	v_permlane32_swap_b32_e32 v144, v145
	s_nop 0
	v_add_f32_e32 v144, v144, v145
	v_fmamk_f32 v144, v144, 0x3a800000, v3
	v_rsq_f32_e32 v144, v144
	s_nop 0
	v_pk_mul_f32 v[128:129], v[128:129], v[144:145] op_sel_hi:[1,0]
	v_pk_mul_f32 v[130:131], v[130:131], v[144:145] op_sel_hi:[1,0]
	v_pk_mul_f32 v[132:133], v[132:133], v[144:145] op_sel_hi:[1,0]
	v_pk_mul_f32 v[134:135], v[134:135], v[144:145] op_sel_hi:[1,0]
	v_pk_mul_f32 v[136:137], v[136:137], v[144:145] op_sel_hi:[1,0]
	v_pk_mul_f32 v[138:139], v[138:139], v[144:145] op_sel_hi:[1,0]
	v_pk_mul_f32 v[140:141], v[140:141], v[144:145] op_sel_hi:[1,0]
	v_pk_mul_f32 v[142:143], v[142:143], v[144:145] op_sel_hi:[1,0]
	v_pk_mul_f32 v[128:129], v[16:17], v[128:129]
	v_pk_mul_f32 v[130:131], v[18:19], v[130:131]
	v_pk_mul_f32 v[132:133], v[20:21], v[132:133]
	v_pk_mul_f32 v[134:135], v[22:23], v[134:135]
	v_pk_mul_f32 v[136:137], v[24:25], v[136:137]
	v_pk_mul_f32 v[138:139], v[26:27], v[138:139]
	v_pk_mul_f32 v[140:141], v[28:29], v[140:141]
	v_pk_mul_f32 v[142:143], v[30:31], v[142:143]
	v_pk_fma_f32 v[128:129], v[32:33], v[128:129], v[48:49]
	v_pk_fma_f32 v[130:131], v[34:35], v[130:131], v[50:51]
	v_pk_fma_f32 v[132:133], v[36:37], v[132:133], v[52:53]
	v_pk_fma_f32 v[134:135], v[38:39], v[134:135], v[54:55]
	v_pk_fma_f32 v[136:137], v[40:41], v[136:137], v[56:57]
	v_pk_fma_f32 v[138:139], v[42:43], v[138:139], v[58:59]
	v_pk_fma_f32 v[140:141], v[44:45], v[140:141], v[60:61]
	v_pk_fma_f32 v[142:143], v[46:47], v[142:143], v[62:63]
	v_cvt_pk_bf16_f32 v148, v128, v129
	v_cvt_pk_bf16_f32 v149, v130, v131
	v_cvt_pk_bf16_f32 v150, v132, v133
	v_cvt_pk_bf16_f32 v151, v134, v135
	v_cvt_pk_bf16_f32 v152, v136, v137
	v_cvt_pk_bf16_f32 v153, v138, v139
	v_cvt_pk_bf16_f32 v154, v140, v141
	v_cvt_pk_bf16_f32 v155, v142, v143
	global_store_dwordx4 v1, v[148:151], s[12:13] sc1
	global_store_dwordx4 v1, v[152:155], s[12:13] offset:1024 sc1
	s_waitcnt vmcnt(18)
; __device__ __forceinline__ unsigned cvt_pk_bf16(float lo, float hi) { unsigned r; asm("v_cvt_pk_bf16_f32 %0, %1, %2" : "=v"(r) : "v"(lo), "v"(hi)); return r; }
; __device__ __forceinline__ void norm_pass_bf16(const Ctx& X, const bf16_t* xs, const bf16_t* cs, int nrows, const float* gain, const float* modl, int si, bf16_t* HN) {
;     ...
;         for (int j = 0; j < 2; ++j) {
;             v[j][0] = bf2f(q[j].x & 0xffffu); v[j][1] = bf2f(q[j].x >> 16); v[j][2] = bf2f(q[j].y & 0xffffu); v[j][3] = bf2f(q[j].y >> 16);
;             v[j][4] = bf2f(q[j].z & 0xffffu); v[j][5] = bf2f(q[j].z >> 16); v[j][6] = bf2f(q[j].w & 0xffffu); v[j][7] = bf2f(q[j].w >> 16);
; #pragma unroll
;             for (int e = 0; e < 8; ++e) s += v[j][e] * v[j][e]; }
;         const float rstd = rsqrtf(wave_sum(s) * (1.0f / 1024.0f) + 1e-6f);
; #pragma unroll
;         for (int j = 0; j < 2; ++j) { const int c = (X.lane + 64 * j) * 8; float o[8];
; #pragma unroll
;             for (int h = 0; h < 2; ++h) { const f32x4 gn = *(const f32x4*)(gain + c + 4 * h), a = *(const f32x4*)(scl + c + 4 * h), b = *(const f32x4*)(sh + c + 4 * h);
; #pragma unroll
;                 for (int e = 0; e < 4; ++e) o[4 * h + e] = v[j][4 * h + e] * rstd * gn[e] * (a[e] + 1.0f) + b[e]; }
;             u32x4 w; w.x = cvt_pk_bf16(o[0], o[1]); w.y = cvt_pk_bf16(o[2], o[3]); w.z = cvt_pk_bf16(o[4], o[5]); w.w = cvt_pk_bf16(o[6], o[7]); *(u32x4*)(HN + (size_t)r * D + c) = w; }
	v_lshlrev_b32_e32 v128, 16, v104
	v_and_b32_e32 v129, 0xffff0000, v104
	v_lshlrev_b32_e32 v130, 16, v105
	v_and_b32_e32 v131, 0xffff0000, v105
	v_lshlrev_b32_e32 v132, 16, v106
	v_and_b32_e32 v133, 0xffff0000, v106
	v_lshlrev_b32_e32 v134, 16, v107
	v_and_b32_e32 v135, 0xffff0000, v107
	v_lshlrev_b32_e32 v136, 16, v108
	v_and_b32_e32 v137, 0xffff0000, v108
	v_lshlrev_b32_e32 v138, 16, v109
	v_and_b32_e32 v139, 0xffff0000, v109
	v_lshlrev_b32_e32 v140, 16, v110
	v_and_b32_e32 v141, 0xffff0000, v110
	v_lshlrev_b32_e32 v142, 16, v111
	v_and_b32_e32 v143, 0xffff0000, v111
	v_pk_mul_f32 v[144:145], v[128:129], v[128:129]
	v_pk_fma_f32 v[144:145], v[130:131], v[130:131], v[144:145]
	v_pk_fma_f32 v[144:145], v[132:133], v[132:133], v[144:145]
	v_pk_fma_f32 v[144:145], v[134:135], v[134:135], v[144:145]
	v_pk_fma_f32 v[144:145], v[136:137], v[136:137], v[144:145]
	v_pk_fma_f32 v[144:145], v[138:139], v[138:139], v[144:145]
	v_pk_fma_f32 v[144:145], v[140:141], v[140:141], v[144:145]
	v_pk_fma_f32 v[144:145], v[142:143], v[142:143], v[144:145]
	v_add_f32_e32 v144, v144, v145
	s_nop 1
	v_add_f32_dpp v144, v144, v144 quad_perm:[1,0,3,2] row_mask:0xf bank_mask:0xf
	s_nop 1
	v_add_f32_dpp v144, v144, v144 quad_perm:[2,3,0,1] row_mask:0xf bank_mask:0xf
	s_nop 1
	v_add_f32_dpp v144, v144, v144 row_half_mirror row_mask:0xf bank_mask:0xf
	s_nop 1
	v_add_f32_dpp v144, v144, v144 row_mirror row_mask:0xf bank_mask:0xf
	s_nop 0
	v_mov_b32_e32 v145, v144
	s_nop 1
	v_permlane16_swap_b32_e32 v144, v145
	s_nop 0
	v_add_f32_e32 v144, v144, v145
	v_mov_b32_e32 v145, v144
	s_nop 1
	v_permlane32_swap_b32_e32 v144, v145
	s_nop 0
	v_add_f32_e32 v144, v144, v145
	v_fmamk_f32 v144, v144, 0x3a800000, v3
	v_rsq_f32_e32 v144, v144
	s_nop 0
	v_pk_mul_f32 v[128:129], v[128:129], v[144:145] op_sel_hi:[1,0]
	v_pk_mul_f32 v[130:131], v[130:131], v[144:145] op_sel_hi:[1,0]
	v_pk_mul_f32 v[132:133], v[132:133], v[144:145] op_sel_hi:[1,0]
	v_pk_mul_f32 v[134:135], v[134:135], v[144:145] op_sel_hi:[1,0]
	v_pk_mul_f32 v[136:137], v[136:137], v[144:145] op_sel_hi:[1,0]
	v_pk_mul_f32 v[138:139], v[138:139], v[144:145] op_sel_hi:[1,0]
	v_pk_mul_f32 v[140:141], v[140:141], v[144:145] op_sel_hi:[1,0]
	v_pk_mul_f32 v[142:143], v[142:143], v[144:145] op_sel_hi:[1,0]
	v_pk_mul_f32 v[128:129], v[16:17], v[128:129]
	v_pk_mul_f32 v[130:131], v[18:19], v[130:131]
	v_pk_mul_f32 v[132:133], v[20:21], v[132:133]
	v_pk_mul_f32 v[134:135], v[22:23], v[134:135]
	v_pk_mul_f32 v[136:137], v[24:25], v[136:137]
	v_pk_mul_f32 v[138:139], v[26:27], v[138:139]
	v_pk_mul_f32 v[140:141], v[28:29], v[140:141]
	v_pk_mul_f32 v[142:143], v[30:31], v[142:143]
	v_pk_fma_f32 v[128:129], v[32:33], v[128:129], v[48:49]
	v_pk_fma_f32 v[130:131], v[34:35], v[130:131], v[50:51]
	v_pk_fma_f32 v[132:133], v[36:37], v[132:133], v[52:53]
	v_pk_fma_f32 v[134:135], v[38:39], v[134:135], v[54:55]
	v_pk_fma_f32 v[136:137], v[40:41], v[136:137], v[56:57]
	v_pk_fma_f32 v[138:139], v[42:43], v[138:139], v[58:59]
	v_pk_fma_f32 v[140:141], v[44:45], v[140:141], v[60:61]
	v_pk_fma_f32 v[142:143], v[46:47], v[142:143], v[62:63]
	v_cvt_pk_bf16_f32 v148, v128, v129
	v_cvt_pk_bf16_f32 v149, v130, v131
	v_cvt_pk_bf16_f32 v150, v132, v133
	v_cvt_pk_bf16_f32 v151, v134, v135
	v_cvt_pk_bf16_f32 v152, v136, v137
	v_cvt_pk_bf16_f32 v153, v138, v139
	v_cvt_pk_bf16_f32 v154, v140, v141
	v_cvt_pk_bf16_f32 v155, v142, v143
	global_store_dwordx4 v1, v[148:151], s[12:13] offset:2048 sc1
	global_store_dwordx4 v1, v[152:155], s[12:13] offset:3072 sc1
	s_add_u32 s12, s12, 0x1000
	s_addc_u32 s13, s13, 0
	s_waitcnt vmcnt(16)
	v_lshlrev_b32_e32 v128, 16, v112
	v_and_b32_e32 v129, 0xffff0000, v112
	v_lshlrev_b32_e32 v130, 16, v113
	v_and_b32_e32 v131, 0xffff0000, v113
	v_lshlrev_b32_e32 v132, 16, v114
	v_and_b32_e32 v133, 0xffff0000, v114
	v_lshlrev_b32_e32 v134, 16, v115
	v_and_b32_e32 v135, 0xffff0000, v115
	v_lshlrev_b32_e32 v136, 16, v116
	v_and_b32_e32 v137, 0xffff0000, v116
	v_lshlrev_b32_e32 v138, 16, v117
	v_and_b32_e32 v139, 0xffff0000, v117
	v_lshlrev_b32_e32 v140, 16, v118
	v_and_b32_e32 v141, 0xffff0000, v118
	v_lshlrev_b32_e32 v142, 16, v119
	v_and_b32_e32 v143, 0xffff0000, v119
	v_pk_mul_f32 v[144:145], v[128:129], v[128:129]
	v_pk_fma_f32 v[144:145], v[130:131], v[130:131], v[144:145]
	v_pk_fma_f32 v[144:145], v[132:133], v[132:133], v[144:145]
	v_pk_fma_f32 v[144:145], v[134:135], v[134:135], v[144:145]
	v_pk_fma_f32 v[144:145], v[136:137], v[136:137], v[144:145]
	v_pk_fma_f32 v[144:145], v[138:139], v[138:139], v[144:145]
	v_pk_fma_f32 v[144:145], v[140:141], v[140:141], v[144:145]
	v_pk_fma_f32 v[144:145], v[142:143], v[142:143], v[144:145]
	v_add_f32_e32 v144, v144, v145
	s_nop 1
	v_add_f32_dpp v144, v144, v144 quad_perm:[1,0,3,2] row_mask:0xf bank_mask:0xf
	s_nop 1
	v_add_f32_dpp v144, v144, v144 quad_perm:[2,3,0,1] row_mask:0xf bank_mask:0xf
	s_nop 1
	v_add_f32_dpp v144, v144, v144 row_half_mirror row_mask:0xf bank_mask:0xf
	s_nop 1
	v_add_f32_dpp v144, v144, v144 row_mirror row_mask:0xf bank_mask:0xf
	s_nop 0
	v_mov_b32_e32 v145, v144
	s_nop 1
	v_permlane16_swap_b32_e32 v144, v145
	s_nop 0
	v_add_f32_e32 v144, v144, v145
	v_mov_b32_e32 v145, v144
	s_nop 1
	v_permlane32_swap_b32_e32 v144, v145
	s_nop 0
	v_add_f32_e32 v144, v144, v145
	v_fmamk_f32 v144, v144, 0x3a800000, v3
	v_rsq_f32_e32 v144, v144
	s_nop 0
	v_pk_mul_f32 v[128:129], v[128:129], v[144:145] op_sel_hi:[1,0]
; __device__ __forceinline__ unsigned cvt_pk_bf16(float lo, float hi) { unsigned r; asm("v_cvt_pk_bf16_f32 %0, %1, %2" : "=v"(r) : "v"(lo), "v"(hi)); return r; }
; __device__ __forceinline__ void norm_pass_bf16(const Ctx& X, const bf16_t* xs, const bf16_t* cs, int nrows, const float* gain, const float* modl, int si, bf16_t* HN) {
;     for (int r = X.gw; r < nrows; r += X.NGW) {
;     ...
;         for (int j = 0; j < 2; ++j) {
;             v[j][0] = bf2f(q[j].x & 0xffffu); v[j][1] = bf2f(q[j].x >> 16); v[j][2] = bf2f(q[j].y & 0xffffu); v[j][3] = bf2f(q[j].y >> 16);
;             v[j][4] = bf2f(q[j].z & 0xffffu); v[j][5] = bf2f(q[j].z >> 16); v[j][6] = bf2f(q[j].w & 0xffffu); v[j][7] = bf2f(q[j].w >> 16);
; #pragma unroll
;             for (int e = 0; e < 8; ++e) s += v[j][e] * v[j][e]; }
;         const float rstd = rsqrtf(wave_sum(s) * (1.0f / 1024.0f) + 1e-6f);
; #pragma unroll
;         for (int j = 0; j < 2; ++j) { const int c = (X.lane + 64 * j) * 8; float o[8];
; #pragma unroll
;             for (int h = 0; h < 2; ++h) { const f32x4 gn = *(const f32x4*)(gain + c + 4 * h), a = *(const f32x4*)(scl + c + 4 * h), b = *(const f32x4*)(sh + c + 4 * h);
; #pragma unroll
;                 for (int e = 0; e < 4; ++e) o[4 * h + e] = v[j][4 * h + e] * rstd * gn[e] * (a[e] + 1.0f) + b[e]; }
;             u32x4 w; w.x = cvt_pk_bf16(o[0], o[1]); w.y = cvt_pk_bf16(o[2], o[3]); w.z = cvt_pk_bf16(o[4], o[5]); w.w = cvt_pk_bf16(o[6], o[7]); *(u32x4*)(HN + (size_t)r * D + c) = w; }
	v_pk_mul_f32 v[130:131], v[130:131], v[144:145] op_sel_hi:[1,0]
	v_pk_mul_f32 v[132:133], v[132:133], v[144:145] op_sel_hi:[1,0]
	v_pk_mul_f32 v[134:135], v[134:135], v[144:145] op_sel_hi:[1,0]
	v_pk_mul_f32 v[136:137], v[136:137], v[144:145] op_sel_hi:[1,0]
	v_pk_mul_f32 v[138:139], v[138:139], v[144:145] op_sel_hi:[1,0]
	v_pk_mul_f32 v[140:141], v[140:141], v[144:145] op_sel_hi:[1,0]
	v_pk_mul_f32 v[142:143], v[142:143], v[144:145] op_sel_hi:[1,0]
	v_pk_mul_f32 v[128:129], v[16:17], v[128:129]
	v_pk_mul_f32 v[130:131], v[18:19], v[130:131]
	v_pk_mul_f32 v[132:133], v[20:21], v[132:133]
	v_pk_mul_f32 v[134:135], v[22:23], v[134:135]
	v_pk_mul_f32 v[136:137], v[24:25], v[136:137]
	v_pk_mul_f32 v[138:139], v[26:27], v[138:139]
	v_pk_mul_f32 v[140:141], v[28:29], v[140:141]
	v_pk_mul_f32 v[142:143], v[30:31], v[142:143]
	v_pk_fma_f32 v[128:129], v[32:33], v[128:129], v[48:49]
	v_pk_fma_f32 v[130:131], v[34:35], v[130:131], v[50:51]
	v_pk_fma_f32 v[132:133], v[36:37], v[132:133], v[52:53]
	v_pk_fma_f32 v[134:135], v[38:39], v[134:135], v[54:55]
	v_pk_fma_f32 v[136:137], v[40:41], v[136:137], v[56:57]
	v_pk_fma_f32 v[138:139], v[42:43], v[138:139], v[58:59]
	v_pk_fma_f32 v[140:141], v[44:45], v[140:141], v[60:61]
	v_pk_fma_f32 v[142:143], v[46:47], v[142:143], v[62:63]
	v_cvt_pk_bf16_f32 v148, v128, v129
	v_cvt_pk_bf16_f32 v149, v130, v131
	v_cvt_pk_bf16_f32 v150, v132, v133
	v_cvt_pk_bf16_f32 v151, v134, v135
	v_cvt_pk_bf16_f32 v152, v136, v137
	v_cvt_pk_bf16_f32 v153, v138, v139
	v_cvt_pk_bf16_f32 v154, v140, v141
	v_cvt_pk_bf16_f32 v155, v142, v143
	global_store_dwordx4 v1, v[148:151], s[12:13] sc1
	global_store_dwordx4 v1, v[152:155], s[12:13] offset:1024 sc1
	s_waitcnt vmcnt(14)
	v_lshlrev_b32_e32 v128, 16, v120
	v_and_b32_e32 v129, 0xffff0000, v120
	v_lshlrev_b32_e32 v130, 16, v121
	v_and_b32_e32 v131, 0xffff0000, v121
	v_lshlrev_b32_e32 v132, 16, v122
	v_and_b32_e32 v133, 0xffff0000, v122
	v_lshlrev_b32_e32 v134, 16, v123
	v_and_b32_e32 v135, 0xffff0000, v123
	v_lshlrev_b32_e32 v136, 16, v124
	v_and_b32_e32 v137, 0xffff0000, v124
	v_lshlrev_b32_e32 v138, 16, v125
	v_and_b32_e32 v139, 0xffff0000, v125
	v_lshlrev_b32_e32 v140, 16, v126
	v_and_b32_e32 v141, 0xffff0000, v126
	v_lshlrev_b32_e32 v142, 16, v127
	v_and_b32_e32 v143, 0xffff0000, v127
	v_pk_mul_f32 v[144:145], v[128:129], v[128:129]
	v_pk_fma_f32 v[144:145], v[130:131], v[130:131], v[144:145]
	v_pk_fma_f32 v[144:145], v[132:133], v[132:133], v[144:145]
	v_pk_fma_f32 v[144:145], v[134:135], v[134:135], v[144:145]
	v_pk_fma_f32 v[144:145], v[136:137], v[136:137], v[144:145]
	v_pk_fma_f32 v[144:145], v[138:139], v[138:139], v[144:145]
	v_pk_fma_f32 v[144:145], v[140:141], v[140:141], v[144:145]
	v_pk_fma_f32 v[144:145], v[142:143], v[142:143], v[144:145]
	v_add_f32_e32 v144, v144, v145
	s_nop 1
	v_add_f32_dpp v144, v144, v144 quad_perm:[1,0,3,2] row_mask:0xf bank_mask:0xf
	s_nop 1
	v_add_f32_dpp v144, v144, v144 quad_perm:[2,3,0,1] row_mask:0xf bank_mask:0xf
	s_nop 1
	v_add_f32_dpp v144, v144, v144 row_half_mirror row_mask:0xf bank_mask:0xf
	s_nop 1
	v_add_f32_dpp v144, v144, v144 row_mirror row_mask:0xf bank_mask:0xf
	s_nop 0
	v_mov_b32_e32 v145, v144
	s_nop 1
	v_permlane16_swap_b32_e32 v144, v145
	s_nop 0
	v_add_f32_e32 v144, v144, v145
	v_mov_b32_e32 v145, v144
	s_nop 1
	v_permlane32_swap_b32_e32 v144, v145
	s_nop 0
	v_add_f32_e32 v144, v144, v145
	v_fmamk_f32 v144, v144, 0x3a800000, v3
	v_rsq_f32_e32 v144, v144
	s_nop 0
	v_pk_mul_f32 v[128:129], v[128:129], v[144:145] op_sel_hi:[1,0]
	v_pk_mul_f32 v[130:131], v[130:131], v[144:145] op_sel_hi:[1,0]
	v_pk_mul_f32 v[132:133], v[132:133], v[144:145] op_sel_hi:[1,0]
	v_pk_mul_f32 v[134:135], v[134:135], v[144:145] op_sel_hi:[1,0]
	v_pk_mul_f32 v[136:137], v[136:137], v[144:145] op_sel_hi:[1,0]
	v_pk_mul_f32 v[138:139], v[138:139], v[144:145] op_sel_hi:[1,0]
	v_pk_mul_f32 v[140:141], v[140:141], v[144:145] op_sel_hi:[1,0]
	v_pk_mul_f32 v[142:143], v[142:143], v[144:145] op_sel_hi:[1,0]
	v_pk_mul_f32 v[128:129], v[16:17], v[128:129]
	v_pk_mul_f32 v[130:131], v[18:19], v[130:131]
	v_pk_mul_f32 v[132:133], v[20:21], v[132:133]
	v_pk_mul_f32 v[134:135], v[22:23], v[134:135]
	v_pk_mul_f32 v[136:137], v[24:25], v[136:137]
	v_pk_mul_f32 v[138:139], v[26:27], v[138:139]
	v_pk_mul_f32 v[140:141], v[28:29], v[140:141]
	v_pk_mul_f32 v[142:143], v[30:31], v[142:143]
	v_pk_fma_f32 v[128:129], v[32:33], v[128:129], v[48:49]
	v_pk_fma_f32 v[130:131], v[34:35], v[130:131], v[50:51]
	v_pk_fma_f32 v[132:133], v[36:37], v[132:133], v[52:53]
	v_pk_fma_f32 v[134:135], v[38:39], v[134:135], v[54:55]
	v_pk_fma_f32 v[136:137], v[40:41], v[136:137], v[56:57]
	v_pk_fma_f32 v[138:139], v[42:43], v[138:139], v[58:59]
	v_pk_fma_f32 v[140:141], v[44:45], v[140:141], v[60:61]
	v_pk_fma_f32 v[142:143], v[46:47], v[142:143], v[62:63]
	v_cvt_pk_bf16_f32 v148, v128, v129
	v_cvt_pk_bf16_f32 v149, v130, v131
	v_cvt_pk_bf16_f32 v150, v132, v133
	v_cvt_pk_bf16_f32 v151, v134, v135
	v_cvt_pk_bf16_f32 v152, v136, v137
	v_cvt_pk_bf16_f32 v153, v138, v139
	v_cvt_pk_bf16_f32 v154, v140, v141
	v_cvt_pk_bf16_f32 v155, v142, v143
	global_store_dwordx4 v1, v[148:151], s[12:13] offset:2048 sc1
	global_store_dwordx4 v1, v[152:155], s[12:13] offset:3072 sc1
	s_add_u32 s12, s12, 0x1000
	s_addc_u32 s13, s13, 0
	s_add_i32 s21, s21, s20
	s_cmp_lt_i32 s21, 0x800
	s_cbranch_scc0 .LBB0_1388
	s_waitcnt vmcnt(0)
	s_branch .Lhn_D_blk

; __device__ __forceinline__ unsigned cvt_pk_bf16(float lo, float hi) { unsigned r; asm("v_cvt_pk_bf16_f32 %0, %1, %2" : "=v"(r) : "v"(lo), "v"(hi)); return r; }
; __device__ __forceinline__ void norm_pass_bf16(const Ctx& X, const bf16_t* xs, const bf16_t* cs, int nrows, const float* gain, const float* modl, int si, bf16_t* HN) {
;     for (int r = X.gw; r < nrows; r += X.NGW) {
;         const int mb = r < MX ? (r >> 12) : 8;
;         const float* sh = modl + (size_t)mb * 9216 + si * 1024; const float* scl = sh + 1024;
;         const bf16_t* rowp = r < MX ? xs + (size_t)r * D : cs + (size_t)(r - MX) * D;
;         u32x4 q[2]; float v[2][8]; float s = 0.f;
; #pragma unroll
;         for (int j = 0; j < 2; ++j) q[j] = *(const u32x4*)(rowp + (X.lane + 64 * j) * 8);
; #pragma unroll
;         for (int j = 0; j < 2; ++j) {
;             v[j][0] = bf2f(q[j].x & 0xffffu); v[j][1] = bf2f(q[j].x >> 16); v[j][2] = bf2f(q[j].y & 0xffffu); v[j][3] = bf2f(q[j].y >> 16);
;             v[j][4] = bf2f(q[j].z & 0xffffu); v[j][5] = bf2f(q[j].z >> 16); v[j][6] = bf2f(q[j].w & 0xffffu); v[j][7] = bf2f(q[j].w >> 16);
; #pragma unroll
;             for (int e = 0; e < 8; ++e) s += v[j][e] * v[j][e]; }
;         const float rstd = rsqrtf(wave_sum(s) * (1.0f / 1024.0f) + 1e-6f);
; #pragma unroll
;         for (int j = 0; j < 2; ++j) { const int c = (X.lane + 64 * j) * 8; float o[8];
; #pragma unroll
;             for (int h = 0; h < 2; ++h) { const f32x4 gn = *(const f32x4*)(gain + c + 4 * h), a = *(const f32x4*)(scl + c + 4 * h), b = *(const f32x4*)(sh + c + 4 * h);
; #pragma unroll
;                 for (int e = 0; e < 4; ++e) o[4 * h + e] = v[j][4 * h + e] * rstd * gn[e] * (a[e] + 1.0f) + b[e]; }
;             u32x4 w; w.x = cvt_pk_bf16(o[0], o[1]); w.y = cvt_pk_bf16(o[2], o[3]); w.z = cvt_pk_bf16(o[4], o[5]); w.w = cvt_pk_bf16(o[6], o[7]); *(u32x4*)(HN + (size_t)r * D + c) = w; }
.Lhn_E_blk:
	s_add_u32 s6, s48, 0x5000
	s_addc_u32 s7, s49, 0
	global_load_dwordx4 v[16:19], v2, s[6:7]
	global_load_dwordx4 v[20:23], v2, s[6:7] offset:16
	global_load_dwordx4 v[24:27], v2, s[6:7] offset:2048
	global_load_dwordx4 v[28:31], v2, s[6:7] offset:2064
	s_lshr_b32 s1, s21, 8
	s_mul_i32 s1, s1, 0x9000
	s_add_u32 s6, s88, s1
	s_addc_u32 s7, s89, 0
	s_add_u32 s6, s6, 0x57000
	s_addc_u32 s7, s7, 0
	global_load_dwordx4 v[48:51], v2, s[6:7]
	global_load_dwordx4 v[52:55], v2, s[6:7] offset:16
	global_load_dwordx4 v[56:59], v2, s[6:7] offset:2048
	global_load_dwordx4 v[60:63], v2, s[6:7] offset:2064
	s_add_u32 s6, s6, 0x1000
	s_addc_u32 s7, s7, 0
	global_load_dwordx4 v[32:35], v2, s[6:7]
	global_load_dwordx4 v[36:39], v2, s[6:7] offset:16
	global_load_dwordx4 v[40:43], v2, s[6:7] offset:2048
	global_load_dwordx4 v[44:47], v2, s[6:7] offset:2064
	s_lshl_b32 s1, s21, 15
	s_add_u32 s8, s88, s1
	s_addc_u32 s9, s89, 0
	s_add_u32 s8, s8, 0x17400000
	s_addc_u32 s9, s9, 0
	s_add_u32 s12, s88, s1
	s_addc_u32 s13, s89, 0
	s_add_u32 s12, s12, 0x13000000
	s_addc_u32 s13, s13, 0
	global_load_dwordx4 v[64:67], v1, s[8:9]
	global_load_dwordx4 v[68:71], v1, s[8:9] offset:1024
	global_load_dwordx4 v[72:75], v1, s[8:9] offset:2048
	global_load_dwordx4 v[76:79], v1, s[8:9] offset:3072
	s_add_u32 s8, s8, 0x1000
	s_addc_u32 s9, s9, 0
	global_load_dwordx4 v[80:83], v1, s[8:9]
	global_load_dwordx4 v[84:87], v1, s[8:9] offset:1024
	global_load_dwordx4 v[88:91], v1, s[8:9] offset:2048
	global_load_dwordx4 v[92:95], v1, s[8:9] offset:3072
	s_add_u32 s8, s8, 0x1000
	s_addc_u32 s9, s9, 0
	global_load_dwordx4 v[96:99], v1, s[8:9]
	global_load_dwordx4 v[100:103], v1, s[8:9] offset:1024
	global_load_dwordx4 v[104:107], v1, s[8:9] offset:2048
	global_load_dwordx4 v[108:111], v1, s[8:9] offset:3072
	s_add_u32 s8, s8, 0x1000
	s_addc_u32 s9, s9, 0
	global_load_dwordx4 v[112:115], v1, s[8:9]
	global_load_dwordx4 v[116:119], v1, s[8:9] offset:1024
	global_load_dwordx4 v[120:123], v1, s[8:9] offset:2048
	global_load_dwordx4 v[124:127], v1, s[8:9] offset:3072
	s_add_u32 s8, s8, 0x1000
	s_addc_u32 s9, s9, 0
	s_waitcnt vmcnt(16)
	v_pk_add_f32 v[32:33], v[32:33], 1.0 op_sel_hi:[1,0]
	v_pk_add_f32 v[34:35], v[34:35], 1.0 op_sel_hi:[1,0]
	v_pk_add_f32 v[36:37], v[36:37], 1.0 op_sel_hi:[1,0]
	v_pk_add_f32 v[38:39], v[38:39], 1.0 op_sel_hi:[1,0]
	v_pk_add_f32 v[40:41], v[40:41], 1.0 op_sel_hi:[1,0]
	v_pk_add_f32 v[42:43], v[42:43], 1.0 op_sel_hi:[1,0]
	v_pk_add_f32 v[44:45], v[44:45], 1.0 op_sel_hi:[1,0]
	v_pk_add_f32 v[46:47], v[46:47], 1.0 op_sel_hi:[1,0]
	s_waitcnt vmcnt(14)
	v_lshlrev_b32_e32 v128, 16, v64
	v_and_b32_e32 v129, 0xffff0000, v64
	v_lshlrev_b32_e32 v130, 16, v65
	v_and_b32_e32 v131, 0xffff0000, v65
	v_lshlrev_b32_e32 v132, 16, v66
	v_and_b32_e32 v133, 0xffff0000, v66
	v_lshlrev_b32_e32 v134, 16, v67
	v_and_b32_e32 v135, 0xffff0000, v67
	v_lshlrev_b32_e32 v136, 16, v68
	v_and_b32_e32 v137, 0xffff0000, v68
	v_lshlrev_b32_e32 v138, 16, v69
	v_and_b32_e32 v139, 0xffff0000, v69
	v_lshlrev_b32_e32 v140, 16, v70
	v_and_b32_e32 v141, 0xffff0000, v70
	v_lshlrev_b32_e32 v142, 16, v71
	v_and_b32_e32 v143, 0xffff0000, v71
	v_pk_mul_f32 v[144:145], v[128:129], v[128:129]
	v_pk_fma_f32 v[144:145], v[130:131], v[130:131], v[144:145]
	v_pk_fma_f32 v[144:145], v[132:133], v[132:133], v[144:145]
	v_pk_fma_f32 v[144:145], v[134:135], v[134:135], v[144:145]
	v_pk_fma_f32 v[144:145], v[136:137], v[136:137], v[144:145]
	v_pk_fma_f32 v[144:145], v[138:139], v[138:139], v[144:145]
	v_pk_fma_f32 v[144:145], v[140:141], v[140:141], v[144:145]
	v_pk_fma_f32 v[144:145], v[142:143], v[142:143], v[144:145]
	v_add_f32_e32 v144, v144, v145
	s_nop 1
	v_add_f32_dpp v144, v144, v144 quad_perm:[1,0,3,2] row_mask:0xf bank_mask:0xf
	s_nop 1
	v_add_f32_dpp v144, v144, v144 quad_perm:[2,3,0,1] row_mask:0xf bank_mask:0xf
	s_nop 1
	v_add_f32_dpp v144, v144, v144 row_half_mirror row_mask:0xf bank_mask:0xf
	s_nop 1
	v_add_f32_dpp v144, v144, v144 row_mirror row_mask:0xf bank_mask:0xf
	s_nop 0
	v_mov_b32_e32 v145, v144
	s_nop 1
	v_permlane16_swap_b32_e32 v144, v145
	s_nop 0
	v_add_f32_e32 v144, v144, v145
	v_mov_b32_e32 v145, v144
	s_nop 1
	v_permlane32_swap_b32_e32 v144, v145
	s_nop 0
	v_add_f32_e32 v144, v144, v145
	v_fmamk_f32 v144, v144, 0x3a800000, v3
	v_rsq_f32_e32 v144, v144
	s_nop 0
	v_pk_mul_f32 v[128:129], v[128:129], v[144:145] op_sel_hi:[1,0]
	v_pk_mul_f32 v[130:131], v[130:131], v[144:145] op_sel_hi:[1,0]
	v_pk_mul_f32 v[132:133], v[132:133], v[144:145] op_sel_hi:[1,0]
	v_pk_mul_f32 v[134:135], v[134:135], v[144:145] op_sel_hi:[1,0]
	v_pk_mul_f32 v[136:137], v[136:137], v[144:145] op_sel_hi:[1,0]
	v_pk_mul_f32 v[138:139], v[138:139], v[144:145] op_sel_hi:[1,0]
	v_pk_mul_f32 v[140:141], v[140:141], v[144:145] op_sel_hi:[1,0]
	v_pk_mul_f32 v[142:143], v[142:143], v[144:145] op_sel_hi:[1,0]
	v_pk_mul_f32 v[128:129], v[16:17], v[128:129]
	v_pk_mul_f32 v[130:131], v[18:19], v[130:131]
	v_pk_mul_f32 v[132:133], v[20:21], v[132:133]
	v_pk_mul_f32 v[134:135], v[22:23], v[134:135]
	v_pk_mul_f32 v[136:137], v[24:25], v[136:137]
	v_pk_mul_f32 v[138:139], v[26:27], v[138:139]
	v_pk_mul_f32 v[140:141], v[28:29], v[140:141]
	v_pk_mul_f32 v[142:143], v[30:31], v[142:143]
	v_pk_fma_f32 v[128:129], v[32:33], v[128:129], v[48:49]
	v_pk_fma_f32 v[130:131], v[34:35], v[130:131], v[50:51]
	v_pk_fma_f32 v[132:133], v[36:37], v[132:133], v[52:53]
	v_pk_fma_f32 v[134:135], v[38:39], v[134:135], v[54:55]
	v_pk_fma_f32 v[136:137], v[40:41], v[136:137], v[56:57]
	v_pk_fma_f32 v[138:139], v[42:43], v[138:139], v[58:59]
	v_pk_fma_f32 v[140:141], v[44:45], v[140:141], v[60:61]
	v_pk_fma_f32 v[142:143], v[46:47], v[142:143], v[62:63]
	v_cvt_pk_bf16_f32 v148, v128, v129
	v_cvt_pk_bf16_f32 v149, v130, v131
	v_cvt_pk_bf16_f32 v150, v132, v133
	v_cvt_pk_bf16_f32 v151, v134, v135
	v_cvt_pk_bf16_f32 v152, v136, v137
	v_cvt_pk_bf16_f32 v153, v138, v139
	v_cvt_pk_bf16_f32 v154, v140, v141
	v_cvt_pk_bf16_f32 v155, v142, v143
	global_store_dwordx4 v1, v[148:151], s[12:13] sc1
	global_store_dwordx4 v1, v[152:155], s[12:13] offset:1024 sc1
	global_load_dwordx4 v[64:67], v1, s[8:9]
	global_load_dwordx4 v[68:71], v1, s[8:9] offset:1024
	s_waitcnt vmcnt(16)
; __device__ __forceinline__ unsigned cvt_pk_bf16(float lo, float hi) { unsigned r; asm("v_cvt_pk_bf16_f32 %0, %1, %2" : "=v"(r) : "v"(lo), "v"(hi)); return r; }
; __device__ __forceinline__ void norm_pass_bf16(const Ctx& X, const bf16_t* xs, const bf16_t* cs, int nrows, const float* gain, const float* modl, int si, bf16_t* HN) {
;     ...
;         for (int j = 0; j < 2; ++j) {
;             v[j][0] = bf2f(q[j].x & 0xffffu); v[j][1] = bf2f(q[j].x >> 16); v[j][2] = bf2f(q[j].y & 0xffffu); v[j][3] = bf2f(q[j].y >> 16);
;             v[j][4] = bf2f(q[j].z & 0xffffu); v[j][5] = bf2f(q[j].z >> 16); v[j][6] = bf2f(q[j].w & 0xffffu); v[j][7] = bf2f(q[j].w >> 16);
; #pragma unroll
;             for (int e = 0; e < 8; ++e) s += v[j][e] * v[j][e]; }
;         const float rstd = rsqrtf(wave_sum(s) * (1.0f / 1024.0f) + 1e-6f);
; #pragma unroll
;         for (int j = 0; j < 2; ++j) { const int c = (X.lane + 64 * j) * 8; float o[8];
; #pragma unroll
;             for (int h = 0; h < 2; ++h) { const f32x4 gn = *(const f32x4*)(gain + c + 4 * h), a = *(const f32x4*)(scl + c + 4 * h), b = *(const f32x4*)(sh + c + 4 * h);
; #pragma unroll
;                 for (int e = 0; e < 4; ++e) o[4 * h + e] = v[j][4 * h + e] * rstd * gn[e] * (a[e] + 1.0f) + b[e]; }
;             u32x4 w; w.x = cvt_pk_bf16(o[0], o[1]); w.y = cvt_pk_bf16(o[2], o[3]); w.z = cvt_pk_bf16(o[4], o[5]); w.w = cvt_pk_bf16(o[6], o[7]); *(u32x4*)(HN + (size_t)r * D + c) = w; }
	v_lshlrev_b32_e32 v128, 16, v72
	v_and_b32_e32 v129, 0xffff0000, v72
	v_lshlrev_b32_e32 v130, 16, v73
	v_and_b32_e32 v131, 0xffff0000, v73
	v_lshlrev_b32_e32 v132, 16, v74
	v_and_b32_e32 v133, 0xffff0000, v74
	v_lshlrev_b32_e32 v134, 16, v75
	v_and_b32_e32 v135, 0xffff0000, v75
	v_lshlrev_b32_e32 v136, 16, v76
	v_and_b32_e32 v137, 0xffff0000, v76
	v_lshlrev_b32_e32 v138, 16, v77
	v_and_b32_e32 v139, 0xffff0000, v77
	v_lshlrev_b32_e32 v140, 16, v78
	v_and_b32_e32 v141, 0xffff0000, v78
	v_lshlrev_b32_e32 v142, 16, v79
	v_and_b32_e32 v143, 0xffff0000, v79
	v_pk_mul_f32 v[144:145], v[128:129], v[128:129]
	v_pk_fma_f32 v[144:145], v[130:131], v[130:131], v[144:145]
	v_pk_fma_f32 v[144:145], v[132:133], v[132:133], v[144:145]
	v_pk_fma_f32 v[144:145], v[134:135], v[134:135], v[144:145]
	v_pk_fma_f32 v[144:145], v[136:137], v[136:137], v[144:145]
	v_pk_fma_f32 v[144:145], v[138:139], v[138:139], v[144:145]
	v_pk_fma_f32 v[144:145], v[140:141], v[140:141], v[144:145]
	v_pk_fma_f32 v[144:145], v[142:143], v[142:143], v[144:145]
	v_add_f32_e32 v144, v144, v145
	s_nop 1
	v_add_f32_dpp v144, v144, v144 quad_perm:[1,0,3,2] row_mask:0xf bank_mask:0xf
	s_nop 1
	v_add_f32_dpp v144, v144, v144 quad_perm:[2,3,0,1] row_mask:0xf bank_mask:0xf
	s_nop 1
	v_add_f32_dpp v144, v144, v144 row_half_mirror row_mask:0xf bank_mask:0xf
	s_nop 1
	v_add_f32_dpp v144, v144, v144 row_mirror row_mask:0xf bank_mask:0xf
	s_nop 0
	v_mov_b32_e32 v145, v144
	s_nop 1
	v_permlane16_swap_b32_e32 v144, v145
	s_nop 0
	v_add_f32_e32 v144, v144, v145
	v_mov_b32_e32 v145, v144
	s_nop 1
	v_permlane32_swap_b32_e32 v144, v145
	s_nop 0
	v_add_f32_e32 v144, v144, v145
	v_fmamk_f32 v144, v144, 0x3a800000, v3
	v_rsq_f32_e32 v144, v144
	s_nop 0
	v_pk_mul_f32 v[128:129], v[128:129], v[144:145] op_sel_hi:[1,0]
	v_pk_mul_f32 v[130:131], v[130:131], v[144:145] op_sel_hi:[1,0]
	v_pk_mul_f32 v[132:133], v[132:133], v[144:145] op_sel_hi:[1,0]
	v_pk_mul_f32 v[134:135], v[134:135], v[144:145] op_sel_hi:[1,0]
	v_pk_mul_f32 v[136:137], v[136:137], v[144:145] op_sel_hi:[1,0]
	v_pk_mul_f32 v[138:139], v[138:139], v[144:145] op_sel_hi:[1,0]
	v_pk_mul_f32 v[140:141], v[140:141], v[144:145] op_sel_hi:[1,0]
	v_pk_mul_f32 v[142:143], v[142:143], v[144:145] op_sel_hi:[1,0]
	v_pk_mul_f32 v[128:129], v[16:17], v[128:129]
	v_pk_mul_f32 v[130:131], v[18:19], v[130:131]
	v_pk_mul_f32 v[132:133], v[20:21], v[132:133]
	v_pk_mul_f32 v[134:135], v[22:23], v[134:135]
	v_pk_mul_f32 v[136:137], v[24:25], v[136:137]
	v_pk_mul_f32 v[138:139], v[26:27], v[138:139]
	v_pk_mul_f32 v[140:141], v[28:29], v[140:141]
	v_pk_mul_f32 v[142:143], v[30:31], v[142:143]
	v_pk_fma_f32 v[128:129], v[32:33], v[128:129], v[48:49]
	v_pk_fma_f32 v[130:131], v[34:35], v[130:131], v[50:51]
	v_pk_fma_f32 v[132:133], v[36:37], v[132:133], v[52:53]
	v_pk_fma_f32 v[134:135], v[38:39], v[134:135], v[54:55]
	v_pk_fma_f32 v[136:137], v[40:41], v[136:137], v[56:57]
	v_pk_fma_f32 v[138:139], v[42:43], v[138:139], v[58:59]
	v_pk_fma_f32 v[140:141], v[44:45], v[140:141], v[60:61]
	v_pk_fma_f32 v[142:143], v[46:47], v[142:143], v[62:63]
	v_cvt_pk_bf16_f32 v148, v128, v129
	v_cvt_pk_bf16_f32 v149, v130, v131
	v_cvt_pk_bf16_f32 v150, v132, v133
	v_cvt_pk_bf16_f32 v151, v134, v135
	v_cvt_pk_bf16_f32 v152, v136, v137
	v_cvt_pk_bf16_f32 v153, v138, v139
	v_cvt_pk_bf16_f32 v154, v140, v141
	v_cvt_pk_bf16_f32 v155, v142, v143
	global_store_dwordx4 v1, v[148:151], s[12:13] offset:2048 sc1
	global_store_dwordx4 v1, v[152:155], s[12:13] offset:3072 sc1
	s_add_u32 s12, s12, 0x1000
	s_addc_u32 s13, s13, 0
	global_load_dwordx4 v[72:75], v1, s[8:9] offset:2048
	global_load_dwordx4 v[76:79], v1, s[8:9] offset:3072
	s_add_u32 s8, s8, 0x1000
	s_addc_u32 s9, s9, 0
	s_waitcnt vmcnt(18)
	v_lshlrev_b32_e32 v128, 16, v80
	v_and_b32_e32 v129, 0xffff0000, v80
	v_lshlrev_b32_e32 v130, 16, v81
	v_and_b32_e32 v131, 0xffff0000, v81
	v_lshlrev_b32_e32 v132, 16, v82
	v_and_b32_e32 v133, 0xffff0000, v82
	v_lshlrev_b32_e32 v134, 16, v83
	v_and_b32_e32 v135, 0xffff0000, v83
	v_lshlrev_b32_e32 v136, 16, v84
	v_and_b32_e32 v137, 0xffff0000, v84
	v_lshlrev_b32_e32 v138, 16, v85
	v_and_b32_e32 v139, 0xffff0000, v85
	v_lshlrev_b32_e32 v140, 16, v86
	v_and_b32_e32 v141, 0xffff0000, v86
	v_lshlrev_b32_e32 v142, 16, v87
	v_and_b32_e32 v143, 0xffff0000, v87
	v_pk_mul_f32 v[144:145], v[128:129], v[128:129]
	v_pk_fma_f32 v[144:145], v[130:131], v[130:131], v[144:145]
	v_pk_fma_f32 v[144:145], v[132:133], v[132:133], v[144:145]
	v_pk_fma_f32 v[144:145], v[134:135], v[134:135], v[144:145]
	v_pk_fma_f32 v[144:145], v[136:137], v[136:137], v[144:145]
	v_pk_fma_f32 v[144:145], v[138:139], v[138:139], v[144:145]
	v_pk_fma_f32 v[144:145], v[140:141], v[140:141], v[144:145]
	v_pk_fma_f32 v[144:145], v[142:143], v[142:143], v[144:145]
	v_add_f32_e32 v144, v144, v145
	s_nop 1
	v_add_f32_dpp v144, v144, v144 quad_perm:[1,0,3,2] row_mask:0xf bank_mask:0xf
	s_nop 1
	v_add_f32_dpp v144, v144, v144 quad_perm:[2,3,0,1] row_mask:0xf bank_mask:0xf
	s_nop 1
	v_add_f32_dpp v144, v144, v144 row_half_mirror row_mask:0xf bank_mask:0xf
	s_nop 1
	v_add_f32_dpp v144, v144, v144 row_mirror row_mask:0xf bank_mask:0xf
	s_nop 0
	v_mov_b32_e32 v145, v144
	s_nop 1
	v_permlane16_swap_b32_e32 v144, v145
	s_nop 0
	v_add_f32_e32 v144, v144, v145
	v_mov_b32_e32 v145, v144
	s_nop 1
	v_permlane32_swap_b32_e32 v144, v145
	s_nop 0
	v_add_f32_e32 v144, v144, v145
	v_fmamk_f32 v144, v144, 0x3a800000, v3
	v_rsq_f32_e32 v144, v144
	s_nop 0
	v_pk_mul_f32 v[128:129], v[128:129], v[144:145] op_sel_hi:[1,0]
	v_pk_mul_f32 v[130:131], v[130:131], v[144:145] op_sel_hi:[1,0]
	v_pk_mul_f32 v[132:133], v[132:133], v[144:145] op_sel_hi:[1,0]
; __device__ __forceinline__ unsigned cvt_pk_bf16(float lo, float hi) { unsigned r; asm("v_cvt_pk_bf16_f32 %0, %1, %2" : "=v"(r) : "v"(lo), "v"(hi)); return r; }
; __device__ __forceinline__ void norm_pass_bf16(const Ctx& X, const bf16_t* xs, const bf16_t* cs, int nrows, const float* gain, const float* modl, int si, bf16_t* HN) {
;     ...
;         for (int j = 0; j < 2; ++j) {
;             v[j][0] = bf2f(q[j].x & 0xffffu); v[j][1] = bf2f(q[j].x >> 16); v[j][2] = bf2f(q[j].y & 0xffffu); v[j][3] = bf2f(q[j].y >> 16);
;             v[j][4] = bf2f(q[j].z & 0xffffu); v[j][5] = bf2f(q[j].z >> 16); v[j][6] = bf2f(q[j].w & 0xffffu); v[j][7] = bf2f(q[j].w >> 16);
; #pragma unroll
;             for (int e = 0; e < 8; ++e) s += v[j][e] * v[j][e]; }
;         const float rstd = rsqrtf(wave_sum(s) * (1.0f / 1024.0f) + 1e-6f);
; #pragma unroll
;         for (int j = 0; j < 2; ++j) { const int c = (X.lane + 64 * j) * 8; float o[8];
; #pragma unroll
;             for (int h = 0; h < 2; ++h) { const f32x4 gn = *(const f32x4*)(gain + c + 4 * h), a = *(const f32x4*)(scl + c + 4 * h), b = *(const f32x4*)(sh + c + 4 * h);
; #pragma unroll
;                 for (int e = 0; e < 4; ++e) o[4 * h + e] = v[j][4 * h + e] * rstd * gn[e] * (a[e] + 1.0f) + b[e]; }
;             u32x4 w; w.x = cvt_pk_bf16(o[0], o[1]); w.y = cvt_pk_bf16(o[2], o[3]); w.z = cvt_pk_bf16(o[4], o[5]); w.w = cvt_pk_bf16(o[6], o[7]); *(u32x4*)(HN + (size_t)r * D + c) = w; }
	v_pk_mul_f32 v[134:135], v[134:135], v[144:145] op_sel_hi:[1,0]
	v_pk_mul_f32 v[136:137], v[136:137], v[144:145] op_sel_hi:[1,0]
	v_pk_mul_f32 v[138:139], v[138:139], v[144:145] op_sel_hi:[1,0]
	v_pk_mul_f32 v[140:141], v[140:141], v[144:145] op_sel_hi:[1,0]
	v_pk_mul_f32 v[142:143], v[142:143], v[144:145] op_sel_hi:[1,0]
	v_pk_mul_f32 v[128:129], v[16:17], v[128:129]
	v_pk_mul_f32 v[130:131], v[18:19], v[130:131]
	v_pk_mul_f32 v[132:133], v[20:21], v[132:133]
	v_pk_mul_f32 v[134:135], v[22:23], v[134:135]
	v_pk_mul_f32 v[136:137], v[24:25], v[136:137]
	v_pk_mul_f32 v[138:139], v[26:27], v[138:139]
	v_pk_mul_f32 v[140:141], v[28:29], v[140:141]
	v_pk_mul_f32 v[142:143], v[30:31], v[142:143]
	v_pk_fma_f32 v[128:129], v[32:33], v[128:129], v[48:49]
	v_pk_fma_f32 v[130:131], v[34:35], v[130:131], v[50:51]
	v_pk_fma_f32 v[132:133], v[36:37], v[132:133], v[52:53]
	v_pk_fma_f32 v[134:135], v[38:39], v[134:135], v[54:55]
	v_pk_fma_f32 v[136:137], v[40:41], v[136:137], v[56:57]
	v_pk_fma_f32 v[138:139], v[42:43], v[138:139], v[58:59]
	v_pk_fma_f32 v[140:141], v[44:45], v[140:141], v[60:61]
	v_pk_fma_f32 v[142:143], v[46:47], v[142:143], v[62:63]
	v_cvt_pk_bf16_f32 v148, v128, v129
	v_cvt_pk_bf16_f32 v149, v130, v131
	v_cvt_pk_bf16_f32 v150, v132, v133
	v_cvt_pk_bf16_f32 v151, v134, v135
	v_cvt_pk_bf16_f32 v152, v136, v137
	v_cvt_pk_bf16_f32 v153, v138, v139
	v_cvt_pk_bf16_f32 v154, v140, v141
	v_cvt_pk_bf16_f32 v155, v142, v143
	global_store_dwordx4 v1, v[148:151], s[12:13] sc1
	global_store_dwordx4 v1, v[152:155], s[12:13] offset:1024 sc1
	global_load_dwordx4 v[80:83], v1, s[8:9]
	global_load_dwordx4 v[84:87], v1, s[8:9] offset:1024
	s_waitcnt vmcnt(20)
	v_lshlrev_b32_e32 v128, 16, v88
	v_and_b32_e32 v129, 0xffff0000, v88
	v_lshlrev_b32_e32 v130, 16, v89
	v_and_b32_e32 v131, 0xffff0000, v89
	v_lshlrev_b32_e32 v132, 16, v90
	v_and_b32_e32 v133, 0xffff0000, v90
	v_lshlrev_b32_e32 v134, 16, v91
	v_and_b32_e32 v135, 0xffff0000, v91
	v_lshlrev_b32_e32 v136, 16, v92
	v_and_b32_e32 v137, 0xffff0000, v92
	v_lshlrev_b32_e32 v138, 16, v93
	v_and_b32_e32 v139, 0xffff0000, v93
	v_lshlrev_b32_e32 v140, 16, v94
	v_and_b32_e32 v141, 0xffff0000, v94
	v_lshlrev_b32_e32 v142, 16, v95
	v_and_b32_e32 v143, 0xffff0000, v95
	v_pk_mul_f32 v[144:145], v[128:129], v[128:129]
	v_pk_fma_f32 v[144:145], v[130:131], v[130:131], v[144:145]
	v_pk_fma_f32 v[144:145], v[132:133], v[132:133], v[144:145]
	v_pk_fma_f32 v[144:145], v[134:135], v[134:135], v[144:145]
	v_pk_fma_f32 v[144:145], v[136:137], v[136:137], v[144:145]
	v_pk_fma_f32 v[144:145], v[138:139], v[138:139], v[144:145]
	v_pk_fma_f32 v[144:145], v[140:141], v[140:141], v[144:145]
	v_pk_fma_f32 v[144:145], v[142:143], v[142:143], v[144:145]
	v_add_f32_e32 v144, v144, v145
	s_nop 1
	v_add_f32_dpp v144, v144, v144 quad_perm:[1,0,3,2] row_mask:0xf bank_mask:0xf
	s_nop 1
	v_add_f32_dpp v144, v144, v144 quad_perm:[2,3,0,1] row_mask:0xf bank_mask:0xf
	s_nop 1
	v_add_f32_dpp v144, v144, v144 row_half_mirror row_mask:0xf bank_mask:0xf
	s_nop 1
	v_add_f32_dpp v144, v144, v144 row_mirror row_mask:0xf bank_mask:0xf
	s_nop 0
	v_mov_b32_e32 v145, v144
	s_nop 1
	v_permlane16_swap_b32_e32 v144, v145
	s_nop 0
	v_add_f32_e32 v144, v144, v145
	v_mov_b32_e32 v145, v144
	s_nop 1
	v_permlane32_swap_b32_e32 v144, v145
	s_nop 0
	v_add_f32_e32 v144, v144, v145
	v_fmamk_f32 v144, v144, 0x3a800000, v3
	v_rsq_f32_e32 v144, v144
	s_nop 0
	v_pk_mul_f32 v[128:129], v[128:129], v[144:145] op_sel_hi:[1,0]
	v_pk_mul_f32 v[130:131], v[130:131], v[144:145] op_sel_hi:[1,0]
	v_pk_mul_f32 v[132:133], v[132:133], v[144:145] op_sel_hi:[1,0]
	v_pk_mul_f32 v[134:135], v[134:135], v[144:145] op_sel_hi:[1,0]
	v_pk_mul_f32 v[136:137], v[136:137], v[144:145] op_sel_hi:[1,0]
	v_pk_mul_f32 v[138:139], v[138:139], v[144:145] op_sel_hi:[1,0]
	v_pk_mul_f32 v[140:141], v[140:141], v[144:145] op_sel_hi:[1,0]
	v_pk_mul_f32 v[142:143], v[142:143], v[144:145] op_sel_hi:[1,0]
	v_pk_mul_f32 v[128:129], v[16:17], v[128:129]
	v_pk_mul_f32 v[130:131], v[18:19], v[130:131]
	v_pk_mul_f32 v[132:133], v[20:21], v[132:133]
	v_pk_mul_f32 v[134:135], v[22:23], v[134:135]
	v_pk_mul_f32 v[136:137], v[24:25], v[136:137]
	v_pk_mul_f32 v[138:139], v[26:27], v[138:139]
	v_pk_mul_f32 v[140:141], v[28:29], v[140:141]
	v_pk_mul_f32 v[142:143], v[30:31], v[142:143]
	v_pk_fma_f32 v[128:129], v[32:33], v[128:129], v[48:49]
	v_pk_fma_f32 v[130:131], v[34:35], v[130:131], v[50:51]
	v_pk_fma_f32 v[132:133], v[36:37], v[132:133], v[52:53]
	v_pk_fma_f32 v[134:135], v[38:39], v[134:135], v[54:55]
	v_pk_fma_f32 v[136:137], v[40:41], v[136:137], v[56:57]
	v_pk_fma_f32 v[138:139], v[42:43], v[138:139], v[58:59]
	v_pk_fma_f32 v[140:141], v[44:45], v[140:141], v[60:61]
	v_pk_fma_f32 v[142:143], v[46:47], v[142:143], v[62:63]
	v_cvt_pk_bf16_f32 v148, v128, v129
	v_cvt_pk_bf16_f32 v149, v130, v131
	v_cvt_pk_bf16_f32 v150, v132, v133
	v_cvt_pk_bf16_f32 v151, v134, v135
	v_cvt_pk_bf16_f32 v152, v136, v137
	v_cvt_pk_bf16_f32 v153, v138, v139
	v_cvt_pk_bf16_f32 v154, v140, v141
	v_cvt_pk_bf16_f32 v155, v142, v143
	global_store_dwordx4 v1, v[148:151], s[12:13] offset:2048 sc1
	global_store_dwordx4 v1, v[152:155], s[12:13] offset:3072 sc1
	s_add_u32 s12, s12, 0x1000
	s_addc_u32 s13, s13, 0
	global_load_dwordx4 v[88:91], v1, s[8:9] offset:2048
	global_load_dwordx4 v[92:95], v1, s[8:9] offset:3072
	s_add_u32 s8, s8, 0x1000
	s_addc_u32 s9, s9, 0
	s_waitcnt vmcnt(22)
; __device__ __forceinline__ unsigned cvt_pk_bf16(float lo, float hi) { unsigned r; asm("v_cvt_pk_bf16_f32 %0, %1, %2" : "=v"(r) : "v"(lo), "v"(hi)); return r; }
; __device__ __forceinline__ void norm_pass_bf16(const Ctx& X, const bf16_t* xs, const bf16_t* cs, int nrows, const float* gain, const float* modl, int si, bf16_t* HN) {
;     ...
;         for (int j = 0; j < 2; ++j) {
;             v[j][0] = bf2f(q[j].x & 0xffffu); v[j][1] = bf2f(q[j].x >> 16); v[j][2] = bf2f(q[j].y & 0xffffu); v[j][3] = bf2f(q[j].y >> 16);
;             v[j][4] = bf2f(q[j].z & 0xffffu); v[j][5] = bf2f(q[j].z >> 16); v[j][6] = bf2f(q[j].w & 0xffffu); v[j][7] = bf2f(q[j].w >> 16);
; #pragma unroll
;             for (int e = 0; e < 8; ++e) s += v[j][e] * v[j][e]; }
;         const float rstd = rsqrtf(wave_sum(s) * (1.0f / 1024.0f) + 1e-6f);
; #pragma unroll
;         for (int j = 0; j < 2; ++j) { const int c = (X.lane + 64 * j) * 8; float o[8];
; #pragma unroll
;             for (int h = 0; h < 2; ++h) { const f32x4 gn = *(const f32x4*)(gain + c + 4 * h), a = *(const f32x4*)(scl + c + 4 * h), b = *(const f32x4*)(sh + c + 4 * h);
; #pragma unroll
;                 for (int e = 0; e < 4; ++e) o[4 * h + e] = v[j][4 * h + e] * rstd * gn[e] * (a[e] + 1.0f) + b[e]; }
;             u32x4 w; w.x = cvt_pk_bf16(o[0], o[1]); w.y = cvt_pk_bf16(o[2], o[3]); w.z = cvt_pk_bf16(o[4], o[5]); w.w = cvt_pk_bf16(o[6], o[7]); *(u32x4*)(HN + (size_t)r * D + c) = w; }
	v_lshlrev_b32_e32 v128, 16, v96
	v_and_b32_e32 v129, 0xffff0000, v96
	v_lshlrev_b32_e32 v130, 16, v97
	v_and_b32_e32 v131, 0xffff0000, v97
	v_lshlrev_b32_e32 v132, 16, v98
	v_and_b32_e32 v133, 0xffff0000, v98
	v_lshlrev_b32_e32 v134, 16, v99
	v_and_b32_e32 v135, 0xffff0000, v99
	v_lshlrev_b32_e32 v136, 16, v100
	v_and_b32_e32 v137, 0xffff0000, v100
	v_lshlrev_b32_e32 v138, 16, v101
	v_and_b32_e32 v139, 0xffff0000, v101
	v_lshlrev_b32_e32 v140, 16, v102
	v_and_b32_e32 v141, 0xffff0000, v102
	v_lshlrev_b32_e32 v142, 16, v103
	v_and_b32_e32 v143, 0xffff0000, v103
	v_pk_mul_f32 v[144:145], v[128:129], v[128:129]
	v_pk_fma_f32 v[144:145], v[130:131], v[130:131], v[144:145]
	v_pk_fma_f32 v[144:145], v[132:133], v[132:133], v[144:145]
	v_pk_fma_f32 v[144:145], v[134:135], v[134:135], v[144:145]
	v_pk_fma_f32 v[144:145], v[136:137], v[136:137], v[144:145]
	v_pk_fma_f32 v[144:145], v[138:139], v[138:139], v[144:145]
	v_pk_fma_f32 v[144:145], v[140:141], v[140:141], v[144:145]
	v_pk_fma_f32 v[144:145], v[142:143], v[142:143], v[144:145]
	v_add_f32_e32 v144, v144, v145
	s_nop 1
	v_add_f32_dpp v144, v144, v144 quad_perm:[1,0,3,2] row_mask:0xf bank_mask:0xf
	s_nop 1
	v_add_f32_dpp v144, v144, v144 quad_perm:[2,3,0,1] row_mask:0xf bank_mask:0xf
	s_nop 1
	v_add_f32_dpp v144, v144, v144 row_half_mirror row_mask:0xf bank_mask:0xf
	s_nop 1
	v_add_f32_dpp v144, v144, v144 row_mirror row_mask:0xf bank_mask:0xf
	s_nop 0
	v_mov_b32_e32 v145, v144
	s_nop 1
	v_permlane16_swap_b32_e32 v144, v145
	s_nop 0
	v_add_f32_e32 v144, v144, v145
	v_mov_b32_e32 v145, v144
	s_nop 1
	v_permlane32_swap_b32_e32 v144, v145
	s_nop 0
	v_add_f32_e32 v144, v144, v145
	v_fmamk_f32 v144, v144, 0x3a800000, v3
	v_rsq_f32_e32 v144, v144
	s_nop 0
	v_pk_mul_f32 v[128:129], v[128:129], v[144:145] op_sel_hi:[1,0]
	v_pk_mul_f32 v[130:131], v[130:131], v[144:145] op_sel_hi:[1,0]
	v_pk_mul_f32 v[132:133], v[132:133], v[144:145] op_sel_hi:[1,0]
	v_pk_mul_f32 v[134:135], v[134:135], v[144:145] op_sel_hi:[1,0]
	v_pk_mul_f32 v[136:137], v[136:137], v[144:145] op_sel_hi:[1,0]
	v_pk_mul_f32 v[138:139], v[138:139], v[144:145] op_sel_hi:[1,0]
	v_pk_mul_f32 v[140:141], v[140:141], v[144:145] op_sel_hi:[1,0]
	v_pk_mul_f32 v[142:143], v[142:143], v[144:145] op_sel_hi:[1,0]
	v_pk_mul_f32 v[128:129], v[16:17], v[128:129]
	v_pk_mul_f32 v[130:131], v[18:19], v[130:131]
	v_pk_mul_f32 v[132:133], v[20:21], v[132:133]
	v_pk_mul_f32 v[134:135], v[22:23], v[134:135]
	v_pk_mul_f32 v[136:137], v[24:25], v[136:137]
	v_pk_mul_f32 v[138:139], v[26:27], v[138:139]
	v_pk_mul_f32 v[140:141], v[28:29], v[140:141]
	v_pk_mul_f32 v[142:143], v[30:31], v[142:143]
	v_pk_fma_f32 v[128:129], v[32:33], v[128:129], v[48:49]
	v_pk_fma_f32 v[130:131], v[34:35], v[130:131], v[50:51]
	v_pk_fma_f32 v[132:133], v[36:37], v[132:133], v[52:53]
	v_pk_fma_f32 v[134:135], v[38:39], v[134:135], v[54:55]
	v_pk_fma_f32 v[136:137], v[40:41], v[136:137], v[56:57]
	v_pk_fma_f32 v[138:139], v[42:43], v[138:139], v[58:59]
	v_pk_fma_f32 v[140:141], v[44:45], v[140:141], v[60:61]
	v_pk_fma_f32 v[142:143], v[46:47], v[142:143], v[62:63]
	v_cvt_pk_bf16_f32 v148, v128, v129
	v_cvt_pk_bf16_f32 v149, v130, v131
	v_cvt_pk_bf16_f32 v150, v132, v133
	v_cvt_pk_bf16_f32 v151, v134, v135
	v_cvt_pk_bf16_f32 v152, v136, v137
	v_cvt_pk_bf16_f32 v153, v138, v139
	v_cvt_pk_bf16_f32 v154, v140, v141
	v_cvt_pk_bf16_f32 v155, v142, v143
	global_store_dwordx4 v1, v[148:151], s[12:13] sc1
	global_store_dwordx4 v1, v[152:155], s[12:13] offset:1024 sc1
	global_load_dwordx4 v[96:99], v1, s[8:9]
	global_load_dwordx4 v[100:103], v1, s[8:9] offset:1024
	s_waitcnt vmcnt(24)
	v_lshlrev_b32_e32 v128, 16, v104
	v_and_b32_e32 v129, 0xffff0000, v104
	v_lshlrev_b32_e32 v130, 16, v105
	v_and_b32_e32 v131, 0xffff0000, v105
	v_lshlrev_b32_e32 v132, 16, v106
	v_and_b32_e32 v133, 0xffff0000, v106
	v_lshlrev_b32_e32 v134, 16, v107
	v_and_b32_e32 v135, 0xffff0000, v107
	v_lshlrev_b32_e32 v136, 16, v108
	v_and_b32_e32 v137, 0xffff0000, v108
	v_lshlrev_b32_e32 v138, 16, v109
	v_and_b32_e32 v139, 0xffff0000, v109
	v_lshlrev_b32_e32 v140, 16, v110
	v_and_b32_e32 v141, 0xffff0000, v110
	v_lshlrev_b32_e32 v142, 16, v111
	v_and_b32_e32 v143, 0xffff0000, v111
	v_pk_mul_f32 v[144:145], v[128:129], v[128:129]
	v_pk_fma_f32 v[144:145], v[130:131], v[130:131], v[144:145]
	v_pk_fma_f32 v[144:145], v[132:133], v[132:133], v[144:145]
	v_pk_fma_f32 v[144:145], v[134:135], v[134:135], v[144:145]
	v_pk_fma_f32 v[144:145], v[136:137], v[136:137], v[144:145]
	v_pk_fma_f32 v[144:145], v[138:139], v[138:139], v[144:145]
	v_pk_fma_f32 v[144:145], v[140:141], v[140:141], v[144:145]
	v_pk_fma_f32 v[144:145], v[142:143], v[142:143], v[144:145]
	v_add_f32_e32 v144, v144, v145
	s_nop 1
	v_add_f32_dpp v144, v144, v144 quad_perm:[1,0,3,2] row_mask:0xf bank_mask:0xf
	s_nop 1
	v_add_f32_dpp v144, v144, v144 quad_perm:[2,3,0,1] row_mask:0xf bank_mask:0xf
	s_nop 1
	v_add_f32_dpp v144, v144, v144 row_half_mirror row_mask:0xf bank_mask:0xf
	s_nop 1
	v_add_f32_dpp v144, v144, v144 row_mirror row_mask:0xf bank_mask:0xf
	s_nop 0
	v_mov_b32_e32 v145, v144
	s_nop 1
	v_permlane16_swap_b32_e32 v144, v145
	s_nop 0
	v_add_f32_e32 v144, v144, v145
	v_mov_b32_e32 v145, v144
	s_nop 1
	v_permlane32_swap_b32_e32 v144, v145
	s_nop 0
	v_add_f32_e32 v144, v144, v145
	v_fmamk_f32 v144, v144, 0x3a800000, v3
	v_rsq_f32_e32 v144, v144
	s_nop 0
	v_pk_mul_f32 v[128:129], v[128:129], v[144:145] op_sel_hi:[1,0]
	v_pk_mul_f32 v[130:131], v[130:131], v[144:145] op_sel_hi:[1,0]
	v_pk_mul_f32 v[132:133], v[132:133], v[144:145] op_sel_hi:[1,0]
	v_pk_mul_f32 v[134:135], v[134:135], v[144:145] op_sel_hi:[1,0]
	v_pk_mul_f32 v[136:137], v[136:137], v[144:145] op_sel_hi:[1,0]
; __device__ __forceinline__ unsigned cvt_pk_bf16(float lo, float hi) { unsigned r; asm("v_cvt_pk_bf16_f32 %0, %1, %2" : "=v"(r) : "v"(lo), "v"(hi)); return r; }
; __device__ __forceinline__ void norm_pass_bf16(const Ctx& X, const bf16_t* xs, const bf16_t* cs, int nrows, const float* gain, const float* modl, int si, bf16_t* HN) {
;     ...
;         for (int j = 0; j < 2; ++j) {
;             v[j][0] = bf2f(q[j].x & 0xffffu); v[j][1] = bf2f(q[j].x >> 16); v[j][2] = bf2f(q[j].y & 0xffffu); v[j][3] = bf2f(q[j].y >> 16);
;             v[j][4] = bf2f(q[j].z & 0xffffu); v[j][5] = bf2f(q[j].z >> 16); v[j][6] = bf2f(q[j].w & 0xffffu); v[j][7] = bf2f(q[j].w >> 16);
; #pragma unroll
;             for (int e = 0; e < 8; ++e) s += v[j][e] * v[j][e]; }
;         const float rstd = rsqrtf(wave_sum(s) * (1.0f / 1024.0f) + 1e-6f);
; #pragma unroll
;         for (int j = 0; j < 2; ++j) { const int c = (X.lane + 64 * j) * 8; float o[8];
; #pragma unroll
;             for (int h = 0; h < 2; ++h) { const f32x4 gn = *(const f32x4*)(gain + c + 4 * h), a = *(const f32x4*)(scl + c + 4 * h), b = *(const f32x4*)(sh + c + 4 * h);
; #pragma unroll
;                 for (int e = 0; e < 4; ++e) o[4 * h + e] = v[j][4 * h + e] * rstd * gn[e] * (a[e] + 1.0f) + b[e]; }
;             u32x4 w; w.x = cvt_pk_bf16(o[0], o[1]); w.y = cvt_pk_bf16(o[2], o[3]); w.z = cvt_pk_bf16(o[4], o[5]); w.w = cvt_pk_bf16(o[6], o[7]); *(u32x4*)(HN + (size_t)r * D + c) = w; }
	v_pk_mul_f32 v[138:139], v[138:139], v[144:145] op_sel_hi:[1,0]
	v_pk_mul_f32 v[140:141], v[140:141], v[144:145] op_sel_hi:[1,0]
	v_pk_mul_f32 v[142:143], v[142:143], v[144:145] op_sel_hi:[1,0]
	v_pk_mul_f32 v[128:129], v[16:17], v[128:129]
	v_pk_mul_f32 v[130:131], v[18:19], v[130:131]
	v_pk_mul_f32 v[132:133], v[20:21], v[132:133]
	v_pk_mul_f32 v[134:135], v[22:23], v[134:135]
	v_pk_mul_f32 v[136:137], v[24:25], v[136:137]
	v_pk_mul_f32 v[138:139], v[26:27], v[138:139]
	v_pk_mul_f32 v[140:141], v[28:29], v[140:141]
	v_pk_mul_f32 v[142:143], v[30:31], v[142:143]
	v_pk_fma_f32 v[128:129], v[32:33], v[128:129], v[48:49]
	v_pk_fma_f32 v[130:131], v[34:35], v[130:131], v[50:51]
	v_pk_fma_f32 v[132:133], v[36:37], v[132:133], v[52:53]
	v_pk_fma_f32 v[134:135], v[38:39], v[134:135], v[54:55]
	v_pk_fma_f32 v[136:137], v[40:41], v[136:137], v[56:57]
	v_pk_fma_f32 v[138:139], v[42:43], v[138:139], v[58:59]
	v_pk_fma_f32 v[140:141], v[44:45], v[140:141], v[60:61]
	v_pk_fma_f32 v[142:143], v[46:47], v[142:143], v[62:63]
	v_cvt_pk_bf16_f32 v148, v128, v129
	v_cvt_pk_bf16_f32 v149, v130, v131
	v_cvt_pk_bf16_f32 v150, v132, v133
	v_cvt_pk_bf16_f32 v151, v134, v135
	v_cvt_pk_bf16_f32 v152, v136, v137
	v_cvt_pk_bf16_f32 v153, v138, v139
	v_cvt_pk_bf16_f32 v154, v140, v141
	v_cvt_pk_bf16_f32 v155, v142, v143
	global_store_dwordx4 v1, v[148:151], s[12:13] offset:2048 sc1
	global_store_dwordx4 v1, v[152:155], s[12:13] offset:3072 sc1
	s_add_u32 s12, s12, 0x1000
	s_addc_u32 s13, s13, 0
	global_load_dwordx4 v[104:107], v1, s[8:9] offset:2048
	global_load_dwordx4 v[108:111], v1, s[8:9] offset:3072
	s_add_u32 s8, s8, 0x1000
	s_addc_u32 s9, s9, 0
	s_waitcnt vmcnt(26)
	v_lshlrev_b32_e32 v128, 16, v112
	v_and_b32_e32 v129, 0xffff0000, v112
	v_lshlrev_b32_e32 v130, 16, v113
	v_and_b32_e32 v131, 0xffff0000, v113
	v_lshlrev_b32_e32 v132, 16, v114
	v_and_b32_e32 v133, 0xffff0000, v114
	v_lshlrev_b32_e32 v134, 16, v115
	v_and_b32_e32 v135, 0xffff0000, v115
	v_lshlrev_b32_e32 v136, 16, v116
	v_and_b32_e32 v137, 0xffff0000, v116
	v_lshlrev_b32_e32 v138, 16, v117
	v_and_b32_e32 v139, 0xffff0000, v117
	v_lshlrev_b32_e32 v140, 16, v118
	v_and_b32_e32 v141, 0xffff0000, v118
	v_lshlrev_b32_e32 v142, 16, v119
	v_and_b32_e32 v143, 0xffff0000, v119
	v_pk_mul_f32 v[144:145], v[128:129], v[128:129]
	v_pk_fma_f32 v[144:145], v[130:131], v[130:131], v[144:145]
	v_pk_fma_f32 v[144:145], v[132:133], v[132:133], v[144:145]
	v_pk_fma_f32 v[144:145], v[134:135], v[134:135], v[144:145]
	v_pk_fma_f32 v[144:145], v[136:137], v[136:137], v[144:145]
	v_pk_fma_f32 v[144:145], v[138:139], v[138:139], v[144:145]
	v_pk_fma_f32 v[144:145], v[140:141], v[140:141], v[144:145]
	v_pk_fma_f32 v[144:145], v[142:143], v[142:143], v[144:145]
	v_add_f32_e32 v144, v144, v145
	s_nop 1
	v_add_f32_dpp v144, v144, v144 quad_perm:[1,0,3,2] row_mask:0xf bank_mask:0xf
	s_nop 1
	v_add_f32_dpp v144, v144, v144 quad_perm:[2,3,0,1] row_mask:0xf bank_mask:0xf
	s_nop 1
	v_add_f32_dpp v144, v144, v144 row_half_mirror row_mask:0xf bank_mask:0xf
	s_nop 1
	v_add_f32_dpp v144, v144, v144 row_mirror row_mask:0xf bank_mask:0xf
	s_nop 0
	v_mov_b32_e32 v145, v144
	s_nop 1
	v_permlane16_swap_b32_e32 v144, v145
	s_nop 0
	v_add_f32_e32 v144, v144, v145
	v_mov_b32_e32 v145, v144
	s_nop 1
	v_permlane32_swap_b32_e32 v144, v145
	s_nop 0
	v_add_f32_e32 v144, v144, v145
	v_fmamk_f32 v144, v144, 0x3a800000, v3
	v_rsq_f32_e32 v144, v144
	s_nop 0
	v_pk_mul_f32 v[128:129], v[128:129], v[144:145] op_sel_hi:[1,0]
	v_pk_mul_f32 v[130:131], v[130:131], v[144:145] op_sel_hi:[1,0]
	v_pk_mul_f32 v[132:133], v[132:133], v[144:145] op_sel_hi:[1,0]
	v_pk_mul_f32 v[134:135], v[134:135], v[144:145] op_sel_hi:[1,0]
	v_pk_mul_f32 v[136:137], v[136:137], v[144:145] op_sel_hi:[1,0]
	v_pk_mul_f32 v[138:139], v[138:139], v[144:145] op_sel_hi:[1,0]
	v_pk_mul_f32 v[140:141], v[140:141], v[144:145] op_sel_hi:[1,0]
	v_pk_mul_f32 v[142:143], v[142:143], v[144:145] op_sel_hi:[1,0]
	v_pk_mul_f32 v[128:129], v[16:17], v[128:129]
	v_pk_mul_f32 v[130:131], v[18:19], v[130:131]
	v_pk_mul_f32 v[132:133], v[20:21], v[132:133]
	v_pk_mul_f32 v[134:135], v[22:23], v[134:135]
	v_pk_mul_f32 v[136:137], v[24:25], v[136:137]
	v_pk_mul_f32 v[138:139], v[26:27], v[138:139]
	v_pk_mul_f32 v[140:141], v[28:29], v[140:141]
	v_pk_mul_f32 v[142:143], v[30:31], v[142:143]
	v_pk_fma_f32 v[128:129], v[32:33], v[128:129], v[48:49]
	v_pk_fma_f32 v[130:131], v[34:35], v[130:131], v[50:51]
	v_pk_fma_f32 v[132:133], v[36:37], v[132:133], v[52:53]
	v_pk_fma_f32 v[134:135], v[38:39], v[134:135], v[54:55]
	v_pk_fma_f32 v[136:137], v[40:41], v[136:137], v[56:57]
	v_pk_fma_f32 v[138:139], v[42:43], v[138:139], v[58:59]
	v_pk_fma_f32 v[140:141], v[44:45], v[140:141], v[60:61]
	v_pk_fma_f32 v[142:143], v[46:47], v[142:143], v[62:63]
	v_cvt_pk_bf16_f32 v148, v128, v129
	v_cvt_pk_bf16_f32 v149, v130, v131
	v_cvt_pk_bf16_f32 v150, v132, v133
	v_cvt_pk_bf16_f32 v151, v134, v135
	v_cvt_pk_bf16_f32 v152, v136, v137
	v_cvt_pk_bf16_f32 v153, v138, v139
	v_cvt_pk_bf16_f32 v154, v140, v141
	v_cvt_pk_bf16_f32 v155, v142, v143
	global_store_dwordx4 v1, v[148:151], s[12:13] sc1
	global_store_dwordx4 v1, v[152:155], s[12:13] offset:1024 sc1
	global_load_dwordx4 v[112:115], v1, s[8:9]
	global_load_dwordx4 v[116:119], v1, s[8:9] offset:1024
	s_waitcnt vmcnt(28)
; __device__ __forceinline__ unsigned cvt_pk_bf16(float lo, float hi) { unsigned r; asm("v_cvt_pk_bf16_f32 %0, %1, %2" : "=v"(r) : "v"(lo), "v"(hi)); return r; }
; __device__ __forceinline__ void norm_pass_bf16(const Ctx& X, const bf16_t* xs, const bf16_t* cs, int nrows, const float* gain, const float* modl, int si, bf16_t* HN) {
;     ...
;         for (int j = 0; j < 2; ++j) {
;             v[j][0] = bf2f(q[j].x & 0xffffu); v[j][1] = bf2f(q[j].x >> 16); v[j][2] = bf2f(q[j].y & 0xffffu); v[j][3] = bf2f(q[j].y >> 16);
;             v[j][4] = bf2f(q[j].z & 0xffffu); v[j][5] = bf2f(q[j].z >> 16); v[j][6] = bf2f(q[j].w & 0xffffu); v[j][7] = bf2f(q[j].w >> 16);
; #pragma unroll
;             for (int e = 0; e < 8; ++e) s += v[j][e] * v[j][e]; }
;         const float rstd = rsqrtf(wave_sum(s) * (1.0f / 1024.0f) + 1e-6f);
; #pragma unroll
;         for (int j = 0; j < 2; ++j) { const int c = (X.lane + 64 * j) * 8; float o[8];
; #pragma unroll
;             for (int h = 0; h < 2; ++h) { const f32x4 gn = *(const f32x4*)(gain + c + 4 * h), a = *(const f32x4*)(scl + c + 4 * h), b = *(const f32x4*)(sh + c + 4 * h);
; #pragma unroll
;                 for (int e = 0; e < 4; ++e) o[4 * h + e] = v[j][4 * h + e] * rstd * gn[e] * (a[e] + 1.0f) + b[e]; }
;             u32x4 w; w.x = cvt_pk_bf16(o[0], o[1]); w.y = cvt_pk_bf16(o[2], o[3]); w.z = cvt_pk_bf16(o[4], o[5]); w.w = cvt_pk_bf16(o[6], o[7]); *(u32x4*)(HN + (size_t)r * D + c) = w; }
	v_lshlrev_b32_e32 v128, 16, v120
	v_and_b32_e32 v129, 0xffff0000, v120
	v_lshlrev_b32_e32 v130, 16, v121
	v_and_b32_e32 v131, 0xffff0000, v121
	v_lshlrev_b32_e32 v132, 16, v122
	v_and_b32_e32 v133, 0xffff0000, v122
	v_lshlrev_b32_e32 v134, 16, v123
	v_and_b32_e32 v135, 0xffff0000, v123
	v_lshlrev_b32_e32 v136, 16, v124
	v_and_b32_e32 v137, 0xffff0000, v124
	v_lshlrev_b32_e32 v138, 16, v125
	v_and_b32_e32 v139, 0xffff0000, v125
	v_lshlrev_b32_e32 v140, 16, v126
	v_and_b32_e32 v141, 0xffff0000, v126
	v_lshlrev_b32_e32 v142, 16, v127
	v_and_b32_e32 v143, 0xffff0000, v127
	v_pk_mul_f32 v[144:145], v[128:129], v[128:129]
	v_pk_fma_f32 v[144:145], v[130:131], v[130:131], v[144:145]
	v_pk_fma_f32 v[144:145], v[132:133], v[132:133], v[144:145]
	v_pk_fma_f32 v[144:145], v[134:135], v[134:135], v[144:145]
	v_pk_fma_f32 v[144:145], v[136:137], v[136:137], v[144:145]
	v_pk_fma_f32 v[144:145], v[138:139], v[138:139], v[144:145]
	v_pk_fma_f32 v[144:145], v[140:141], v[140:141], v[144:145]
	v_pk_fma_f32 v[144:145], v[142:143], v[142:143], v[144:145]
	v_add_f32_e32 v144, v144, v145
	s_nop 1
	v_add_f32_dpp v144, v144, v144 quad_perm:[1,0,3,2] row_mask:0xf bank_mask:0xf
	s_nop 1
	v_add_f32_dpp v144, v144, v144 quad_perm:[2,3,0,1] row_mask:0xf bank_mask:0xf
	s_nop 1
	v_add_f32_dpp v144, v144, v144 row_half_mirror row_mask:0xf bank_mask:0xf
	s_nop 1
	v_add_f32_dpp v144, v144, v144 row_mirror row_mask:0xf bank_mask:0xf
	s_nop 0
	v_mov_b32_e32 v145, v144
	s_nop 1
	v_permlane16_swap_b32_e32 v144, v145
	s_nop 0
	v_add_f32_e32 v144, v144, v145
	v_mov_b32_e32 v145, v144
	s_nop 1
	v_permlane32_swap_b32_e32 v144, v145
	s_nop 0
	v_add_f32_e32 v144, v144, v145
	v_fmamk_f32 v144, v144, 0x3a800000, v3
	v_rsq_f32_e32 v144, v144
	s_nop 0
	v_pk_mul_f32 v[128:129], v[128:129], v[144:145] op_sel_hi:[1,0]
	v_pk_mul_f32 v[130:131], v[130:131], v[144:145] op_sel_hi:[1,0]
	v_pk_mul_f32 v[132:133], v[132:133], v[144:145] op_sel_hi:[1,0]
	v_pk_mul_f32 v[134:135], v[134:135], v[144:145] op_sel_hi:[1,0]
	v_pk_mul_f32 v[136:137], v[136:137], v[144:145] op_sel_hi:[1,0]
	v_pk_mul_f32 v[138:139], v[138:139], v[144:145] op_sel_hi:[1,0]
	v_pk_mul_f32 v[140:141], v[140:141], v[144:145] op_sel_hi:[1,0]
	v_pk_mul_f32 v[142:143], v[142:143], v[144:145] op_sel_hi:[1,0]
	v_pk_mul_f32 v[128:129], v[16:17], v[128:129]
	v_pk_mul_f32 v[130:131], v[18:19], v[130:131]
	v_pk_mul_f32 v[132:133], v[20:21], v[132:133]
	v_pk_mul_f32 v[134:135], v[22:23], v[134:135]
	v_pk_mul_f32 v[136:137], v[24:25], v[136:137]
	v_pk_mul_f32 v[138:139], v[26:27], v[138:139]
	v_pk_mul_f32 v[140:141], v[28:29], v[140:141]
	v_pk_mul_f32 v[142:143], v[30:31], v[142:143]
	v_pk_fma_f32 v[128:129], v[32:33], v[128:129], v[48:49]
	v_pk_fma_f32 v[130:131], v[34:35], v[130:131], v[50:51]
	v_pk_fma_f32 v[132:133], v[36:37], v[132:133], v[52:53]
	v_pk_fma_f32 v[134:135], v[38:39], v[134:135], v[54:55]
	v_pk_fma_f32 v[136:137], v[40:41], v[136:137], v[56:57]
	v_pk_fma_f32 v[138:139], v[42:43], v[138:139], v[58:59]
	v_pk_fma_f32 v[140:141], v[44:45], v[140:141], v[60:61]
	v_pk_fma_f32 v[142:143], v[46:47], v[142:143], v[62:63]
	v_cvt_pk_bf16_f32 v148, v128, v129
	v_cvt_pk_bf16_f32 v149, v130, v131
	v_cvt_pk_bf16_f32 v150, v132, v133
	v_cvt_pk_bf16_f32 v151, v134, v135
	v_cvt_pk_bf16_f32 v152, v136, v137
	v_cvt_pk_bf16_f32 v153, v138, v139
	v_cvt_pk_bf16_f32 v154, v140, v141
	v_cvt_pk_bf16_f32 v155, v142, v143
	global_store_dwordx4 v1, v[148:151], s[12:13] offset:2048 sc1
	global_store_dwordx4 v1, v[152:155], s[12:13] offset:3072 sc1
	s_add_u32 s12, s12, 0x1000
	s_addc_u32 s13, s13, 0
	global_load_dwordx4 v[120:123], v1, s[8:9] offset:2048
	global_load_dwordx4 v[124:127], v1, s[8:9] offset:3072
	s_add_u32 s8, s8, 0x1000
	s_addc_u32 s9, s9, 0
	s_waitcnt vmcnt(28)
	v_lshlrev_b32_e32 v128, 16, v64
	v_and_b32_e32 v129, 0xffff0000, v64
	v_lshlrev_b32_e32 v130, 16, v65
	v_and_b32_e32 v131, 0xffff0000, v65
	v_lshlrev_b32_e32 v132, 16, v66
	v_and_b32_e32 v133, 0xffff0000, v66
	v_lshlrev_b32_e32 v134, 16, v67
	v_and_b32_e32 v135, 0xffff0000, v67
	v_lshlrev_b32_e32 v136, 16, v68
	v_and_b32_e32 v137, 0xffff0000, v68
	v_lshlrev_b32_e32 v138, 16, v69
	v_and_b32_e32 v139, 0xffff0000, v69
	v_lshlrev_b32_e32 v140, 16, v70
	v_and_b32_e32 v141, 0xffff0000, v70
	v_lshlrev_b32_e32 v142, 16, v71
	v_and_b32_e32 v143, 0xffff0000, v71
	v_pk_mul_f32 v[144:145], v[128:129], v[128:129]
	v_pk_fma_f32 v[144:145], v[130:131], v[130:131], v[144:145]
	v_pk_fma_f32 v[144:145], v[132:133], v[132:133], v[144:145]
	v_pk_fma_f32 v[144:145], v[134:135], v[134:135], v[144:145]
	v_pk_fma_f32 v[144:145], v[136:137], v[136:137], v[144:145]
	v_pk_fma_f32 v[144:145], v[138:139], v[138:139], v[144:145]
	v_pk_fma_f32 v[144:145], v[140:141], v[140:141], v[144:145]
	v_pk_fma_f32 v[144:145], v[142:143], v[142:143], v[144:145]
	v_add_f32_e32 v144, v144, v145
	s_nop 1
	v_add_f32_dpp v144, v144, v144 quad_perm:[1,0,3,2] row_mask:0xf bank_mask:0xf
	s_nop 1
	v_add_f32_dpp v144, v144, v144 quad_perm:[2,3,0,1] row_mask:0xf bank_mask:0xf
	s_nop 1
	v_add_f32_dpp v144, v144, v144 row_half_mirror row_mask:0xf bank_mask:0xf
	s_nop 1
	v_add_f32_dpp v144, v144, v144 row_mirror row_mask:0xf bank_mask:0xf
	s_nop 0
	v_mov_b32_e32 v145, v144
	s_nop 1
	v_permlane16_swap_b32_e32 v144, v145
	s_nop 0
	v_add_f32_e32 v144, v144, v145
	v_mov_b32_e32 v145, v144
	s_nop 1
	v_permlane32_swap_b32_e32 v144, v145
	s_nop 0
	v_add_f32_e32 v144, v144, v145
	v_fmamk_f32 v144, v144, 0x3a800000, v3
	v_rsq_f32_e32 v144, v144
	s_nop 0
	v_pk_mul_f32 v[128:129], v[128:129], v[144:145] op_sel_hi:[1,0]
	v_pk_mul_f32 v[130:131], v[130:131], v[144:145] op_sel_hi:[1,0]
	v_pk_mul_f32 v[132:133], v[132:133], v[144:145] op_sel_hi:[1,0]
; __device__ __forceinline__ unsigned cvt_pk_bf16(float lo, float hi) { unsigned r; asm("v_cvt_pk_bf16_f32 %0, %1, %2" : "=v"(r) : "v"(lo), "v"(hi)); return r; }
; __device__ __forceinline__ void norm_pass_bf16(const Ctx& X, const bf16_t* xs, const bf16_t* cs, int nrows, const float* gain, const float* modl, int si, bf16_t* HN) {
;     ...
;         for (int j = 0; j < 2; ++j) {
;             v[j][0] = bf2f(q[j].x & 0xffffu); v[j][1] = bf2f(q[j].x >> 16); v[j][2] = bf2f(q[j].y & 0xffffu); v[j][3] = bf2f(q[j].y >> 16);
;             v[j][4] = bf2f(q[j].z & 0xffffu); v[j][5] = bf2f(q[j].z >> 16); v[j][6] = bf2f(q[j].w & 0xffffu); v[j][7] = bf2f(q[j].w >> 16);
; #pragma unroll
;             for (int e = 0; e < 8; ++e) s += v[j][e] * v[j][e]; }
;         const float rstd = rsqrtf(wave_sum(s) * (1.0f / 1024.0f) + 1e-6f);
; #pragma unroll
;         for (int j = 0; j < 2; ++j) { const int c = (X.lane + 64 * j) * 8; float o[8];
; #pragma unroll
;             for (int h = 0; h < 2; ++h) { const f32x4 gn = *(const f32x4*)(gain + c + 4 * h), a = *(const f32x4*)(scl + c + 4 * h), b = *(const f32x4*)(sh + c + 4 * h);
; #pragma unroll
;                 for (int e = 0; e < 4; ++e) o[4 * h + e] = v[j][4 * h + e] * rstd * gn[e] * (a[e] + 1.0f) + b[e]; }
;             u32x4 w; w.x = cvt_pk_bf16(o[0], o[1]); w.y = cvt_pk_bf16(o[2], o[3]); w.z = cvt_pk_bf16(o[4], o[5]); w.w = cvt_pk_bf16(o[6], o[7]); *(u32x4*)(HN + (size_t)r * D + c) = w; }
	v_pk_mul_f32 v[134:135], v[134:135], v[144:145] op_sel_hi:[1,0]
	v_pk_mul_f32 v[136:137], v[136:137], v[144:145] op_sel_hi:[1,0]
	v_pk_mul_f32 v[138:139], v[138:139], v[144:145] op_sel_hi:[1,0]
	v_pk_mul_f32 v[140:141], v[140:141], v[144:145] op_sel_hi:[1,0]
	v_pk_mul_f32 v[142:143], v[142:143], v[144:145] op_sel_hi:[1,0]
	v_pk_mul_f32 v[128:129], v[16:17], v[128:129]
	v_pk_mul_f32 v[130:131], v[18:19], v[130:131]
	v_pk_mul_f32 v[132:133], v[20:21], v[132:133]
	v_pk_mul_f32 v[134:135], v[22:23], v[134:135]
	v_pk_mul_f32 v[136:137], v[24:25], v[136:137]
	v_pk_mul_f32 v[138:139], v[26:27], v[138:139]
	v_pk_mul_f32 v[140:141], v[28:29], v[140:141]
	v_pk_mul_f32 v[142:143], v[30:31], v[142:143]
	v_pk_fma_f32 v[128:129], v[32:33], v[128:129], v[48:49]
	v_pk_fma_f32 v[130:131], v[34:35], v[130:131], v[50:51]
	v_pk_fma_f32 v[132:133], v[36:37], v[132:133], v[52:53]
	v_pk_fma_f32 v[134:135], v[38:39], v[134:135], v[54:55]
	v_pk_fma_f32 v[136:137], v[40:41], v[136:137], v[56:57]
	v_pk_fma_f32 v[138:139], v[42:43], v[138:139], v[58:59]
	v_pk_fma_f32 v[140:141], v[44:45], v[140:141], v[60:61]
	v_pk_fma_f32 v[142:143], v[46:47], v[142:143], v[62:63]
	v_cvt_pk_bf16_f32 v148, v128, v129
	v_cvt_pk_bf16_f32 v149, v130, v131
	v_cvt_pk_bf16_f32 v150, v132, v133
	v_cvt_pk_bf16_f32 v151, v134, v135
	v_cvt_pk_bf16_f32 v152, v136, v137
	v_cvt_pk_bf16_f32 v153, v138, v139
	v_cvt_pk_bf16_f32 v154, v140, v141
	v_cvt_pk_bf16_f32 v155, v142, v143
	global_store_dwordx4 v1, v[148:151], s[12:13] sc1
	global_store_dwordx4 v1, v[152:155], s[12:13] offset:1024 sc1
	s_waitcnt vmcnt(26)
	v_lshlrev_b32_e32 v128, 16, v72
	v_and_b32_e32 v129, 0xffff0000, v72
	v_lshlrev_b32_e32 v130, 16, v73
	v_and_b32_e32 v131, 0xffff0000, v73
	v_lshlrev_b32_e32 v132, 16, v74
	v_and_b32_e32 v133, 0xffff0000, v74
	v_lshlrev_b32_e32 v134, 16, v75
	v_and_b32_e32 v135, 0xffff0000, v75
	v_lshlrev_b32_e32 v136, 16, v76
	v_and_b32_e32 v137, 0xffff0000, v76
	v_lshlrev_b32_e32 v138, 16, v77
	v_and_b32_e32 v139, 0xffff0000, v77
	v_lshlrev_b32_e32 v140, 16, v78
	v_and_b32_e32 v141, 0xffff0000, v78
	v_lshlrev_b32_e32 v142, 16, v79
	v_and_b32_e32 v143, 0xffff0000, v79
	v_pk_mul_f32 v[144:145], v[128:129], v[128:129]
	v_pk_fma_f32 v[144:145], v[130:131], v[130:131], v[144:145]
	v_pk_fma_f32 v[144:145], v[132:133], v[132:133], v[144:145]
	v_pk_fma_f32 v[144:145], v[134:135], v[134:135], v[144:145]
	v_pk_fma_f32 v[144:145], v[136:137], v[136:137], v[144:145]
	v_pk_fma_f32 v[144:145], v[138:139], v[138:139], v[144:145]
	v_pk_fma_f32 v[144:145], v[140:141], v[140:141], v[144:145]
	v_pk_fma_f32 v[144:145], v[142:143], v[142:143], v[144:145]
	v_add_f32_e32 v144, v144, v145
	s_nop 1
	v_add_f32_dpp v144, v144, v144 quad_perm:[1,0,3,2] row_mask:0xf bank_mask:0xf
	s_nop 1
	v_add_f32_dpp v144, v144, v144 quad_perm:[2,3,0,1] row_mask:0xf bank_mask:0xf
	s_nop 1
	v_add_f32_dpp v144, v144, v144 row_half_mirror row_mask:0xf bank_mask:0xf
	s_nop 1
	v_add_f32_dpp v144, v144, v144 row_mirror row_mask:0xf bank_mask:0xf
	s_nop 0
	v_mov_b32_e32 v145, v144
	s_nop 1
	v_permlane16_swap_b32_e32 v144, v145
	s_nop 0
	v_add_f32_e32 v144, v144, v145
	v_mov_b32_e32 v145, v144
	s_nop 1
	v_permlane32_swap_b32_e32 v144, v145
	s_nop 0
	v_add_f32_e32 v144, v144, v145
	v_fmamk_f32 v144, v144, 0x3a800000, v3
	v_rsq_f32_e32 v144, v144
	s_nop 0
	v_pk_mul_f32 v[128:129], v[128:129], v[144:145] op_sel_hi:[1,0]
	v_pk_mul_f32 v[130:131], v[130:131], v[144:145] op_sel_hi:[1,0]
	v_pk_mul_f32 v[132:133], v[132:133], v[144:145] op_sel_hi:[1,0]
	v_pk_mul_f32 v[134:135], v[134:135], v[144:145] op_sel_hi:[1,0]
	v_pk_mul_f32 v[136:137], v[136:137], v[144:145] op_sel_hi:[1,0]
	v_pk_mul_f32 v[138:139], v[138:139], v[144:145] op_sel_hi:[1,0]
	v_pk_mul_f32 v[140:141], v[140:141], v[144:145] op_sel_hi:[1,0]
	v_pk_mul_f32 v[142:143], v[142:143], v[144:145] op_sel_hi:[1,0]
	v_pk_mul_f32 v[128:129], v[16:17], v[128:129]
	v_pk_mul_f32 v[130:131], v[18:19], v[130:131]
	v_pk_mul_f32 v[132:133], v[20:21], v[132:133]
	v_pk_mul_f32 v[134:135], v[22:23], v[134:135]
	v_pk_mul_f32 v[136:137], v[24:25], v[136:137]
	v_pk_mul_f32 v[138:139], v[26:27], v[138:139]
	v_pk_mul_f32 v[140:141], v[28:29], v[140:141]
	v_pk_mul_f32 v[142:143], v[30:31], v[142:143]
	v_pk_fma_f32 v[128:129], v[32:33], v[128:129], v[48:49]
	v_pk_fma_f32 v[130:131], v[34:35], v[130:131], v[50:51]
	v_pk_fma_f32 v[132:133], v[36:37], v[132:133], v[52:53]
	v_pk_fma_f32 v[134:135], v[38:39], v[134:135], v[54:55]
	v_pk_fma_f32 v[136:137], v[40:41], v[136:137], v[56:57]
	v_pk_fma_f32 v[138:139], v[42:43], v[138:139], v[58:59]
	v_pk_fma_f32 v[140:141], v[44:45], v[140:141], v[60:61]
	v_pk_fma_f32 v[142:143], v[46:47], v[142:143], v[62:63]
	v_cvt_pk_bf16_f32 v148, v128, v129
	v_cvt_pk_bf16_f32 v149, v130, v131
	v_cvt_pk_bf16_f32 v150, v132, v133
	v_cvt_pk_bf16_f32 v151, v134, v135
	v_cvt_pk_bf16_f32 v152, v136, v137
	v_cvt_pk_bf16_f32 v153, v138, v139
	v_cvt_pk_bf16_f32 v154, v140, v141
	v_cvt_pk_bf16_f32 v155, v142, v143
	global_store_dwordx4 v1, v[148:151], s[12:13] offset:2048 sc1
	global_store_dwordx4 v1, v[152:155], s[12:13] offset:3072 sc1
	s_add_u32 s12, s12, 0x1000
	s_addc_u32 s13, s13, 0
	s_waitcnt vmcnt(24)
; __device__ __forceinline__ unsigned cvt_pk_bf16(float lo, float hi) { unsigned r; asm("v_cvt_pk_bf16_f32 %0, %1, %2" : "=v"(r) : "v"(lo), "v"(hi)); return r; }
; __device__ __forceinline__ void norm_pass_bf16(const Ctx& X, const bf16_t* xs, const bf16_t* cs, int nrows, const float* gain, const float* modl, int si, bf16_t* HN) {
;     ...
;         for (int j = 0; j < 2; ++j) {
;             v[j][0] = bf2f(q[j].x & 0xffffu); v[j][1] = bf2f(q[j].x >> 16); v[j][2] = bf2f(q[j].y & 0xffffu); v[j][3] = bf2f(q[j].y >> 16);
;             v[j][4] = bf2f(q[j].z & 0xffffu); v[j][5] = bf2f(q[j].z >> 16); v[j][6] = bf2f(q[j].w & 0xffffu); v[j][7] = bf2f(q[j].w >> 16);
; #pragma unroll
;             for (int e = 0; e < 8; ++e) s += v[j][e] * v[j][e]; }
;         const float rstd = rsqrtf(wave_sum(s) * (1.0f / 1024.0f) + 1e-6f);
; #pragma unroll
;         for (int j = 0; j < 2; ++j) { const int c = (X.lane + 64 * j) * 8; float o[8];
; #pragma unroll
;             for (int h = 0; h < 2; ++h) { const f32x4 gn = *(const f32x4*)(gain + c + 4 * h), a = *(const f32x4*)(scl + c + 4 * h), b = *(const f32x4*)(sh + c + 4 * h);
; #pragma unroll
;                 for (int e = 0; e < 4; ++e) o[4 * h + e] = v[j][4 * h + e] * rstd * gn[e] * (a[e] + 1.0f) + b[e]; }
;             u32x4 w; w.x = cvt_pk_bf16(o[0], o[1]); w.y = cvt_pk_bf16(o[2], o[3]); w.z = cvt_pk_bf16(o[4], o[5]); w.w = cvt_pk_bf16(o[6], o[7]); *(u32x4*)(HN + (size_t)r * D + c) = w; }
	v_lshlrev_b32_e32 v128, 16, v80
	v_and_b32_e32 v129, 0xffff0000, v80
	v_lshlrev_b32_e32 v130, 16, v81
	v_and_b32_e32 v131, 0xffff0000, v81
	v_lshlrev_b32_e32 v132, 16, v82
	v_and_b32_e32 v133, 0xffff0000, v82
	v_lshlrev_b32_e32 v134, 16, v83
	v_and_b32_e32 v135, 0xffff0000, v83
	v_lshlrev_b32_e32 v136, 16, v84
	v_and_b32_e32 v137, 0xffff0000, v84
	v_lshlrev_b32_e32 v138, 16, v85
	v_and_b32_e32 v139, 0xffff0000, v85
	v_lshlrev_b32_e32 v140, 16, v86
	v_and_b32_e32 v141, 0xffff0000, v86
	v_lshlrev_b32_e32 v142, 16, v87
	v_and_b32_e32 v143, 0xffff0000, v87
	v_pk_mul_f32 v[144:145], v[128:129], v[128:129]
	v_pk_fma_f32 v[144:145], v[130:131], v[130:131], v[144:145]
	v_pk_fma_f32 v[144:145], v[132:133], v[132:133], v[144:145]
	v_pk_fma_f32 v[144:145], v[134:135], v[134:135], v[144:145]
	v_pk_fma_f32 v[144:145], v[136:137], v[136:137], v[144:145]
	v_pk_fma_f32 v[144:145], v[138:139], v[138:139], v[144:145]
	v_pk_fma_f32 v[144:145], v[140:141], v[140:141], v[144:145]
	v_pk_fma_f32 v[144:145], v[142:143], v[142:143], v[144:145]
	v_add_f32_e32 v144, v144, v145
	s_nop 1
	v_add_f32_dpp v144, v144, v144 quad_perm:[1,0,3,2] row_mask:0xf bank_mask:0xf
	s_nop 1
	v_add_f32_dpp v144, v144, v144 quad_perm:[2,3,0,1] row_mask:0xf bank_mask:0xf
	s_nop 1
	v_add_f32_dpp v144, v144, v144 row_half_mirror row_mask:0xf bank_mask:0xf
	s_nop 1
	v_add_f32_dpp v144, v144, v144 row_mirror row_mask:0xf bank_mask:0xf
	s_nop 0
	v_mov_b32_e32 v145, v144
	s_nop 1
	v_permlane16_swap_b32_e32 v144, v145
	s_nop 0
	v_add_f32_e32 v144, v144, v145
	v_mov_b32_e32 v145, v144
	s_nop 1
	v_permlane32_swap_b32_e32 v144, v145
	s_nop 0
	v_add_f32_e32 v144, v144, v145
	v_fmamk_f32 v144, v144, 0x3a800000, v3
	v_rsq_f32_e32 v144, v144
	s_nop 0
	v_pk_mul_f32 v[128:129], v[128:129], v[144:145] op_sel_hi:[1,0]
	v_pk_mul_f32 v[130:131], v[130:131], v[144:145] op_sel_hi:[1,0]
	v_pk_mul_f32 v[132:133], v[132:133], v[144:145] op_sel_hi:[1,0]
	v_pk_mul_f32 v[134:135], v[134:135], v[144:145] op_sel_hi:[1,0]
	v_pk_mul_f32 v[136:137], v[136:137], v[144:145] op_sel_hi:[1,0]
	v_pk_mul_f32 v[138:139], v[138:139], v[144:145] op_sel_hi:[1,0]
	v_pk_mul_f32 v[140:141], v[140:141], v[144:145] op_sel_hi:[1,0]
	v_pk_mul_f32 v[142:143], v[142:143], v[144:145] op_sel_hi:[1,0]
	v_pk_mul_f32 v[128:129], v[16:17], v[128:129]
	v_pk_mul_f32 v[130:131], v[18:19], v[130:131]
	v_pk_mul_f32 v[132:133], v[20:21], v[132:133]
	v_pk_mul_f32 v[134:135], v[22:23], v[134:135]
	v_pk_mul_f32 v[136:137], v[24:25], v[136:137]
	v_pk_mul_f32 v[138:139], v[26:27], v[138:139]
	v_pk_mul_f32 v[140:141], v[28:29], v[140:141]
	v_pk_mul_f32 v[142:143], v[30:31], v[142:143]
	v_pk_fma_f32 v[128:129], v[32:33], v[128:129], v[48:49]
	v_pk_fma_f32 v[130:131], v[34:35], v[130:131], v[50:51]
	v_pk_fma_f32 v[132:133], v[36:37], v[132:133], v[52:53]
	v_pk_fma_f32 v[134:135], v[38:39], v[134:135], v[54:55]
	v_pk_fma_f32 v[136:137], v[40:41], v[136:137], v[56:57]
	v_pk_fma_f32 v[138:139], v[42:43], v[138:139], v[58:59]
	v_pk_fma_f32 v[140:141], v[44:45], v[140:141], v[60:61]
	v_pk_fma_f32 v[142:143], v[46:47], v[142:143], v[62:63]
	v_cvt_pk_bf16_f32 v148, v128, v129
	v_cvt_pk_bf16_f32 v149, v130, v131
	v_cvt_pk_bf16_f32 v150, v132, v133
	v_cvt_pk_bf16_f32 v151, v134, v135
	v_cvt_pk_bf16_f32 v152, v136, v137
	v_cvt_pk_bf16_f32 v153, v138, v139
	v_cvt_pk_bf16_f32 v154, v140, v141
	v_cvt_pk_bf16_f32 v155, v142, v143
	global_store_dwordx4 v1, v[148:151], s[12:13] sc1
	global_store_dwordx4 v1, v[152:155], s[12:13] offset:1024 sc1
	s_waitcnt vmcnt(22)
	v_lshlrev_b32_e32 v128, 16, v88
	v_and_b32_e32 v129, 0xffff0000, v88
	v_lshlrev_b32_e32 v130, 16, v89
	v_and_b32_e32 v131, 0xffff0000, v89
	v_lshlrev_b32_e32 v132, 16, v90
	v_and_b32_e32 v133, 0xffff0000, v90
	v_lshlrev_b32_e32 v134, 16, v91
	v_and_b32_e32 v135, 0xffff0000, v91
	v_lshlrev_b32_e32 v136, 16, v92
	v_and_b32_e32 v137, 0xffff0000, v92
	v_lshlrev_b32_e32 v138, 16, v93
	v_and_b32_e32 v139, 0xffff0000, v93
	v_lshlrev_b32_e32 v140, 16, v94
	v_and_b32_e32 v141, 0xffff0000, v94
	v_lshlrev_b32_e32 v142, 16, v95
	v_and_b32_e32 v143, 0xffff0000, v95
	v_pk_mul_f32 v[144:145], v[128:129], v[128:129]
	v_pk_fma_f32 v[144:145], v[130:131], v[130:131], v[144:145]
	v_pk_fma_f32 v[144:145], v[132:133], v[132:133], v[144:145]
	v_pk_fma_f32 v[144:145], v[134:135], v[134:135], v[144:145]
	v_pk_fma_f32 v[144:145], v[136:137], v[136:137], v[144:145]
	v_pk_fma_f32 v[144:145], v[138:139], v[138:139], v[144:145]
	v_pk_fma_f32 v[144:145], v[140:141], v[140:141], v[144:145]
	v_pk_fma_f32 v[144:145], v[142:143], v[142:143], v[144:145]
	v_add_f32_e32 v144, v144, v145
	s_nop 1
	v_add_f32_dpp v144, v144, v144 quad_perm:[1,0,3,2] row_mask:0xf bank_mask:0xf
	s_nop 1
	v_add_f32_dpp v144, v144, v144 quad_perm:[2,3,0,1] row_mask:0xf bank_mask:0xf
	s_nop 1
	v_add_f32_dpp v144, v144, v144 row_half_mirror row_mask:0xf bank_mask:0xf
	s_nop 1
	v_add_f32_dpp v144, v144, v144 row_mirror row_mask:0xf bank_mask:0xf
	s_nop 0
	v_mov_b32_e32 v145, v144
	s_nop 1
	v_permlane16_swap_b32_e32 v144, v145
	s_nop 0
	v_add_f32_e32 v144, v144, v145
	v_mov_b32_e32 v145, v144
	s_nop 1
	v_permlane32_swap_b32_e32 v144, v145
	s_nop 0
	v_add_f32_e32 v144, v144, v145
	v_fmamk_f32 v144, v144, 0x3a800000, v3
	v_rsq_f32_e32 v144, v144
	s_nop 0
	v_pk_mul_f32 v[128:129], v[128:129], v[144:145] op_sel_hi:[1,0]
	v_pk_mul_f32 v[130:131], v[130:131], v[144:145] op_sel_hi:[1,0]
	v_pk_mul_f32 v[132:133], v[132:133], v[144:145] op_sel_hi:[1,0]
	v_pk_mul_f32 v[134:135], v[134:135], v[144:145] op_sel_hi:[1,0]
	v_pk_mul_f32 v[136:137], v[136:137], v[144:145] op_sel_hi:[1,0]
	v_pk_mul_f32 v[138:139], v[138:139], v[144:145] op_sel_hi:[1,0]
	v_pk_mul_f32 v[140:141], v[140:141], v[144:145] op_sel_hi:[1,0]
; __device__ __forceinline__ unsigned cvt_pk_bf16(float lo, float hi) { unsigned r; asm("v_cvt_pk_bf16_f32 %0, %1, %2" : "=v"(r) : "v"(lo), "v"(hi)); return r; }
; __device__ __forceinline__ void norm_pass_bf16(const Ctx& X, const bf16_t* xs, const bf16_t* cs, int nrows, const float* gain, const float* modl, int si, bf16_t* HN) {
;     ...
;         for (int j = 0; j < 2; ++j) {
;             v[j][0] = bf2f(q[j].x & 0xffffu); v[j][1] = bf2f(q[j].x >> 16); v[j][2] = bf2f(q[j].y & 0xffffu); v[j][3] = bf2f(q[j].y >> 16);
;             v[j][4] = bf2f(q[j].z & 0xffffu); v[j][5] = bf2f(q[j].z >> 16); v[j][6] = bf2f(q[j].w & 0xffffu); v[j][7] = bf2f(q[j].w >> 16);
; #pragma unroll
;             for (int e = 0; e < 8; ++e) s += v[j][e] * v[j][e]; }
;         const float rstd = rsqrtf(wave_sum(s) * (1.0f / 1024.0f) + 1e-6f);
; #pragma unroll
;         for (int j = 0; j < 2; ++j) { const int c = (X.lane + 64 * j) * 8; float o[8];
; #pragma unroll
;             for (int h = 0; h < 2; ++h) { const f32x4 gn = *(const f32x4*)(gain + c + 4 * h), a = *(const f32x4*)(scl + c + 4 * h), b = *(const f32x4*)(sh + c + 4 * h);
; #pragma unroll
;                 for (int e = 0; e < 4; ++e) o[4 * h + e] = v[j][4 * h + e] * rstd * gn[e] * (a[e] + 1.0f) + b[e]; }
;             u32x4 w; w.x = cvt_pk_bf16(o[0], o[1]); w.y = cvt_pk_bf16(o[2], o[3]); w.z = cvt_pk_bf16(o[4], o[5]); w.w = cvt_pk_bf16(o[6], o[7]); *(u32x4*)(HN + (size_t)r * D + c) = w; }
	v_pk_mul_f32 v[142:143], v[142:143], v[144:145] op_sel_hi:[1,0]
	v_pk_mul_f32 v[128:129], v[16:17], v[128:129]
	v_pk_mul_f32 v[130:131], v[18:19], v[130:131]
	v_pk_mul_f32 v[132:133], v[20:21], v[132:133]
	v_pk_mul_f32 v[134:135], v[22:23], v[134:135]
	v_pk_mul_f32 v[136:137], v[24:25], v[136:137]
	v_pk_mul_f32 v[138:139], v[26:27], v[138:139]
	v_pk_mul_f32 v[140:141], v[28:29], v[140:141]
	v_pk_mul_f32 v[142:143], v[30:31], v[142:143]
	v_pk_fma_f32 v[128:129], v[32:33], v[128:129], v[48:49]
	v_pk_fma_f32 v[130:131], v[34:35], v[130:131], v[50:51]
	v_pk_fma_f32 v[132:133], v[36:37], v[132:133], v[52:53]
	v_pk_fma_f32 v[134:135], v[38:39], v[134:135], v[54:55]
	v_pk_fma_f32 v[136:137], v[40:41], v[136:137], v[56:57]
	v_pk_fma_f32 v[138:139], v[42:43], v[138:139], v[58:59]
	v_pk_fma_f32 v[140:141], v[44:45], v[140:141], v[60:61]
	v_pk_fma_f32 v[142:143], v[46:47], v[142:143], v[62:63]
	v_cvt_pk_bf16_f32 v148, v128, v129
	v_cvt_pk_bf16_f32 v149, v130, v131
	v_cvt_pk_bf16_f32 v150, v132, v133
	v_cvt_pk_bf16_f32 v151, v134, v135
	v_cvt_pk_bf16_f32 v152, v136, v137
	v_cvt_pk_bf16_f32 v153, v138, v139
	v_cvt_pk_bf16_f32 v154, v140, v141
	v_cvt_pk_bf16_f32 v155, v142, v143
	global_store_dwordx4 v1, v[148:151], s[12:13] offset:2048 sc1
	global_store_dwordx4 v1, v[152:155], s[12:13] offset:3072 sc1
	s_add_u32 s12, s12, 0x1000
	s_addc_u32 s13, s13, 0
	s_waitcnt vmcnt(20)
	v_lshlrev_b32_e32 v128, 16, v96
	v_and_b32_e32 v129, 0xffff0000, v96
	v_lshlrev_b32_e32 v130, 16, v97
	v_and_b32_e32 v131, 0xffff0000, v97
	v_lshlrev_b32_e32 v132, 16, v98
	v_and_b32_e32 v133, 0xffff0000, v98
	v_lshlrev_b32_e32 v134, 16, v99
	v_and_b32_e32 v135, 0xffff0000, v99
	v_lshlrev_b32_e32 v136, 16, v100
	v_and_b32_e32 v137, 0xffff0000, v100
	v_lshlrev_b32_e32 v138, 16, v101
	v_and_b32_e32 v139, 0xffff0000, v101
	v_lshlrev_b32_e32 v140, 16, v102
	v_and_b32_e32 v141, 0xffff0000, v102
	v_lshlrev_b32_e32 v142, 16, v103
	v_and_b32_e32 v143, 0xffff0000, v103
	v_pk_mul_f32 v[144:145], v[128:129], v[128:129]
	v_pk_fma_f32 v[144:145], v[130:131], v[130:131], v[144:145]
	v_pk_fma_f32 v[144:145], v[132:133], v[132:133], v[144:145]
	v_pk_fma_f32 v[144:145], v[134:135], v[134:135], v[144:145]
	v_pk_fma_f32 v[144:145], v[136:137], v[136:137], v[144:145]
	v_pk_fma_f32 v[144:145], v[138:139], v[138:139], v[144:145]
	v_pk_fma_f32 v[144:145], v[140:141], v[140:141], v[144:145]
	v_pk_fma_f32 v[144:145], v[142:143], v[142:143], v[144:145]
	v_add_f32_e32 v144, v144, v145
	s_nop 1
	v_add_f32_dpp v144, v144, v144 quad_perm:[1,0,3,2] row_mask:0xf bank_mask:0xf
	s_nop 1
	v_add_f32_dpp v144, v144, v144 quad_perm:[2,3,0,1] row_mask:0xf bank_mask:0xf
	s_nop 1
	v_add_f32_dpp v144, v144, v144 row_half_mirror row_mask:0xf bank_mask:0xf
	s_nop 1
	v_add_f32_dpp v144, v144, v144 row_mirror row_mask:0xf bank_mask:0xf
	s_nop 0
	v_mov_b32_e32 v145, v144
	s_nop 1
	v_permlane16_swap_b32_e32 v144, v145
	s_nop 0
	v_add_f32_e32 v144, v144, v145
	v_mov_b32_e32 v145, v144
	s_nop 1
	v_permlane32_swap_b32_e32 v144, v145
	s_nop 0
	v_add_f32_e32 v144, v144, v145
	v_fmamk_f32 v144, v144, 0x3a800000, v3
	v_rsq_f32_e32 v144, v144
	s_nop 0
	v_pk_mul_f32 v[128:129], v[128:129], v[144:145] op_sel_hi:[1,0]
	v_pk_mul_f32 v[130:131], v[130:131], v[144:145] op_sel_hi:[1,0]
	v_pk_mul_f32 v[132:133], v[132:133], v[144:145] op_sel_hi:[1,0]
	v_pk_mul_f32 v[134:135], v[134:135], v[144:145] op_sel_hi:[1,0]
	v_pk_mul_f32 v[136:137], v[136:137], v[144:145] op_sel_hi:[1,0]
	v_pk_mul_f32 v[138:139], v[138:139], v[144:145] op_sel_hi:[1,0]
	v_pk_mul_f32 v[140:141], v[140:141], v[144:145] op_sel_hi:[1,0]
	v_pk_mul_f32 v[142:143], v[142:143], v[144:145] op_sel_hi:[1,0]
	v_pk_mul_f32 v[128:129], v[16:17], v[128:129]
	v_pk_mul_f32 v[130:131], v[18:19], v[130:131]
	v_pk_mul_f32 v[132:133], v[20:21], v[132:133]
	v_pk_mul_f32 v[134:135], v[22:23], v[134:135]
	v_pk_mul_f32 v[136:137], v[24:25], v[136:137]
	v_pk_mul_f32 v[138:139], v[26:27], v[138:139]
	v_pk_mul_f32 v[140:141], v[28:29], v[140:141]
	v_pk_mul_f32 v[142:143], v[30:31], v[142:143]
	v_pk_fma_f32 v[128:129], v[32:33], v[128:129], v[48:49]
	v_pk_fma_f32 v[130:131], v[34:35], v[130:131], v[50:51]
	v_pk_fma_f32 v[132:133], v[36:37], v[132:133], v[52:53]
	v_pk_fma_f32 v[134:135], v[38:39], v[134:135], v[54:55]
	v_pk_fma_f32 v[136:137], v[40:41], v[136:137], v[56:57]
	v_pk_fma_f32 v[138:139], v[42:43], v[138:139], v[58:59]
	v_pk_fma_f32 v[140:141], v[44:45], v[140:141], v[60:61]
	v_pk_fma_f32 v[142:143], v[46:47], v[142:143], v[62:63]
	v_cvt_pk_bf16_f32 v148, v128, v129
	v_cvt_pk_bf16_f32 v149, v130, v131
	v_cvt_pk_bf16_f32 v150, v132, v133
	v_cvt_pk_bf16_f32 v151, v134, v135
	v_cvt_pk_bf16_f32 v152, v136, v137
	v_cvt_pk_bf16_f32 v153, v138, v139
	v_cvt_pk_bf16_f32 v154, v140, v141
	v_cvt_pk_bf16_f32 v155, v142, v143
	global_store_dwordx4 v1, v[148:151], s[12:13] sc1
	global_store_dwordx4 v1, v[152:155], s[12:13] offset:1024 sc1
	s_waitcnt vmcnt(18)
; __device__ __forceinline__ unsigned cvt_pk_bf16(float lo, float hi) { unsigned r; asm("v_cvt_pk_bf16_f32 %0, %1, %2" : "=v"(r) : "v"(lo), "v"(hi)); return r; }
; __device__ __forceinline__ void norm_pass_bf16(const Ctx& X, const bf16_t* xs, const bf16_t* cs, int nrows, const float* gain, const float* modl, int si, bf16_t* HN) {
;     ...
;         for (int j = 0; j < 2; ++j) {
;             v[j][0] = bf2f(q[j].x & 0xffffu); v[j][1] = bf2f(q[j].x >> 16); v[j][2] = bf2f(q[j].y & 0xffffu); v[j][3] = bf2f(q[j].y >> 16);
;             v[j][4] = bf2f(q[j].z & 0xffffu); v[j][5] = bf2f(q[j].z >> 16); v[j][6] = bf2f(q[j].w & 0xffffu); v[j][7] = bf2f(q[j].w >> 16);
; #pragma unroll
;             for (int e = 0; e < 8; ++e) s += v[j][e] * v[j][e]; }
;         const float rstd = rsqrtf(wave_sum(s) * (1.0f / 1024.0f) + 1e-6f);
; #pragma unroll
;         for (int j = 0; j < 2; ++j) { const int c = (X.lane + 64 * j) * 8; float o[8];
; #pragma unroll
;             for (int h = 0; h < 2; ++h) { const f32x4 gn = *(const f32x4*)(gain + c + 4 * h), a = *(const f32x4*)(scl + c + 4 * h), b = *(const f32x4*)(sh + c + 4 * h);
; #pragma unroll
;                 for (int e = 0; e < 4; ++e) o[4 * h + e] = v[j][4 * h + e] * rstd * gn[e] * (a[e] + 1.0f) + b[e]; }
;             u32x4 w; w.x = cvt_pk_bf16(o[0], o[1]); w.y = cvt_pk_bf16(o[2], o[3]); w.z = cvt_pk_bf16(o[4], o[5]); w.w = cvt_pk_bf16(o[6], o[7]); *(u32x4*)(HN + (size_t)r * D + c) = w; }
	v_lshlrev_b32_e32 v128, 16, v104
	v_and_b32_e32 v129, 0xffff0000, v104
	v_lshlrev_b32_e32 v130, 16, v105
	v_and_b32_e32 v131, 0xffff0000, v105
	v_lshlrev_b32_e32 v132, 16, v106
	v_and_b32_e32 v133, 0xffff0000, v106
	v_lshlrev_b32_e32 v134, 16, v107
	v_and_b32_e32 v135, 0xffff0000, v107
	v_lshlrev_b32_e32 v136, 16, v108
	v_and_b32_e32 v137, 0xffff0000, v108
	v_lshlrev_b32_e32 v138, 16, v109
	v_and_b32_e32 v139, 0xffff0000, v109
	v_lshlrev_b32_e32 v140, 16, v110
	v_and_b32_e32 v141, 0xffff0000, v110
	v_lshlrev_b32_e32 v142, 16, v111
	v_and_b32_e32 v143, 0xffff0000, v111
	v_pk_mul_f32 v[144:145], v[128:129], v[128:129]
	v_pk_fma_f32 v[144:145], v[130:131], v[130:131], v[144:145]
	v_pk_fma_f32 v[144:145], v[132:133], v[132:133], v[144:145]
	v_pk_fma_f32 v[144:145], v[134:135], v[134:135], v[144:145]
	v_pk_fma_f32 v[144:145], v[136:137], v[136:137], v[144:145]
	v_pk_fma_f32 v[144:145], v[138:139], v[138:139], v[144:145]
	v_pk_fma_f32 v[144:145], v[140:141], v[140:141], v[144:145]
	v_pk_fma_f32 v[144:145], v[142:143], v[142:143], v[144:145]
	v_add_f32_e32 v144, v144, v145
	s_nop 1
	v_add_f32_dpp v144, v144, v144 quad_perm:[1,0,3,2] row_mask:0xf bank_mask:0xf
	s_nop 1
	v_add_f32_dpp v144, v144, v144 quad_perm:[2,3,0,1] row_mask:0xf bank_mask:0xf
	s_nop 1
	v_add_f32_dpp v144, v144, v144 row_half_mirror row_mask:0xf bank_mask:0xf
	s_nop 1
	v_add_f32_dpp v144, v144, v144 row_mirror row_mask:0xf bank_mask:0xf
	s_nop 0
	v_mov_b32_e32 v145, v144
	s_nop 1
	v_permlane16_swap_b32_e32 v144, v145
	s_nop 0
	v_add_f32_e32 v144, v144, v145
	v_mov_b32_e32 v145, v144
	s_nop 1
	v_permlane32_swap_b32_e32 v144, v145
	s_nop 0
	v_add_f32_e32 v144, v144, v145
	v_fmamk_f32 v144, v144, 0x3a800000, v3
	v_rsq_f32_e32 v144, v144
	s_nop 0
	v_pk_mul_f32 v[128:129], v[128:129], v[144:145] op_sel_hi:[1,0]
	v_pk_mul_f32 v[130:131], v[130:131], v[144:145] op_sel_hi:[1,0]
	v_pk_mul_f32 v[132:133], v[132:133], v[144:145] op_sel_hi:[1,0]
	v_pk_mul_f32 v[134:135], v[134:135], v[144:145] op_sel_hi:[1,0]
	v_pk_mul_f32 v[136:137], v[136:137], v[144:145] op_sel_hi:[1,0]
	v_pk_mul_f32 v[138:139], v[138:139], v[144:145] op_sel_hi:[1,0]
	v_pk_mul_f32 v[140:141], v[140:141], v[144:145] op_sel_hi:[1,0]
	v_pk_mul_f32 v[142:143], v[142:143], v[144:145] op_sel_hi:[1,0]
	v_pk_mul_f32 v[128:129], v[16:17], v[128:129]
	v_pk_mul_f32 v[130:131], v[18:19], v[130:131]
	v_pk_mul_f32 v[132:133], v[20:21], v[132:133]
	v_pk_mul_f32 v[134:135], v[22:23], v[134:135]
	v_pk_mul_f32 v[136:137], v[24:25], v[136:137]
	v_pk_mul_f32 v[138:139], v[26:27], v[138:139]
	v_pk_mul_f32 v[140:141], v[28:29], v[140:141]
	v_pk_mul_f32 v[142:143], v[30:31], v[142:143]
	v_pk_fma_f32 v[128:129], v[32:33], v[128:129], v[48:49]
	v_pk_fma_f32 v[130:131], v[34:35], v[130:131], v[50:51]
	v_pk_fma_f32 v[132:133], v[36:37], v[132:133], v[52:53]
	v_pk_fma_f32 v[134:135], v[38:39], v[134:135], v[54:55]
	v_pk_fma_f32 v[136:137], v[40:41], v[136:137], v[56:57]
	v_pk_fma_f32 v[138:139], v[42:43], v[138:139], v[58:59]
	v_pk_fma_f32 v[140:141], v[44:45], v[140:141], v[60:61]
	v_pk_fma_f32 v[142:143], v[46:47], v[142:143], v[62:63]
	v_cvt_pk_bf16_f32 v148, v128, v129
	v_cvt_pk_bf16_f32 v149, v130, v131
	v_cvt_pk_bf16_f32 v150, v132, v133
	v_cvt_pk_bf16_f32 v151, v134, v135
	v_cvt_pk_bf16_f32 v152, v136, v137
	v_cvt_pk_bf16_f32 v153, v138, v139
	v_cvt_pk_bf16_f32 v154, v140, v141
	v_cvt_pk_bf16_f32 v155, v142, v143
	global_store_dwordx4 v1, v[148:151], s[12:13] offset:2048 sc1
	global_store_dwordx4 v1, v[152:155], s[12:13] offset:3072 sc1
	s_add_u32 s12, s12, 0x1000
	s_addc_u32 s13, s13, 0
	s_waitcnt vmcnt(16)
	v_lshlrev_b32_e32 v128, 16, v112
	v_and_b32_e32 v129, 0xffff0000, v112
	v_lshlrev_b32_e32 v130, 16, v113
	v_and_b32_e32 v131, 0xffff0000, v113
	v_lshlrev_b32_e32 v132, 16, v114
	v_and_b32_e32 v133, 0xffff0000, v114
	v_lshlrev_b32_e32 v134, 16, v115
	v_and_b32_e32 v135, 0xffff0000, v115
	v_lshlrev_b32_e32 v136, 16, v116
	v_and_b32_e32 v137, 0xffff0000, v116
	v_lshlrev_b32_e32 v138, 16, v117
	v_and_b32_e32 v139, 0xffff0000, v117
	v_lshlrev_b32_e32 v140, 16, v118
	v_and_b32_e32 v141, 0xffff0000, v118
	v_lshlrev_b32_e32 v142, 16, v119
	v_and_b32_e32 v143, 0xffff0000, v119
	v_pk_mul_f32 v[144:145], v[128:129], v[128:129]
	v_pk_fma_f32 v[144:145], v[130:131], v[130:131], v[144:145]
	v_pk_fma_f32 v[144:145], v[132:133], v[132:133], v[144:145]
	v_pk_fma_f32 v[144:145], v[134:135], v[134:135], v[144:145]
	v_pk_fma_f32 v[144:145], v[136:137], v[136:137], v[144:145]
	v_pk_fma_f32 v[144:145], v[138:139], v[138:139], v[144:145]
	v_pk_fma_f32 v[144:145], v[140:141], v[140:141], v[144:145]
	v_pk_fma_f32 v[144:145], v[142:143], v[142:143], v[144:145]
	v_add_f32_e32 v144, v144, v145
	s_nop 1
	v_add_f32_dpp v144, v144, v144 quad_perm:[1,0,3,2] row_mask:0xf bank_mask:0xf
	s_nop 1
	v_add_f32_dpp v144, v144, v144 quad_perm:[2,3,0,1] row_mask:0xf bank_mask:0xf
	s_nop 1
	v_add_f32_dpp v144, v144, v144 row_half_mirror row_mask:0xf bank_mask:0xf
	s_nop 1
	v_add_f32_dpp v144, v144, v144 row_mirror row_mask:0xf bank_mask:0xf
	s_nop 0
	v_mov_b32_e32 v145, v144
	s_nop 1
	v_permlane16_swap_b32_e32 v144, v145
	s_nop 0
	v_add_f32_e32 v144, v144, v145
	v_mov_b32_e32 v145, v144
	s_nop 1
	v_permlane32_swap_b32_e32 v144, v145
	s_nop 0
	v_add_f32_e32 v144, v144, v145
	v_fmamk_f32 v144, v144, 0x3a800000, v3
	v_rsq_f32_e32 v144, v144
	s_nop 0
	v_pk_mul_f32 v[128:129], v[128:129], v[144:145] op_sel_hi:[1,0]
; __device__ __forceinline__ unsigned cvt_pk_bf16(float lo, float hi) { unsigned r; asm("v_cvt_pk_bf16_f32 %0, %1, %2" : "=v"(r) : "v"(lo), "v"(hi)); return r; }
; __device__ __forceinline__ void norm_pass_bf16(const Ctx& X, const bf16_t* xs, const bf16_t* cs, int nrows, const float* gain, const float* modl, int si, bf16_t* HN) {
;     ...
;         for (int j = 0; j < 2; ++j) {
;             v[j][0] = bf2f(q[j].x & 0xffffu); v[j][1] = bf2f(q[j].x >> 16); v[j][2] = bf2f(q[j].y & 0xffffu); v[j][3] = bf2f(q[j].y >> 16);
;             v[j][4] = bf2f(q[j].z & 0xffffu); v[j][5] = bf2f(q[j].z >> 16); v[j][6] = bf2f(q[j].w & 0xffffu); v[j][7] = bf2f(q[j].w >> 16);
; #pragma unroll
;             for (int e = 0; e < 8; ++e) s += v[j][e] * v[j][e]; }
;         const float rstd = rsqrtf(wave_sum(s) * (1.0f / 1024.0f) + 1e-6f);
; #pragma unroll
;         for (int j = 0; j < 2; ++j) { const int c = (X.lane + 64 * j) * 8; float o[8];
; #pragma unroll
;             for (int h = 0; h < 2; ++h) { const f32x4 gn = *(const f32x4*)(gain + c + 4 * h), a = *(const f32x4*)(scl + c + 4 * h), b = *(const f32x4*)(sh + c + 4 * h);
; #pragma unroll
;                 for (int e = 0; e < 4; ++e) o[4 * h + e] = v[j][4 * h + e] * rstd * gn[e] * (a[e] + 1.0f) + b[e]; }
;             u32x4 w; w.x = cvt_pk_bf16(o[0], o[1]); w.y = cvt_pk_bf16(o[2], o[3]); w.z = cvt_pk_bf16(o[4], o[5]); w.w = cvt_pk_bf16(o[6], o[7]); *(u32x4*)(HN + (size_t)r * D + c) = w; }
	v_pk_mul_f32 v[130:131], v[130:131], v[144:145] op_sel_hi:[1,0]
	v_pk_mul_f32 v[132:133], v[132:133], v[144:145] op_sel_hi:[1,0]
	v_pk_mul_f32 v[134:135], v[134:135], v[144:145] op_sel_hi:[1,0]
	v_pk_mul_f32 v[136:137], v[136:137], v[144:145] op_sel_hi:[1,0]
	v_pk_mul_f32 v[138:139], v[138:139], v[144:145] op_sel_hi:[1,0]
	v_pk_mul_f32 v[140:141], v[140:141], v[144:145] op_sel_hi:[1,0]
	v_pk_mul_f32 v[142:143], v[142:143], v[144:145] op_sel_hi:[1,0]
	v_pk_mul_f32 v[128:129], v[16:17], v[128:129]
	v_pk_mul_f32 v[130:131], v[18:19], v[130:131]
	v_pk_mul_f32 v[132:133], v[20:21], v[132:133]
	v_pk_mul_f32 v[134:135], v[22:23], v[134:135]
	v_pk_mul_f32 v[136:137], v[24:25], v[136:137]
	v_pk_mul_f32 v[138:139], v[26:27], v[138:139]
	v_pk_mul_f32 v[140:141], v[28:29], v[140:141]
	v_pk_mul_f32 v[142:143], v[30:31], v[142:143]
	v_pk_fma_f32 v[128:129], v[32:33], v[128:129], v[48:49]
	v_pk_fma_f32 v[130:131], v[34:35], v[130:131], v[50:51]
	v_pk_fma_f32 v[132:133], v[36:37], v[132:133], v[52:53]
	v_pk_fma_f32 v[134:135], v[38:39], v[134:135], v[54:55]
	v_pk_fma_f32 v[136:137], v[40:41], v[136:137], v[56:57]
	v_pk_fma_f32 v[138:139], v[42:43], v[138:139], v[58:59]
	v_pk_fma_f32 v[140:141], v[44:45], v[140:141], v[60:61]
	v_pk_fma_f32 v[142:143], v[46:47], v[142:143], v[62:63]
	v_cvt_pk_bf16_f32 v148, v128, v129
	v_cvt_pk_bf16_f32 v149, v130, v131
	v_cvt_pk_bf16_f32 v150, v132, v133
	v_cvt_pk_bf16_f32 v151, v134, v135
	v_cvt_pk_bf16_f32 v152, v136, v137
	v_cvt_pk_bf16_f32 v153, v138, v139
	v_cvt_pk_bf16_f32 v154, v140, v141
	v_cvt_pk_bf16_f32 v155, v142, v143
	global_store_dwordx4 v1, v[148:151], s[12:13] sc1
	global_store_dwordx4 v1, v[152:155], s[12:13] offset:1024 sc1
	s_waitcnt vmcnt(14)
	v_lshlrev_b32_e32 v128, 16, v120
	v_and_b32_e32 v129, 0xffff0000, v120
	v_lshlrev_b32_e32 v130, 16, v121
	v_and_b32_e32 v131, 0xffff0000, v121
	v_lshlrev_b32_e32 v132, 16, v122
	v_and_b32_e32 v133, 0xffff0000, v122
	v_lshlrev_b32_e32 v134, 16, v123
	v_and_b32_e32 v135, 0xffff0000, v123
	v_lshlrev_b32_e32 v136, 16, v124
	v_and_b32_e32 v137, 0xffff0000, v124
	v_lshlrev_b32_e32 v138, 16, v125
	v_and_b32_e32 v139, 0xffff0000, v125
	v_lshlrev_b32_e32 v140, 16, v126
	v_and_b32_e32 v141, 0xffff0000, v126
	v_lshlrev_b32_e32 v142, 16, v127
	v_and_b32_e32 v143, 0xffff0000, v127
	v_pk_mul_f32 v[144:145], v[128:129], v[128:129]
	v_pk_fma_f32 v[144:145], v[130:131], v[130:131], v[144:145]
	v_pk_fma_f32 v[144:145], v[132:133], v[132:133], v[144:145]
	v_pk_fma_f32 v[144:145], v[134:135], v[134:135], v[144:145]
	v_pk_fma_f32 v[144:145], v[136:137], v[136:137], v[144:145]
	v_pk_fma_f32 v[144:145], v[138:139], v[138:139], v[144:145]
	v_pk_fma_f32 v[144:145], v[140:141], v[140:141], v[144:145]
	v_pk_fma_f32 v[144:145], v[142:143], v[142:143], v[144:145]
	v_add_f32_e32 v144, v144, v145
	s_nop 1
	v_add_f32_dpp v144, v144, v144 quad_perm:[1,0,3,2] row_mask:0xf bank_mask:0xf
	s_nop 1
	v_add_f32_dpp v144, v144, v144 quad_perm:[2,3,0,1] row_mask:0xf bank_mask:0xf
	s_nop 1
	v_add_f32_dpp v144, v144, v144 row_half_mirror row_mask:0xf bank_mask:0xf
	s_nop 1
	v_add_f32_dpp v144, v144, v144 row_mirror row_mask:0xf bank_mask:0xf
	s_nop 0
	v_mov_b32_e32 v145, v144
	s_nop 1
	v_permlane16_swap_b32_e32 v144, v145
	s_nop 0
	v_add_f32_e32 v144, v144, v145
	v_mov_b32_e32 v145, v144
	s_nop 1
	v_permlane32_swap_b32_e32 v144, v145
	s_nop 0
	v_add_f32_e32 v144, v144, v145
	v_fmamk_f32 v144, v144, 0x3a800000, v3
	v_rsq_f32_e32 v144, v144
	s_nop 0
	v_pk_mul_f32 v[128:129], v[128:129], v[144:145] op_sel_hi:[1,0]
	v_pk_mul_f32 v[130:131], v[130:131], v[144:145] op_sel_hi:[1,0]
	v_pk_mul_f32 v[132:133], v[132:133], v[144:145] op_sel_hi:[1,0]
	v_pk_mul_f32 v[134:135], v[134:135], v[144:145] op_sel_hi:[1,0]
	v_pk_mul_f32 v[136:137], v[136:137], v[144:145] op_sel_hi:[1,0]
	v_pk_mul_f32 v[138:139], v[138:139], v[144:145] op_sel_hi:[1,0]
	v_pk_mul_f32 v[140:141], v[140:141], v[144:145] op_sel_hi:[1,0]
	v_pk_mul_f32 v[142:143], v[142:143], v[144:145] op_sel_hi:[1,0]
	v_pk_mul_f32 v[128:129], v[16:17], v[128:129]
	v_pk_mul_f32 v[130:131], v[18:19], v[130:131]
	v_pk_mul_f32 v[132:133], v[20:21], v[132:133]
	v_pk_mul_f32 v[134:135], v[22:23], v[134:135]
	v_pk_mul_f32 v[136:137], v[24:25], v[136:137]
	v_pk_mul_f32 v[138:139], v[26:27], v[138:139]
	v_pk_mul_f32 v[140:141], v[28:29], v[140:141]
	v_pk_mul_f32 v[142:143], v[30:31], v[142:143]
	v_pk_fma_f32 v[128:129], v[32:33], v[128:129], v[48:49]
	v_pk_fma_f32 v[130:131], v[34:35], v[130:131], v[50:51]
	v_pk_fma_f32 v[132:133], v[36:37], v[132:133], v[52:53]
	v_pk_fma_f32 v[134:135], v[38:39], v[134:135], v[54:55]
	v_pk_fma_f32 v[136:137], v[40:41], v[136:137], v[56:57]
	v_pk_fma_f32 v[138:139], v[42:43], v[138:139], v[58:59]
	v_pk_fma_f32 v[140:141], v[44:45], v[140:141], v[60:61]
	v_pk_fma_f32 v[142:143], v[46:47], v[142:143], v[62:63]
	v_cvt_pk_bf16_f32 v148, v128, v129
	v_cvt_pk_bf16_f32 v149, v130, v131
	v_cvt_pk_bf16_f32 v150, v132, v133
	v_cvt_pk_bf16_f32 v151, v134, v135
	v_cvt_pk_bf16_f32 v152, v136, v137
	v_cvt_pk_bf16_f32 v153, v138, v139
	v_cvt_pk_bf16_f32 v154, v140, v141
	v_cvt_pk_bf16_f32 v155, v142, v143
	global_store_dwordx4 v1, v[148:151], s[12:13] offset:2048 sc1
	global_store_dwordx4 v1, v[152:155], s[12:13] offset:3072 sc1
	s_add_u32 s12, s12, 0x1000
	s_addc_u32 s13, s13, 0
	s_add_i32 s21, s21, s20
	s_cmp_lt_i32 s21, 0x800
	s_cbranch_scc0 .LBB0_1801
	s_waitcnt vmcnt(0)
	s_branch .Lhn_E_blk
